# v15 + 2-trip pair passes as straight-line code: both iterations' LDS reads issued up front (second data set in v188-v217), twiddle setup under the reads
# baseline (speedup 1.0000x reference)
; DI float2 twid(float r) { return float2{__builtin_amdgcn_cosf(r), -__builtin_amdgcn_sinf(r)}; }
;   const int lq2 = lq1 - 2, Q1 = 1 << lq1, Q2 = 1 << lq2; const float invM1 = 1.f / (float)(4 << lq1), invM2 = 1.f / (float)(4 << lq2);
;   for (int gg = tid; gg < NBT * (N / 16); gg += NTHR) { const int g = gg & (N / 16 - 1); float2* z = z0 + (gg / (N / 16)) * N; const int jp = g & (Q2 - 1), base = ((g >> lq2) << (lq2 + 4)) + jp; float2 x[4][4];
; #pragma unroll
;     for (int q1 = 0; q1 < 4; ++q1)
; #pragma unroll
;       for (int q2 = 0; q2 < 4; ++q2) x[q1][q2] = z[base + q1 * Q1 + q2 * Q2];
; #pragma unroll
;     for (int q2 = 0; q2 < 4; ++q2) bfly_fwd(x[0][q2], x[1][q2], x[2][q2], x[3][q2], (float)(jp + q2 * Q2) * invM1, x[0][q2], x[1][q2], x[2][q2], x[3][q2]);
; #pragma unroll
;     for (int q1 = 0; q1 < 4; ++q1) bfly_fwd(x[q1][0], x[q1][1], x[q1][2], x[q1][3], (float)jp * invM2, x[q1][0], x[q1][1], x[q1][2], x[q1][3]);
; #pragma unroll
;     for (int q1 = 0; q1 < 4; ++q1)
; #pragma unroll
;       for (int q2 = 0; q2 < 4; ++q2) z[base + q1 * Q1 + q2 * Q2] = x[q1][q2]; }
;   __syncthreads();
; }
; template <int LOGN, bool R2DONE = false> DI void fft_fwd(float2* z, int tid) {
;   constexpr int N = 1 << LOGN;
;   if constexpr (LOGN & 1) {
;     if constexpr (!R2DONE) {
;       for (int b = tid; b < N / 2; b += NTHR) { float2 a0 = z[b], a1 = z[b + N / 2]; float2 w = twid((float)b * (1.f / N));
;         z[b] = float2{a0.x + a1.x, a0.y + a1.y}; z[b + N / 2] = cmul(float2{a0.x - a1.x, a0.y - a1.y}, w); }
;       __syncthreads();
;     }
;     fft_pair_fwd<N>(z, tid, 10); fft_pair_fwd<N>(z, tid, 6); fft_level_fwd<N>(z, tid, 2); fft_level_fwd<N>(z, tid, 0);
;   } else {
;     if constexpr (!R2DONE) fft_level_fwd<N>(z, tid, 12);
;     fft_pair_fwd<N>(z, tid, 10); fft_pair_fwd<N>(z, tid, 6); fft_level_fwd<N>(z, tid, 2); fft_level_fwd<N>(z, tid, 0);
;   }
; }
.LBB0_1518:
	v_ashrrev_i32_e32 v216, 31, v73
	v_lshrrev_b32_e32 v216, 22, v216
	v_add_lshl_u32 v216, v73, v216, 7
	v_and_b32_e32 v216, 0xfffe0000, v216
	v_and_b32_e32 v217, 0x3000, v72
	v_add_u32_e32 v216, 16, v216
	v_lshlrev_b32_e32 v217, 3, v217
	v_lshlrev_b32_sdwa v148, v151, v10 dst_sel:DWORD dst_unused:UNUSED_PAD src0_sel:DWORD src1_sel:BYTE_0
	v_add3_u32 v251, v216, v217, v148
	ds_read2st64_b64 v[78:81], v251 offset1:4
	ds_read2st64_b64 v[82:85], v251 offset0:8 offset1:12
	ds_read2st64_b64 v[86:89], v251 offset0:16 offset1:20
	ds_read2st64_b64 v[92:95], v251 offset0:24 offset1:28
	ds_read2st64_b64 v[96:99], v251 offset0:32 offset1:36
	ds_read2st64_b64 v[100:103], v251 offset0:40 offset1:44
	ds_read2st64_b64 v[104:107], v251 offset0:48 offset1:52
	ds_read2st64_b64 v[108:111], v251 offset0:56 offset1:60
	v_add_u32_e32 v72, 0x2000, v72
	v_add_u32_e32 v74, 0x200, v73
	v_mov_b32_e32 v73, v74
	v_ashrrev_i32_e32 v136, 31, v73
	v_lshrrev_b32_e32 v136, 22, v136
	v_add_lshl_u32 v136, v73, v136, 7
	v_and_b32_e32 v136, 0xfffe0000, v136
	v_and_b32_e32 v137, 0x3000, v72
	v_add_u32_e32 v136, 16, v136
	v_lshlrev_b32_e32 v137, 3, v137
	v_lshlrev_b32_sdwa v138, v151, v10 dst_sel:DWORD dst_unused:UNUSED_PAD src0_sel:DWORD src1_sel:BYTE_0
	v_add3_u32 v139, v136, v137, v138
	ds_read2st64_b64 v[188:191], v139 offset1:4
	ds_read2st64_b64 v[192:195], v139 offset0:8 offset1:12
	ds_read2st64_b64 v[196:199], v139 offset0:16 offset1:20
	ds_read2st64_b64 v[200:203], v139 offset0:24 offset1:28
	ds_read2st64_b64 v[204:207], v139 offset0:32 offset1:36
	ds_read2st64_b64 v[208:211], v139 offset0:40 offset1:44
	ds_read2st64_b64 v[212:215], v139 offset0:48 offset1:52
	ds_read2st64_b64 v[252:255], v139 offset0:56 offset1:60
	v_add_u32_e32 v72, 0x2000, v72
	v_add_u32_e32 v74, 0x200, v73
	v_mov_b32_e32 v73, v74
	v_and_b32_e32 v241, 0xff, v73
	v_cvt_f32_u32_e32 v250, v241
	v_mul_f32_e32 v250, 0x39800000, v250
	v_cos_f32_e32 v218, v250
	v_sin_f32_e32 v219, v250
	s_nop 1
	v_xor_b32_e32 v219, 0x80000000, v219
	s_nop 0
	v_pk_mul_f32 v[128:129], v[218:219], v[218:219] op_sel:[1,1] op_sel_hi:[1,0]
	s_nop 0
	v_pk_fma_f32 v[220:221], v[218:219], v[218:219], v[128:129] op_sel_hi:[0,1,1] neg_lo:[0,0,1]
	s_nop 0
	v_pk_mul_f32 v[128:129], v[220:221], v[218:219] op_sel:[1,1] op_sel_hi:[1,0]
	s_nop 0
	v_pk_fma_f32 v[222:223], v[220:221], v[218:219], v[128:129] op_sel_hi:[0,1,1] neg_lo:[0,0,1]
	v_pk_mul_f32 v[128:129], v[220:221], v[220:221] op_sel:[1,1] op_sel_hi:[1,0]
	s_nop 0
	v_pk_fma_f32 v[244:245], v[220:221], v[220:221], v[128:129] op_sel_hi:[0,1,1] neg_lo:[0,0,1]
	s_nop 0
	v_mul_f32_e32 v241, 0x3ec3ef15, v219
	v_mul_f32_e32 v250, 0xbec3ef15, v218
	v_fmamk_f32 v224, v218, 0x3f6c835e, v241
	v_fmamk_f32 v225, v219, 0x3f6c835e, v250
	v_mul_f32_e32 v241, 0x3f3504f3, v219
	v_mul_f32_e32 v250, 0xbf3504f3, v218
	v_fmamk_f32 v230, v218, 0x3f3504f3, v241
	v_fmamk_f32 v231, v219, 0x3f3504f3, v250
	v_mul_f32_e32 v241, 0x3f6c835e, v219
	v_mul_f32_e32 v250, 0xbf6c835e, v218
	v_fmamk_f32 v236, v218, 0x3ec3ef15, v241
	v_fmamk_f32 v237, v219, 0x3ec3ef15, v250
	v_mul_f32_e32 v241, 0x3f3504f3, v221
	v_mul_f32_e32 v250, 0xbf3504f3, v220
	v_fmamk_f32 v226, v220, 0x3f3504f3, v241
	v_fmamk_f32 v227, v221, 0x3f3504f3, v250
	v_mul_f32_e32 v241, 0x3f800000, v221
	v_mul_f32_e32 v250, 0xbf800000, v220
	v_fmamk_f32 v232, v220, 0x00000000, v241
	v_fmamk_f32 v233, v221, 0x00000000, v250
	v_mul_f32_e32 v241, 0x3f3504f3, v221
	v_mul_f32_e32 v250, 0xbf3504f3, v220
	v_fmamk_f32 v238, v220, 0xbf3504f3, v241
	v_fmamk_f32 v239, v221, 0xbf3504f3, v250
	v_mul_f32_e32 v241, 0x3f6c835e, v223
	v_mul_f32_e32 v250, 0xbf6c835e, v222
	v_fmamk_f32 v228, v222, 0x3ec3ef15, v241
	v_fmamk_f32 v229, v223, 0x3ec3ef15, v250
	v_mul_f32_e32 v241, 0x3f3504f3, v223
	v_mul_f32_e32 v250, 0xbf3504f3, v222
	v_fmamk_f32 v234, v222, 0xbf3504f3, v241
	v_fmamk_f32 v235, v223, 0xbf3504f3, v250
	v_mul_f32_e32 v241, 0xbec3ef15, v223
	v_mul_f32_e32 v250, 0x3ec3ef15, v222
	v_fmamk_f32 v242, v222, 0xbf6c835e, v241
	v_fmamk_f32 v243, v223, 0xbf6c835e, v250
	v_pk_mul_f32 v[128:129], v[244:245], v[244:245] op_sel:[1,1] op_sel_hi:[1,0]
	s_nop 0
	v_pk_fma_f32 v[246:247], v[244:245], v[244:245], v[128:129] op_sel_hi:[0,1,1] neg_lo:[0,0,1]
	s_nop 0
	v_pk_mul_f32 v[128:129], v[246:247], v[244:245] op_sel:[1,1] op_sel_hi:[1,0]
	s_nop 0
	v_pk_fma_f32 v[248:249], v[246:247], v[244:245], v[128:129] op_sel_hi:[0,1,1] neg_lo:[0,0,1]
	s_nop 0
	s_waitcnt lgkmcnt(8)
; DI float2 twid(float r) { return float2{__builtin_amdgcn_cosf(r), -__builtin_amdgcn_sinf(r)}; }
; DI void bfly_fwd(float2 a0, float2 a1, float2 a2, float2 a3, float r, float2& o0, float2& o1, float2& o2, float2& o3) {
;   float2 t0 = {a0.x + a2.x, a0.y + a2.y}, t1 = {a0.x - a2.x, a0.y - a2.y}, t2 = {a1.x + a3.x, a1.y + a3.y}, t3 = {a1.x - a3.x, a1.y - a3.y};
;   float2 b0 = {t0.x + t2.x, t0.y + t2.y}, b2 = {t0.x - t2.x, t0.y - t2.y}, b1 = {t1.x + t3.y, t1.y - t3.x}, b3 = {t1.x - t3.y, t1.y + t3.x};
;   float2 w1 = twid(r), w2 = cmul(w1, w1), w3 = cmul(w2, w1);
;   o0 = b0; o1 = cmul(b1, w1); o2 = cmul(b2, w2); o3 = cmul(b3, w3);
; }
;   const int lq2 = lq1 - 2, Q1 = 1 << lq1, Q2 = 1 << lq2; const float invM1 = 1.f / (float)(4 << lq1), invM2 = 1.f / (float)(4 << lq2);
;   for (int gg = tid; gg < NBT * (N / 16); gg += NTHR) { const int g = gg & (N / 16 - 1); float2* z = z0 + (gg / (N / 16)) * N; const int jp = g & (Q2 - 1), base = ((g >> lq2) << (lq2 + 4)) + jp; float2 x[4][4];
; #pragma unroll
;     for (int q1 = 0; q1 < 4; ++q1)
; #pragma unroll
;       for (int q2 = 0; q2 < 4; ++q2) x[q1][q2] = z[base + q1 * Q1 + q2 * Q2];
; #pragma unroll
;     for (int q2 = 0; q2 < 4; ++q2) bfly_fwd(x[0][q2], x[1][q2], x[2][q2], x[3][q2], (float)(jp + q2 * Q2) * invM1, x[0][q2], x[1][q2], x[2][q2], x[3][q2]);
; #pragma unroll
;     for (int q1 = 0; q1 < 4; ++q1) bfly_fwd(x[q1][0], x[q1][1], x[q1][2], x[q1][3], (float)jp * invM2, x[q1][0], x[q1][1], x[q1][2], x[q1][3]);
; #pragma unroll
;     for (int q1 = 0; q1 < 4; ++q1)
; #pragma unroll
;       for (int q2 = 0; q2 < 4; ++q2) z[base + q1 * Q1 + q2 * Q2] = x[q1][q2]; }
;   __syncthreads();
; }
	v_pk_add_f32 v[112:113], v[78:79], v[96:97]
	v_pk_add_f32 v[120:121], v[80:81], v[98:99]
	v_pk_add_f32 v[116:117], v[86:87], v[104:105]
	v_pk_add_f32 v[124:125], v[88:89], v[106:107]
	v_pk_add_f32 v[114:115], v[78:79], v[96:97] neg_lo:[0,1] neg_hi:[0,1]
	v_pk_add_f32 v[122:123], v[80:81], v[98:99] neg_lo:[0,1] neg_hi:[0,1]
	v_pk_add_f32 v[118:119], v[86:87], v[104:105] neg_lo:[0,1] neg_hi:[0,1]
	v_pk_add_f32 v[126:127], v[88:89], v[106:107] neg_lo:[0,1] neg_hi:[0,1]
	v_pk_add_f32 v[78:79], v[112:113], v[116:117]
	v_pk_add_f32 v[80:81], v[120:121], v[124:125]
	v_pk_add_f32 v[112:113], v[112:113], v[116:117] neg_lo:[0,1] neg_hi:[0,1]
	v_pk_add_f32 v[120:121], v[120:121], v[124:125] neg_lo:[0,1] neg_hi:[0,1]
	v_pk_add_f32 v[116:117], v[114:115], v[118:119] op_sel:[0,1] op_sel_hi:[1,0] neg_hi:[0,1]
	v_pk_add_f32 v[124:125], v[122:123], v[126:127] op_sel:[0,1] op_sel_hi:[1,0] neg_hi:[0,1]
	v_pk_add_f32 v[114:115], v[114:115], v[118:119] op_sel:[0,1] op_sel_hi:[1,0] neg_lo:[0,1]
	v_pk_add_f32 v[122:123], v[122:123], v[126:127] op_sel:[0,1] op_sel_hi:[1,0] neg_lo:[0,1]
	v_pk_mul_f32 v[128:129], v[112:113], v[220:221] op_sel:[1,1] op_sel_hi:[1,0]
	v_pk_mul_f32 v[132:133], v[120:121], v[226:227] op_sel:[1,1] op_sel_hi:[1,0]
	v_pk_mul_f32 v[130:131], v[116:117], v[218:219] op_sel:[1,1] op_sel_hi:[1,0]
	v_pk_mul_f32 v[134:135], v[124:125], v[224:225] op_sel:[1,1] op_sel_hi:[1,0]
	v_pk_fma_f32 v[96:97], v[112:113], v[220:221], v[128:129] op_sel_hi:[0,1,1] neg_lo:[0,0,1]
	v_pk_fma_f32 v[98:99], v[120:121], v[226:227], v[132:133] op_sel_hi:[0,1,1] neg_lo:[0,0,1]
	v_pk_mul_f32 v[128:129], v[114:115], v[222:223] op_sel:[1,1] op_sel_hi:[1,0]
	v_pk_mul_f32 v[132:133], v[122:123], v[228:229] op_sel:[1,1] op_sel_hi:[1,0]
	v_pk_fma_f32 v[86:87], v[116:117], v[218:219], v[130:131] op_sel_hi:[0,1,1] neg_lo:[0,0,1]
	v_pk_fma_f32 v[88:89], v[124:125], v[224:225], v[134:135] op_sel_hi:[0,1,1] neg_lo:[0,0,1]
	v_pk_fma_f32 v[104:105], v[114:115], v[222:223], v[128:129] op_sel_hi:[0,1,1] neg_lo:[0,0,1]
	v_pk_fma_f32 v[106:107], v[122:123], v[228:229], v[132:133] op_sel_hi:[0,1,1] neg_lo:[0,0,1]
	v_pk_add_f32 v[112:113], v[82:83], v[100:101]
	v_pk_add_f32 v[120:121], v[84:85], v[102:103]
	v_pk_add_f32 v[116:117], v[92:93], v[108:109]
	v_pk_add_f32 v[124:125], v[94:95], v[110:111]
	v_pk_add_f32 v[114:115], v[82:83], v[100:101] neg_lo:[0,1] neg_hi:[0,1]
	v_pk_add_f32 v[122:123], v[84:85], v[102:103] neg_lo:[0,1] neg_hi:[0,1]
	v_pk_add_f32 v[118:119], v[92:93], v[108:109] neg_lo:[0,1] neg_hi:[0,1]
	v_pk_add_f32 v[126:127], v[94:95], v[110:111] neg_lo:[0,1] neg_hi:[0,1]
	v_pk_add_f32 v[82:83], v[112:113], v[116:117]
	v_pk_add_f32 v[84:85], v[120:121], v[124:125]
	v_pk_add_f32 v[112:113], v[112:113], v[116:117] neg_lo:[0,1] neg_hi:[0,1]
	v_pk_add_f32 v[120:121], v[120:121], v[124:125] neg_lo:[0,1] neg_hi:[0,1]
	v_pk_add_f32 v[116:117], v[114:115], v[118:119] op_sel:[0,1] op_sel_hi:[1,0] neg_hi:[0,1]
	v_pk_add_f32 v[124:125], v[122:123], v[126:127] op_sel:[0,1] op_sel_hi:[1,0] neg_hi:[0,1]
	v_pk_add_f32 v[114:115], v[114:115], v[118:119] op_sel:[0,1] op_sel_hi:[1,0] neg_lo:[0,1]
	v_pk_add_f32 v[122:123], v[122:123], v[126:127] op_sel:[0,1] op_sel_hi:[1,0] neg_lo:[0,1]
	v_pk_mul_f32 v[128:129], v[112:113], v[232:233] op_sel:[1,1] op_sel_hi:[1,0]
	v_pk_mul_f32 v[132:133], v[120:121], v[238:239] op_sel:[1,1] op_sel_hi:[1,0]
	v_pk_mul_f32 v[130:131], v[116:117], v[230:231] op_sel:[1,1] op_sel_hi:[1,0]
	v_pk_mul_f32 v[134:135], v[124:125], v[236:237] op_sel:[1,1] op_sel_hi:[1,0]
	v_pk_fma_f32 v[100:101], v[112:113], v[232:233], v[128:129] op_sel_hi:[0,1,1] neg_lo:[0,0,1]
	v_pk_fma_f32 v[102:103], v[120:121], v[238:239], v[132:133] op_sel_hi:[0,1,1] neg_lo:[0,0,1]
	v_pk_mul_f32 v[128:129], v[114:115], v[234:235] op_sel:[1,1] op_sel_hi:[1,0]
	v_pk_mul_f32 v[132:133], v[122:123], v[242:243] op_sel:[1,1] op_sel_hi:[1,0]
	v_pk_fma_f32 v[92:93], v[116:117], v[230:231], v[130:131] op_sel_hi:[0,1,1] neg_lo:[0,0,1]
	v_pk_fma_f32 v[94:95], v[124:125], v[236:237], v[134:135] op_sel_hi:[0,1,1] neg_lo:[0,0,1]
	v_pk_fma_f32 v[108:109], v[114:115], v[234:235], v[128:129] op_sel_hi:[0,1,1] neg_lo:[0,0,1]
	v_pk_fma_f32 v[110:111], v[122:123], v[242:243], v[132:133] op_sel_hi:[0,1,1] neg_lo:[0,0,1]
	v_pk_add_f32 v[112:113], v[78:79], v[82:83]
	v_pk_add_f32 v[120:121], v[86:87], v[92:93]
	v_pk_add_f32 v[116:117], v[80:81], v[84:85]
	v_pk_add_f32 v[124:125], v[88:89], v[94:95]
	v_pk_add_f32 v[114:115], v[78:79], v[82:83] neg_lo:[0,1] neg_hi:[0,1]
	v_pk_add_f32 v[122:123], v[86:87], v[92:93] neg_lo:[0,1] neg_hi:[0,1]
	v_pk_add_f32 v[118:119], v[80:81], v[84:85] neg_lo:[0,1] neg_hi:[0,1]
	v_pk_add_f32 v[126:127], v[88:89], v[94:95] neg_lo:[0,1] neg_hi:[0,1]
	v_pk_add_f32 v[78:79], v[112:113], v[116:117]
	v_pk_add_f32 v[86:87], v[120:121], v[124:125]
	v_pk_add_f32 v[112:113], v[112:113], v[116:117] neg_lo:[0,1] neg_hi:[0,1]
	v_pk_add_f32 v[120:121], v[120:121], v[124:125] neg_lo:[0,1] neg_hi:[0,1]
	v_pk_add_f32 v[116:117], v[114:115], v[118:119] op_sel:[0,1] op_sel_hi:[1,0] neg_hi:[0,1]
	v_pk_add_f32 v[124:125], v[122:123], v[126:127] op_sel:[0,1] op_sel_hi:[1,0] neg_hi:[0,1]
	v_pk_add_f32 v[114:115], v[114:115], v[118:119] op_sel:[0,1] op_sel_hi:[1,0] neg_lo:[0,1]
	v_pk_add_f32 v[122:123], v[122:123], v[126:127] op_sel:[0,1] op_sel_hi:[1,0] neg_lo:[0,1]
	v_pk_mul_f32 v[128:129], v[112:113], v[246:247] op_sel:[1,1] op_sel_hi:[1,0]
	v_pk_mul_f32 v[132:133], v[120:121], v[246:247] op_sel:[1,1] op_sel_hi:[1,0]
	v_pk_mul_f32 v[130:131], v[116:117], v[244:245] op_sel:[1,1] op_sel_hi:[1,0]
	v_pk_mul_f32 v[134:135], v[124:125], v[244:245] op_sel:[1,1] op_sel_hi:[1,0]
;   const int lq2 = lq1 - 2, Q1 = 1 << lq1, Q2 = 1 << lq2; const float invM1 = 1.f / (float)(4 << lq1), invM2 = 1.f / (float)(4 << lq2);
;   for (int gg = tid; gg < NBT * (N / 16); gg += NTHR) { const int g = gg & (N / 16 - 1); float2* z = z0 + (gg / (N / 16)) * N; const int jp = g & (Q2 - 1), base = ((g >> lq2) << (lq2 + 4)) + jp; float2 x[4][4];
; #pragma unroll
;     for (int q1 = 0; q1 < 4; ++q1)
; #pragma unroll
;       for (int q2 = 0; q2 < 4; ++q2) x[q1][q2] = z[base + q1 * Q1 + q2 * Q2];
; #pragma unroll
;     for (int q2 = 0; q2 < 4; ++q2) bfly_fwd(x[0][q2], x[1][q2], x[2][q2], x[3][q2], (float)(jp + q2 * Q2) * invM1, x[0][q2], x[1][q2], x[2][q2], x[3][q2]);
; #pragma unroll
;     for (int q1 = 0; q1 < 4; ++q1) bfly_fwd(x[q1][0], x[q1][1], x[q1][2], x[q1][3], (float)jp * invM2, x[q1][0], x[q1][1], x[q1][2], x[q1][3]);
; #pragma unroll
;     for (int q1 = 0; q1 < 4; ++q1)
; #pragma unroll
;       for (int q2 = 0; q2 < 4; ++q2) z[base + q1 * Q1 + q2 * Q2] = x[q1][q2]; }
;   __syncthreads();
; }
	v_pk_fma_f32 v[82:83], v[112:113], v[246:247], v[128:129] op_sel_hi:[0,1,1] neg_lo:[0,0,1]
	v_pk_fma_f32 v[92:93], v[120:121], v[246:247], v[132:133] op_sel_hi:[0,1,1] neg_lo:[0,0,1]
	v_pk_mul_f32 v[128:129], v[114:115], v[248:249] op_sel:[1,1] op_sel_hi:[1,0]
	v_pk_mul_f32 v[132:133], v[122:123], v[248:249] op_sel:[1,1] op_sel_hi:[1,0]
	v_pk_fma_f32 v[80:81], v[116:117], v[244:245], v[130:131] op_sel_hi:[0,1,1] neg_lo:[0,0,1]
	v_pk_fma_f32 v[88:89], v[124:125], v[244:245], v[134:135] op_sel_hi:[0,1,1] neg_lo:[0,0,1]
	v_pk_fma_f32 v[84:85], v[114:115], v[248:249], v[128:129] op_sel_hi:[0,1,1] neg_lo:[0,0,1]
	v_pk_fma_f32 v[94:95], v[122:123], v[248:249], v[132:133] op_sel_hi:[0,1,1] neg_lo:[0,0,1]
	v_pk_add_f32 v[112:113], v[96:97], v[100:101]
	v_pk_add_f32 v[120:121], v[104:105], v[108:109]
	v_pk_add_f32 v[116:117], v[98:99], v[102:103]
	v_pk_add_f32 v[124:125], v[106:107], v[110:111]
	v_pk_add_f32 v[114:115], v[96:97], v[100:101] neg_lo:[0,1] neg_hi:[0,1]
	v_pk_add_f32 v[122:123], v[104:105], v[108:109] neg_lo:[0,1] neg_hi:[0,1]
	v_pk_add_f32 v[118:119], v[98:99], v[102:103] neg_lo:[0,1] neg_hi:[0,1]
	v_pk_add_f32 v[126:127], v[106:107], v[110:111] neg_lo:[0,1] neg_hi:[0,1]
	v_pk_add_f32 v[96:97], v[112:113], v[116:117]
	v_pk_add_f32 v[104:105], v[120:121], v[124:125]
	v_pk_add_f32 v[112:113], v[112:113], v[116:117] neg_lo:[0,1] neg_hi:[0,1]
	v_pk_add_f32 v[120:121], v[120:121], v[124:125] neg_lo:[0,1] neg_hi:[0,1]
	v_pk_add_f32 v[116:117], v[114:115], v[118:119] op_sel:[0,1] op_sel_hi:[1,0] neg_hi:[0,1]
	v_pk_add_f32 v[124:125], v[122:123], v[126:127] op_sel:[0,1] op_sel_hi:[1,0] neg_hi:[0,1]
	v_pk_add_f32 v[114:115], v[114:115], v[118:119] op_sel:[0,1] op_sel_hi:[1,0] neg_lo:[0,1]
	v_pk_add_f32 v[122:123], v[122:123], v[126:127] op_sel:[0,1] op_sel_hi:[1,0] neg_lo:[0,1]
	v_pk_mul_f32 v[128:129], v[112:113], v[246:247] op_sel:[1,1] op_sel_hi:[1,0]
	v_pk_mul_f32 v[132:133], v[120:121], v[246:247] op_sel:[1,1] op_sel_hi:[1,0]
	v_pk_mul_f32 v[130:131], v[116:117], v[244:245] op_sel:[1,1] op_sel_hi:[1,0]
	v_pk_mul_f32 v[134:135], v[124:125], v[244:245] op_sel:[1,1] op_sel_hi:[1,0]
	v_pk_fma_f32 v[100:101], v[112:113], v[246:247], v[128:129] op_sel_hi:[0,1,1] neg_lo:[0,0,1]
	v_pk_fma_f32 v[108:109], v[120:121], v[246:247], v[132:133] op_sel_hi:[0,1,1] neg_lo:[0,0,1]
	v_pk_mul_f32 v[128:129], v[114:115], v[248:249] op_sel:[1,1] op_sel_hi:[1,0]
	v_pk_mul_f32 v[132:133], v[122:123], v[248:249] op_sel:[1,1] op_sel_hi:[1,0]
	v_pk_fma_f32 v[98:99], v[116:117], v[244:245], v[130:131] op_sel_hi:[0,1,1] neg_lo:[0,0,1]
	v_pk_fma_f32 v[106:107], v[124:125], v[244:245], v[134:135] op_sel_hi:[0,1,1] neg_lo:[0,0,1]
	v_pk_fma_f32 v[102:103], v[114:115], v[248:249], v[128:129] op_sel_hi:[0,1,1] neg_lo:[0,0,1]
	v_pk_fma_f32 v[110:111], v[122:123], v[248:249], v[132:133] op_sel_hi:[0,1,1] neg_lo:[0,0,1]
	s_nop 0
	ds_write2st64_b64 v251, v[78:79], v[80:81] offset1:4
	ds_write2st64_b64 v251, v[82:83], v[84:85] offset0:8 offset1:12
	ds_write2st64_b64 v251, v[86:87], v[88:89] offset0:16 offset1:20
	ds_write2st64_b64 v251, v[92:93], v[94:95] offset0:24 offset1:28
	ds_write2st64_b64 v251, v[96:97], v[98:99] offset0:32 offset1:36
	ds_write2st64_b64 v251, v[100:101], v[102:103] offset0:40 offset1:44
	ds_write2st64_b64 v251, v[104:105], v[106:107] offset0:48 offset1:52
	ds_write2st64_b64 v251, v[108:109], v[110:111] offset0:56 offset1:60
	s_waitcnt lgkmcnt(8)
	v_pk_add_f32 v[112:113], v[188:189], v[204:205]
	v_pk_add_f32 v[120:121], v[190:191], v[206:207]
	v_pk_add_f32 v[116:117], v[196:197], v[212:213]
	v_pk_add_f32 v[124:125], v[198:199], v[214:215]
	v_pk_add_f32 v[114:115], v[188:189], v[204:205] neg_lo:[0,1] neg_hi:[0,1]
	v_pk_add_f32 v[122:123], v[190:191], v[206:207] neg_lo:[0,1] neg_hi:[0,1]
	v_pk_add_f32 v[118:119], v[196:197], v[212:213] neg_lo:[0,1] neg_hi:[0,1]
	v_pk_add_f32 v[126:127], v[198:199], v[214:215] neg_lo:[0,1] neg_hi:[0,1]
	v_pk_add_f32 v[188:189], v[112:113], v[116:117]
	v_pk_add_f32 v[190:191], v[120:121], v[124:125]
	v_pk_add_f32 v[112:113], v[112:113], v[116:117] neg_lo:[0,1] neg_hi:[0,1]
	v_pk_add_f32 v[120:121], v[120:121], v[124:125] neg_lo:[0,1] neg_hi:[0,1]
	v_pk_add_f32 v[116:117], v[114:115], v[118:119] op_sel:[0,1] op_sel_hi:[1,0] neg_hi:[0,1]
	v_pk_add_f32 v[124:125], v[122:123], v[126:127] op_sel:[0,1] op_sel_hi:[1,0] neg_hi:[0,1]
	v_pk_add_f32 v[114:115], v[114:115], v[118:119] op_sel:[0,1] op_sel_hi:[1,0] neg_lo:[0,1]
	v_pk_add_f32 v[122:123], v[122:123], v[126:127] op_sel:[0,1] op_sel_hi:[1,0] neg_lo:[0,1]
	v_pk_mul_f32 v[128:129], v[112:113], v[220:221] op_sel:[1,1] op_sel_hi:[1,0]
	v_pk_mul_f32 v[132:133], v[120:121], v[226:227] op_sel:[1,1] op_sel_hi:[1,0]
	v_pk_mul_f32 v[130:131], v[116:117], v[218:219] op_sel:[1,1] op_sel_hi:[1,0]
	v_pk_mul_f32 v[134:135], v[124:125], v[224:225] op_sel:[1,1] op_sel_hi:[1,0]
	v_pk_fma_f32 v[204:205], v[112:113], v[220:221], v[128:129] op_sel_hi:[0,1,1] neg_lo:[0,0,1]
	v_pk_fma_f32 v[206:207], v[120:121], v[226:227], v[132:133] op_sel_hi:[0,1,1] neg_lo:[0,0,1]
	v_pk_mul_f32 v[128:129], v[114:115], v[222:223] op_sel:[1,1] op_sel_hi:[1,0]
	v_pk_mul_f32 v[132:133], v[122:123], v[228:229] op_sel:[1,1] op_sel_hi:[1,0]
	v_pk_fma_f32 v[196:197], v[116:117], v[218:219], v[130:131] op_sel_hi:[0,1,1] neg_lo:[0,0,1]
	v_pk_fma_f32 v[198:199], v[124:125], v[224:225], v[134:135] op_sel_hi:[0,1,1] neg_lo:[0,0,1]
	v_pk_fma_f32 v[212:213], v[114:115], v[222:223], v[128:129] op_sel_hi:[0,1,1] neg_lo:[0,0,1]
	v_pk_fma_f32 v[214:215], v[122:123], v[228:229], v[132:133] op_sel_hi:[0,1,1] neg_lo:[0,0,1]
	v_pk_add_f32 v[112:113], v[192:193], v[208:209]
	v_pk_add_f32 v[120:121], v[194:195], v[210:211]
;   const int lq2 = lq1 - 2, Q1 = 1 << lq1, Q2 = 1 << lq2; const float invM1 = 1.f / (float)(4 << lq1), invM2 = 1.f / (float)(4 << lq2);
;   for (int gg = tid; gg < NBT * (N / 16); gg += NTHR) { const int g = gg & (N / 16 - 1); float2* z = z0 + (gg / (N / 16)) * N; const int jp = g & (Q2 - 1), base = ((g >> lq2) << (lq2 + 4)) + jp; float2 x[4][4];
; #pragma unroll
;     for (int q1 = 0; q1 < 4; ++q1)
; #pragma unroll
;       for (int q2 = 0; q2 < 4; ++q2) x[q1][q2] = z[base + q1 * Q1 + q2 * Q2];
; #pragma unroll
;     for (int q2 = 0; q2 < 4; ++q2) bfly_fwd(x[0][q2], x[1][q2], x[2][q2], x[3][q2], (float)(jp + q2 * Q2) * invM1, x[0][q2], x[1][q2], x[2][q2], x[3][q2]);
; #pragma unroll
;     for (int q1 = 0; q1 < 4; ++q1) bfly_fwd(x[q1][0], x[q1][1], x[q1][2], x[q1][3], (float)jp * invM2, x[q1][0], x[q1][1], x[q1][2], x[q1][3]);
; #pragma unroll
;     for (int q1 = 0; q1 < 4; ++q1)
; #pragma unroll
;       for (int q2 = 0; q2 < 4; ++q2) z[base + q1 * Q1 + q2 * Q2] = x[q1][q2]; }
;   __syncthreads();
; }
	v_pk_add_f32 v[116:117], v[200:201], v[252:253]
	v_pk_add_f32 v[124:125], v[202:203], v[254:255]
	v_pk_add_f32 v[114:115], v[192:193], v[208:209] neg_lo:[0,1] neg_hi:[0,1]
	v_pk_add_f32 v[122:123], v[194:195], v[210:211] neg_lo:[0,1] neg_hi:[0,1]
	v_pk_add_f32 v[118:119], v[200:201], v[252:253] neg_lo:[0,1] neg_hi:[0,1]
	v_pk_add_f32 v[126:127], v[202:203], v[254:255] neg_lo:[0,1] neg_hi:[0,1]
	v_pk_add_f32 v[192:193], v[112:113], v[116:117]
	v_pk_add_f32 v[194:195], v[120:121], v[124:125]
	v_pk_add_f32 v[112:113], v[112:113], v[116:117] neg_lo:[0,1] neg_hi:[0,1]
	v_pk_add_f32 v[120:121], v[120:121], v[124:125] neg_lo:[0,1] neg_hi:[0,1]
	v_pk_add_f32 v[116:117], v[114:115], v[118:119] op_sel:[0,1] op_sel_hi:[1,0] neg_hi:[0,1]
	v_pk_add_f32 v[124:125], v[122:123], v[126:127] op_sel:[0,1] op_sel_hi:[1,0] neg_hi:[0,1]
	v_pk_add_f32 v[114:115], v[114:115], v[118:119] op_sel:[0,1] op_sel_hi:[1,0] neg_lo:[0,1]
	v_pk_add_f32 v[122:123], v[122:123], v[126:127] op_sel:[0,1] op_sel_hi:[1,0] neg_lo:[0,1]
	v_pk_mul_f32 v[128:129], v[112:113], v[232:233] op_sel:[1,1] op_sel_hi:[1,0]
	v_pk_mul_f32 v[132:133], v[120:121], v[238:239] op_sel:[1,1] op_sel_hi:[1,0]
	v_pk_mul_f32 v[130:131], v[116:117], v[230:231] op_sel:[1,1] op_sel_hi:[1,0]
	v_pk_mul_f32 v[134:135], v[124:125], v[236:237] op_sel:[1,1] op_sel_hi:[1,0]
	v_pk_fma_f32 v[208:209], v[112:113], v[232:233], v[128:129] op_sel_hi:[0,1,1] neg_lo:[0,0,1]
	v_pk_fma_f32 v[210:211], v[120:121], v[238:239], v[132:133] op_sel_hi:[0,1,1] neg_lo:[0,0,1]
	v_pk_mul_f32 v[128:129], v[114:115], v[234:235] op_sel:[1,1] op_sel_hi:[1,0]
	v_pk_mul_f32 v[132:133], v[122:123], v[242:243] op_sel:[1,1] op_sel_hi:[1,0]
	v_pk_fma_f32 v[200:201], v[116:117], v[230:231], v[130:131] op_sel_hi:[0,1,1] neg_lo:[0,0,1]
	v_pk_fma_f32 v[202:203], v[124:125], v[236:237], v[134:135] op_sel_hi:[0,1,1] neg_lo:[0,0,1]
	v_pk_fma_f32 v[252:253], v[114:115], v[234:235], v[128:129] op_sel_hi:[0,1,1] neg_lo:[0,0,1]
	v_pk_fma_f32 v[254:255], v[122:123], v[242:243], v[132:133] op_sel_hi:[0,1,1] neg_lo:[0,0,1]
	v_pk_add_f32 v[112:113], v[188:189], v[192:193]
	v_pk_add_f32 v[120:121], v[196:197], v[200:201]
	v_pk_add_f32 v[116:117], v[190:191], v[194:195]
	v_pk_add_f32 v[124:125], v[198:199], v[202:203]
	v_pk_add_f32 v[114:115], v[188:189], v[192:193] neg_lo:[0,1] neg_hi:[0,1]
	v_pk_add_f32 v[122:123], v[196:197], v[200:201] neg_lo:[0,1] neg_hi:[0,1]
	v_pk_add_f32 v[118:119], v[190:191], v[194:195] neg_lo:[0,1] neg_hi:[0,1]
	v_pk_add_f32 v[126:127], v[198:199], v[202:203] neg_lo:[0,1] neg_hi:[0,1]
	v_pk_add_f32 v[188:189], v[112:113], v[116:117]
	v_pk_add_f32 v[196:197], v[120:121], v[124:125]
	v_pk_add_f32 v[112:113], v[112:113], v[116:117] neg_lo:[0,1] neg_hi:[0,1]
	v_pk_add_f32 v[120:121], v[120:121], v[124:125] neg_lo:[0,1] neg_hi:[0,1]
	v_pk_add_f32 v[116:117], v[114:115], v[118:119] op_sel:[0,1] op_sel_hi:[1,0] neg_hi:[0,1]
	v_pk_add_f32 v[124:125], v[122:123], v[126:127] op_sel:[0,1] op_sel_hi:[1,0] neg_hi:[0,1]
	v_pk_add_f32 v[114:115], v[114:115], v[118:119] op_sel:[0,1] op_sel_hi:[1,0] neg_lo:[0,1]
	v_pk_add_f32 v[122:123], v[122:123], v[126:127] op_sel:[0,1] op_sel_hi:[1,0] neg_lo:[0,1]
	v_pk_mul_f32 v[128:129], v[112:113], v[246:247] op_sel:[1,1] op_sel_hi:[1,0]
	v_pk_mul_f32 v[132:133], v[120:121], v[246:247] op_sel:[1,1] op_sel_hi:[1,0]
	v_pk_mul_f32 v[130:131], v[116:117], v[244:245] op_sel:[1,1] op_sel_hi:[1,0]
	v_pk_mul_f32 v[134:135], v[124:125], v[244:245] op_sel:[1,1] op_sel_hi:[1,0]
	v_pk_fma_f32 v[192:193], v[112:113], v[246:247], v[128:129] op_sel_hi:[0,1,1] neg_lo:[0,0,1]
	v_pk_fma_f32 v[200:201], v[120:121], v[246:247], v[132:133] op_sel_hi:[0,1,1] neg_lo:[0,0,1]
	v_pk_mul_f32 v[128:129], v[114:115], v[248:249] op_sel:[1,1] op_sel_hi:[1,0]
	v_pk_mul_f32 v[132:133], v[122:123], v[248:249] op_sel:[1,1] op_sel_hi:[1,0]
	v_pk_fma_f32 v[190:191], v[116:117], v[244:245], v[130:131] op_sel_hi:[0,1,1] neg_lo:[0,0,1]
	v_pk_fma_f32 v[198:199], v[124:125], v[244:245], v[134:135] op_sel_hi:[0,1,1] neg_lo:[0,0,1]
	v_pk_fma_f32 v[194:195], v[114:115], v[248:249], v[128:129] op_sel_hi:[0,1,1] neg_lo:[0,0,1]
	v_pk_fma_f32 v[202:203], v[122:123], v[248:249], v[132:133] op_sel_hi:[0,1,1] neg_lo:[0,0,1]
	v_pk_add_f32 v[112:113], v[204:205], v[208:209]
	v_pk_add_f32 v[120:121], v[212:213], v[252:253]
	v_pk_add_f32 v[116:117], v[206:207], v[210:211]
	v_pk_add_f32 v[124:125], v[214:215], v[254:255]
	v_pk_add_f32 v[114:115], v[204:205], v[208:209] neg_lo:[0,1] neg_hi:[0,1]
	v_pk_add_f32 v[122:123], v[212:213], v[252:253] neg_lo:[0,1] neg_hi:[0,1]
	v_pk_add_f32 v[118:119], v[206:207], v[210:211] neg_lo:[0,1] neg_hi:[0,1]
	v_pk_add_f32 v[126:127], v[214:215], v[254:255] neg_lo:[0,1] neg_hi:[0,1]
	v_pk_add_f32 v[204:205], v[112:113], v[116:117]
	v_pk_add_f32 v[212:213], v[120:121], v[124:125]
	v_pk_add_f32 v[112:113], v[112:113], v[116:117] neg_lo:[0,1] neg_hi:[0,1]
	v_pk_add_f32 v[120:121], v[120:121], v[124:125] neg_lo:[0,1] neg_hi:[0,1]
	v_pk_add_f32 v[116:117], v[114:115], v[118:119] op_sel:[0,1] op_sel_hi:[1,0] neg_hi:[0,1]
	v_pk_add_f32 v[124:125], v[122:123], v[126:127] op_sel:[0,1] op_sel_hi:[1,0] neg_hi:[0,1]
	v_pk_add_f32 v[114:115], v[114:115], v[118:119] op_sel:[0,1] op_sel_hi:[1,0] neg_lo:[0,1]
	v_pk_add_f32 v[122:123], v[122:123], v[126:127] op_sel:[0,1] op_sel_hi:[1,0] neg_lo:[0,1]
	v_pk_mul_f32 v[128:129], v[112:113], v[246:247] op_sel:[1,1] op_sel_hi:[1,0]
	v_pk_mul_f32 v[132:133], v[120:121], v[246:247] op_sel:[1,1] op_sel_hi:[1,0]
	v_pk_mul_f32 v[130:131], v[116:117], v[244:245] op_sel:[1,1] op_sel_hi:[1,0]
	v_pk_mul_f32 v[134:135], v[124:125], v[244:245] op_sel:[1,1] op_sel_hi:[1,0]
	v_pk_fma_f32 v[208:209], v[112:113], v[246:247], v[128:129] op_sel_hi:[0,1,1] neg_lo:[0,0,1]
	v_pk_fma_f32 v[252:253], v[120:121], v[246:247], v[132:133] op_sel_hi:[0,1,1] neg_lo:[0,0,1]
	v_pk_mul_f32 v[128:129], v[114:115], v[248:249] op_sel:[1,1] op_sel_hi:[1,0]
	v_pk_mul_f32 v[132:133], v[122:123], v[248:249] op_sel:[1,1] op_sel_hi:[1,0]
	v_pk_fma_f32 v[206:207], v[116:117], v[244:245], v[130:131] op_sel_hi:[0,1,1] neg_lo:[0,0,1]
	v_pk_fma_f32 v[214:215], v[124:125], v[244:245], v[134:135] op_sel_hi:[0,1,1] neg_lo:[0,0,1]
	v_pk_fma_f32 v[210:211], v[114:115], v[248:249], v[128:129] op_sel_hi:[0,1,1] neg_lo:[0,0,1]
	v_pk_fma_f32 v[254:255], v[122:123], v[248:249], v[132:133] op_sel_hi:[0,1,1] neg_lo:[0,0,1]
	s_nop 0
	ds_write2st64_b64 v139, v[188:189], v[190:191] offset1:4
	ds_write2st64_b64 v139, v[192:193], v[194:195] offset0:8 offset1:12
	ds_write2st64_b64 v139, v[196:197], v[198:199] offset0:16 offset1:20
	ds_write2st64_b64 v139, v[200:201], v[202:203] offset0:24 offset1:28
	ds_write2st64_b64 v139, v[204:205], v[206:207] offset0:32 offset1:36
	ds_write2st64_b64 v139, v[208:209], v[210:211] offset0:40 offset1:44
	ds_write2st64_b64 v139, v[212:213], v[214:215] offset0:48 offset1:52
	ds_write2st64_b64 v139, v[252:253], v[254:255] offset0:56 offset1:60
	s_mov_b64 s[12:13], exec

;   const int lq2 = lq1 - 2, Q1 = 1 << lq1, Q2 = 1 << lq2; const float invM1 = 1.f / (float)(4 << lq1), invM2 = 1.f / (float)(4 << lq2);
;   for (int gg = tid; gg < NBT * (N / 16); gg += NTHR) { const int g = gg & (N / 16 - 1); float2* z = z0 + (gg / (N / 16)) * N; const int jp = g & (Q2 - 1), base = ((g >> lq2) << (lq2 + 4)) + jp; float2 x[4][4];
; #pragma unroll
;     for (int q1 = 0; q1 < 4; ++q1)
; #pragma unroll
;       for (int q2 = 0; q2 < 4; ++q2) x[q1][q2] = z[base + q1 * Q1 + q2 * Q2];
; #pragma unroll
;     for (int q2 = 0; q2 < 4; ++q2) bfly_fwd(x[0][q2], x[1][q2], x[2][q2], x[3][q2], (float)(jp + q2 * Q2) * invM1, x[0][q2], x[1][q2], x[2][q2], x[3][q2]);
; #pragma unroll
;     for (int q1 = 0; q1 < 4; ++q1) bfly_fwd(x[q1][0], x[q1][1], x[q1][2], x[q1][3], (float)jp * invM2, x[q1][0], x[q1][1], x[q1][2], x[q1][3]);
; #pragma unroll
;     for (int q1 = 0; q1 < 4; ++q1)
; #pragma unroll
;       for (int q2 = 0; q2 < 4; ++q2) z[base + q1 * Q1 + q2 * Q2] = x[q1][q2]; }
;   __syncthreads();
; }
.LBB0_1521:
	v_ashrrev_i32_e32 v216, 31, v73
	v_lshrrev_b32_e32 v216, 22, v216
	v_add_lshl_u32 v216, v73, v216, 7
	v_and_b32_e32 v216, 0xfffe0000, v216
	v_and_b32_e32 v217, 0x3f00, v11
	v_add_u32_e32 v216, 16, v216
	v_lshlrev_b32_e32 v217, 3, v217
	v_lshlrev_b32_e32 v148, 3, v72
	v_add3_u32 v251, v216, v217, v148
	ds_read2_b64 v[78:81], v251 offset1:16
	ds_read2_b64 v[82:85], v251 offset0:32 offset1:48
	ds_read2_b64 v[86:89], v251 offset0:64 offset1:80
	ds_read2_b64 v[92:95], v251 offset0:96 offset1:112
	ds_read2_b64 v[96:99], v251 offset0:128 offset1:144
	ds_read2_b64 v[100:103], v251 offset0:160 offset1:176
	ds_read2_b64 v[104:107], v251 offset0:192 offset1:208
	ds_read2_b64 v[108:111], v251 offset0:224 offset1:240
	v_add_u32_e32 v11, 0x2000, v11
	v_add_u32_e32 v74, 0x200, v73
	v_mov_b32_e32 v73, v74
	v_ashrrev_i32_e32 v136, 31, v73
	v_lshrrev_b32_e32 v136, 22, v136
	v_add_lshl_u32 v136, v73, v136, 7
	v_and_b32_e32 v136, 0xfffe0000, v136
	v_and_b32_e32 v137, 0x3f00, v11
	v_add_u32_e32 v136, 16, v136
	v_lshlrev_b32_e32 v137, 3, v137
	v_lshlrev_b32_e32 v138, 3, v72
	v_add3_u32 v139, v136, v137, v138
	ds_read2_b64 v[188:191], v139 offset1:16
	ds_read2_b64 v[192:195], v139 offset0:32 offset1:48
	ds_read2_b64 v[196:199], v139 offset0:64 offset1:80
	ds_read2_b64 v[200:203], v139 offset0:96 offset1:112
	ds_read2_b64 v[204:207], v139 offset0:128 offset1:144
	ds_read2_b64 v[208:211], v139 offset0:160 offset1:176
	ds_read2_b64 v[212:215], v139 offset0:192 offset1:208
	ds_read2_b64 v[252:255], v139 offset0:224 offset1:240
	v_add_u32_e32 v11, 0x2000, v11
	v_add_u32_e32 v74, 0x200, v73
	v_mov_b32_e32 v73, v74
	v_and_b32_e32 v241, 0xf, v73
	v_cvt_f32_u32_e32 v250, v241
	v_mul_f32_e32 v250, 0x3b800000, v250
	v_cos_f32_e32 v218, v250
	v_sin_f32_e32 v219, v250
	s_nop 1
	v_xor_b32_e32 v219, 0x80000000, v219
	s_nop 0
	v_pk_mul_f32 v[128:129], v[218:219], v[218:219] op_sel:[1,1] op_sel_hi:[1,0]
	s_nop 0
	v_pk_fma_f32 v[220:221], v[218:219], v[218:219], v[128:129] op_sel_hi:[0,1,1] neg_lo:[0,0,1]
	s_nop 0
	v_pk_mul_f32 v[128:129], v[220:221], v[218:219] op_sel:[1,1] op_sel_hi:[1,0]
	s_nop 0
	v_pk_fma_f32 v[222:223], v[220:221], v[218:219], v[128:129] op_sel_hi:[0,1,1] neg_lo:[0,0,1]
	v_pk_mul_f32 v[128:129], v[220:221], v[220:221] op_sel:[1,1] op_sel_hi:[1,0]
	s_nop 0
	v_pk_fma_f32 v[244:245], v[220:221], v[220:221], v[128:129] op_sel_hi:[0,1,1] neg_lo:[0,0,1]
	s_nop 0
	v_mul_f32_e32 v241, 0x3ec3ef15, v219
	v_mul_f32_e32 v250, 0xbec3ef15, v218
	v_fmamk_f32 v224, v218, 0x3f6c835e, v241
	v_fmamk_f32 v225, v219, 0x3f6c835e, v250
	v_mul_f32_e32 v241, 0x3f3504f3, v219
	v_mul_f32_e32 v250, 0xbf3504f3, v218
	v_fmamk_f32 v230, v218, 0x3f3504f3, v241
	v_fmamk_f32 v231, v219, 0x3f3504f3, v250
	v_mul_f32_e32 v241, 0x3f6c835e, v219
	v_mul_f32_e32 v250, 0xbf6c835e, v218
	v_fmamk_f32 v236, v218, 0x3ec3ef15, v241
	v_fmamk_f32 v237, v219, 0x3ec3ef15, v250
	v_mul_f32_e32 v241, 0x3f3504f3, v221
	v_mul_f32_e32 v250, 0xbf3504f3, v220
	v_fmamk_f32 v226, v220, 0x3f3504f3, v241
	v_fmamk_f32 v227, v221, 0x3f3504f3, v250
	v_mul_f32_e32 v241, 0x3f800000, v221
	v_mul_f32_e32 v250, 0xbf800000, v220
	v_fmamk_f32 v232, v220, 0x00000000, v241
	v_fmamk_f32 v233, v221, 0x00000000, v250
	v_mul_f32_e32 v241, 0x3f3504f3, v221
	v_mul_f32_e32 v250, 0xbf3504f3, v220
	v_fmamk_f32 v238, v220, 0xbf3504f3, v241
	v_fmamk_f32 v239, v221, 0xbf3504f3, v250
	v_mul_f32_e32 v241, 0x3f6c835e, v223
	v_mul_f32_e32 v250, 0xbf6c835e, v222
	v_fmamk_f32 v228, v222, 0x3ec3ef15, v241
	v_fmamk_f32 v229, v223, 0x3ec3ef15, v250
	v_mul_f32_e32 v241, 0x3f3504f3, v223
	v_mul_f32_e32 v250, 0xbf3504f3, v222
	v_fmamk_f32 v234, v222, 0xbf3504f3, v241
	v_fmamk_f32 v235, v223, 0xbf3504f3, v250
	v_mul_f32_e32 v241, 0xbec3ef15, v223
	v_mul_f32_e32 v250, 0x3ec3ef15, v222
	v_fmamk_f32 v242, v222, 0xbf6c835e, v241
	v_fmamk_f32 v243, v223, 0xbf6c835e, v250
	v_pk_mul_f32 v[128:129], v[244:245], v[244:245] op_sel:[1,1] op_sel_hi:[1,0]
	s_nop 0
	v_pk_fma_f32 v[246:247], v[244:245], v[244:245], v[128:129] op_sel_hi:[0,1,1] neg_lo:[0,0,1]
	s_nop 0
	v_pk_mul_f32 v[128:129], v[246:247], v[244:245] op_sel:[1,1] op_sel_hi:[1,0]
	s_nop 0
	v_pk_fma_f32 v[248:249], v[246:247], v[244:245], v[128:129] op_sel_hi:[0,1,1] neg_lo:[0,0,1]
	s_nop 0
	s_waitcnt lgkmcnt(8)
; DI float2 twid(float r) { return float2{__builtin_amdgcn_cosf(r), -__builtin_amdgcn_sinf(r)}; }
; DI void bfly_fwd(float2 a0, float2 a1, float2 a2, float2 a3, float r, float2& o0, float2& o1, float2& o2, float2& o3) {
;   float2 t0 = {a0.x + a2.x, a0.y + a2.y}, t1 = {a0.x - a2.x, a0.y - a2.y}, t2 = {a1.x + a3.x, a1.y + a3.y}, t3 = {a1.x - a3.x, a1.y - a3.y};
;   float2 b0 = {t0.x + t2.x, t0.y + t2.y}, b2 = {t0.x - t2.x, t0.y - t2.y}, b1 = {t1.x + t3.y, t1.y - t3.x}, b3 = {t1.x - t3.y, t1.y + t3.x};
;   float2 w1 = twid(r), w2 = cmul(w1, w1), w3 = cmul(w2, w1);
;   o0 = b0; o1 = cmul(b1, w1); o2 = cmul(b2, w2); o3 = cmul(b3, w3);
; }
;   const int lq2 = lq1 - 2, Q1 = 1 << lq1, Q2 = 1 << lq2; const float invM1 = 1.f / (float)(4 << lq1), invM2 = 1.f / (float)(4 << lq2);
;   for (int gg = tid; gg < NBT * (N / 16); gg += NTHR) { const int g = gg & (N / 16 - 1); float2* z = z0 + (gg / (N / 16)) * N; const int jp = g & (Q2 - 1), base = ((g >> lq2) << (lq2 + 4)) + jp; float2 x[4][4];
; #pragma unroll
;     for (int q1 = 0; q1 < 4; ++q1)
; #pragma unroll
;       for (int q2 = 0; q2 < 4; ++q2) x[q1][q2] = z[base + q1 * Q1 + q2 * Q2];
; #pragma unroll
;     for (int q2 = 0; q2 < 4; ++q2) bfly_fwd(x[0][q2], x[1][q2], x[2][q2], x[3][q2], (float)(jp + q2 * Q2) * invM1, x[0][q2], x[1][q2], x[2][q2], x[3][q2]);
; #pragma unroll
;     for (int q1 = 0; q1 < 4; ++q1) bfly_fwd(x[q1][0], x[q1][1], x[q1][2], x[q1][3], (float)jp * invM2, x[q1][0], x[q1][1], x[q1][2], x[q1][3]);
; #pragma unroll
;     for (int q1 = 0; q1 < 4; ++q1)
; #pragma unroll
;       for (int q2 = 0; q2 < 4; ++q2) z[base + q1 * Q1 + q2 * Q2] = x[q1][q2]; }
;   __syncthreads();
; }
	v_pk_add_f32 v[112:113], v[78:79], v[96:97]
	v_pk_add_f32 v[120:121], v[80:81], v[98:99]
	v_pk_add_f32 v[116:117], v[86:87], v[104:105]
	v_pk_add_f32 v[124:125], v[88:89], v[106:107]
	v_pk_add_f32 v[114:115], v[78:79], v[96:97] neg_lo:[0,1] neg_hi:[0,1]
	v_pk_add_f32 v[122:123], v[80:81], v[98:99] neg_lo:[0,1] neg_hi:[0,1]
	v_pk_add_f32 v[118:119], v[86:87], v[104:105] neg_lo:[0,1] neg_hi:[0,1]
	v_pk_add_f32 v[126:127], v[88:89], v[106:107] neg_lo:[0,1] neg_hi:[0,1]
	v_pk_add_f32 v[78:79], v[112:113], v[116:117]
	v_pk_add_f32 v[80:81], v[120:121], v[124:125]
	v_pk_add_f32 v[112:113], v[112:113], v[116:117] neg_lo:[0,1] neg_hi:[0,1]
	v_pk_add_f32 v[120:121], v[120:121], v[124:125] neg_lo:[0,1] neg_hi:[0,1]
	v_pk_add_f32 v[116:117], v[114:115], v[118:119] op_sel:[0,1] op_sel_hi:[1,0] neg_hi:[0,1]
	v_pk_add_f32 v[124:125], v[122:123], v[126:127] op_sel:[0,1] op_sel_hi:[1,0] neg_hi:[0,1]
	v_pk_add_f32 v[114:115], v[114:115], v[118:119] op_sel:[0,1] op_sel_hi:[1,0] neg_lo:[0,1]
	v_pk_add_f32 v[122:123], v[122:123], v[126:127] op_sel:[0,1] op_sel_hi:[1,0] neg_lo:[0,1]
	v_pk_mul_f32 v[128:129], v[112:113], v[220:221] op_sel:[1,1] op_sel_hi:[1,0]
	v_pk_mul_f32 v[132:133], v[120:121], v[226:227] op_sel:[1,1] op_sel_hi:[1,0]
	v_pk_mul_f32 v[130:131], v[116:117], v[218:219] op_sel:[1,1] op_sel_hi:[1,0]
	v_pk_mul_f32 v[134:135], v[124:125], v[224:225] op_sel:[1,1] op_sel_hi:[1,0]
	v_pk_fma_f32 v[96:97], v[112:113], v[220:221], v[128:129] op_sel_hi:[0,1,1] neg_lo:[0,0,1]
	v_pk_fma_f32 v[98:99], v[120:121], v[226:227], v[132:133] op_sel_hi:[0,1,1] neg_lo:[0,0,1]
	v_pk_mul_f32 v[128:129], v[114:115], v[222:223] op_sel:[1,1] op_sel_hi:[1,0]
	v_pk_mul_f32 v[132:133], v[122:123], v[228:229] op_sel:[1,1] op_sel_hi:[1,0]
	v_pk_fma_f32 v[86:87], v[116:117], v[218:219], v[130:131] op_sel_hi:[0,1,1] neg_lo:[0,0,1]
	v_pk_fma_f32 v[88:89], v[124:125], v[224:225], v[134:135] op_sel_hi:[0,1,1] neg_lo:[0,0,1]
	v_pk_fma_f32 v[104:105], v[114:115], v[222:223], v[128:129] op_sel_hi:[0,1,1] neg_lo:[0,0,1]
	v_pk_fma_f32 v[106:107], v[122:123], v[228:229], v[132:133] op_sel_hi:[0,1,1] neg_lo:[0,0,1]
	v_pk_add_f32 v[112:113], v[82:83], v[100:101]
	v_pk_add_f32 v[120:121], v[84:85], v[102:103]
	v_pk_add_f32 v[116:117], v[92:93], v[108:109]
	v_pk_add_f32 v[124:125], v[94:95], v[110:111]
	v_pk_add_f32 v[114:115], v[82:83], v[100:101] neg_lo:[0,1] neg_hi:[0,1]
	v_pk_add_f32 v[122:123], v[84:85], v[102:103] neg_lo:[0,1] neg_hi:[0,1]
	v_pk_add_f32 v[118:119], v[92:93], v[108:109] neg_lo:[0,1] neg_hi:[0,1]
	v_pk_add_f32 v[126:127], v[94:95], v[110:111] neg_lo:[0,1] neg_hi:[0,1]
	v_pk_add_f32 v[82:83], v[112:113], v[116:117]
	v_pk_add_f32 v[84:85], v[120:121], v[124:125]
	v_pk_add_f32 v[112:113], v[112:113], v[116:117] neg_lo:[0,1] neg_hi:[0,1]
	v_pk_add_f32 v[120:121], v[120:121], v[124:125] neg_lo:[0,1] neg_hi:[0,1]
	v_pk_add_f32 v[116:117], v[114:115], v[118:119] op_sel:[0,1] op_sel_hi:[1,0] neg_hi:[0,1]
	v_pk_add_f32 v[124:125], v[122:123], v[126:127] op_sel:[0,1] op_sel_hi:[1,0] neg_hi:[0,1]
	v_pk_add_f32 v[114:115], v[114:115], v[118:119] op_sel:[0,1] op_sel_hi:[1,0] neg_lo:[0,1]
	v_pk_add_f32 v[122:123], v[122:123], v[126:127] op_sel:[0,1] op_sel_hi:[1,0] neg_lo:[0,1]
	v_pk_mul_f32 v[128:129], v[112:113], v[232:233] op_sel:[1,1] op_sel_hi:[1,0]
	v_pk_mul_f32 v[132:133], v[120:121], v[238:239] op_sel:[1,1] op_sel_hi:[1,0]
	v_pk_mul_f32 v[130:131], v[116:117], v[230:231] op_sel:[1,1] op_sel_hi:[1,0]
	v_pk_mul_f32 v[134:135], v[124:125], v[236:237] op_sel:[1,1] op_sel_hi:[1,0]
	v_pk_fma_f32 v[100:101], v[112:113], v[232:233], v[128:129] op_sel_hi:[0,1,1] neg_lo:[0,0,1]
	v_pk_fma_f32 v[102:103], v[120:121], v[238:239], v[132:133] op_sel_hi:[0,1,1] neg_lo:[0,0,1]
	v_pk_mul_f32 v[128:129], v[114:115], v[234:235] op_sel:[1,1] op_sel_hi:[1,0]
	v_pk_mul_f32 v[132:133], v[122:123], v[242:243] op_sel:[1,1] op_sel_hi:[1,0]
	v_pk_fma_f32 v[92:93], v[116:117], v[230:231], v[130:131] op_sel_hi:[0,1,1] neg_lo:[0,0,1]
	v_pk_fma_f32 v[94:95], v[124:125], v[236:237], v[134:135] op_sel_hi:[0,1,1] neg_lo:[0,0,1]
	v_pk_fma_f32 v[108:109], v[114:115], v[234:235], v[128:129] op_sel_hi:[0,1,1] neg_lo:[0,0,1]
	v_pk_fma_f32 v[110:111], v[122:123], v[242:243], v[132:133] op_sel_hi:[0,1,1] neg_lo:[0,0,1]
	v_pk_add_f32 v[112:113], v[78:79], v[82:83]
	v_pk_add_f32 v[120:121], v[86:87], v[92:93]
	v_pk_add_f32 v[116:117], v[80:81], v[84:85]
	v_pk_add_f32 v[124:125], v[88:89], v[94:95]
	v_pk_add_f32 v[114:115], v[78:79], v[82:83] neg_lo:[0,1] neg_hi:[0,1]
	v_pk_add_f32 v[122:123], v[86:87], v[92:93] neg_lo:[0,1] neg_hi:[0,1]
	v_pk_add_f32 v[118:119], v[80:81], v[84:85] neg_lo:[0,1] neg_hi:[0,1]
	v_pk_add_f32 v[126:127], v[88:89], v[94:95] neg_lo:[0,1] neg_hi:[0,1]
	v_pk_add_f32 v[78:79], v[112:113], v[116:117]
	v_pk_add_f32 v[86:87], v[120:121], v[124:125]
	v_pk_add_f32 v[112:113], v[112:113], v[116:117] neg_lo:[0,1] neg_hi:[0,1]
	v_pk_add_f32 v[120:121], v[120:121], v[124:125] neg_lo:[0,1] neg_hi:[0,1]
	v_pk_add_f32 v[116:117], v[114:115], v[118:119] op_sel:[0,1] op_sel_hi:[1,0] neg_hi:[0,1]
	v_pk_add_f32 v[124:125], v[122:123], v[126:127] op_sel:[0,1] op_sel_hi:[1,0] neg_hi:[0,1]
	v_pk_add_f32 v[114:115], v[114:115], v[118:119] op_sel:[0,1] op_sel_hi:[1,0] neg_lo:[0,1]
	v_pk_add_f32 v[122:123], v[122:123], v[126:127] op_sel:[0,1] op_sel_hi:[1,0] neg_lo:[0,1]
	v_pk_mul_f32 v[128:129], v[112:113], v[246:247] op_sel:[1,1] op_sel_hi:[1,0]
	v_pk_mul_f32 v[132:133], v[120:121], v[246:247] op_sel:[1,1] op_sel_hi:[1,0]
	v_pk_mul_f32 v[130:131], v[116:117], v[244:245] op_sel:[1,1] op_sel_hi:[1,0]
	v_pk_mul_f32 v[134:135], v[124:125], v[244:245] op_sel:[1,1] op_sel_hi:[1,0]
;   const int lq2 = lq1 - 2, Q1 = 1 << lq1, Q2 = 1 << lq2; const float invM1 = 1.f / (float)(4 << lq1), invM2 = 1.f / (float)(4 << lq2);
;   for (int gg = tid; gg < NBT * (N / 16); gg += NTHR) { const int g = gg & (N / 16 - 1); float2* z = z0 + (gg / (N / 16)) * N; const int jp = g & (Q2 - 1), base = ((g >> lq2) << (lq2 + 4)) + jp; float2 x[4][4];
; #pragma unroll
;     for (int q1 = 0; q1 < 4; ++q1)
; #pragma unroll
;       for (int q2 = 0; q2 < 4; ++q2) x[q1][q2] = z[base + q1 * Q1 + q2 * Q2];
; #pragma unroll
;     for (int q2 = 0; q2 < 4; ++q2) bfly_fwd(x[0][q2], x[1][q2], x[2][q2], x[3][q2], (float)(jp + q2 * Q2) * invM1, x[0][q2], x[1][q2], x[2][q2], x[3][q2]);
; #pragma unroll
;     for (int q1 = 0; q1 < 4; ++q1) bfly_fwd(x[q1][0], x[q1][1], x[q1][2], x[q1][3], (float)jp * invM2, x[q1][0], x[q1][1], x[q1][2], x[q1][3]);
; #pragma unroll
;     for (int q1 = 0; q1 < 4; ++q1)
; #pragma unroll
;       for (int q2 = 0; q2 < 4; ++q2) z[base + q1 * Q1 + q2 * Q2] = x[q1][q2]; }
;   __syncthreads();
; }
	v_pk_fma_f32 v[82:83], v[112:113], v[246:247], v[128:129] op_sel_hi:[0,1,1] neg_lo:[0,0,1]
	v_pk_fma_f32 v[92:93], v[120:121], v[246:247], v[132:133] op_sel_hi:[0,1,1] neg_lo:[0,0,1]
	v_pk_mul_f32 v[128:129], v[114:115], v[248:249] op_sel:[1,1] op_sel_hi:[1,0]
	v_pk_mul_f32 v[132:133], v[122:123], v[248:249] op_sel:[1,1] op_sel_hi:[1,0]
	v_pk_fma_f32 v[80:81], v[116:117], v[244:245], v[130:131] op_sel_hi:[0,1,1] neg_lo:[0,0,1]
	v_pk_fma_f32 v[88:89], v[124:125], v[244:245], v[134:135] op_sel_hi:[0,1,1] neg_lo:[0,0,1]
	v_pk_fma_f32 v[84:85], v[114:115], v[248:249], v[128:129] op_sel_hi:[0,1,1] neg_lo:[0,0,1]
	v_pk_fma_f32 v[94:95], v[122:123], v[248:249], v[132:133] op_sel_hi:[0,1,1] neg_lo:[0,0,1]
	v_pk_add_f32 v[112:113], v[96:97], v[100:101]
	v_pk_add_f32 v[120:121], v[104:105], v[108:109]
	v_pk_add_f32 v[116:117], v[98:99], v[102:103]
	v_pk_add_f32 v[124:125], v[106:107], v[110:111]
	v_pk_add_f32 v[114:115], v[96:97], v[100:101] neg_lo:[0,1] neg_hi:[0,1]
	v_pk_add_f32 v[122:123], v[104:105], v[108:109] neg_lo:[0,1] neg_hi:[0,1]
	v_pk_add_f32 v[118:119], v[98:99], v[102:103] neg_lo:[0,1] neg_hi:[0,1]
	v_pk_add_f32 v[126:127], v[106:107], v[110:111] neg_lo:[0,1] neg_hi:[0,1]
	v_pk_add_f32 v[96:97], v[112:113], v[116:117]
	v_pk_add_f32 v[104:105], v[120:121], v[124:125]
	v_pk_add_f32 v[112:113], v[112:113], v[116:117] neg_lo:[0,1] neg_hi:[0,1]
	v_pk_add_f32 v[120:121], v[120:121], v[124:125] neg_lo:[0,1] neg_hi:[0,1]
	v_pk_add_f32 v[116:117], v[114:115], v[118:119] op_sel:[0,1] op_sel_hi:[1,0] neg_hi:[0,1]
	v_pk_add_f32 v[124:125], v[122:123], v[126:127] op_sel:[0,1] op_sel_hi:[1,0] neg_hi:[0,1]
	v_pk_add_f32 v[114:115], v[114:115], v[118:119] op_sel:[0,1] op_sel_hi:[1,0] neg_lo:[0,1]
	v_pk_add_f32 v[122:123], v[122:123], v[126:127] op_sel:[0,1] op_sel_hi:[1,0] neg_lo:[0,1]
	v_pk_mul_f32 v[128:129], v[112:113], v[246:247] op_sel:[1,1] op_sel_hi:[1,0]
	v_pk_mul_f32 v[132:133], v[120:121], v[246:247] op_sel:[1,1] op_sel_hi:[1,0]
	v_pk_mul_f32 v[130:131], v[116:117], v[244:245] op_sel:[1,1] op_sel_hi:[1,0]
	v_pk_mul_f32 v[134:135], v[124:125], v[244:245] op_sel:[1,1] op_sel_hi:[1,0]
	v_pk_fma_f32 v[100:101], v[112:113], v[246:247], v[128:129] op_sel_hi:[0,1,1] neg_lo:[0,0,1]
	v_pk_fma_f32 v[108:109], v[120:121], v[246:247], v[132:133] op_sel_hi:[0,1,1] neg_lo:[0,0,1]
	v_pk_mul_f32 v[128:129], v[114:115], v[248:249] op_sel:[1,1] op_sel_hi:[1,0]
	v_pk_mul_f32 v[132:133], v[122:123], v[248:249] op_sel:[1,1] op_sel_hi:[1,0]
	v_pk_fma_f32 v[98:99], v[116:117], v[244:245], v[130:131] op_sel_hi:[0,1,1] neg_lo:[0,0,1]
	v_pk_fma_f32 v[106:107], v[124:125], v[244:245], v[134:135] op_sel_hi:[0,1,1] neg_lo:[0,0,1]
	v_pk_fma_f32 v[102:103], v[114:115], v[248:249], v[128:129] op_sel_hi:[0,1,1] neg_lo:[0,0,1]
	v_pk_fma_f32 v[110:111], v[122:123], v[248:249], v[132:133] op_sel_hi:[0,1,1] neg_lo:[0,0,1]
	s_nop 0
	ds_write2_b64 v251, v[78:79], v[80:81] offset1:16
	ds_write2_b64 v251, v[82:83], v[84:85] offset0:32 offset1:48
	ds_write2_b64 v251, v[86:87], v[88:89] offset0:64 offset1:80
	ds_write2_b64 v251, v[92:93], v[94:95] offset0:96 offset1:112
	ds_write2_b64 v251, v[96:97], v[98:99] offset0:128 offset1:144
	ds_write2_b64 v251, v[100:101], v[102:103] offset0:160 offset1:176
	ds_write2_b64 v251, v[104:105], v[106:107] offset0:192 offset1:208
	ds_write2_b64 v251, v[108:109], v[110:111] offset0:224 offset1:240
	s_waitcnt lgkmcnt(8)
	v_pk_add_f32 v[112:113], v[188:189], v[204:205]
	v_pk_add_f32 v[120:121], v[190:191], v[206:207]
	v_pk_add_f32 v[116:117], v[196:197], v[212:213]
	v_pk_add_f32 v[124:125], v[198:199], v[214:215]
	v_pk_add_f32 v[114:115], v[188:189], v[204:205] neg_lo:[0,1] neg_hi:[0,1]
	v_pk_add_f32 v[122:123], v[190:191], v[206:207] neg_lo:[0,1] neg_hi:[0,1]
	v_pk_add_f32 v[118:119], v[196:197], v[212:213] neg_lo:[0,1] neg_hi:[0,1]
	v_pk_add_f32 v[126:127], v[198:199], v[214:215] neg_lo:[0,1] neg_hi:[0,1]
	v_pk_add_f32 v[188:189], v[112:113], v[116:117]
	v_pk_add_f32 v[190:191], v[120:121], v[124:125]
	v_pk_add_f32 v[112:113], v[112:113], v[116:117] neg_lo:[0,1] neg_hi:[0,1]
	v_pk_add_f32 v[120:121], v[120:121], v[124:125] neg_lo:[0,1] neg_hi:[0,1]
	v_pk_add_f32 v[116:117], v[114:115], v[118:119] op_sel:[0,1] op_sel_hi:[1,0] neg_hi:[0,1]
	v_pk_add_f32 v[124:125], v[122:123], v[126:127] op_sel:[0,1] op_sel_hi:[1,0] neg_hi:[0,1]
	v_pk_add_f32 v[114:115], v[114:115], v[118:119] op_sel:[0,1] op_sel_hi:[1,0] neg_lo:[0,1]
	v_pk_add_f32 v[122:123], v[122:123], v[126:127] op_sel:[0,1] op_sel_hi:[1,0] neg_lo:[0,1]
	v_pk_mul_f32 v[128:129], v[112:113], v[220:221] op_sel:[1,1] op_sel_hi:[1,0]
	v_pk_mul_f32 v[132:133], v[120:121], v[226:227] op_sel:[1,1] op_sel_hi:[1,0]
	v_pk_mul_f32 v[130:131], v[116:117], v[218:219] op_sel:[1,1] op_sel_hi:[1,0]
	v_pk_mul_f32 v[134:135], v[124:125], v[224:225] op_sel:[1,1] op_sel_hi:[1,0]
	v_pk_fma_f32 v[204:205], v[112:113], v[220:221], v[128:129] op_sel_hi:[0,1,1] neg_lo:[0,0,1]
	v_pk_fma_f32 v[206:207], v[120:121], v[226:227], v[132:133] op_sel_hi:[0,1,1] neg_lo:[0,0,1]
	v_pk_mul_f32 v[128:129], v[114:115], v[222:223] op_sel:[1,1] op_sel_hi:[1,0]
	v_pk_mul_f32 v[132:133], v[122:123], v[228:229] op_sel:[1,1] op_sel_hi:[1,0]
	v_pk_fma_f32 v[196:197], v[116:117], v[218:219], v[130:131] op_sel_hi:[0,1,1] neg_lo:[0,0,1]
	v_pk_fma_f32 v[198:199], v[124:125], v[224:225], v[134:135] op_sel_hi:[0,1,1] neg_lo:[0,0,1]
	v_pk_fma_f32 v[212:213], v[114:115], v[222:223], v[128:129] op_sel_hi:[0,1,1] neg_lo:[0,0,1]
	v_pk_fma_f32 v[214:215], v[122:123], v[228:229], v[132:133] op_sel_hi:[0,1,1] neg_lo:[0,0,1]
	v_pk_add_f32 v[112:113], v[192:193], v[208:209]
	v_pk_add_f32 v[120:121], v[194:195], v[210:211]
	v_pk_add_f32 v[116:117], v[200:201], v[252:253]
;   const int lq2 = lq1 - 2, Q1 = 1 << lq1, Q2 = 1 << lq2; const float invM1 = 1.f / (float)(4 << lq1), invM2 = 1.f / (float)(4 << lq2);
;   for (int gg = tid; gg < NBT * (N / 16); gg += NTHR) { const int g = gg & (N / 16 - 1); float2* z = z0 + (gg / (N / 16)) * N; const int jp = g & (Q2 - 1), base = ((g >> lq2) << (lq2 + 4)) + jp; float2 x[4][4];
; #pragma unroll
;     for (int q1 = 0; q1 < 4; ++q1)
; #pragma unroll
;       for (int q2 = 0; q2 < 4; ++q2) x[q1][q2] = z[base + q1 * Q1 + q2 * Q2];
; #pragma unroll
;     for (int q2 = 0; q2 < 4; ++q2) bfly_fwd(x[0][q2], x[1][q2], x[2][q2], x[3][q2], (float)(jp + q2 * Q2) * invM1, x[0][q2], x[1][q2], x[2][q2], x[3][q2]);
; #pragma unroll
;     for (int q1 = 0; q1 < 4; ++q1) bfly_fwd(x[q1][0], x[q1][1], x[q1][2], x[q1][3], (float)jp * invM2, x[q1][0], x[q1][1], x[q1][2], x[q1][3]);
; #pragma unroll
;     for (int q1 = 0; q1 < 4; ++q1)
; #pragma unroll
;       for (int q2 = 0; q2 < 4; ++q2) z[base + q1 * Q1 + q2 * Q2] = x[q1][q2]; }
;   __syncthreads();
; }
	v_pk_add_f32 v[124:125], v[202:203], v[254:255]
	v_pk_add_f32 v[114:115], v[192:193], v[208:209] neg_lo:[0,1] neg_hi:[0,1]
	v_pk_add_f32 v[122:123], v[194:195], v[210:211] neg_lo:[0,1] neg_hi:[0,1]
	v_pk_add_f32 v[118:119], v[200:201], v[252:253] neg_lo:[0,1] neg_hi:[0,1]
	v_pk_add_f32 v[126:127], v[202:203], v[254:255] neg_lo:[0,1] neg_hi:[0,1]
	v_pk_add_f32 v[192:193], v[112:113], v[116:117]
	v_pk_add_f32 v[194:195], v[120:121], v[124:125]
	v_pk_add_f32 v[112:113], v[112:113], v[116:117] neg_lo:[0,1] neg_hi:[0,1]
	v_pk_add_f32 v[120:121], v[120:121], v[124:125] neg_lo:[0,1] neg_hi:[0,1]
	v_pk_add_f32 v[116:117], v[114:115], v[118:119] op_sel:[0,1] op_sel_hi:[1,0] neg_hi:[0,1]
	v_pk_add_f32 v[124:125], v[122:123], v[126:127] op_sel:[0,1] op_sel_hi:[1,0] neg_hi:[0,1]
	v_pk_add_f32 v[114:115], v[114:115], v[118:119] op_sel:[0,1] op_sel_hi:[1,0] neg_lo:[0,1]
	v_pk_add_f32 v[122:123], v[122:123], v[126:127] op_sel:[0,1] op_sel_hi:[1,0] neg_lo:[0,1]
	v_pk_mul_f32 v[128:129], v[112:113], v[232:233] op_sel:[1,1] op_sel_hi:[1,0]
	v_pk_mul_f32 v[132:133], v[120:121], v[238:239] op_sel:[1,1] op_sel_hi:[1,0]
	v_pk_mul_f32 v[130:131], v[116:117], v[230:231] op_sel:[1,1] op_sel_hi:[1,0]
	v_pk_mul_f32 v[134:135], v[124:125], v[236:237] op_sel:[1,1] op_sel_hi:[1,0]
	v_pk_fma_f32 v[208:209], v[112:113], v[232:233], v[128:129] op_sel_hi:[0,1,1] neg_lo:[0,0,1]
	v_pk_fma_f32 v[210:211], v[120:121], v[238:239], v[132:133] op_sel_hi:[0,1,1] neg_lo:[0,0,1]
	v_pk_mul_f32 v[128:129], v[114:115], v[234:235] op_sel:[1,1] op_sel_hi:[1,0]
	v_pk_mul_f32 v[132:133], v[122:123], v[242:243] op_sel:[1,1] op_sel_hi:[1,0]
	v_pk_fma_f32 v[200:201], v[116:117], v[230:231], v[130:131] op_sel_hi:[0,1,1] neg_lo:[0,0,1]
	v_pk_fma_f32 v[202:203], v[124:125], v[236:237], v[134:135] op_sel_hi:[0,1,1] neg_lo:[0,0,1]
	v_pk_fma_f32 v[252:253], v[114:115], v[234:235], v[128:129] op_sel_hi:[0,1,1] neg_lo:[0,0,1]
	v_pk_fma_f32 v[254:255], v[122:123], v[242:243], v[132:133] op_sel_hi:[0,1,1] neg_lo:[0,0,1]
	v_pk_add_f32 v[112:113], v[188:189], v[192:193]
	v_pk_add_f32 v[120:121], v[196:197], v[200:201]
	v_pk_add_f32 v[116:117], v[190:191], v[194:195]
	v_pk_add_f32 v[124:125], v[198:199], v[202:203]
	v_pk_add_f32 v[114:115], v[188:189], v[192:193] neg_lo:[0,1] neg_hi:[0,1]
	v_pk_add_f32 v[122:123], v[196:197], v[200:201] neg_lo:[0,1] neg_hi:[0,1]
	v_pk_add_f32 v[118:119], v[190:191], v[194:195] neg_lo:[0,1] neg_hi:[0,1]
	v_pk_add_f32 v[126:127], v[198:199], v[202:203] neg_lo:[0,1] neg_hi:[0,1]
	v_pk_add_f32 v[188:189], v[112:113], v[116:117]
	v_pk_add_f32 v[196:197], v[120:121], v[124:125]
	v_pk_add_f32 v[112:113], v[112:113], v[116:117] neg_lo:[0,1] neg_hi:[0,1]
	v_pk_add_f32 v[120:121], v[120:121], v[124:125] neg_lo:[0,1] neg_hi:[0,1]
	v_pk_add_f32 v[116:117], v[114:115], v[118:119] op_sel:[0,1] op_sel_hi:[1,0] neg_hi:[0,1]
	v_pk_add_f32 v[124:125], v[122:123], v[126:127] op_sel:[0,1] op_sel_hi:[1,0] neg_hi:[0,1]
	v_pk_add_f32 v[114:115], v[114:115], v[118:119] op_sel:[0,1] op_sel_hi:[1,0] neg_lo:[0,1]
	v_pk_add_f32 v[122:123], v[122:123], v[126:127] op_sel:[0,1] op_sel_hi:[1,0] neg_lo:[0,1]
	v_pk_mul_f32 v[128:129], v[112:113], v[246:247] op_sel:[1,1] op_sel_hi:[1,0]
	v_pk_mul_f32 v[132:133], v[120:121], v[246:247] op_sel:[1,1] op_sel_hi:[1,0]
	v_pk_mul_f32 v[130:131], v[116:117], v[244:245] op_sel:[1,1] op_sel_hi:[1,0]
	v_pk_mul_f32 v[134:135], v[124:125], v[244:245] op_sel:[1,1] op_sel_hi:[1,0]
	v_pk_fma_f32 v[192:193], v[112:113], v[246:247], v[128:129] op_sel_hi:[0,1,1] neg_lo:[0,0,1]
	v_pk_fma_f32 v[200:201], v[120:121], v[246:247], v[132:133] op_sel_hi:[0,1,1] neg_lo:[0,0,1]
	v_pk_mul_f32 v[128:129], v[114:115], v[248:249] op_sel:[1,1] op_sel_hi:[1,0]
	v_pk_mul_f32 v[132:133], v[122:123], v[248:249] op_sel:[1,1] op_sel_hi:[1,0]
	v_pk_fma_f32 v[190:191], v[116:117], v[244:245], v[130:131] op_sel_hi:[0,1,1] neg_lo:[0,0,1]
	v_pk_fma_f32 v[198:199], v[124:125], v[244:245], v[134:135] op_sel_hi:[0,1,1] neg_lo:[0,0,1]
	v_pk_fma_f32 v[194:195], v[114:115], v[248:249], v[128:129] op_sel_hi:[0,1,1] neg_lo:[0,0,1]
	v_pk_fma_f32 v[202:203], v[122:123], v[248:249], v[132:133] op_sel_hi:[0,1,1] neg_lo:[0,0,1]
	v_pk_add_f32 v[112:113], v[204:205], v[208:209]
	v_pk_add_f32 v[120:121], v[212:213], v[252:253]
	v_pk_add_f32 v[116:117], v[206:207], v[210:211]
	v_pk_add_f32 v[124:125], v[214:215], v[254:255]
	v_pk_add_f32 v[114:115], v[204:205], v[208:209] neg_lo:[0,1] neg_hi:[0,1]
	v_pk_add_f32 v[122:123], v[212:213], v[252:253] neg_lo:[0,1] neg_hi:[0,1]
	v_pk_add_f32 v[118:119], v[206:207], v[210:211] neg_lo:[0,1] neg_hi:[0,1]
	v_pk_add_f32 v[126:127], v[214:215], v[254:255] neg_lo:[0,1] neg_hi:[0,1]
	v_pk_add_f32 v[204:205], v[112:113], v[116:117]
	v_pk_add_f32 v[212:213], v[120:121], v[124:125]
	v_pk_add_f32 v[112:113], v[112:113], v[116:117] neg_lo:[0,1] neg_hi:[0,1]
	v_pk_add_f32 v[120:121], v[120:121], v[124:125] neg_lo:[0,1] neg_hi:[0,1]
	v_pk_add_f32 v[116:117], v[114:115], v[118:119] op_sel:[0,1] op_sel_hi:[1,0] neg_hi:[0,1]
	v_pk_add_f32 v[124:125], v[122:123], v[126:127] op_sel:[0,1] op_sel_hi:[1,0] neg_hi:[0,1]
	v_pk_add_f32 v[114:115], v[114:115], v[118:119] op_sel:[0,1] op_sel_hi:[1,0] neg_lo:[0,1]
	v_pk_add_f32 v[122:123], v[122:123], v[126:127] op_sel:[0,1] op_sel_hi:[1,0] neg_lo:[0,1]
	v_pk_mul_f32 v[128:129], v[112:113], v[246:247] op_sel:[1,1] op_sel_hi:[1,0]
	v_pk_mul_f32 v[132:133], v[120:121], v[246:247] op_sel:[1,1] op_sel_hi:[1,0]
	v_pk_mul_f32 v[130:131], v[116:117], v[244:245] op_sel:[1,1] op_sel_hi:[1,0]
	v_pk_mul_f32 v[134:135], v[124:125], v[244:245] op_sel:[1,1] op_sel_hi:[1,0]
	v_pk_fma_f32 v[208:209], v[112:113], v[246:247], v[128:129] op_sel_hi:[0,1,1] neg_lo:[0,0,1]
	v_pk_fma_f32 v[252:253], v[120:121], v[246:247], v[132:133] op_sel_hi:[0,1,1] neg_lo:[0,0,1]
	v_pk_mul_f32 v[128:129], v[114:115], v[248:249] op_sel:[1,1] op_sel_hi:[1,0]
	v_pk_mul_f32 v[132:133], v[122:123], v[248:249] op_sel:[1,1] op_sel_hi:[1,0]
	v_pk_fma_f32 v[206:207], v[116:117], v[244:245], v[130:131] op_sel_hi:[0,1,1] neg_lo:[0,0,1]
	v_pk_fma_f32 v[214:215], v[124:125], v[244:245], v[134:135] op_sel_hi:[0,1,1] neg_lo:[0,0,1]
	v_pk_fma_f32 v[210:211], v[114:115], v[248:249], v[128:129] op_sel_hi:[0,1,1] neg_lo:[0,0,1]
	v_pk_fma_f32 v[254:255], v[122:123], v[248:249], v[132:133] op_sel_hi:[0,1,1] neg_lo:[0,0,1]
	s_nop 0
	ds_write2_b64 v139, v[188:189], v[190:191] offset1:16
	ds_write2_b64 v139, v[192:193], v[194:195] offset0:32 offset1:48
	ds_write2_b64 v139, v[196:197], v[198:199] offset0:64 offset1:80
	ds_write2_b64 v139, v[200:201], v[202:203] offset0:96 offset1:112
	ds_write2_b64 v139, v[204:205], v[206:207] offset0:128 offset1:144
	ds_write2_b64 v139, v[208:209], v[210:211] offset0:160 offset1:176
	ds_write2_b64 v139, v[212:213], v[214:215] offset0:192 offset1:208
	ds_write2_b64 v139, v[252:253], v[254:255] offset0:224 offset1:240
	s_mov_b64 s[10:11], exec

;   const int lq2 = lq1 - 2, Q1 = 1 << lq1, Q2 = 1 << lq2; const float invM1 = 1.f / (float)(4 << lq1), invM2 = 1.f / (float)(4 << lq2);
;   for (int gg = tid; gg < NBT * (N / 16); gg += NTHR) { const int g = gg & (N / 16 - 1); float2* z = z0 + (gg / (N / 16)) * N; const int jp = g & (Q2 - 1), base = ((g >> lq2) << (lq2 + 4)) + jp; float2 x[4][4];
; #pragma unroll
;     for (int q1 = 0; q1 < 4; ++q1)
; #pragma unroll
;       for (int q2 = 0; q2 < 4; ++q2) x[q1][q2] = z[base + q1 * Q1 + q2 * Q2];
; #pragma unroll
;     for (int q2 = 0; q2 < 4; ++q2) bfly_fwd(x[0][q2], x[1][q2], x[2][q2], x[3][q2], (float)(jp + q2 * Q2) * invM1, x[0][q2], x[1][q2], x[2][q2], x[3][q2]);
; #pragma unroll
;     for (int q1 = 0; q1 < 4; ++q1) bfly_fwd(x[q1][0], x[q1][1], x[q1][2], x[q1][3], (float)jp * invM2, x[q1][0], x[q1][1], x[q1][2], x[q1][3]);
; #pragma unroll
;     for (int q1 = 0; q1 < 4; ++q1)
; #pragma unroll
;       for (int q2 = 0; q2 < 4; ++q2) z[base + q1 * Q1 + q2 * Q2] = x[q1][q2]; }
;   __syncthreads();
; }
;   fft_pair_fwd<N, 2>(z, tid, 10); fft_pair_fwd<N, 2>(z, tid, 6); fft_level_fwd<N, 2>(z, tid, 2); fft_level_fwd<N, 2>(z, tid, 0); }
.LBB0_1600:
	v_ashrrev_i32_e32 v216, 31, v64
	v_lshrrev_b32_e32 v216, 23, v216
	v_add_lshl_u32 v216, v64, v216, 7
	v_and_b32_e32 v216, 0xffff0000, v216
	v_add_u32_e32 v216, v63, v216
	ds_read2st64_b64 v[66:69], v216 offset1:4
	ds_read2st64_b64 v[70:73], v216 offset0:8 offset1:12
	ds_read2st64_b64 v[82:85], v216 offset0:16 offset1:20
	ds_read2st64_b64 v[86:89], v216 offset0:24 offset1:28
	ds_read2st64_b64 v[90:93], v216 offset0:32 offset1:36
	ds_read2st64_b64 v[94:97], v216 offset0:40 offset1:44
	ds_read2st64_b64 v[98:101], v216 offset0:48 offset1:52
	ds_read2st64_b64 v[102:105], v216 offset0:56 offset1:60
	v_add_u32_e32 v65, 0x200, v64
	v_mov_b32_e32 v64, v65
	v_ashrrev_i32_e32 v217, 31, v64
	v_lshrrev_b32_e32 v217, 23, v217
	v_add_lshl_u32 v217, v64, v217, 7
	v_and_b32_e32 v217, 0xffff0000, v217
	v_add_u32_e32 v217, v63, v217
	ds_read2st64_b64 v[188:191], v217 offset1:4
	ds_read2st64_b64 v[192:195], v217 offset0:8 offset1:12
	ds_read2st64_b64 v[196:199], v217 offset0:16 offset1:20
	ds_read2st64_b64 v[200:203], v217 offset0:24 offset1:28
	ds_read2st64_b64 v[204:207], v217 offset0:32 offset1:36
	ds_read2st64_b64 v[208:211], v217 offset0:40 offset1:44
	ds_read2st64_b64 v[212:215], v217 offset0:48 offset1:52
	ds_read2st64_b64 v[252:255], v217 offset0:56 offset1:60
	v_add_u32_e32 v65, 0x200, v64
	v_mov_b32_e32 v64, v65
	v_and_b32_e32 v241, 0xff, v64
	v_cvt_f32_u32_e32 v250, v241
	v_mul_f32_e32 v250, 0x39800000, v250
	v_cos_f32_e32 v218, v250
	v_sin_f32_e32 v219, v250
	s_nop 1
	v_xor_b32_e32 v219, 0x80000000, v219
	s_nop 0
	v_pk_mul_f32 v[122:123], v[218:219], v[218:219] op_sel:[1,1] op_sel_hi:[1,0]
	s_nop 0
	v_pk_fma_f32 v[220:221], v[218:219], v[218:219], v[122:123] op_sel_hi:[0,1,1] neg_lo:[0,0,1]
	s_nop 0
	v_pk_mul_f32 v[122:123], v[220:221], v[218:219] op_sel:[1,1] op_sel_hi:[1,0]
	s_nop 0
	v_pk_fma_f32 v[222:223], v[220:221], v[218:219], v[122:123] op_sel_hi:[0,1,1] neg_lo:[0,0,1]
	v_pk_mul_f32 v[122:123], v[220:221], v[220:221] op_sel:[1,1] op_sel_hi:[1,0]
	s_nop 0
	v_pk_fma_f32 v[244:245], v[220:221], v[220:221], v[122:123] op_sel_hi:[0,1,1] neg_lo:[0,0,1]
	s_nop 0
	v_mul_f32_e32 v241, 0x3ec3ef15, v219
	v_mul_f32_e32 v250, 0xbec3ef15, v218
	v_fmamk_f32 v224, v218, 0x3f6c835e, v241
	v_fmamk_f32 v225, v219, 0x3f6c835e, v250
	v_mul_f32_e32 v241, 0x3f3504f3, v219
	v_mul_f32_e32 v250, 0xbf3504f3, v218
	v_fmamk_f32 v230, v218, 0x3f3504f3, v241
	v_fmamk_f32 v231, v219, 0x3f3504f3, v250
	v_mul_f32_e32 v241, 0x3f6c835e, v219
	v_mul_f32_e32 v250, 0xbf6c835e, v218
	v_fmamk_f32 v236, v218, 0x3ec3ef15, v241
	v_fmamk_f32 v237, v219, 0x3ec3ef15, v250
	v_mul_f32_e32 v241, 0x3f3504f3, v221
	v_mul_f32_e32 v250, 0xbf3504f3, v220
	v_fmamk_f32 v226, v220, 0x3f3504f3, v241
	v_fmamk_f32 v227, v221, 0x3f3504f3, v250
	v_mul_f32_e32 v241, 0x3f800000, v221
	v_mul_f32_e32 v250, 0xbf800000, v220
	v_fmamk_f32 v232, v220, 0x00000000, v241
	v_fmamk_f32 v233, v221, 0x00000000, v250
	v_mul_f32_e32 v241, 0x3f3504f3, v221
	v_mul_f32_e32 v250, 0xbf3504f3, v220
	v_fmamk_f32 v238, v220, 0xbf3504f3, v241
	v_fmamk_f32 v239, v221, 0xbf3504f3, v250
	v_mul_f32_e32 v241, 0x3f6c835e, v223
	v_mul_f32_e32 v250, 0xbf6c835e, v222
	v_fmamk_f32 v228, v222, 0x3ec3ef15, v241
	v_fmamk_f32 v229, v223, 0x3ec3ef15, v250
	v_mul_f32_e32 v241, 0x3f3504f3, v223
	v_mul_f32_e32 v250, 0xbf3504f3, v222
	v_fmamk_f32 v234, v222, 0xbf3504f3, v241
	v_fmamk_f32 v235, v223, 0xbf3504f3, v250
	v_mul_f32_e32 v241, 0xbec3ef15, v223
	v_mul_f32_e32 v250, 0x3ec3ef15, v222
	v_fmamk_f32 v242, v222, 0xbf6c835e, v241
	v_fmamk_f32 v243, v223, 0xbf6c835e, v250
	v_pk_mul_f32 v[122:123], v[244:245], v[244:245] op_sel:[1,1] op_sel_hi:[1,0]
	s_nop 0
	v_pk_fma_f32 v[246:247], v[244:245], v[244:245], v[122:123] op_sel_hi:[0,1,1] neg_lo:[0,0,1]
	s_nop 0
	v_pk_mul_f32 v[122:123], v[246:247], v[244:245] op_sel:[1,1] op_sel_hi:[1,0]
	s_nop 0
	v_pk_fma_f32 v[248:249], v[246:247], v[244:245], v[122:123] op_sel_hi:[0,1,1] neg_lo:[0,0,1]
	s_nop 0
	s_waitcnt lgkmcnt(8)
	v_pk_add_f32 v[106:107], v[66:67], v[90:91]
	v_pk_add_f32 v[114:115], v[68:69], v[92:93]
	v_pk_add_f32 v[110:111], v[82:83], v[98:99]
	v_pk_add_f32 v[118:119], v[84:85], v[100:101]
	v_pk_add_f32 v[108:109], v[66:67], v[90:91] neg_lo:[0,1] neg_hi:[0,1]
	v_pk_add_f32 v[116:117], v[68:69], v[92:93] neg_lo:[0,1] neg_hi:[0,1]
	v_pk_add_f32 v[112:113], v[82:83], v[98:99] neg_lo:[0,1] neg_hi:[0,1]
	v_pk_add_f32 v[120:121], v[84:85], v[100:101] neg_lo:[0,1] neg_hi:[0,1]
	v_pk_add_f32 v[66:67], v[106:107], v[110:111]
	v_pk_add_f32 v[68:69], v[114:115], v[118:119]
	v_pk_add_f32 v[106:107], v[106:107], v[110:111] neg_lo:[0,1] neg_hi:[0,1]
	v_pk_add_f32 v[114:115], v[114:115], v[118:119] neg_lo:[0,1] neg_hi:[0,1]
	v_pk_add_f32 v[110:111], v[108:109], v[112:113] op_sel:[0,1] op_sel_hi:[1,0] neg_hi:[0,1]
	v_pk_add_f32 v[118:119], v[116:117], v[120:121] op_sel:[0,1] op_sel_hi:[1,0] neg_hi:[0,1]
	v_pk_add_f32 v[108:109], v[108:109], v[112:113] op_sel:[0,1] op_sel_hi:[1,0] neg_lo:[0,1]
	v_pk_add_f32 v[116:117], v[116:117], v[120:121] op_sel:[0,1] op_sel_hi:[1,0] neg_lo:[0,1]
	v_pk_mul_f32 v[122:123], v[106:107], v[220:221] op_sel:[1,1] op_sel_hi:[1,0]
	v_pk_mul_f32 v[126:127], v[114:115], v[226:227] op_sel:[1,1] op_sel_hi:[1,0]
	v_pk_mul_f32 v[124:125], v[110:111], v[218:219] op_sel:[1,1] op_sel_hi:[1,0]
	v_pk_mul_f32 v[128:129], v[118:119], v[224:225] op_sel:[1,1] op_sel_hi:[1,0]
	v_pk_fma_f32 v[90:91], v[106:107], v[220:221], v[122:123] op_sel_hi:[0,1,1] neg_lo:[0,0,1]
	v_pk_fma_f32 v[92:93], v[114:115], v[226:227], v[126:127] op_sel_hi:[0,1,1] neg_lo:[0,0,1]
	v_pk_mul_f32 v[122:123], v[108:109], v[222:223] op_sel:[1,1] op_sel_hi:[1,0]
	v_pk_mul_f32 v[126:127], v[116:117], v[228:229] op_sel:[1,1] op_sel_hi:[1,0]
; DI float2 twid(float r) { return float2{__builtin_amdgcn_cosf(r), -__builtin_amdgcn_sinf(r)}; }
; DI void bfly_fwd(float2 a0, float2 a1, float2 a2, float2 a3, float r, float2& o0, float2& o1, float2& o2, float2& o3) {
;   float2 t0 = {a0.x + a2.x, a0.y + a2.y}, t1 = {a0.x - a2.x, a0.y - a2.y}, t2 = {a1.x + a3.x, a1.y + a3.y}, t3 = {a1.x - a3.x, a1.y - a3.y};
;   float2 b0 = {t0.x + t2.x, t0.y + t2.y}, b2 = {t0.x - t2.x, t0.y - t2.y}, b1 = {t1.x + t3.y, t1.y - t3.x}, b3 = {t1.x - t3.y, t1.y + t3.x};
;   float2 w1 = twid(r), w2 = cmul(w1, w1), w3 = cmul(w2, w1);
;   o0 = b0; o1 = cmul(b1, w1); o2 = cmul(b2, w2); o3 = cmul(b3, w3);
; }
;   const int lq2 = lq1 - 2, Q1 = 1 << lq1, Q2 = 1 << lq2; const float invM1 = 1.f / (float)(4 << lq1), invM2 = 1.f / (float)(4 << lq2);
;   for (int gg = tid; gg < NBT * (N / 16); gg += NTHR) { const int g = gg & (N / 16 - 1); float2* z = z0 + (gg / (N / 16)) * N; const int jp = g & (Q2 - 1), base = ((g >> lq2) << (lq2 + 4)) + jp; float2 x[4][4];
; #pragma unroll
;     for (int q1 = 0; q1 < 4; ++q1)
; #pragma unroll
;       for (int q2 = 0; q2 < 4; ++q2) x[q1][q2] = z[base + q1 * Q1 + q2 * Q2];
; #pragma unroll
;     for (int q2 = 0; q2 < 4; ++q2) bfly_fwd(x[0][q2], x[1][q2], x[2][q2], x[3][q2], (float)(jp + q2 * Q2) * invM1, x[0][q2], x[1][q2], x[2][q2], x[3][q2]);
; #pragma unroll
;     for (int q1 = 0; q1 < 4; ++q1) bfly_fwd(x[q1][0], x[q1][1], x[q1][2], x[q1][3], (float)jp * invM2, x[q1][0], x[q1][1], x[q1][2], x[q1][3]);
; #pragma unroll
;     for (int q1 = 0; q1 < 4; ++q1)
; #pragma unroll
;       for (int q2 = 0; q2 < 4; ++q2) z[base + q1 * Q1 + q2 * Q2] = x[q1][q2]; }
;   __syncthreads();
; }
	v_pk_fma_f32 v[82:83], v[110:111], v[218:219], v[124:125] op_sel_hi:[0,1,1] neg_lo:[0,0,1]
	v_pk_fma_f32 v[84:85], v[118:119], v[224:225], v[128:129] op_sel_hi:[0,1,1] neg_lo:[0,0,1]
	v_pk_fma_f32 v[98:99], v[108:109], v[222:223], v[122:123] op_sel_hi:[0,1,1] neg_lo:[0,0,1]
	v_pk_fma_f32 v[100:101], v[116:117], v[228:229], v[126:127] op_sel_hi:[0,1,1] neg_lo:[0,0,1]
	v_pk_add_f32 v[106:107], v[70:71], v[94:95]
	v_pk_add_f32 v[114:115], v[72:73], v[96:97]
	v_pk_add_f32 v[110:111], v[86:87], v[102:103]
	v_pk_add_f32 v[118:119], v[88:89], v[104:105]
	v_pk_add_f32 v[108:109], v[70:71], v[94:95] neg_lo:[0,1] neg_hi:[0,1]
	v_pk_add_f32 v[116:117], v[72:73], v[96:97] neg_lo:[0,1] neg_hi:[0,1]
	v_pk_add_f32 v[112:113], v[86:87], v[102:103] neg_lo:[0,1] neg_hi:[0,1]
	v_pk_add_f32 v[120:121], v[88:89], v[104:105] neg_lo:[0,1] neg_hi:[0,1]
	v_pk_add_f32 v[70:71], v[106:107], v[110:111]
	v_pk_add_f32 v[72:73], v[114:115], v[118:119]
	v_pk_add_f32 v[106:107], v[106:107], v[110:111] neg_lo:[0,1] neg_hi:[0,1]
	v_pk_add_f32 v[114:115], v[114:115], v[118:119] neg_lo:[0,1] neg_hi:[0,1]
	v_pk_add_f32 v[110:111], v[108:109], v[112:113] op_sel:[0,1] op_sel_hi:[1,0] neg_hi:[0,1]
	v_pk_add_f32 v[118:119], v[116:117], v[120:121] op_sel:[0,1] op_sel_hi:[1,0] neg_hi:[0,1]
	v_pk_add_f32 v[108:109], v[108:109], v[112:113] op_sel:[0,1] op_sel_hi:[1,0] neg_lo:[0,1]
	v_pk_add_f32 v[116:117], v[116:117], v[120:121] op_sel:[0,1] op_sel_hi:[1,0] neg_lo:[0,1]
	v_pk_mul_f32 v[122:123], v[106:107], v[232:233] op_sel:[1,1] op_sel_hi:[1,0]
	v_pk_mul_f32 v[126:127], v[114:115], v[238:239] op_sel:[1,1] op_sel_hi:[1,0]
	v_pk_mul_f32 v[124:125], v[110:111], v[230:231] op_sel:[1,1] op_sel_hi:[1,0]
	v_pk_mul_f32 v[128:129], v[118:119], v[236:237] op_sel:[1,1] op_sel_hi:[1,0]
	v_pk_fma_f32 v[94:95], v[106:107], v[232:233], v[122:123] op_sel_hi:[0,1,1] neg_lo:[0,0,1]
	v_pk_fma_f32 v[96:97], v[114:115], v[238:239], v[126:127] op_sel_hi:[0,1,1] neg_lo:[0,0,1]
	v_pk_mul_f32 v[122:123], v[108:109], v[234:235] op_sel:[1,1] op_sel_hi:[1,0]
	v_pk_mul_f32 v[126:127], v[116:117], v[242:243] op_sel:[1,1] op_sel_hi:[1,0]
	v_pk_fma_f32 v[86:87], v[110:111], v[230:231], v[124:125] op_sel_hi:[0,1,1] neg_lo:[0,0,1]
	v_pk_fma_f32 v[88:89], v[118:119], v[236:237], v[128:129] op_sel_hi:[0,1,1] neg_lo:[0,0,1]
	v_pk_fma_f32 v[102:103], v[108:109], v[234:235], v[122:123] op_sel_hi:[0,1,1] neg_lo:[0,0,1]
	v_pk_fma_f32 v[104:105], v[116:117], v[242:243], v[126:127] op_sel_hi:[0,1,1] neg_lo:[0,0,1]
	v_pk_add_f32 v[106:107], v[66:67], v[70:71]
	v_pk_add_f32 v[114:115], v[82:83], v[86:87]
	v_pk_add_f32 v[110:111], v[68:69], v[72:73]
	v_pk_add_f32 v[118:119], v[84:85], v[88:89]
	v_pk_add_f32 v[108:109], v[66:67], v[70:71] neg_lo:[0,1] neg_hi:[0,1]
	v_pk_add_f32 v[116:117], v[82:83], v[86:87] neg_lo:[0,1] neg_hi:[0,1]
	v_pk_add_f32 v[112:113], v[68:69], v[72:73] neg_lo:[0,1] neg_hi:[0,1]
	v_pk_add_f32 v[120:121], v[84:85], v[88:89] neg_lo:[0,1] neg_hi:[0,1]
	v_pk_add_f32 v[66:67], v[106:107], v[110:111]
	v_pk_add_f32 v[82:83], v[114:115], v[118:119]
	v_pk_add_f32 v[106:107], v[106:107], v[110:111] neg_lo:[0,1] neg_hi:[0,1]
	v_pk_add_f32 v[114:115], v[114:115], v[118:119] neg_lo:[0,1] neg_hi:[0,1]
	v_pk_add_f32 v[110:111], v[108:109], v[112:113] op_sel:[0,1] op_sel_hi:[1,0] neg_hi:[0,1]
	v_pk_add_f32 v[118:119], v[116:117], v[120:121] op_sel:[0,1] op_sel_hi:[1,0] neg_hi:[0,1]
	v_pk_add_f32 v[108:109], v[108:109], v[112:113] op_sel:[0,1] op_sel_hi:[1,0] neg_lo:[0,1]
	v_pk_add_f32 v[116:117], v[116:117], v[120:121] op_sel:[0,1] op_sel_hi:[1,0] neg_lo:[0,1]
	v_pk_mul_f32 v[122:123], v[106:107], v[246:247] op_sel:[1,1] op_sel_hi:[1,0]
	v_pk_mul_f32 v[126:127], v[114:115], v[246:247] op_sel:[1,1] op_sel_hi:[1,0]
	v_pk_mul_f32 v[124:125], v[110:111], v[244:245] op_sel:[1,1] op_sel_hi:[1,0]
	v_pk_mul_f32 v[128:129], v[118:119], v[244:245] op_sel:[1,1] op_sel_hi:[1,0]
	v_pk_fma_f32 v[70:71], v[106:107], v[246:247], v[122:123] op_sel_hi:[0,1,1] neg_lo:[0,0,1]
	v_pk_fma_f32 v[86:87], v[114:115], v[246:247], v[126:127] op_sel_hi:[0,1,1] neg_lo:[0,0,1]
	v_pk_mul_f32 v[122:123], v[108:109], v[248:249] op_sel:[1,1] op_sel_hi:[1,0]
	v_pk_mul_f32 v[126:127], v[116:117], v[248:249] op_sel:[1,1] op_sel_hi:[1,0]
	v_pk_fma_f32 v[68:69], v[110:111], v[244:245], v[124:125] op_sel_hi:[0,1,1] neg_lo:[0,0,1]
	v_pk_fma_f32 v[84:85], v[118:119], v[244:245], v[128:129] op_sel_hi:[0,1,1] neg_lo:[0,0,1]
	v_pk_fma_f32 v[72:73], v[108:109], v[248:249], v[122:123] op_sel_hi:[0,1,1] neg_lo:[0,0,1]
	v_pk_fma_f32 v[88:89], v[116:117], v[248:249], v[126:127] op_sel_hi:[0,1,1] neg_lo:[0,0,1]
	v_pk_add_f32 v[106:107], v[90:91], v[94:95]
	v_pk_add_f32 v[114:115], v[98:99], v[102:103]
	v_pk_add_f32 v[110:111], v[92:93], v[96:97]
	v_pk_add_f32 v[118:119], v[100:101], v[104:105]
	v_pk_add_f32 v[108:109], v[90:91], v[94:95] neg_lo:[0,1] neg_hi:[0,1]
	v_pk_add_f32 v[116:117], v[98:99], v[102:103] neg_lo:[0,1] neg_hi:[0,1]
	v_pk_add_f32 v[112:113], v[92:93], v[96:97] neg_lo:[0,1] neg_hi:[0,1]
	v_pk_add_f32 v[120:121], v[100:101], v[104:105] neg_lo:[0,1] neg_hi:[0,1]
	v_pk_add_f32 v[90:91], v[106:107], v[110:111]
	v_pk_add_f32 v[98:99], v[114:115], v[118:119]
	v_pk_add_f32 v[106:107], v[106:107], v[110:111] neg_lo:[0,1] neg_hi:[0,1]
	v_pk_add_f32 v[114:115], v[114:115], v[118:119] neg_lo:[0,1] neg_hi:[0,1]
	v_pk_add_f32 v[110:111], v[108:109], v[112:113] op_sel:[0,1] op_sel_hi:[1,0] neg_hi:[0,1]
	v_pk_add_f32 v[118:119], v[116:117], v[120:121] op_sel:[0,1] op_sel_hi:[1,0] neg_hi:[0,1]
	v_pk_add_f32 v[108:109], v[108:109], v[112:113] op_sel:[0,1] op_sel_hi:[1,0] neg_lo:[0,1]
	v_pk_add_f32 v[116:117], v[116:117], v[120:121] op_sel:[0,1] op_sel_hi:[1,0] neg_lo:[0,1]
;   const int lq2 = lq1 - 2, Q1 = 1 << lq1, Q2 = 1 << lq2; const float invM1 = 1.f / (float)(4 << lq1), invM2 = 1.f / (float)(4 << lq2);
;   for (int gg = tid; gg < NBT * (N / 16); gg += NTHR) { const int g = gg & (N / 16 - 1); float2* z = z0 + (gg / (N / 16)) * N; const int jp = g & (Q2 - 1), base = ((g >> lq2) << (lq2 + 4)) + jp; float2 x[4][4];
; #pragma unroll
;     for (int q1 = 0; q1 < 4; ++q1)
; #pragma unroll
;       for (int q2 = 0; q2 < 4; ++q2) x[q1][q2] = z[base + q1 * Q1 + q2 * Q2];
; #pragma unroll
;     for (int q2 = 0; q2 < 4; ++q2) bfly_fwd(x[0][q2], x[1][q2], x[2][q2], x[3][q2], (float)(jp + q2 * Q2) * invM1, x[0][q2], x[1][q2], x[2][q2], x[3][q2]);
; #pragma unroll
;     for (int q1 = 0; q1 < 4; ++q1) bfly_fwd(x[q1][0], x[q1][1], x[q1][2], x[q1][3], (float)jp * invM2, x[q1][0], x[q1][1], x[q1][2], x[q1][3]);
; #pragma unroll
;     for (int q1 = 0; q1 < 4; ++q1)
; #pragma unroll
;       for (int q2 = 0; q2 < 4; ++q2) z[base + q1 * Q1 + q2 * Q2] = x[q1][q2]; }
;   __syncthreads();
; }
	v_pk_mul_f32 v[122:123], v[106:107], v[246:247] op_sel:[1,1] op_sel_hi:[1,0]
	v_pk_mul_f32 v[126:127], v[114:115], v[246:247] op_sel:[1,1] op_sel_hi:[1,0]
	v_pk_mul_f32 v[124:125], v[110:111], v[244:245] op_sel:[1,1] op_sel_hi:[1,0]
	v_pk_mul_f32 v[128:129], v[118:119], v[244:245] op_sel:[1,1] op_sel_hi:[1,0]
	v_pk_fma_f32 v[94:95], v[106:107], v[246:247], v[122:123] op_sel_hi:[0,1,1] neg_lo:[0,0,1]
	v_pk_fma_f32 v[102:103], v[114:115], v[246:247], v[126:127] op_sel_hi:[0,1,1] neg_lo:[0,0,1]
	v_pk_mul_f32 v[122:123], v[108:109], v[248:249] op_sel:[1,1] op_sel_hi:[1,0]
	v_pk_mul_f32 v[126:127], v[116:117], v[248:249] op_sel:[1,1] op_sel_hi:[1,0]
	v_pk_fma_f32 v[92:93], v[110:111], v[244:245], v[124:125] op_sel_hi:[0,1,1] neg_lo:[0,0,1]
	v_pk_fma_f32 v[100:101], v[118:119], v[244:245], v[128:129] op_sel_hi:[0,1,1] neg_lo:[0,0,1]
	v_pk_fma_f32 v[96:97], v[108:109], v[248:249], v[122:123] op_sel_hi:[0,1,1] neg_lo:[0,0,1]
	v_pk_fma_f32 v[104:105], v[116:117], v[248:249], v[126:127] op_sel_hi:[0,1,1] neg_lo:[0,0,1]
	s_nop 0
	ds_write2st64_b64 v216, v[66:67], v[68:69] offset1:4
	ds_write2st64_b64 v216, v[70:71], v[72:73] offset0:8 offset1:12
	ds_write2st64_b64 v216, v[82:83], v[84:85] offset0:16 offset1:20
	ds_write2st64_b64 v216, v[86:87], v[88:89] offset0:24 offset1:28
	ds_write2st64_b64 v216, v[90:91], v[92:93] offset0:32 offset1:36
	ds_write2st64_b64 v216, v[94:95], v[96:97] offset0:40 offset1:44
	ds_write2st64_b64 v216, v[98:99], v[100:101] offset0:48 offset1:52
	ds_write2st64_b64 v216, v[102:103], v[104:105] offset0:56 offset1:60
	s_waitcnt lgkmcnt(8)
	v_pk_add_f32 v[106:107], v[188:189], v[204:205]
	v_pk_add_f32 v[114:115], v[190:191], v[206:207]
	v_pk_add_f32 v[110:111], v[196:197], v[212:213]
	v_pk_add_f32 v[118:119], v[198:199], v[214:215]
	v_pk_add_f32 v[108:109], v[188:189], v[204:205] neg_lo:[0,1] neg_hi:[0,1]
	v_pk_add_f32 v[116:117], v[190:191], v[206:207] neg_lo:[0,1] neg_hi:[0,1]
	v_pk_add_f32 v[112:113], v[196:197], v[212:213] neg_lo:[0,1] neg_hi:[0,1]
	v_pk_add_f32 v[120:121], v[198:199], v[214:215] neg_lo:[0,1] neg_hi:[0,1]
	v_pk_add_f32 v[188:189], v[106:107], v[110:111]
	v_pk_add_f32 v[190:191], v[114:115], v[118:119]
	v_pk_add_f32 v[106:107], v[106:107], v[110:111] neg_lo:[0,1] neg_hi:[0,1]
	v_pk_add_f32 v[114:115], v[114:115], v[118:119] neg_lo:[0,1] neg_hi:[0,1]
	v_pk_add_f32 v[110:111], v[108:109], v[112:113] op_sel:[0,1] op_sel_hi:[1,0] neg_hi:[0,1]
	v_pk_add_f32 v[118:119], v[116:117], v[120:121] op_sel:[0,1] op_sel_hi:[1,0] neg_hi:[0,1]
	v_pk_add_f32 v[108:109], v[108:109], v[112:113] op_sel:[0,1] op_sel_hi:[1,0] neg_lo:[0,1]
	v_pk_add_f32 v[116:117], v[116:117], v[120:121] op_sel:[0,1] op_sel_hi:[1,0] neg_lo:[0,1]
	v_pk_mul_f32 v[122:123], v[106:107], v[220:221] op_sel:[1,1] op_sel_hi:[1,0]
	v_pk_mul_f32 v[126:127], v[114:115], v[226:227] op_sel:[1,1] op_sel_hi:[1,0]
	v_pk_mul_f32 v[124:125], v[110:111], v[218:219] op_sel:[1,1] op_sel_hi:[1,0]
	v_pk_mul_f32 v[128:129], v[118:119], v[224:225] op_sel:[1,1] op_sel_hi:[1,0]
	v_pk_fma_f32 v[204:205], v[106:107], v[220:221], v[122:123] op_sel_hi:[0,1,1] neg_lo:[0,0,1]
	v_pk_fma_f32 v[206:207], v[114:115], v[226:227], v[126:127] op_sel_hi:[0,1,1] neg_lo:[0,0,1]
	v_pk_mul_f32 v[122:123], v[108:109], v[222:223] op_sel:[1,1] op_sel_hi:[1,0]
	v_pk_mul_f32 v[126:127], v[116:117], v[228:229] op_sel:[1,1] op_sel_hi:[1,0]
	v_pk_fma_f32 v[196:197], v[110:111], v[218:219], v[124:125] op_sel_hi:[0,1,1] neg_lo:[0,0,1]
	v_pk_fma_f32 v[198:199], v[118:119], v[224:225], v[128:129] op_sel_hi:[0,1,1] neg_lo:[0,0,1]
	v_pk_fma_f32 v[212:213], v[108:109], v[222:223], v[122:123] op_sel_hi:[0,1,1] neg_lo:[0,0,1]
	v_pk_fma_f32 v[214:215], v[116:117], v[228:229], v[126:127] op_sel_hi:[0,1,1] neg_lo:[0,0,1]
	v_pk_add_f32 v[106:107], v[192:193], v[208:209]
	v_pk_add_f32 v[114:115], v[194:195], v[210:211]
	v_pk_add_f32 v[110:111], v[200:201], v[252:253]
	v_pk_add_f32 v[118:119], v[202:203], v[254:255]
	v_pk_add_f32 v[108:109], v[192:193], v[208:209] neg_lo:[0,1] neg_hi:[0,1]
	v_pk_add_f32 v[116:117], v[194:195], v[210:211] neg_lo:[0,1] neg_hi:[0,1]
	v_pk_add_f32 v[112:113], v[200:201], v[252:253] neg_lo:[0,1] neg_hi:[0,1]
	v_pk_add_f32 v[120:121], v[202:203], v[254:255] neg_lo:[0,1] neg_hi:[0,1]
	v_pk_add_f32 v[192:193], v[106:107], v[110:111]
	v_pk_add_f32 v[194:195], v[114:115], v[118:119]
	v_pk_add_f32 v[106:107], v[106:107], v[110:111] neg_lo:[0,1] neg_hi:[0,1]
	v_pk_add_f32 v[114:115], v[114:115], v[118:119] neg_lo:[0,1] neg_hi:[0,1]
	v_pk_add_f32 v[110:111], v[108:109], v[112:113] op_sel:[0,1] op_sel_hi:[1,0] neg_hi:[0,1]
	v_pk_add_f32 v[118:119], v[116:117], v[120:121] op_sel:[0,1] op_sel_hi:[1,0] neg_hi:[0,1]
	v_pk_add_f32 v[108:109], v[108:109], v[112:113] op_sel:[0,1] op_sel_hi:[1,0] neg_lo:[0,1]
	v_pk_add_f32 v[116:117], v[116:117], v[120:121] op_sel:[0,1] op_sel_hi:[1,0] neg_lo:[0,1]
	v_pk_mul_f32 v[122:123], v[106:107], v[232:233] op_sel:[1,1] op_sel_hi:[1,0]
	v_pk_mul_f32 v[126:127], v[114:115], v[238:239] op_sel:[1,1] op_sel_hi:[1,0]
	v_pk_mul_f32 v[124:125], v[110:111], v[230:231] op_sel:[1,1] op_sel_hi:[1,0]
	v_pk_mul_f32 v[128:129], v[118:119], v[236:237] op_sel:[1,1] op_sel_hi:[1,0]
	v_pk_fma_f32 v[208:209], v[106:107], v[232:233], v[122:123] op_sel_hi:[0,1,1] neg_lo:[0,0,1]
	v_pk_fma_f32 v[210:211], v[114:115], v[238:239], v[126:127] op_sel_hi:[0,1,1] neg_lo:[0,0,1]
;   const int lq2 = lq1 - 2, Q1 = 1 << lq1, Q2 = 1 << lq2; const float invM1 = 1.f / (float)(4 << lq1), invM2 = 1.f / (float)(4 << lq2);
;   for (int gg = tid; gg < NBT * (N / 16); gg += NTHR) { const int g = gg & (N / 16 - 1); float2* z = z0 + (gg / (N / 16)) * N; const int jp = g & (Q2 - 1), base = ((g >> lq2) << (lq2 + 4)) + jp; float2 x[4][4];
; #pragma unroll
;     for (int q1 = 0; q1 < 4; ++q1)
; #pragma unroll
;       for (int q2 = 0; q2 < 4; ++q2) x[q1][q2] = z[base + q1 * Q1 + q2 * Q2];
; #pragma unroll
;     for (int q2 = 0; q2 < 4; ++q2) bfly_fwd(x[0][q2], x[1][q2], x[2][q2], x[3][q2], (float)(jp + q2 * Q2) * invM1, x[0][q2], x[1][q2], x[2][q2], x[3][q2]);
; #pragma unroll
;     for (int q1 = 0; q1 < 4; ++q1) bfly_fwd(x[q1][0], x[q1][1], x[q1][2], x[q1][3], (float)jp * invM2, x[q1][0], x[q1][1], x[q1][2], x[q1][3]);
; #pragma unroll
;     for (int q1 = 0; q1 < 4; ++q1)
; #pragma unroll
;       for (int q2 = 0; q2 < 4; ++q2) z[base + q1 * Q1 + q2 * Q2] = x[q1][q2]; }
;   __syncthreads();
; }
	v_pk_mul_f32 v[122:123], v[108:109], v[234:235] op_sel:[1,1] op_sel_hi:[1,0]
	v_pk_mul_f32 v[126:127], v[116:117], v[242:243] op_sel:[1,1] op_sel_hi:[1,0]
	v_pk_fma_f32 v[200:201], v[110:111], v[230:231], v[124:125] op_sel_hi:[0,1,1] neg_lo:[0,0,1]
	v_pk_fma_f32 v[202:203], v[118:119], v[236:237], v[128:129] op_sel_hi:[0,1,1] neg_lo:[0,0,1]
	v_pk_fma_f32 v[252:253], v[108:109], v[234:235], v[122:123] op_sel_hi:[0,1,1] neg_lo:[0,0,1]
	v_pk_fma_f32 v[254:255], v[116:117], v[242:243], v[126:127] op_sel_hi:[0,1,1] neg_lo:[0,0,1]
	v_pk_add_f32 v[106:107], v[188:189], v[192:193]
	v_pk_add_f32 v[114:115], v[196:197], v[200:201]
	v_pk_add_f32 v[110:111], v[190:191], v[194:195]
	v_pk_add_f32 v[118:119], v[198:199], v[202:203]
	v_pk_add_f32 v[108:109], v[188:189], v[192:193] neg_lo:[0,1] neg_hi:[0,1]
	v_pk_add_f32 v[116:117], v[196:197], v[200:201] neg_lo:[0,1] neg_hi:[0,1]
	v_pk_add_f32 v[112:113], v[190:191], v[194:195] neg_lo:[0,1] neg_hi:[0,1]
	v_pk_add_f32 v[120:121], v[198:199], v[202:203] neg_lo:[0,1] neg_hi:[0,1]
	v_pk_add_f32 v[188:189], v[106:107], v[110:111]
	v_pk_add_f32 v[196:197], v[114:115], v[118:119]
	v_pk_add_f32 v[106:107], v[106:107], v[110:111] neg_lo:[0,1] neg_hi:[0,1]
	v_pk_add_f32 v[114:115], v[114:115], v[118:119] neg_lo:[0,1] neg_hi:[0,1]
	v_pk_add_f32 v[110:111], v[108:109], v[112:113] op_sel:[0,1] op_sel_hi:[1,0] neg_hi:[0,1]
	v_pk_add_f32 v[118:119], v[116:117], v[120:121] op_sel:[0,1] op_sel_hi:[1,0] neg_hi:[0,1]
	v_pk_add_f32 v[108:109], v[108:109], v[112:113] op_sel:[0,1] op_sel_hi:[1,0] neg_lo:[0,1]
	v_pk_add_f32 v[116:117], v[116:117], v[120:121] op_sel:[0,1] op_sel_hi:[1,0] neg_lo:[0,1]
	v_pk_mul_f32 v[122:123], v[106:107], v[246:247] op_sel:[1,1] op_sel_hi:[1,0]
	v_pk_mul_f32 v[126:127], v[114:115], v[246:247] op_sel:[1,1] op_sel_hi:[1,0]
	v_pk_mul_f32 v[124:125], v[110:111], v[244:245] op_sel:[1,1] op_sel_hi:[1,0]
	v_pk_mul_f32 v[128:129], v[118:119], v[244:245] op_sel:[1,1] op_sel_hi:[1,0]
	v_pk_fma_f32 v[192:193], v[106:107], v[246:247], v[122:123] op_sel_hi:[0,1,1] neg_lo:[0,0,1]
	v_pk_fma_f32 v[200:201], v[114:115], v[246:247], v[126:127] op_sel_hi:[0,1,1] neg_lo:[0,0,1]
	v_pk_mul_f32 v[122:123], v[108:109], v[248:249] op_sel:[1,1] op_sel_hi:[1,0]
	v_pk_mul_f32 v[126:127], v[116:117], v[248:249] op_sel:[1,1] op_sel_hi:[1,0]
	v_pk_fma_f32 v[190:191], v[110:111], v[244:245], v[124:125] op_sel_hi:[0,1,1] neg_lo:[0,0,1]
	v_pk_fma_f32 v[198:199], v[118:119], v[244:245], v[128:129] op_sel_hi:[0,1,1] neg_lo:[0,0,1]
	v_pk_fma_f32 v[194:195], v[108:109], v[248:249], v[122:123] op_sel_hi:[0,1,1] neg_lo:[0,0,1]
	v_pk_fma_f32 v[202:203], v[116:117], v[248:249], v[126:127] op_sel_hi:[0,1,1] neg_lo:[0,0,1]
	v_pk_add_f32 v[106:107], v[204:205], v[208:209]
	v_pk_add_f32 v[114:115], v[212:213], v[252:253]
	v_pk_add_f32 v[110:111], v[206:207], v[210:211]
	v_pk_add_f32 v[118:119], v[214:215], v[254:255]
	v_pk_add_f32 v[108:109], v[204:205], v[208:209] neg_lo:[0,1] neg_hi:[0,1]
	v_pk_add_f32 v[116:117], v[212:213], v[252:253] neg_lo:[0,1] neg_hi:[0,1]
	v_pk_add_f32 v[112:113], v[206:207], v[210:211] neg_lo:[0,1] neg_hi:[0,1]
	v_pk_add_f32 v[120:121], v[214:215], v[254:255] neg_lo:[0,1] neg_hi:[0,1]
	v_pk_add_f32 v[204:205], v[106:107], v[110:111]
	v_pk_add_f32 v[212:213], v[114:115], v[118:119]
	v_pk_add_f32 v[106:107], v[106:107], v[110:111] neg_lo:[0,1] neg_hi:[0,1]
	v_pk_add_f32 v[114:115], v[114:115], v[118:119] neg_lo:[0,1] neg_hi:[0,1]
	v_pk_add_f32 v[110:111], v[108:109], v[112:113] op_sel:[0,1] op_sel_hi:[1,0] neg_hi:[0,1]
	v_pk_add_f32 v[118:119], v[116:117], v[120:121] op_sel:[0,1] op_sel_hi:[1,0] neg_hi:[0,1]
	v_pk_add_f32 v[108:109], v[108:109], v[112:113] op_sel:[0,1] op_sel_hi:[1,0] neg_lo:[0,1]
	v_pk_add_f32 v[116:117], v[116:117], v[120:121] op_sel:[0,1] op_sel_hi:[1,0] neg_lo:[0,1]
	v_pk_mul_f32 v[122:123], v[106:107], v[246:247] op_sel:[1,1] op_sel_hi:[1,0]
	v_pk_mul_f32 v[126:127], v[114:115], v[246:247] op_sel:[1,1] op_sel_hi:[1,0]
	v_pk_mul_f32 v[124:125], v[110:111], v[244:245] op_sel:[1,1] op_sel_hi:[1,0]
	v_pk_mul_f32 v[128:129], v[118:119], v[244:245] op_sel:[1,1] op_sel_hi:[1,0]
	v_pk_fma_f32 v[208:209], v[106:107], v[246:247], v[122:123] op_sel_hi:[0,1,1] neg_lo:[0,0,1]
	v_pk_fma_f32 v[252:253], v[114:115], v[246:247], v[126:127] op_sel_hi:[0,1,1] neg_lo:[0,0,1]
	v_pk_mul_f32 v[122:123], v[108:109], v[248:249] op_sel:[1,1] op_sel_hi:[1,0]
	v_pk_mul_f32 v[126:127], v[116:117], v[248:249] op_sel:[1,1] op_sel_hi:[1,0]
	v_pk_fma_f32 v[206:207], v[110:111], v[244:245], v[124:125] op_sel_hi:[0,1,1] neg_lo:[0,0,1]
	v_pk_fma_f32 v[214:215], v[118:119], v[244:245], v[128:129] op_sel_hi:[0,1,1] neg_lo:[0,0,1]
	v_pk_fma_f32 v[210:211], v[108:109], v[248:249], v[122:123] op_sel_hi:[0,1,1] neg_lo:[0,0,1]
	v_pk_fma_f32 v[254:255], v[116:117], v[248:249], v[126:127] op_sel_hi:[0,1,1] neg_lo:[0,0,1]
	s_nop 0
	ds_write2st64_b64 v217, v[188:189], v[190:191] offset1:4
	ds_write2st64_b64 v217, v[192:193], v[194:195] offset0:8 offset1:12
	ds_write2st64_b64 v217, v[196:197], v[198:199] offset0:16 offset1:20
	ds_write2st64_b64 v217, v[200:201], v[202:203] offset0:24 offset1:28
	ds_write2st64_b64 v217, v[204:205], v[206:207] offset0:32 offset1:36
	ds_write2st64_b64 v217, v[208:209], v[210:211] offset0:40 offset1:44
	ds_write2st64_b64 v217, v[212:213], v[214:215] offset0:48 offset1:52
	ds_write2st64_b64 v217, v[252:253], v[254:255] offset0:56 offset1:60
	s_mov_b64 s[80:81], exec

;   const int lq2 = lq1 - 2, Q1 = 1 << lq1, Q2 = 1 << lq2; const float invM1 = 1.f / (float)(4 << lq1), invM2 = 1.f / (float)(4 << lq2);
;   for (int gg = tid; gg < NBT * (N / 16); gg += NTHR) { const int g = gg & (N / 16 - 1); float2* z = z0 + (gg / (N / 16)) * N; const int jp = g & (Q2 - 1), base = ((g >> lq2) << (lq2 + 4)) + jp; float2 x[4][4];
; #pragma unroll
;     for (int q1 = 0; q1 < 4; ++q1)
; #pragma unroll
;       for (int q2 = 0; q2 < 4; ++q2) x[q1][q2] = z[base + q1 * Q1 + q2 * Q2];
; #pragma unroll
;     for (int q2 = 0; q2 < 4; ++q2) bfly_fwd(x[0][q2], x[1][q2], x[2][q2], x[3][q2], (float)(jp + q2 * Q2) * invM1, x[0][q2], x[1][q2], x[2][q2], x[3][q2]);
; #pragma unroll
;     for (int q1 = 0; q1 < 4; ++q1) bfly_fwd(x[q1][0], x[q1][1], x[q1][2], x[q1][3], (float)jp * invM2, x[q1][0], x[q1][1], x[q1][2], x[q1][3]);
; #pragma unroll
;     for (int q1 = 0; q1 < 4; ++q1)
; #pragma unroll
;       for (int q2 = 0; q2 < 4; ++q2) z[base + q1 * Q1 + q2 * Q2] = x[q1][q2]; }
;   __syncthreads();
; }
.LBB0_1603:
	v_ashrrev_i32_e32 v216, 31, v69
	v_lshrrev_b32_e32 v216, 23, v216
	v_add_lshl_u32 v216, v69, v216, 7
	v_and_b32_e32 v216, 0xffff0000, v216
	v_add_u32_e32 v217, v68, v216
	ds_read2_b64 v[82:85], v217 offset1:16
	ds_read2_b64 v[86:89], v217 offset0:32 offset1:48
	ds_read2_b64 v[90:93], v217 offset0:64 offset1:80
	ds_read2_b64 v[94:97], v217 offset0:96 offset1:112
	ds_read2_b64 v[98:101], v217 offset0:128 offset1:144
	ds_read2_b64 v[102:105], v217 offset0:160 offset1:176
	ds_read2_b64 v[106:109], v217 offset0:192 offset1:208
	ds_read2_b64 v[110:113], v217 offset0:224 offset1:240
	v_add_u32_e32 v70, 0x200, v69
	v_mov_b32_e32 v69, v70
	v_ashrrev_i32_e32 v148, 31, v69
	v_lshrrev_b32_e32 v148, 23, v148
	v_add_lshl_u32 v148, v69, v148, 7
	v_and_b32_e32 v148, 0xffff0000, v148
	v_add_u32_e32 v251, v68, v148
	ds_read2_b64 v[188:191], v251 offset1:16
	ds_read2_b64 v[192:195], v251 offset0:32 offset1:48
	ds_read2_b64 v[196:199], v251 offset0:64 offset1:80
	ds_read2_b64 v[200:203], v251 offset0:96 offset1:112
	ds_read2_b64 v[204:207], v251 offset0:128 offset1:144
	ds_read2_b64 v[208:211], v251 offset0:160 offset1:176
	ds_read2_b64 v[212:215], v251 offset0:192 offset1:208
	ds_read2_b64 v[252:255], v251 offset0:224 offset1:240
	v_add_u32_e32 v70, 0x200, v69
	v_mov_b32_e32 v69, v70
	v_and_b32_e32 v241, 0xf, v69
	v_cvt_f32_u32_e32 v250, v241
	v_mul_f32_e32 v250, 0x3b800000, v250
	v_cos_f32_e32 v218, v250
	v_sin_f32_e32 v219, v250
	s_nop 1
	v_xor_b32_e32 v219, 0x80000000, v219
	s_nop 0
	v_pk_mul_f32 v[128:129], v[218:219], v[218:219] op_sel:[1,1] op_sel_hi:[1,0]
	s_nop 0
	v_pk_fma_f32 v[220:221], v[218:219], v[218:219], v[128:129] op_sel_hi:[0,1,1] neg_lo:[0,0,1]
	s_nop 0
	v_pk_mul_f32 v[128:129], v[220:221], v[218:219] op_sel:[1,1] op_sel_hi:[1,0]
	s_nop 0
	v_pk_fma_f32 v[222:223], v[220:221], v[218:219], v[128:129] op_sel_hi:[0,1,1] neg_lo:[0,0,1]
	v_pk_mul_f32 v[128:129], v[220:221], v[220:221] op_sel:[1,1] op_sel_hi:[1,0]
	s_nop 0
	v_pk_fma_f32 v[244:245], v[220:221], v[220:221], v[128:129] op_sel_hi:[0,1,1] neg_lo:[0,0,1]
	s_nop 0
	v_mul_f32_e32 v241, 0x3ec3ef15, v219
	v_mul_f32_e32 v250, 0xbec3ef15, v218
	v_fmamk_f32 v224, v218, 0x3f6c835e, v241
	v_fmamk_f32 v225, v219, 0x3f6c835e, v250
	v_mul_f32_e32 v241, 0x3f3504f3, v219
	v_mul_f32_e32 v250, 0xbf3504f3, v218
	v_fmamk_f32 v230, v218, 0x3f3504f3, v241
	v_fmamk_f32 v231, v219, 0x3f3504f3, v250
	v_mul_f32_e32 v241, 0x3f6c835e, v219
	v_mul_f32_e32 v250, 0xbf6c835e, v218
	v_fmamk_f32 v236, v218, 0x3ec3ef15, v241
	v_fmamk_f32 v237, v219, 0x3ec3ef15, v250
	v_mul_f32_e32 v241, 0x3f3504f3, v221
	v_mul_f32_e32 v250, 0xbf3504f3, v220
	v_fmamk_f32 v226, v220, 0x3f3504f3, v241
	v_fmamk_f32 v227, v221, 0x3f3504f3, v250
	v_mul_f32_e32 v241, 0x3f800000, v221
	v_mul_f32_e32 v250, 0xbf800000, v220
	v_fmamk_f32 v232, v220, 0x00000000, v241
	v_fmamk_f32 v233, v221, 0x00000000, v250
	v_mul_f32_e32 v241, 0x3f3504f3, v221
	v_mul_f32_e32 v250, 0xbf3504f3, v220
	v_fmamk_f32 v238, v220, 0xbf3504f3, v241
	v_fmamk_f32 v239, v221, 0xbf3504f3, v250
	v_mul_f32_e32 v241, 0x3f6c835e, v223
	v_mul_f32_e32 v250, 0xbf6c835e, v222
	v_fmamk_f32 v228, v222, 0x3ec3ef15, v241
	v_fmamk_f32 v229, v223, 0x3ec3ef15, v250
	v_mul_f32_e32 v241, 0x3f3504f3, v223
	v_mul_f32_e32 v250, 0xbf3504f3, v222
	v_fmamk_f32 v234, v222, 0xbf3504f3, v241
	v_fmamk_f32 v235, v223, 0xbf3504f3, v250
	v_mul_f32_e32 v241, 0xbec3ef15, v223
	v_mul_f32_e32 v250, 0x3ec3ef15, v222
	v_fmamk_f32 v242, v222, 0xbf6c835e, v241
	v_fmamk_f32 v243, v223, 0xbf6c835e, v250
	v_pk_mul_f32 v[128:129], v[244:245], v[244:245] op_sel:[1,1] op_sel_hi:[1,0]
	s_nop 0
	v_pk_fma_f32 v[246:247], v[244:245], v[244:245], v[128:129] op_sel_hi:[0,1,1] neg_lo:[0,0,1]
	s_nop 0
	v_pk_mul_f32 v[128:129], v[246:247], v[244:245] op_sel:[1,1] op_sel_hi:[1,0]
	s_nop 0
	v_pk_fma_f32 v[248:249], v[246:247], v[244:245], v[128:129] op_sel_hi:[0,1,1] neg_lo:[0,0,1]
	s_nop 0
	s_waitcnt lgkmcnt(8)
	v_pk_add_f32 v[72:73], v[82:83], v[98:99]
	v_pk_add_f32 v[120:121], v[84:85], v[100:101]
	v_pk_add_f32 v[116:117], v[90:91], v[106:107]
	v_pk_add_f32 v[124:125], v[92:93], v[108:109]
	v_pk_add_f32 v[114:115], v[82:83], v[98:99] neg_lo:[0,1] neg_hi:[0,1]
	v_pk_add_f32 v[122:123], v[84:85], v[100:101] neg_lo:[0,1] neg_hi:[0,1]
	v_pk_add_f32 v[118:119], v[90:91], v[106:107] neg_lo:[0,1] neg_hi:[0,1]
	v_pk_add_f32 v[126:127], v[92:93], v[108:109] neg_lo:[0,1] neg_hi:[0,1]
	v_pk_add_f32 v[82:83], v[72:73], v[116:117]
	v_pk_add_f32 v[84:85], v[120:121], v[124:125]
	v_pk_add_f32 v[72:73], v[72:73], v[116:117] neg_lo:[0,1] neg_hi:[0,1]
	v_pk_add_f32 v[120:121], v[120:121], v[124:125] neg_lo:[0,1] neg_hi:[0,1]
	v_pk_add_f32 v[116:117], v[114:115], v[118:119] op_sel:[0,1] op_sel_hi:[1,0] neg_hi:[0,1]
	v_pk_add_f32 v[124:125], v[122:123], v[126:127] op_sel:[0,1] op_sel_hi:[1,0] neg_hi:[0,1]
	v_pk_add_f32 v[114:115], v[114:115], v[118:119] op_sel:[0,1] op_sel_hi:[1,0] neg_lo:[0,1]
	v_pk_add_f32 v[122:123], v[122:123], v[126:127] op_sel:[0,1] op_sel_hi:[1,0] neg_lo:[0,1]
	v_pk_mul_f32 v[128:129], v[72:73], v[220:221] op_sel:[1,1] op_sel_hi:[1,0]
	v_pk_mul_f32 v[132:133], v[120:121], v[226:227] op_sel:[1,1] op_sel_hi:[1,0]
	v_pk_mul_f32 v[130:131], v[116:117], v[218:219] op_sel:[1,1] op_sel_hi:[1,0]
	v_pk_mul_f32 v[134:135], v[124:125], v[224:225] op_sel:[1,1] op_sel_hi:[1,0]
	v_pk_fma_f32 v[98:99], v[72:73], v[220:221], v[128:129] op_sel_hi:[0,1,1] neg_lo:[0,0,1]
	v_pk_fma_f32 v[100:101], v[120:121], v[226:227], v[132:133] op_sel_hi:[0,1,1] neg_lo:[0,0,1]
	v_pk_mul_f32 v[128:129], v[114:115], v[222:223] op_sel:[1,1] op_sel_hi:[1,0]
	v_pk_mul_f32 v[132:133], v[122:123], v[228:229] op_sel:[1,1] op_sel_hi:[1,0]
; DI float2 twid(float r) { return float2{__builtin_amdgcn_cosf(r), -__builtin_amdgcn_sinf(r)}; }
; DI void bfly_fwd(float2 a0, float2 a1, float2 a2, float2 a3, float r, float2& o0, float2& o1, float2& o2, float2& o3) {
;   float2 t0 = {a0.x + a2.x, a0.y + a2.y}, t1 = {a0.x - a2.x, a0.y - a2.y}, t2 = {a1.x + a3.x, a1.y + a3.y}, t3 = {a1.x - a3.x, a1.y - a3.y};
;   float2 b0 = {t0.x + t2.x, t0.y + t2.y}, b2 = {t0.x - t2.x, t0.y - t2.y}, b1 = {t1.x + t3.y, t1.y - t3.x}, b3 = {t1.x - t3.y, t1.y + t3.x};
;   float2 w1 = twid(r), w2 = cmul(w1, w1), w3 = cmul(w2, w1);
;   o0 = b0; o1 = cmul(b1, w1); o2 = cmul(b2, w2); o3 = cmul(b3, w3);
; }
;   const int lq2 = lq1 - 2, Q1 = 1 << lq1, Q2 = 1 << lq2; const float invM1 = 1.f / (float)(4 << lq1), invM2 = 1.f / (float)(4 << lq2);
;   for (int gg = tid; gg < NBT * (N / 16); gg += NTHR) { const int g = gg & (N / 16 - 1); float2* z = z0 + (gg / (N / 16)) * N; const int jp = g & (Q2 - 1), base = ((g >> lq2) << (lq2 + 4)) + jp; float2 x[4][4];
; #pragma unroll
;     for (int q1 = 0; q1 < 4; ++q1)
; #pragma unroll
;       for (int q2 = 0; q2 < 4; ++q2) x[q1][q2] = z[base + q1 * Q1 + q2 * Q2];
; #pragma unroll
;     for (int q2 = 0; q2 < 4; ++q2) bfly_fwd(x[0][q2], x[1][q2], x[2][q2], x[3][q2], (float)(jp + q2 * Q2) * invM1, x[0][q2], x[1][q2], x[2][q2], x[3][q2]);
; #pragma unroll
;     for (int q1 = 0; q1 < 4; ++q1) bfly_fwd(x[q1][0], x[q1][1], x[q1][2], x[q1][3], (float)jp * invM2, x[q1][0], x[q1][1], x[q1][2], x[q1][3]);
; #pragma unroll
;     for (int q1 = 0; q1 < 4; ++q1)
; #pragma unroll
;       for (int q2 = 0; q2 < 4; ++q2) z[base + q1 * Q1 + q2 * Q2] = x[q1][q2]; }
;   __syncthreads();
; }
	v_pk_fma_f32 v[90:91], v[116:117], v[218:219], v[130:131] op_sel_hi:[0,1,1] neg_lo:[0,0,1]
	v_pk_fma_f32 v[92:93], v[124:125], v[224:225], v[134:135] op_sel_hi:[0,1,1] neg_lo:[0,0,1]
	v_pk_fma_f32 v[106:107], v[114:115], v[222:223], v[128:129] op_sel_hi:[0,1,1] neg_lo:[0,0,1]
	v_pk_fma_f32 v[108:109], v[122:123], v[228:229], v[132:133] op_sel_hi:[0,1,1] neg_lo:[0,0,1]
	v_pk_add_f32 v[72:73], v[86:87], v[102:103]
	v_pk_add_f32 v[120:121], v[88:89], v[104:105]
	v_pk_add_f32 v[116:117], v[94:95], v[110:111]
	v_pk_add_f32 v[124:125], v[96:97], v[112:113]
	v_pk_add_f32 v[114:115], v[86:87], v[102:103] neg_lo:[0,1] neg_hi:[0,1]
	v_pk_add_f32 v[122:123], v[88:89], v[104:105] neg_lo:[0,1] neg_hi:[0,1]
	v_pk_add_f32 v[118:119], v[94:95], v[110:111] neg_lo:[0,1] neg_hi:[0,1]
	v_pk_add_f32 v[126:127], v[96:97], v[112:113] neg_lo:[0,1] neg_hi:[0,1]
	v_pk_add_f32 v[86:87], v[72:73], v[116:117]
	v_pk_add_f32 v[88:89], v[120:121], v[124:125]
	v_pk_add_f32 v[72:73], v[72:73], v[116:117] neg_lo:[0,1] neg_hi:[0,1]
	v_pk_add_f32 v[120:121], v[120:121], v[124:125] neg_lo:[0,1] neg_hi:[0,1]
	v_pk_add_f32 v[116:117], v[114:115], v[118:119] op_sel:[0,1] op_sel_hi:[1,0] neg_hi:[0,1]
	v_pk_add_f32 v[124:125], v[122:123], v[126:127] op_sel:[0,1] op_sel_hi:[1,0] neg_hi:[0,1]
	v_pk_add_f32 v[114:115], v[114:115], v[118:119] op_sel:[0,1] op_sel_hi:[1,0] neg_lo:[0,1]
	v_pk_add_f32 v[122:123], v[122:123], v[126:127] op_sel:[0,1] op_sel_hi:[1,0] neg_lo:[0,1]
	v_pk_mul_f32 v[128:129], v[72:73], v[232:233] op_sel:[1,1] op_sel_hi:[1,0]
	v_pk_mul_f32 v[132:133], v[120:121], v[238:239] op_sel:[1,1] op_sel_hi:[1,0]
	v_pk_mul_f32 v[130:131], v[116:117], v[230:231] op_sel:[1,1] op_sel_hi:[1,0]
	v_pk_mul_f32 v[134:135], v[124:125], v[236:237] op_sel:[1,1] op_sel_hi:[1,0]
	v_pk_fma_f32 v[102:103], v[72:73], v[232:233], v[128:129] op_sel_hi:[0,1,1] neg_lo:[0,0,1]
	v_pk_fma_f32 v[104:105], v[120:121], v[238:239], v[132:133] op_sel_hi:[0,1,1] neg_lo:[0,0,1]
	v_pk_mul_f32 v[128:129], v[114:115], v[234:235] op_sel:[1,1] op_sel_hi:[1,0]
	v_pk_mul_f32 v[132:133], v[122:123], v[242:243] op_sel:[1,1] op_sel_hi:[1,0]
	v_pk_fma_f32 v[94:95], v[116:117], v[230:231], v[130:131] op_sel_hi:[0,1,1] neg_lo:[0,0,1]
	v_pk_fma_f32 v[96:97], v[124:125], v[236:237], v[134:135] op_sel_hi:[0,1,1] neg_lo:[0,0,1]
	v_pk_fma_f32 v[110:111], v[114:115], v[234:235], v[128:129] op_sel_hi:[0,1,1] neg_lo:[0,0,1]
	v_pk_fma_f32 v[112:113], v[122:123], v[242:243], v[132:133] op_sel_hi:[0,1,1] neg_lo:[0,0,1]
	v_pk_add_f32 v[72:73], v[82:83], v[86:87]
	v_pk_add_f32 v[120:121], v[90:91], v[94:95]
	v_pk_add_f32 v[116:117], v[84:85], v[88:89]
	v_pk_add_f32 v[124:125], v[92:93], v[96:97]
	v_pk_add_f32 v[114:115], v[82:83], v[86:87] neg_lo:[0,1] neg_hi:[0,1]
	v_pk_add_f32 v[122:123], v[90:91], v[94:95] neg_lo:[0,1] neg_hi:[0,1]
	v_pk_add_f32 v[118:119], v[84:85], v[88:89] neg_lo:[0,1] neg_hi:[0,1]
	v_pk_add_f32 v[126:127], v[92:93], v[96:97] neg_lo:[0,1] neg_hi:[0,1]
	v_pk_add_f32 v[82:83], v[72:73], v[116:117]
	v_pk_add_f32 v[90:91], v[120:121], v[124:125]
	v_pk_add_f32 v[72:73], v[72:73], v[116:117] neg_lo:[0,1] neg_hi:[0,1]
	v_pk_add_f32 v[120:121], v[120:121], v[124:125] neg_lo:[0,1] neg_hi:[0,1]
	v_pk_add_f32 v[116:117], v[114:115], v[118:119] op_sel:[0,1] op_sel_hi:[1,0] neg_hi:[0,1]
	v_pk_add_f32 v[124:125], v[122:123], v[126:127] op_sel:[0,1] op_sel_hi:[1,0] neg_hi:[0,1]
	v_pk_add_f32 v[114:115], v[114:115], v[118:119] op_sel:[0,1] op_sel_hi:[1,0] neg_lo:[0,1]
	v_pk_add_f32 v[122:123], v[122:123], v[126:127] op_sel:[0,1] op_sel_hi:[1,0] neg_lo:[0,1]
	v_pk_mul_f32 v[128:129], v[72:73], v[246:247] op_sel:[1,1] op_sel_hi:[1,0]
	v_pk_mul_f32 v[132:133], v[120:121], v[246:247] op_sel:[1,1] op_sel_hi:[1,0]
	v_pk_mul_f32 v[130:131], v[116:117], v[244:245] op_sel:[1,1] op_sel_hi:[1,0]
	v_pk_mul_f32 v[134:135], v[124:125], v[244:245] op_sel:[1,1] op_sel_hi:[1,0]
	v_pk_fma_f32 v[86:87], v[72:73], v[246:247], v[128:129] op_sel_hi:[0,1,1] neg_lo:[0,0,1]
	v_pk_fma_f32 v[94:95], v[120:121], v[246:247], v[132:133] op_sel_hi:[0,1,1] neg_lo:[0,0,1]
	v_pk_mul_f32 v[128:129], v[114:115], v[248:249] op_sel:[1,1] op_sel_hi:[1,0]
	v_pk_mul_f32 v[132:133], v[122:123], v[248:249] op_sel:[1,1] op_sel_hi:[1,0]
	v_pk_fma_f32 v[84:85], v[116:117], v[244:245], v[130:131] op_sel_hi:[0,1,1] neg_lo:[0,0,1]
	v_pk_fma_f32 v[92:93], v[124:125], v[244:245], v[134:135] op_sel_hi:[0,1,1] neg_lo:[0,0,1]
	v_pk_fma_f32 v[88:89], v[114:115], v[248:249], v[128:129] op_sel_hi:[0,1,1] neg_lo:[0,0,1]
	v_pk_fma_f32 v[96:97], v[122:123], v[248:249], v[132:133] op_sel_hi:[0,1,1] neg_lo:[0,0,1]
	v_pk_add_f32 v[72:73], v[98:99], v[102:103]
	v_pk_add_f32 v[120:121], v[106:107], v[110:111]
	v_pk_add_f32 v[116:117], v[100:101], v[104:105]
	v_pk_add_f32 v[124:125], v[108:109], v[112:113]
	v_pk_add_f32 v[114:115], v[98:99], v[102:103] neg_lo:[0,1] neg_hi:[0,1]
	v_pk_add_f32 v[122:123], v[106:107], v[110:111] neg_lo:[0,1] neg_hi:[0,1]
	v_pk_add_f32 v[118:119], v[100:101], v[104:105] neg_lo:[0,1] neg_hi:[0,1]
	v_pk_add_f32 v[126:127], v[108:109], v[112:113] neg_lo:[0,1] neg_hi:[0,1]
	v_pk_add_f32 v[98:99], v[72:73], v[116:117]
	v_pk_add_f32 v[106:107], v[120:121], v[124:125]
	v_pk_add_f32 v[72:73], v[72:73], v[116:117] neg_lo:[0,1] neg_hi:[0,1]
	v_pk_add_f32 v[120:121], v[120:121], v[124:125] neg_lo:[0,1] neg_hi:[0,1]
	v_pk_add_f32 v[116:117], v[114:115], v[118:119] op_sel:[0,1] op_sel_hi:[1,0] neg_hi:[0,1]
	v_pk_add_f32 v[124:125], v[122:123], v[126:127] op_sel:[0,1] op_sel_hi:[1,0] neg_hi:[0,1]
	v_pk_add_f32 v[114:115], v[114:115], v[118:119] op_sel:[0,1] op_sel_hi:[1,0] neg_lo:[0,1]
	v_pk_add_f32 v[122:123], v[122:123], v[126:127] op_sel:[0,1] op_sel_hi:[1,0] neg_lo:[0,1]
;   const int lq2 = lq1 - 2, Q1 = 1 << lq1, Q2 = 1 << lq2; const float invM1 = 1.f / (float)(4 << lq1), invM2 = 1.f / (float)(4 << lq2);
;   for (int gg = tid; gg < NBT * (N / 16); gg += NTHR) { const int g = gg & (N / 16 - 1); float2* z = z0 + (gg / (N / 16)) * N; const int jp = g & (Q2 - 1), base = ((g >> lq2) << (lq2 + 4)) + jp; float2 x[4][4];
; #pragma unroll
;     for (int q1 = 0; q1 < 4; ++q1)
; #pragma unroll
;       for (int q2 = 0; q2 < 4; ++q2) x[q1][q2] = z[base + q1 * Q1 + q2 * Q2];
; #pragma unroll
;     for (int q2 = 0; q2 < 4; ++q2) bfly_fwd(x[0][q2], x[1][q2], x[2][q2], x[3][q2], (float)(jp + q2 * Q2) * invM1, x[0][q2], x[1][q2], x[2][q2], x[3][q2]);
; #pragma unroll
;     for (int q1 = 0; q1 < 4; ++q1) bfly_fwd(x[q1][0], x[q1][1], x[q1][2], x[q1][3], (float)jp * invM2, x[q1][0], x[q1][1], x[q1][2], x[q1][3]);
; #pragma unroll
;     for (int q1 = 0; q1 < 4; ++q1)
; #pragma unroll
;       for (int q2 = 0; q2 < 4; ++q2) z[base + q1 * Q1 + q2 * Q2] = x[q1][q2]; }
;   __syncthreads();
; }
	v_pk_mul_f32 v[128:129], v[72:73], v[246:247] op_sel:[1,1] op_sel_hi:[1,0]
	v_pk_mul_f32 v[132:133], v[120:121], v[246:247] op_sel:[1,1] op_sel_hi:[1,0]
	v_pk_mul_f32 v[130:131], v[116:117], v[244:245] op_sel:[1,1] op_sel_hi:[1,0]
	v_pk_mul_f32 v[134:135], v[124:125], v[244:245] op_sel:[1,1] op_sel_hi:[1,0]
	v_pk_fma_f32 v[102:103], v[72:73], v[246:247], v[128:129] op_sel_hi:[0,1,1] neg_lo:[0,0,1]
	v_pk_fma_f32 v[110:111], v[120:121], v[246:247], v[132:133] op_sel_hi:[0,1,1] neg_lo:[0,0,1]
	v_pk_mul_f32 v[128:129], v[114:115], v[248:249] op_sel:[1,1] op_sel_hi:[1,0]
	v_pk_mul_f32 v[132:133], v[122:123], v[248:249] op_sel:[1,1] op_sel_hi:[1,0]
	v_pk_fma_f32 v[100:101], v[116:117], v[244:245], v[130:131] op_sel_hi:[0,1,1] neg_lo:[0,0,1]
	v_pk_fma_f32 v[108:109], v[124:125], v[244:245], v[134:135] op_sel_hi:[0,1,1] neg_lo:[0,0,1]
	v_pk_fma_f32 v[104:105], v[114:115], v[248:249], v[128:129] op_sel_hi:[0,1,1] neg_lo:[0,0,1]
	v_pk_fma_f32 v[112:113], v[122:123], v[248:249], v[132:133] op_sel_hi:[0,1,1] neg_lo:[0,0,1]
	s_nop 0
	ds_write2_b64 v217, v[82:83], v[84:85] offset1:16
	ds_write2_b64 v217, v[86:87], v[88:89] offset0:32 offset1:48
	ds_write2_b64 v217, v[90:91], v[92:93] offset0:64 offset1:80
	ds_write2_b64 v217, v[94:95], v[96:97] offset0:96 offset1:112
	ds_write2_b64 v217, v[98:99], v[100:101] offset0:128 offset1:144
	ds_write2_b64 v217, v[102:103], v[104:105] offset0:160 offset1:176
	ds_write2_b64 v217, v[106:107], v[108:109] offset0:192 offset1:208
	ds_write2_b64 v217, v[110:111], v[112:113] offset0:224 offset1:240
	s_waitcnt lgkmcnt(8)
	v_pk_add_f32 v[72:73], v[188:189], v[204:205]
	v_pk_add_f32 v[120:121], v[190:191], v[206:207]
	v_pk_add_f32 v[116:117], v[196:197], v[212:213]
	v_pk_add_f32 v[124:125], v[198:199], v[214:215]
	v_pk_add_f32 v[114:115], v[188:189], v[204:205] neg_lo:[0,1] neg_hi:[0,1]
	v_pk_add_f32 v[122:123], v[190:191], v[206:207] neg_lo:[0,1] neg_hi:[0,1]
	v_pk_add_f32 v[118:119], v[196:197], v[212:213] neg_lo:[0,1] neg_hi:[0,1]
	v_pk_add_f32 v[126:127], v[198:199], v[214:215] neg_lo:[0,1] neg_hi:[0,1]
	v_pk_add_f32 v[188:189], v[72:73], v[116:117]
	v_pk_add_f32 v[190:191], v[120:121], v[124:125]
	v_pk_add_f32 v[72:73], v[72:73], v[116:117] neg_lo:[0,1] neg_hi:[0,1]
	v_pk_add_f32 v[120:121], v[120:121], v[124:125] neg_lo:[0,1] neg_hi:[0,1]
	v_pk_add_f32 v[116:117], v[114:115], v[118:119] op_sel:[0,1] op_sel_hi:[1,0] neg_hi:[0,1]
	v_pk_add_f32 v[124:125], v[122:123], v[126:127] op_sel:[0,1] op_sel_hi:[1,0] neg_hi:[0,1]
	v_pk_add_f32 v[114:115], v[114:115], v[118:119] op_sel:[0,1] op_sel_hi:[1,0] neg_lo:[0,1]
	v_pk_add_f32 v[122:123], v[122:123], v[126:127] op_sel:[0,1] op_sel_hi:[1,0] neg_lo:[0,1]
	v_pk_mul_f32 v[128:129], v[72:73], v[220:221] op_sel:[1,1] op_sel_hi:[1,0]
	v_pk_mul_f32 v[132:133], v[120:121], v[226:227] op_sel:[1,1] op_sel_hi:[1,0]
	v_pk_mul_f32 v[130:131], v[116:117], v[218:219] op_sel:[1,1] op_sel_hi:[1,0]
	v_pk_mul_f32 v[134:135], v[124:125], v[224:225] op_sel:[1,1] op_sel_hi:[1,0]
	v_pk_fma_f32 v[204:205], v[72:73], v[220:221], v[128:129] op_sel_hi:[0,1,1] neg_lo:[0,0,1]
	v_pk_fma_f32 v[206:207], v[120:121], v[226:227], v[132:133] op_sel_hi:[0,1,1] neg_lo:[0,0,1]
	v_pk_mul_f32 v[128:129], v[114:115], v[222:223] op_sel:[1,1] op_sel_hi:[1,0]
	v_pk_mul_f32 v[132:133], v[122:123], v[228:229] op_sel:[1,1] op_sel_hi:[1,0]
	v_pk_fma_f32 v[196:197], v[116:117], v[218:219], v[130:131] op_sel_hi:[0,1,1] neg_lo:[0,0,1]
	v_pk_fma_f32 v[198:199], v[124:125], v[224:225], v[134:135] op_sel_hi:[0,1,1] neg_lo:[0,0,1]
	v_pk_fma_f32 v[212:213], v[114:115], v[222:223], v[128:129] op_sel_hi:[0,1,1] neg_lo:[0,0,1]
	v_pk_fma_f32 v[214:215], v[122:123], v[228:229], v[132:133] op_sel_hi:[0,1,1] neg_lo:[0,0,1]
	v_pk_add_f32 v[72:73], v[192:193], v[208:209]
	v_pk_add_f32 v[120:121], v[194:195], v[210:211]
	v_pk_add_f32 v[116:117], v[200:201], v[252:253]
	v_pk_add_f32 v[124:125], v[202:203], v[254:255]
	v_pk_add_f32 v[114:115], v[192:193], v[208:209] neg_lo:[0,1] neg_hi:[0,1]
	v_pk_add_f32 v[122:123], v[194:195], v[210:211] neg_lo:[0,1] neg_hi:[0,1]
	v_pk_add_f32 v[118:119], v[200:201], v[252:253] neg_lo:[0,1] neg_hi:[0,1]
	v_pk_add_f32 v[126:127], v[202:203], v[254:255] neg_lo:[0,1] neg_hi:[0,1]
	v_pk_add_f32 v[192:193], v[72:73], v[116:117]
	v_pk_add_f32 v[194:195], v[120:121], v[124:125]
	v_pk_add_f32 v[72:73], v[72:73], v[116:117] neg_lo:[0,1] neg_hi:[0,1]
	v_pk_add_f32 v[120:121], v[120:121], v[124:125] neg_lo:[0,1] neg_hi:[0,1]
	v_pk_add_f32 v[116:117], v[114:115], v[118:119] op_sel:[0,1] op_sel_hi:[1,0] neg_hi:[0,1]
	v_pk_add_f32 v[124:125], v[122:123], v[126:127] op_sel:[0,1] op_sel_hi:[1,0] neg_hi:[0,1]
	v_pk_add_f32 v[114:115], v[114:115], v[118:119] op_sel:[0,1] op_sel_hi:[1,0] neg_lo:[0,1]
	v_pk_add_f32 v[122:123], v[122:123], v[126:127] op_sel:[0,1] op_sel_hi:[1,0] neg_lo:[0,1]
	v_pk_mul_f32 v[128:129], v[72:73], v[232:233] op_sel:[1,1] op_sel_hi:[1,0]
	v_pk_mul_f32 v[132:133], v[120:121], v[238:239] op_sel:[1,1] op_sel_hi:[1,0]
	v_pk_mul_f32 v[130:131], v[116:117], v[230:231] op_sel:[1,1] op_sel_hi:[1,0]
	v_pk_mul_f32 v[134:135], v[124:125], v[236:237] op_sel:[1,1] op_sel_hi:[1,0]
	v_pk_fma_f32 v[208:209], v[72:73], v[232:233], v[128:129] op_sel_hi:[0,1,1] neg_lo:[0,0,1]
	v_pk_fma_f32 v[210:211], v[120:121], v[238:239], v[132:133] op_sel_hi:[0,1,1] neg_lo:[0,0,1]
;   const int lq2 = lq1 - 2, Q1 = 1 << lq1, Q2 = 1 << lq2; const float invM1 = 1.f / (float)(4 << lq1), invM2 = 1.f / (float)(4 << lq2);
;   for (int gg = tid; gg < NBT * (N / 16); gg += NTHR) { const int g = gg & (N / 16 - 1); float2* z = z0 + (gg / (N / 16)) * N; const int jp = g & (Q2 - 1), base = ((g >> lq2) << (lq2 + 4)) + jp; float2 x[4][4];
; #pragma unroll
;     for (int q1 = 0; q1 < 4; ++q1)
; #pragma unroll
;       for (int q2 = 0; q2 < 4; ++q2) x[q1][q2] = z[base + q1 * Q1 + q2 * Q2];
; #pragma unroll
;     for (int q2 = 0; q2 < 4; ++q2) bfly_fwd(x[0][q2], x[1][q2], x[2][q2], x[3][q2], (float)(jp + q2 * Q2) * invM1, x[0][q2], x[1][q2], x[2][q2], x[3][q2]);
; #pragma unroll
;     for (int q1 = 0; q1 < 4; ++q1) bfly_fwd(x[q1][0], x[q1][1], x[q1][2], x[q1][3], (float)jp * invM2, x[q1][0], x[q1][1], x[q1][2], x[q1][3]);
; #pragma unroll
;     for (int q1 = 0; q1 < 4; ++q1)
; #pragma unroll
;       for (int q2 = 0; q2 < 4; ++q2) z[base + q1 * Q1 + q2 * Q2] = x[q1][q2]; }
;   __syncthreads();
; }
	v_pk_mul_f32 v[128:129], v[114:115], v[234:235] op_sel:[1,1] op_sel_hi:[1,0]
	v_pk_mul_f32 v[132:133], v[122:123], v[242:243] op_sel:[1,1] op_sel_hi:[1,0]
	v_pk_fma_f32 v[200:201], v[116:117], v[230:231], v[130:131] op_sel_hi:[0,1,1] neg_lo:[0,0,1]
	v_pk_fma_f32 v[202:203], v[124:125], v[236:237], v[134:135] op_sel_hi:[0,1,1] neg_lo:[0,0,1]
	v_pk_fma_f32 v[252:253], v[114:115], v[234:235], v[128:129] op_sel_hi:[0,1,1] neg_lo:[0,0,1]
	v_pk_fma_f32 v[254:255], v[122:123], v[242:243], v[132:133] op_sel_hi:[0,1,1] neg_lo:[0,0,1]
	v_pk_add_f32 v[72:73], v[188:189], v[192:193]
	v_pk_add_f32 v[120:121], v[196:197], v[200:201]
	v_pk_add_f32 v[116:117], v[190:191], v[194:195]
	v_pk_add_f32 v[124:125], v[198:199], v[202:203]
	v_pk_add_f32 v[114:115], v[188:189], v[192:193] neg_lo:[0,1] neg_hi:[0,1]
	v_pk_add_f32 v[122:123], v[196:197], v[200:201] neg_lo:[0,1] neg_hi:[0,1]
	v_pk_add_f32 v[118:119], v[190:191], v[194:195] neg_lo:[0,1] neg_hi:[0,1]
	v_pk_add_f32 v[126:127], v[198:199], v[202:203] neg_lo:[0,1] neg_hi:[0,1]
	v_pk_add_f32 v[188:189], v[72:73], v[116:117]
	v_pk_add_f32 v[196:197], v[120:121], v[124:125]
	v_pk_add_f32 v[72:73], v[72:73], v[116:117] neg_lo:[0,1] neg_hi:[0,1]
	v_pk_add_f32 v[120:121], v[120:121], v[124:125] neg_lo:[0,1] neg_hi:[0,1]
	v_pk_add_f32 v[116:117], v[114:115], v[118:119] op_sel:[0,1] op_sel_hi:[1,0] neg_hi:[0,1]
	v_pk_add_f32 v[124:125], v[122:123], v[126:127] op_sel:[0,1] op_sel_hi:[1,0] neg_hi:[0,1]
	v_pk_add_f32 v[114:115], v[114:115], v[118:119] op_sel:[0,1] op_sel_hi:[1,0] neg_lo:[0,1]
	v_pk_add_f32 v[122:123], v[122:123], v[126:127] op_sel:[0,1] op_sel_hi:[1,0] neg_lo:[0,1]
	v_pk_mul_f32 v[128:129], v[72:73], v[246:247] op_sel:[1,1] op_sel_hi:[1,0]
	v_pk_mul_f32 v[132:133], v[120:121], v[246:247] op_sel:[1,1] op_sel_hi:[1,0]
	v_pk_mul_f32 v[130:131], v[116:117], v[244:245] op_sel:[1,1] op_sel_hi:[1,0]
	v_pk_mul_f32 v[134:135], v[124:125], v[244:245] op_sel:[1,1] op_sel_hi:[1,0]
	v_pk_fma_f32 v[192:193], v[72:73], v[246:247], v[128:129] op_sel_hi:[0,1,1] neg_lo:[0,0,1]
	v_pk_fma_f32 v[200:201], v[120:121], v[246:247], v[132:133] op_sel_hi:[0,1,1] neg_lo:[0,0,1]
	v_pk_mul_f32 v[128:129], v[114:115], v[248:249] op_sel:[1,1] op_sel_hi:[1,0]
	v_pk_mul_f32 v[132:133], v[122:123], v[248:249] op_sel:[1,1] op_sel_hi:[1,0]
	v_pk_fma_f32 v[190:191], v[116:117], v[244:245], v[130:131] op_sel_hi:[0,1,1] neg_lo:[0,0,1]
	v_pk_fma_f32 v[198:199], v[124:125], v[244:245], v[134:135] op_sel_hi:[0,1,1] neg_lo:[0,0,1]
	v_pk_fma_f32 v[194:195], v[114:115], v[248:249], v[128:129] op_sel_hi:[0,1,1] neg_lo:[0,0,1]
	v_pk_fma_f32 v[202:203], v[122:123], v[248:249], v[132:133] op_sel_hi:[0,1,1] neg_lo:[0,0,1]
	v_pk_add_f32 v[72:73], v[204:205], v[208:209]
	v_pk_add_f32 v[120:121], v[212:213], v[252:253]
	v_pk_add_f32 v[116:117], v[206:207], v[210:211]
	v_pk_add_f32 v[124:125], v[214:215], v[254:255]
	v_pk_add_f32 v[114:115], v[204:205], v[208:209] neg_lo:[0,1] neg_hi:[0,1]
	v_pk_add_f32 v[122:123], v[212:213], v[252:253] neg_lo:[0,1] neg_hi:[0,1]
	v_pk_add_f32 v[118:119], v[206:207], v[210:211] neg_lo:[0,1] neg_hi:[0,1]
	v_pk_add_f32 v[126:127], v[214:215], v[254:255] neg_lo:[0,1] neg_hi:[0,1]
	v_pk_add_f32 v[204:205], v[72:73], v[116:117]
	v_pk_add_f32 v[212:213], v[120:121], v[124:125]
	v_pk_add_f32 v[72:73], v[72:73], v[116:117] neg_lo:[0,1] neg_hi:[0,1]
	v_pk_add_f32 v[120:121], v[120:121], v[124:125] neg_lo:[0,1] neg_hi:[0,1]
	v_pk_add_f32 v[116:117], v[114:115], v[118:119] op_sel:[0,1] op_sel_hi:[1,0] neg_hi:[0,1]
	v_pk_add_f32 v[124:125], v[122:123], v[126:127] op_sel:[0,1] op_sel_hi:[1,0] neg_hi:[0,1]
	v_pk_add_f32 v[114:115], v[114:115], v[118:119] op_sel:[0,1] op_sel_hi:[1,0] neg_lo:[0,1]
	v_pk_add_f32 v[122:123], v[122:123], v[126:127] op_sel:[0,1] op_sel_hi:[1,0] neg_lo:[0,1]
	v_pk_mul_f32 v[128:129], v[72:73], v[246:247] op_sel:[1,1] op_sel_hi:[1,0]
	v_pk_mul_f32 v[132:133], v[120:121], v[246:247] op_sel:[1,1] op_sel_hi:[1,0]
	v_pk_mul_f32 v[130:131], v[116:117], v[244:245] op_sel:[1,1] op_sel_hi:[1,0]
	v_pk_mul_f32 v[134:135], v[124:125], v[244:245] op_sel:[1,1] op_sel_hi:[1,0]
	v_pk_fma_f32 v[208:209], v[72:73], v[246:247], v[128:129] op_sel_hi:[0,1,1] neg_lo:[0,0,1]
	v_pk_fma_f32 v[252:253], v[120:121], v[246:247], v[132:133] op_sel_hi:[0,1,1] neg_lo:[0,0,1]
	v_pk_mul_f32 v[128:129], v[114:115], v[248:249] op_sel:[1,1] op_sel_hi:[1,0]
	v_pk_mul_f32 v[132:133], v[122:123], v[248:249] op_sel:[1,1] op_sel_hi:[1,0]
	v_pk_fma_f32 v[206:207], v[116:117], v[244:245], v[130:131] op_sel_hi:[0,1,1] neg_lo:[0,0,1]
	v_pk_fma_f32 v[214:215], v[124:125], v[244:245], v[134:135] op_sel_hi:[0,1,1] neg_lo:[0,0,1]
	v_pk_fma_f32 v[210:211], v[114:115], v[248:249], v[128:129] op_sel_hi:[0,1,1] neg_lo:[0,0,1]
	v_pk_fma_f32 v[254:255], v[122:123], v[248:249], v[132:133] op_sel_hi:[0,1,1] neg_lo:[0,0,1]
	s_nop 0
	ds_write2_b64 v251, v[188:189], v[190:191] offset1:16
	ds_write2_b64 v251, v[192:193], v[194:195] offset0:32 offset1:48
	ds_write2_b64 v251, v[196:197], v[198:199] offset0:64 offset1:80
	ds_write2_b64 v251, v[200:201], v[202:203] offset0:96 offset1:112
	ds_write2_b64 v251, v[204:205], v[206:207] offset0:128 offset1:144
	ds_write2_b64 v251, v[208:209], v[210:211] offset0:160 offset1:176
	ds_write2_b64 v251, v[212:213], v[214:215] offset0:192 offset1:208
	ds_write2_b64 v251, v[252:253], v[254:255] offset0:224 offset1:240
	s_mov_b64 s[80:81], exec

; DI float2 twid(float r) { return float2{__builtin_amdgcn_cosf(r), -__builtin_amdgcn_sinf(r)}; }
; DI void bfly_inv(float2 s0, float2 s1, float2 s2, float2 s3, float r, float2& o0, float2& o1, float2& o2, float2& o3) {
;   float2 w1 = twid(r), w2 = cmul(w1, w1), w3 = cmul(w2, w1);
;   float2 c0 = s0, c1 = cmulc(s1, w1), c2 = cmulc(s2, w2), c3 = cmulc(s3, w3);
;   float2 t0 = {c0.x + c2.x, c0.y + c2.y}, t1 = {c0.x - c2.x, c0.y - c2.y}, t2 = {c1.x + c3.x, c1.y + c3.y}, t3 = {c1.x - c3.x, c1.y - c3.y};
;   o0 = float2{t0.x + t2.x, t0.y + t2.y}; o2 = float2{t0.x - t2.x, t0.y - t2.y}; o1 = float2{t1.x - t3.y, t1.y + t3.x}; o3 = float2{t1.x + t3.y, t1.y - t3.x};
; }
;   const int lq1 = lq2 + 2, Q1 = 1 << lq1, Q2 = 1 << lq2; const float invM1 = 1.f / (float)(4 << lq1), invM2 = 1.f / (float)(4 << lq2);
;   for (int gg = tid; gg < NBT * (N / 16); gg += NTHR) { const int g = gg & (N / 16 - 1); float2* z = z0 + (gg / (N / 16)) * N; const int jp = g & (Q2 - 1), base = ((g >> lq2) << (lq2 + 4)) + jp; float2 x[4][4];
; #pragma unroll
;     for (int q1 = 0; q1 < 4; ++q1)
; #pragma unroll
;       for (int q2 = 0; q2 < 4; ++q2) x[q1][q2] = z[base + q1 * Q1 + q2 * Q2];
; #pragma unroll
;     for (int q1 = 0; q1 < 4; ++q1) bfly_inv(x[q1][0], x[q1][1], x[q1][2], x[q1][3], (float)jp * invM2, x[q1][0], x[q1][1], x[q1][2], x[q1][3]);
; #pragma unroll
;     for (int q2 = 0; q2 < 4; ++q2) bfly_inv(x[0][q2], x[1][q2], x[2][q2], x[3][q2], (float)(jp + q2 * Q2) * invM1, x[0][q2], x[1][q2], x[2][q2], x[3][q2]);
; #pragma unroll
;     for (int q1 = 0; q1 < 4; ++q1)
; #pragma unroll
;       for (int q2 = 0; q2 < 4; ++q2) z[base + q1 * Q1 + q2 * Q2] = x[q1][q2]; }
;   __syncthreads();
; }
.LBB0_1618:
	v_ashrrev_i32_e32 v216, 31, v82
	v_lshrrev_b32_e32 v216, 23, v216
	v_add_lshl_u32 v216, v82, v216, 7
	v_and_b32_e32 v216, 0xffff0000, v216
	v_add_u32_e32 v217, v20, v216
	ds_read2_b64 v[84:87], v217 offset0:32 offset1:48
	ds_read2_b64 v[88:91], v217 offset1:16
	ds_read2_b64 v[92:95], v217 offset0:64 offset1:80
	ds_read2_b64 v[96:99], v217 offset0:96 offset1:112
	ds_read2_b64 v[100:103], v217 offset0:128 offset1:144
	ds_read2_b64 v[104:107], v217 offset0:160 offset1:176
	ds_read2_b64 v[108:111], v217 offset0:192 offset1:208
	ds_read2_b64 v[112:115], v217 offset0:224 offset1:240
	v_add_u32_e32 v13, 0x200, v82
	v_mov_b32_e32 v82, v13
	v_ashrrev_i32_e32 v148, 31, v82
	v_lshrrev_b32_e32 v148, 23, v148
	v_add_lshl_u32 v148, v82, v148, 7
	v_and_b32_e32 v148, 0xffff0000, v148
	v_add_u32_e32 v251, v20, v148
	ds_read2_b64 v[188:191], v251 offset0:32 offset1:48
	ds_read2_b64 v[192:195], v251 offset1:16
	ds_read2_b64 v[196:199], v251 offset0:64 offset1:80
	ds_read2_b64 v[200:203], v251 offset0:96 offset1:112
	ds_read2_b64 v[204:207], v251 offset0:128 offset1:144
	ds_read2_b64 v[208:211], v251 offset0:160 offset1:176
	ds_read2_b64 v[212:215], v251 offset0:192 offset1:208
	ds_read2_b64 v[252:255], v251 offset0:224 offset1:240
	v_add_u32_e32 v13, 0x200, v82
	v_mov_b32_e32 v82, v13
	v_and_b32_e32 v241, 0xf, v82
	v_cvt_f32_u32_e32 v250, v241
	v_mul_f32_e32 v250, 0x3b800000, v250
	v_cos_f32_e32 v218, v250
	v_sin_f32_e32 v219, v250
	s_nop 1
	s_nop 0
	v_pk_mul_f32 v[132:133], v[218:219], v[218:219] op_sel:[1,1] op_sel_hi:[1,0]
	s_nop 0
	v_pk_fma_f32 v[220:221], v[218:219], v[218:219], v[132:133] op_sel_hi:[0,1,1] neg_lo:[0,0,1]
	s_nop 0
	v_pk_mul_f32 v[132:133], v[220:221], v[218:219] op_sel:[1,1] op_sel_hi:[1,0]
	s_nop 0
	v_pk_fma_f32 v[222:223], v[220:221], v[218:219], v[132:133] op_sel_hi:[0,1,1] neg_lo:[0,0,1]
	v_pk_mul_f32 v[132:133], v[220:221], v[220:221] op_sel:[1,1] op_sel_hi:[1,0]
	s_nop 0
	v_pk_fma_f32 v[244:245], v[220:221], v[220:221], v[132:133] op_sel_hi:[0,1,1] neg_lo:[0,0,1]
	s_nop 0
	v_mul_f32_e32 v241, 0xbec3ef15, v219
	v_mul_f32_e32 v250, 0x3ec3ef15, v218
	v_fmamk_f32 v224, v218, 0x3f6c835e, v241
	v_fmamk_f32 v225, v219, 0x3f6c835e, v250
	v_mul_f32_e32 v241, 0xbf3504f3, v219
	v_mul_f32_e32 v250, 0x3f3504f3, v218
	v_fmamk_f32 v230, v218, 0x3f3504f3, v241
	v_fmamk_f32 v231, v219, 0x3f3504f3, v250
	v_mul_f32_e32 v241, 0xbf6c835e, v219
	v_mul_f32_e32 v250, 0x3f6c835e, v218
	v_fmamk_f32 v236, v218, 0x3ec3ef15, v241
	v_fmamk_f32 v237, v219, 0x3ec3ef15, v250
	v_mul_f32_e32 v241, 0xbf3504f3, v221
	v_mul_f32_e32 v250, 0x3f3504f3, v220
	v_fmamk_f32 v226, v220, 0x3f3504f3, v241
	v_fmamk_f32 v227, v221, 0x3f3504f3, v250
	v_mul_f32_e32 v241, 0xbf800000, v221
	v_mul_f32_e32 v250, 0x3f800000, v220
	v_fmamk_f32 v232, v220, 0x00000000, v241
	v_fmamk_f32 v233, v221, 0x00000000, v250
	v_mul_f32_e32 v241, 0xbf3504f3, v221
	v_mul_f32_e32 v250, 0x3f3504f3, v220
	v_fmamk_f32 v238, v220, 0xbf3504f3, v241
	v_fmamk_f32 v239, v221, 0xbf3504f3, v250
	v_mul_f32_e32 v241, 0xbf6c835e, v223
	v_mul_f32_e32 v250, 0x3f6c835e, v222
	v_fmamk_f32 v228, v222, 0x3ec3ef15, v241
	v_fmamk_f32 v229, v223, 0x3ec3ef15, v250
	v_mul_f32_e32 v241, 0xbf3504f3, v223
	v_mul_f32_e32 v250, 0x3f3504f3, v222
	v_fmamk_f32 v234, v222, 0xbf3504f3, v241
	v_fmamk_f32 v235, v223, 0xbf3504f3, v250
	v_mul_f32_e32 v241, 0x3ec3ef15, v223
	v_mul_f32_e32 v250, 0xbec3ef15, v222
	v_fmamk_f32 v242, v222, 0xbf6c835e, v241
	v_fmamk_f32 v243, v223, 0xbf6c835e, v250
	v_pk_mul_f32 v[132:133], v[244:245], v[244:245] op_sel:[1,1] op_sel_hi:[1,0]
	s_nop 0
	v_pk_fma_f32 v[246:247], v[244:245], v[244:245], v[132:133] op_sel_hi:[0,1,1] neg_lo:[0,0,1]
	s_nop 0
	v_pk_mul_f32 v[132:133], v[246:247], v[244:245] op_sel:[1,1] op_sel_hi:[1,0]
	s_nop 0
	v_pk_fma_f32 v[248:249], v[246:247], v[244:245], v[132:133] op_sel_hi:[0,1,1] neg_lo:[0,0,1]
	s_nop 0
	s_waitcnt lgkmcnt(8)
	v_pk_mul_f32 v[132:133], v[90:91], v[244:245] op_sel:[1,1] op_sel_hi:[1,0]
	v_pk_mul_f32 v[136:137], v[94:95], v[244:245] op_sel:[1,1] op_sel_hi:[1,0]
	v_pk_mul_f32 v[134:135], v[84:85], v[246:247] op_sel:[1,1] op_sel_hi:[1,0]
	v_pk_mul_f32 v[138:139], v[96:97], v[246:247] op_sel:[1,1] op_sel_hi:[1,0]
	v_pk_fma_f32 v[90:91], v[90:91], v[244:245], v[132:133] op_sel_hi:[0,1,1] neg_lo:[0,0,1]
	v_pk_fma_f32 v[94:95], v[94:95], v[244:245], v[136:137] op_sel_hi:[0,1,1] neg_lo:[0,0,1]
	v_pk_mul_f32 v[132:133], v[86:87], v[248:249] op_sel:[1,1] op_sel_hi:[1,0]
	v_pk_mul_f32 v[136:137], v[98:99], v[248:249] op_sel:[1,1] op_sel_hi:[1,0]
	v_pk_fma_f32 v[84:85], v[84:85], v[246:247], v[134:135] op_sel_hi:[0,1,1] neg_lo:[0,0,1]
	v_pk_fma_f32 v[96:97], v[96:97], v[246:247], v[138:139] op_sel_hi:[0,1,1] neg_lo:[0,0,1]
	v_pk_fma_f32 v[86:87], v[86:87], v[248:249], v[132:133] op_sel_hi:[0,1,1] neg_lo:[0,0,1]
	v_pk_fma_f32 v[98:99], v[98:99], v[248:249], v[136:137] op_sel_hi:[0,1,1] neg_lo:[0,0,1]
	v_pk_add_f32 v[116:117], v[88:89], v[84:85]
	v_pk_add_f32 v[124:125], v[92:93], v[96:97]
	v_pk_add_f32 v[120:121], v[90:91], v[86:87]
	v_pk_add_f32 v[128:129], v[94:95], v[98:99]
	v_pk_add_f32 v[118:119], v[88:89], v[84:85] neg_lo:[0,1] neg_hi:[0,1]
	v_pk_add_f32 v[126:127], v[92:93], v[96:97] neg_lo:[0,1] neg_hi:[0,1]
	v_pk_add_f32 v[122:123], v[90:91], v[86:87] neg_lo:[0,1] neg_hi:[0,1]
	v_pk_add_f32 v[130:131], v[94:95], v[98:99] neg_lo:[0,1] neg_hi:[0,1]
	v_pk_add_f32 v[88:89], v[116:117], v[120:121]
	v_pk_add_f32 v[92:93], v[124:125], v[128:129]
	v_pk_add_f32 v[84:85], v[116:117], v[120:121] neg_lo:[0,1] neg_hi:[0,1]
	v_pk_add_f32 v[96:97], v[124:125], v[128:129] neg_lo:[0,1] neg_hi:[0,1]
	v_pk_add_f32 v[90:91], v[118:119], v[122:123] op_sel:[0,1] op_sel_hi:[1,0] neg_lo:[0,1]
; DI float2 twid(float r) { return float2{__builtin_amdgcn_cosf(r), -__builtin_amdgcn_sinf(r)}; }
; DI void bfly_inv(float2 s0, float2 s1, float2 s2, float2 s3, float r, float2& o0, float2& o1, float2& o2, float2& o3) {
;   float2 w1 = twid(r), w2 = cmul(w1, w1), w3 = cmul(w2, w1);
;   float2 c0 = s0, c1 = cmulc(s1, w1), c2 = cmulc(s2, w2), c3 = cmulc(s3, w3);
;   float2 t0 = {c0.x + c2.x, c0.y + c2.y}, t1 = {c0.x - c2.x, c0.y - c2.y}, t2 = {c1.x + c3.x, c1.y + c3.y}, t3 = {c1.x - c3.x, c1.y - c3.y};
;   o0 = float2{t0.x + t2.x, t0.y + t2.y}; o2 = float2{t0.x - t2.x, t0.y - t2.y}; o1 = float2{t1.x - t3.y, t1.y + t3.x}; o3 = float2{t1.x + t3.y, t1.y - t3.x};
; }
;   const int lq1 = lq2 + 2, Q1 = 1 << lq1, Q2 = 1 << lq2; const float invM1 = 1.f / (float)(4 << lq1), invM2 = 1.f / (float)(4 << lq2);
;   for (int gg = tid; gg < NBT * (N / 16); gg += NTHR) { const int g = gg & (N / 16 - 1); float2* z = z0 + (gg / (N / 16)) * N; const int jp = g & (Q2 - 1), base = ((g >> lq2) << (lq2 + 4)) + jp; float2 x[4][4];
; #pragma unroll
;     for (int q1 = 0; q1 < 4; ++q1)
; #pragma unroll
;       for (int q2 = 0; q2 < 4; ++q2) x[q1][q2] = z[base + q1 * Q1 + q2 * Q2];
; #pragma unroll
;     for (int q1 = 0; q1 < 4; ++q1) bfly_inv(x[q1][0], x[q1][1], x[q1][2], x[q1][3], (float)jp * invM2, x[q1][0], x[q1][1], x[q1][2], x[q1][3]);
; #pragma unroll
;     for (int q2 = 0; q2 < 4; ++q2) bfly_inv(x[0][q2], x[1][q2], x[2][q2], x[3][q2], (float)(jp + q2 * Q2) * invM1, x[0][q2], x[1][q2], x[2][q2], x[3][q2]);
; #pragma unroll
;     for (int q1 = 0; q1 < 4; ++q1)
; #pragma unroll
;       for (int q2 = 0; q2 < 4; ++q2) z[base + q1 * Q1 + q2 * Q2] = x[q1][q2]; }
;   __syncthreads();
; }
	v_pk_add_f32 v[94:95], v[126:127], v[130:131] op_sel:[0,1] op_sel_hi:[1,0] neg_lo:[0,1]
	v_pk_add_f32 v[86:87], v[118:119], v[122:123] op_sel:[0,1] op_sel_hi:[1,0] neg_hi:[0,1]
	v_pk_add_f32 v[98:99], v[126:127], v[130:131] op_sel:[0,1] op_sel_hi:[1,0] neg_hi:[0,1]
	v_pk_mul_f32 v[132:133], v[102:103], v[244:245] op_sel:[1,1] op_sel_hi:[1,0]
	v_pk_mul_f32 v[136:137], v[110:111], v[244:245] op_sel:[1,1] op_sel_hi:[1,0]
	v_pk_mul_f32 v[134:135], v[104:105], v[246:247] op_sel:[1,1] op_sel_hi:[1,0]
	v_pk_mul_f32 v[138:139], v[112:113], v[246:247] op_sel:[1,1] op_sel_hi:[1,0]
	v_pk_fma_f32 v[102:103], v[102:103], v[244:245], v[132:133] op_sel_hi:[0,1,1] neg_lo:[0,0,1]
	v_pk_fma_f32 v[110:111], v[110:111], v[244:245], v[136:137] op_sel_hi:[0,1,1] neg_lo:[0,0,1]
	v_pk_mul_f32 v[132:133], v[106:107], v[248:249] op_sel:[1,1] op_sel_hi:[1,0]
	v_pk_mul_f32 v[136:137], v[114:115], v[248:249] op_sel:[1,1] op_sel_hi:[1,0]
	v_pk_fma_f32 v[104:105], v[104:105], v[246:247], v[134:135] op_sel_hi:[0,1,1] neg_lo:[0,0,1]
	v_pk_fma_f32 v[112:113], v[112:113], v[246:247], v[138:139] op_sel_hi:[0,1,1] neg_lo:[0,0,1]
	v_pk_fma_f32 v[106:107], v[106:107], v[248:249], v[132:133] op_sel_hi:[0,1,1] neg_lo:[0,0,1]
	v_pk_fma_f32 v[114:115], v[114:115], v[248:249], v[136:137] op_sel_hi:[0,1,1] neg_lo:[0,0,1]
	v_pk_add_f32 v[116:117], v[100:101], v[104:105]
	v_pk_add_f32 v[124:125], v[108:109], v[112:113]
	v_pk_add_f32 v[120:121], v[102:103], v[106:107]
	v_pk_add_f32 v[128:129], v[110:111], v[114:115]
	v_pk_add_f32 v[118:119], v[100:101], v[104:105] neg_lo:[0,1] neg_hi:[0,1]
	v_pk_add_f32 v[126:127], v[108:109], v[112:113] neg_lo:[0,1] neg_hi:[0,1]
	v_pk_add_f32 v[122:123], v[102:103], v[106:107] neg_lo:[0,1] neg_hi:[0,1]
	v_pk_add_f32 v[130:131], v[110:111], v[114:115] neg_lo:[0,1] neg_hi:[0,1]
	v_pk_add_f32 v[100:101], v[116:117], v[120:121]
	v_pk_add_f32 v[108:109], v[124:125], v[128:129]
	v_pk_add_f32 v[104:105], v[116:117], v[120:121] neg_lo:[0,1] neg_hi:[0,1]
	v_pk_add_f32 v[112:113], v[124:125], v[128:129] neg_lo:[0,1] neg_hi:[0,1]
	v_pk_add_f32 v[102:103], v[118:119], v[122:123] op_sel:[0,1] op_sel_hi:[1,0] neg_lo:[0,1]
	v_pk_add_f32 v[110:111], v[126:127], v[130:131] op_sel:[0,1] op_sel_hi:[1,0] neg_lo:[0,1]
	v_pk_add_f32 v[106:107], v[118:119], v[122:123] op_sel:[0,1] op_sel_hi:[1,0] neg_hi:[0,1]
	v_pk_add_f32 v[114:115], v[126:127], v[130:131] op_sel:[0,1] op_sel_hi:[1,0] neg_hi:[0,1]
	v_pk_mul_f32 v[132:133], v[92:93], v[218:219] op_sel:[1,1] op_sel_hi:[1,0]
	v_pk_mul_f32 v[136:137], v[94:95], v[224:225] op_sel:[1,1] op_sel_hi:[1,0]
	v_pk_mul_f32 v[134:135], v[100:101], v[220:221] op_sel:[1,1] op_sel_hi:[1,0]
	v_pk_mul_f32 v[138:139], v[102:103], v[226:227] op_sel:[1,1] op_sel_hi:[1,0]
	v_pk_fma_f32 v[92:93], v[92:93], v[218:219], v[132:133] op_sel_hi:[0,1,1] neg_lo:[0,0,1]
	v_pk_fma_f32 v[94:95], v[94:95], v[224:225], v[136:137] op_sel_hi:[0,1,1] neg_lo:[0,0,1]
	v_pk_mul_f32 v[132:133], v[108:109], v[222:223] op_sel:[1,1] op_sel_hi:[1,0]
	v_pk_mul_f32 v[136:137], v[110:111], v[228:229] op_sel:[1,1] op_sel_hi:[1,0]
	v_pk_fma_f32 v[100:101], v[100:101], v[220:221], v[134:135] op_sel_hi:[0,1,1] neg_lo:[0,0,1]
	v_pk_fma_f32 v[102:103], v[102:103], v[226:227], v[138:139] op_sel_hi:[0,1,1] neg_lo:[0,0,1]
	v_pk_fma_f32 v[108:109], v[108:109], v[222:223], v[132:133] op_sel_hi:[0,1,1] neg_lo:[0,0,1]
	v_pk_fma_f32 v[110:111], v[110:111], v[228:229], v[136:137] op_sel_hi:[0,1,1] neg_lo:[0,0,1]
	v_pk_add_f32 v[116:117], v[88:89], v[100:101]
	v_pk_add_f32 v[124:125], v[90:91], v[102:103]
	v_pk_add_f32 v[120:121], v[92:93], v[108:109]
	v_pk_add_f32 v[128:129], v[94:95], v[110:111]
	v_pk_add_f32 v[118:119], v[88:89], v[100:101] neg_lo:[0,1] neg_hi:[0,1]
	v_pk_add_f32 v[126:127], v[90:91], v[102:103] neg_lo:[0,1] neg_hi:[0,1]
	v_pk_add_f32 v[122:123], v[92:93], v[108:109] neg_lo:[0,1] neg_hi:[0,1]
	v_pk_add_f32 v[130:131], v[94:95], v[110:111] neg_lo:[0,1] neg_hi:[0,1]
	v_pk_add_f32 v[88:89], v[116:117], v[120:121]
	v_pk_add_f32 v[90:91], v[124:125], v[128:129]
	v_pk_add_f32 v[100:101], v[116:117], v[120:121] neg_lo:[0,1] neg_hi:[0,1]
	v_pk_add_f32 v[102:103], v[124:125], v[128:129] neg_lo:[0,1] neg_hi:[0,1]
	v_pk_add_f32 v[92:93], v[118:119], v[122:123] op_sel:[0,1] op_sel_hi:[1,0] neg_lo:[0,1]
	v_pk_add_f32 v[94:95], v[126:127], v[130:131] op_sel:[0,1] op_sel_hi:[1,0] neg_lo:[0,1]
	v_pk_add_f32 v[108:109], v[118:119], v[122:123] op_sel:[0,1] op_sel_hi:[1,0] neg_hi:[0,1]
	v_pk_add_f32 v[110:111], v[126:127], v[130:131] op_sel:[0,1] op_sel_hi:[1,0] neg_hi:[0,1]
	v_pk_mul_f32 v[132:133], v[96:97], v[230:231] op_sel:[1,1] op_sel_hi:[1,0]
	v_pk_mul_f32 v[136:137], v[98:99], v[236:237] op_sel:[1,1] op_sel_hi:[1,0]
	v_pk_mul_f32 v[134:135], v[104:105], v[232:233] op_sel:[1,1] op_sel_hi:[1,0]
	v_pk_mul_f32 v[138:139], v[106:107], v[238:239] op_sel:[1,1] op_sel_hi:[1,0]
	v_pk_fma_f32 v[96:97], v[96:97], v[230:231], v[132:133] op_sel_hi:[0,1,1] neg_lo:[0,0,1]
	v_pk_fma_f32 v[98:99], v[98:99], v[236:237], v[136:137] op_sel_hi:[0,1,1] neg_lo:[0,0,1]
	v_pk_mul_f32 v[132:133], v[112:113], v[234:235] op_sel:[1,1] op_sel_hi:[1,0]
	v_pk_mul_f32 v[136:137], v[114:115], v[242:243] op_sel:[1,1] op_sel_hi:[1,0]
	v_pk_fma_f32 v[104:105], v[104:105], v[232:233], v[134:135] op_sel_hi:[0,1,1] neg_lo:[0,0,1]
	v_pk_fma_f32 v[106:107], v[106:107], v[238:239], v[138:139] op_sel_hi:[0,1,1] neg_lo:[0,0,1]
	v_pk_fma_f32 v[112:113], v[112:113], v[234:235], v[132:133] op_sel_hi:[0,1,1] neg_lo:[0,0,1]
	v_pk_fma_f32 v[114:115], v[114:115], v[242:243], v[136:137] op_sel_hi:[0,1,1] neg_lo:[0,0,1]
	v_pk_add_f32 v[116:117], v[84:85], v[104:105]
	v_pk_add_f32 v[124:125], v[86:87], v[106:107]
;   const int lq1 = lq2 + 2, Q1 = 1 << lq1, Q2 = 1 << lq2; const float invM1 = 1.f / (float)(4 << lq1), invM2 = 1.f / (float)(4 << lq2);
;   for (int gg = tid; gg < NBT * (N / 16); gg += NTHR) { const int g = gg & (N / 16 - 1); float2* z = z0 + (gg / (N / 16)) * N; const int jp = g & (Q2 - 1), base = ((g >> lq2) << (lq2 + 4)) + jp; float2 x[4][4];
; #pragma unroll
;     for (int q1 = 0; q1 < 4; ++q1)
; #pragma unroll
;       for (int q2 = 0; q2 < 4; ++q2) x[q1][q2] = z[base + q1 * Q1 + q2 * Q2];
; #pragma unroll
;     for (int q1 = 0; q1 < 4; ++q1) bfly_inv(x[q1][0], x[q1][1], x[q1][2], x[q1][3], (float)jp * invM2, x[q1][0], x[q1][1], x[q1][2], x[q1][3]);
; #pragma unroll
;     for (int q2 = 0; q2 < 4; ++q2) bfly_inv(x[0][q2], x[1][q2], x[2][q2], x[3][q2], (float)(jp + q2 * Q2) * invM1, x[0][q2], x[1][q2], x[2][q2], x[3][q2]);
; #pragma unroll
;     for (int q1 = 0; q1 < 4; ++q1)
; #pragma unroll
;       for (int q2 = 0; q2 < 4; ++q2) z[base + q1 * Q1 + q2 * Q2] = x[q1][q2]; }
;   __syncthreads();
; }
	v_pk_add_f32 v[120:121], v[96:97], v[112:113]
	v_pk_add_f32 v[128:129], v[98:99], v[114:115]
	v_pk_add_f32 v[118:119], v[84:85], v[104:105] neg_lo:[0,1] neg_hi:[0,1]
	v_pk_add_f32 v[126:127], v[86:87], v[106:107] neg_lo:[0,1] neg_hi:[0,1]
	v_pk_add_f32 v[122:123], v[96:97], v[112:113] neg_lo:[0,1] neg_hi:[0,1]
	v_pk_add_f32 v[130:131], v[98:99], v[114:115] neg_lo:[0,1] neg_hi:[0,1]
	v_pk_add_f32 v[84:85], v[116:117], v[120:121]
	v_pk_add_f32 v[86:87], v[124:125], v[128:129]
	v_pk_add_f32 v[104:105], v[116:117], v[120:121] neg_lo:[0,1] neg_hi:[0,1]
	v_pk_add_f32 v[106:107], v[124:125], v[128:129] neg_lo:[0,1] neg_hi:[0,1]
	v_pk_add_f32 v[96:97], v[118:119], v[122:123] op_sel:[0,1] op_sel_hi:[1,0] neg_lo:[0,1]
	v_pk_add_f32 v[98:99], v[126:127], v[130:131] op_sel:[0,1] op_sel_hi:[1,0] neg_lo:[0,1]
	v_pk_add_f32 v[112:113], v[118:119], v[122:123] op_sel:[0,1] op_sel_hi:[1,0] neg_hi:[0,1]
	v_pk_add_f32 v[114:115], v[126:127], v[130:131] op_sel:[0,1] op_sel_hi:[1,0] neg_hi:[0,1]
	s_nop 0
	ds_write2_b64 v217, v[88:89], v[90:91] offset1:16
	ds_write2_b64 v217, v[84:85], v[86:87] offset0:32 offset1:48
	ds_write2_b64 v217, v[92:93], v[94:95] offset0:64 offset1:80
	ds_write2_b64 v217, v[96:97], v[98:99] offset0:96 offset1:112
	ds_write2_b64 v217, v[100:101], v[102:103] offset0:128 offset1:144
	ds_write2_b64 v217, v[104:105], v[106:107] offset0:160 offset1:176
	ds_write2_b64 v217, v[108:109], v[110:111] offset0:192 offset1:208
	ds_write2_b64 v217, v[112:113], v[114:115] offset0:224 offset1:240
	s_waitcnt lgkmcnt(8)
	v_pk_mul_f32 v[132:133], v[194:195], v[244:245] op_sel:[1,1] op_sel_hi:[1,0]
	v_pk_mul_f32 v[136:137], v[198:199], v[244:245] op_sel:[1,1] op_sel_hi:[1,0]
	v_pk_mul_f32 v[134:135], v[188:189], v[246:247] op_sel:[1,1] op_sel_hi:[1,0]
	v_pk_mul_f32 v[138:139], v[200:201], v[246:247] op_sel:[1,1] op_sel_hi:[1,0]
	v_pk_fma_f32 v[194:195], v[194:195], v[244:245], v[132:133] op_sel_hi:[0,1,1] neg_lo:[0,0,1]
	v_pk_fma_f32 v[198:199], v[198:199], v[244:245], v[136:137] op_sel_hi:[0,1,1] neg_lo:[0,0,1]
	v_pk_mul_f32 v[132:133], v[190:191], v[248:249] op_sel:[1,1] op_sel_hi:[1,0]
	v_pk_mul_f32 v[136:137], v[202:203], v[248:249] op_sel:[1,1] op_sel_hi:[1,0]
	v_pk_fma_f32 v[188:189], v[188:189], v[246:247], v[134:135] op_sel_hi:[0,1,1] neg_lo:[0,0,1]
	v_pk_fma_f32 v[200:201], v[200:201], v[246:247], v[138:139] op_sel_hi:[0,1,1] neg_lo:[0,0,1]
	v_pk_fma_f32 v[190:191], v[190:191], v[248:249], v[132:133] op_sel_hi:[0,1,1] neg_lo:[0,0,1]
	v_pk_fma_f32 v[202:203], v[202:203], v[248:249], v[136:137] op_sel_hi:[0,1,1] neg_lo:[0,0,1]
	v_pk_add_f32 v[116:117], v[192:193], v[188:189]
	v_pk_add_f32 v[124:125], v[196:197], v[200:201]
	v_pk_add_f32 v[120:121], v[194:195], v[190:191]
	v_pk_add_f32 v[128:129], v[198:199], v[202:203]
	v_pk_add_f32 v[118:119], v[192:193], v[188:189] neg_lo:[0,1] neg_hi:[0,1]
	v_pk_add_f32 v[126:127], v[196:197], v[200:201] neg_lo:[0,1] neg_hi:[0,1]
	v_pk_add_f32 v[122:123], v[194:195], v[190:191] neg_lo:[0,1] neg_hi:[0,1]
	v_pk_add_f32 v[130:131], v[198:199], v[202:203] neg_lo:[0,1] neg_hi:[0,1]
	v_pk_add_f32 v[192:193], v[116:117], v[120:121]
	v_pk_add_f32 v[196:197], v[124:125], v[128:129]
	v_pk_add_f32 v[188:189], v[116:117], v[120:121] neg_lo:[0,1] neg_hi:[0,1]
	v_pk_add_f32 v[200:201], v[124:125], v[128:129] neg_lo:[0,1] neg_hi:[0,1]
	v_pk_add_f32 v[194:195], v[118:119], v[122:123] op_sel:[0,1] op_sel_hi:[1,0] neg_lo:[0,1]
	v_pk_add_f32 v[198:199], v[126:127], v[130:131] op_sel:[0,1] op_sel_hi:[1,0] neg_lo:[0,1]
	v_pk_add_f32 v[190:191], v[118:119], v[122:123] op_sel:[0,1] op_sel_hi:[1,0] neg_hi:[0,1]
	v_pk_add_f32 v[202:203], v[126:127], v[130:131] op_sel:[0,1] op_sel_hi:[1,0] neg_hi:[0,1]
	v_pk_mul_f32 v[132:133], v[206:207], v[244:245] op_sel:[1,1] op_sel_hi:[1,0]
	v_pk_mul_f32 v[136:137], v[214:215], v[244:245] op_sel:[1,1] op_sel_hi:[1,0]
	v_pk_mul_f32 v[134:135], v[208:209], v[246:247] op_sel:[1,1] op_sel_hi:[1,0]
	v_pk_mul_f32 v[138:139], v[252:253], v[246:247] op_sel:[1,1] op_sel_hi:[1,0]
	v_pk_fma_f32 v[206:207], v[206:207], v[244:245], v[132:133] op_sel_hi:[0,1,1] neg_lo:[0,0,1]
	v_pk_fma_f32 v[214:215], v[214:215], v[244:245], v[136:137] op_sel_hi:[0,1,1] neg_lo:[0,0,1]
	v_pk_mul_f32 v[132:133], v[210:211], v[248:249] op_sel:[1,1] op_sel_hi:[1,0]
	v_pk_mul_f32 v[136:137], v[254:255], v[248:249] op_sel:[1,1] op_sel_hi:[1,0]
	v_pk_fma_f32 v[208:209], v[208:209], v[246:247], v[134:135] op_sel_hi:[0,1,1] neg_lo:[0,0,1]
	v_pk_fma_f32 v[252:253], v[252:253], v[246:247], v[138:139] op_sel_hi:[0,1,1] neg_lo:[0,0,1]
	v_pk_fma_f32 v[210:211], v[210:211], v[248:249], v[132:133] op_sel_hi:[0,1,1] neg_lo:[0,0,1]
	v_pk_fma_f32 v[254:255], v[254:255], v[248:249], v[136:137] op_sel_hi:[0,1,1] neg_lo:[0,0,1]
	v_pk_add_f32 v[116:117], v[204:205], v[208:209]
	v_pk_add_f32 v[124:125], v[212:213], v[252:253]
	v_pk_add_f32 v[120:121], v[206:207], v[210:211]
	v_pk_add_f32 v[128:129], v[214:215], v[254:255]
	v_pk_add_f32 v[118:119], v[204:205], v[208:209] neg_lo:[0,1] neg_hi:[0,1]
	v_pk_add_f32 v[126:127], v[212:213], v[252:253] neg_lo:[0,1] neg_hi:[0,1]
	v_pk_add_f32 v[122:123], v[206:207], v[210:211] neg_lo:[0,1] neg_hi:[0,1]
	v_pk_add_f32 v[130:131], v[214:215], v[254:255] neg_lo:[0,1] neg_hi:[0,1]
	v_pk_add_f32 v[204:205], v[116:117], v[120:121]
	v_pk_add_f32 v[212:213], v[124:125], v[128:129]
;   const int lq1 = lq2 + 2, Q1 = 1 << lq1, Q2 = 1 << lq2; const float invM1 = 1.f / (float)(4 << lq1), invM2 = 1.f / (float)(4 << lq2);
;   for (int gg = tid; gg < NBT * (N / 16); gg += NTHR) { const int g = gg & (N / 16 - 1); float2* z = z0 + (gg / (N / 16)) * N; const int jp = g & (Q2 - 1), base = ((g >> lq2) << (lq2 + 4)) + jp; float2 x[4][4];
; #pragma unroll
;     for (int q1 = 0; q1 < 4; ++q1)
; #pragma unroll
;       for (int q2 = 0; q2 < 4; ++q2) x[q1][q2] = z[base + q1 * Q1 + q2 * Q2];
; #pragma unroll
;     for (int q1 = 0; q1 < 4; ++q1) bfly_inv(x[q1][0], x[q1][1], x[q1][2], x[q1][3], (float)jp * invM2, x[q1][0], x[q1][1], x[q1][2], x[q1][3]);
; #pragma unroll
;     for (int q2 = 0; q2 < 4; ++q2) bfly_inv(x[0][q2], x[1][q2], x[2][q2], x[3][q2], (float)(jp + q2 * Q2) * invM1, x[0][q2], x[1][q2], x[2][q2], x[3][q2]);
; #pragma unroll
;     for (int q1 = 0; q1 < 4; ++q1)
; #pragma unroll
;       for (int q2 = 0; q2 < 4; ++q2) z[base + q1 * Q1 + q2 * Q2] = x[q1][q2]; }
;   __syncthreads();
; }
	v_pk_add_f32 v[208:209], v[116:117], v[120:121] neg_lo:[0,1] neg_hi:[0,1]
	v_pk_add_f32 v[252:253], v[124:125], v[128:129] neg_lo:[0,1] neg_hi:[0,1]
	v_pk_add_f32 v[206:207], v[118:119], v[122:123] op_sel:[0,1] op_sel_hi:[1,0] neg_lo:[0,1]
	v_pk_add_f32 v[214:215], v[126:127], v[130:131] op_sel:[0,1] op_sel_hi:[1,0] neg_lo:[0,1]
	v_pk_add_f32 v[210:211], v[118:119], v[122:123] op_sel:[0,1] op_sel_hi:[1,0] neg_hi:[0,1]
	v_pk_add_f32 v[254:255], v[126:127], v[130:131] op_sel:[0,1] op_sel_hi:[1,0] neg_hi:[0,1]
	v_pk_mul_f32 v[132:133], v[196:197], v[218:219] op_sel:[1,1] op_sel_hi:[1,0]
	v_pk_mul_f32 v[136:137], v[198:199], v[224:225] op_sel:[1,1] op_sel_hi:[1,0]
	v_pk_mul_f32 v[134:135], v[204:205], v[220:221] op_sel:[1,1] op_sel_hi:[1,0]
	v_pk_mul_f32 v[138:139], v[206:207], v[226:227] op_sel:[1,1] op_sel_hi:[1,0]
	v_pk_fma_f32 v[196:197], v[196:197], v[218:219], v[132:133] op_sel_hi:[0,1,1] neg_lo:[0,0,1]
	v_pk_fma_f32 v[198:199], v[198:199], v[224:225], v[136:137] op_sel_hi:[0,1,1] neg_lo:[0,0,1]
	v_pk_mul_f32 v[132:133], v[212:213], v[222:223] op_sel:[1,1] op_sel_hi:[1,0]
	v_pk_mul_f32 v[136:137], v[214:215], v[228:229] op_sel:[1,1] op_sel_hi:[1,0]
	v_pk_fma_f32 v[204:205], v[204:205], v[220:221], v[134:135] op_sel_hi:[0,1,1] neg_lo:[0,0,1]
	v_pk_fma_f32 v[206:207], v[206:207], v[226:227], v[138:139] op_sel_hi:[0,1,1] neg_lo:[0,0,1]
	v_pk_fma_f32 v[212:213], v[212:213], v[222:223], v[132:133] op_sel_hi:[0,1,1] neg_lo:[0,0,1]
	v_pk_fma_f32 v[214:215], v[214:215], v[228:229], v[136:137] op_sel_hi:[0,1,1] neg_lo:[0,0,1]
	v_pk_add_f32 v[116:117], v[192:193], v[204:205]
	v_pk_add_f32 v[124:125], v[194:195], v[206:207]
	v_pk_add_f32 v[120:121], v[196:197], v[212:213]
	v_pk_add_f32 v[128:129], v[198:199], v[214:215]
	v_pk_add_f32 v[118:119], v[192:193], v[204:205] neg_lo:[0,1] neg_hi:[0,1]
	v_pk_add_f32 v[126:127], v[194:195], v[206:207] neg_lo:[0,1] neg_hi:[0,1]
	v_pk_add_f32 v[122:123], v[196:197], v[212:213] neg_lo:[0,1] neg_hi:[0,1]
	v_pk_add_f32 v[130:131], v[198:199], v[214:215] neg_lo:[0,1] neg_hi:[0,1]
	v_pk_add_f32 v[192:193], v[116:117], v[120:121]
	v_pk_add_f32 v[194:195], v[124:125], v[128:129]
	v_pk_add_f32 v[204:205], v[116:117], v[120:121] neg_lo:[0,1] neg_hi:[0,1]
	v_pk_add_f32 v[206:207], v[124:125], v[128:129] neg_lo:[0,1] neg_hi:[0,1]
	v_pk_add_f32 v[196:197], v[118:119], v[122:123] op_sel:[0,1] op_sel_hi:[1,0] neg_lo:[0,1]
	v_pk_add_f32 v[198:199], v[126:127], v[130:131] op_sel:[0,1] op_sel_hi:[1,0] neg_lo:[0,1]
	v_pk_add_f32 v[212:213], v[118:119], v[122:123] op_sel:[0,1] op_sel_hi:[1,0] neg_hi:[0,1]
	v_pk_add_f32 v[214:215], v[126:127], v[130:131] op_sel:[0,1] op_sel_hi:[1,0] neg_hi:[0,1]
	v_pk_mul_f32 v[132:133], v[200:201], v[230:231] op_sel:[1,1] op_sel_hi:[1,0]
	v_pk_mul_f32 v[136:137], v[202:203], v[236:237] op_sel:[1,1] op_sel_hi:[1,0]
	v_pk_mul_f32 v[134:135], v[208:209], v[232:233] op_sel:[1,1] op_sel_hi:[1,0]
	v_pk_mul_f32 v[138:139], v[210:211], v[238:239] op_sel:[1,1] op_sel_hi:[1,0]
	v_pk_fma_f32 v[200:201], v[200:201], v[230:231], v[132:133] op_sel_hi:[0,1,1] neg_lo:[0,0,1]
	v_pk_fma_f32 v[202:203], v[202:203], v[236:237], v[136:137] op_sel_hi:[0,1,1] neg_lo:[0,0,1]
	v_pk_mul_f32 v[132:133], v[252:253], v[234:235] op_sel:[1,1] op_sel_hi:[1,0]
	v_pk_mul_f32 v[136:137], v[254:255], v[242:243] op_sel:[1,1] op_sel_hi:[1,0]
	v_pk_fma_f32 v[208:209], v[208:209], v[232:233], v[134:135] op_sel_hi:[0,1,1] neg_lo:[0,0,1]
	v_pk_fma_f32 v[210:211], v[210:211], v[238:239], v[138:139] op_sel_hi:[0,1,1] neg_lo:[0,0,1]
	v_pk_fma_f32 v[252:253], v[252:253], v[234:235], v[132:133] op_sel_hi:[0,1,1] neg_lo:[0,0,1]
	v_pk_fma_f32 v[254:255], v[254:255], v[242:243], v[136:137] op_sel_hi:[0,1,1] neg_lo:[0,0,1]
	v_pk_add_f32 v[116:117], v[188:189], v[208:209]
	v_pk_add_f32 v[124:125], v[190:191], v[210:211]
	v_pk_add_f32 v[120:121], v[200:201], v[252:253]
	v_pk_add_f32 v[128:129], v[202:203], v[254:255]
	v_pk_add_f32 v[118:119], v[188:189], v[208:209] neg_lo:[0,1] neg_hi:[0,1]
	v_pk_add_f32 v[126:127], v[190:191], v[210:211] neg_lo:[0,1] neg_hi:[0,1]
	v_pk_add_f32 v[122:123], v[200:201], v[252:253] neg_lo:[0,1] neg_hi:[0,1]
	v_pk_add_f32 v[130:131], v[202:203], v[254:255] neg_lo:[0,1] neg_hi:[0,1]
	v_pk_add_f32 v[188:189], v[116:117], v[120:121]
	v_pk_add_f32 v[190:191], v[124:125], v[128:129]
	v_pk_add_f32 v[208:209], v[116:117], v[120:121] neg_lo:[0,1] neg_hi:[0,1]
	v_pk_add_f32 v[210:211], v[124:125], v[128:129] neg_lo:[0,1] neg_hi:[0,1]
	v_pk_add_f32 v[200:201], v[118:119], v[122:123] op_sel:[0,1] op_sel_hi:[1,0] neg_lo:[0,1]
	v_pk_add_f32 v[202:203], v[126:127], v[130:131] op_sel:[0,1] op_sel_hi:[1,0] neg_lo:[0,1]
	v_pk_add_f32 v[252:253], v[118:119], v[122:123] op_sel:[0,1] op_sel_hi:[1,0] neg_hi:[0,1]
	v_pk_add_f32 v[254:255], v[126:127], v[130:131] op_sel:[0,1] op_sel_hi:[1,0] neg_hi:[0,1]
	s_nop 0
	ds_write2_b64 v251, v[192:193], v[194:195] offset1:16
	ds_write2_b64 v251, v[188:189], v[190:191] offset0:32 offset1:48
	ds_write2_b64 v251, v[196:197], v[198:199] offset0:64 offset1:80
	ds_write2_b64 v251, v[200:201], v[202:203] offset0:96 offset1:112
	ds_write2_b64 v251, v[204:205], v[206:207] offset0:128 offset1:144
	ds_write2_b64 v251, v[208:209], v[210:211] offset0:160 offset1:176
	ds_write2_b64 v251, v[212:213], v[214:215] offset0:192 offset1:208
	ds_write2_b64 v251, v[252:253], v[254:255] offset0:224 offset1:240
	s_mov_b64 s[80:81], exec

; DI float2 twid(float r) { return float2{__builtin_amdgcn_cosf(r), -__builtin_amdgcn_sinf(r)}; }
; DI void bfly_inv(float2 s0, float2 s1, float2 s2, float2 s3, float r, float2& o0, float2& o1, float2& o2, float2& o3) {
;   float2 w1 = twid(r), w2 = cmul(w1, w1), w3 = cmul(w2, w1);
;   float2 c0 = s0, c1 = cmulc(s1, w1), c2 = cmulc(s2, w2), c3 = cmulc(s3, w3);
;   float2 t0 = {c0.x + c2.x, c0.y + c2.y}, t1 = {c0.x - c2.x, c0.y - c2.y}, t2 = {c1.x + c3.x, c1.y + c3.y}, t3 = {c1.x - c3.x, c1.y - c3.y};
;   o0 = float2{t0.x + t2.x, t0.y + t2.y}; o2 = float2{t0.x - t2.x, t0.y - t2.y}; o1 = float2{t1.x - t3.y, t1.y + t3.x}; o3 = float2{t1.x + t3.y, t1.y - t3.x};
; }
;   const int lq1 = lq2 + 2, Q1 = 1 << lq1, Q2 = 1 << lq2; const float invM1 = 1.f / (float)(4 << lq1), invM2 = 1.f / (float)(4 << lq2);
;   for (int gg = tid; gg < NBT * (N / 16); gg += NTHR) { const int g = gg & (N / 16 - 1); float2* z = z0 + (gg / (N / 16)) * N; const int jp = g & (Q2 - 1), base = ((g >> lq2) << (lq2 + 4)) + jp; float2 x[4][4];
; #pragma unroll
;     for (int q1 = 0; q1 < 4; ++q1)
; #pragma unroll
;       for (int q2 = 0; q2 < 4; ++q2) x[q1][q2] = z[base + q1 * Q1 + q2 * Q2];
; #pragma unroll
;     for (int q1 = 0; q1 < 4; ++q1) bfly_inv(x[q1][0], x[q1][1], x[q1][2], x[q1][3], (float)jp * invM2, x[q1][0], x[q1][1], x[q1][2], x[q1][3]);
; #pragma unroll
;     for (int q2 = 0; q2 < 4; ++q2) bfly_inv(x[0][q2], x[1][q2], x[2][q2], x[3][q2], (float)(jp + q2 * Q2) * invM1, x[0][q2], x[1][q2], x[2][q2], x[3][q2]);
; #pragma unroll
;     for (int q1 = 0; q1 < 4; ++q1)
; #pragma unroll
;       for (int q2 = 0; q2 < 4; ++q2) z[base + q1 * Q1 + q2 * Q2] = x[q1][q2]; }
;   __syncthreads();
; }
.LBB0_1621:
	v_ashrrev_i32_e32 v216, 31, v75
	v_lshrrev_b32_e32 v216, 23, v216
	v_add_lshl_u32 v216, v75, v216, 7
	v_and_b32_e32 v216, 0xffff0000, v216
	v_add_u32_e32 v217, v20, v216
	ds_read2st64_b64 v[76:79], v217 offset0:8 offset1:12
	ds_read2st64_b64 v[80:83], v217 offset1:4
	ds_read2st64_b64 v[84:87], v217 offset0:16 offset1:20
	ds_read2st64_b64 v[88:91], v217 offset0:24 offset1:28
	ds_read2st64_b64 v[92:95], v217 offset0:32 offset1:36
	ds_read2st64_b64 v[96:99], v217 offset0:40 offset1:44
	ds_read2st64_b64 v[100:103], v217 offset0:48 offset1:52
	ds_read2st64_b64 v[104:107], v217 offset0:56 offset1:60
	v_add_u32_e32 v0, 0x200, v75
	v_mov_b32_e32 v75, v0
	v_ashrrev_i32_e32 v148, 31, v75
	v_lshrrev_b32_e32 v148, 23, v148
	v_add_lshl_u32 v148, v75, v148, 7
	v_and_b32_e32 v148, 0xffff0000, v148
	v_add_u32_e32 v251, v20, v148
	ds_read2st64_b64 v[188:191], v251 offset0:8 offset1:12
	ds_read2st64_b64 v[192:195], v251 offset1:4
	ds_read2st64_b64 v[196:199], v251 offset0:16 offset1:20
	ds_read2st64_b64 v[200:203], v251 offset0:24 offset1:28
	ds_read2st64_b64 v[204:207], v251 offset0:32 offset1:36
	ds_read2st64_b64 v[208:211], v251 offset0:40 offset1:44
	ds_read2st64_b64 v[212:215], v251 offset0:48 offset1:52
	ds_read2st64_b64 v[252:255], v251 offset0:56 offset1:60
	v_add_u32_e32 v0, 0x200, v75
	v_mov_b32_e32 v75, v0
	v_and_b32_e32 v241, 0xff, v75
	v_cvt_f32_u32_e32 v250, v241
	v_mul_f32_e32 v250, 0x39800000, v250
	v_cos_f32_e32 v218, v250
	v_sin_f32_e32 v219, v250
	s_nop 1
	s_nop 0
	v_pk_mul_f32 v[124:125], v[218:219], v[218:219] op_sel:[1,1] op_sel_hi:[1,0]
	s_nop 0
	v_pk_fma_f32 v[220:221], v[218:219], v[218:219], v[124:125] op_sel_hi:[0,1,1] neg_lo:[0,0,1]
	s_nop 0
	v_pk_mul_f32 v[124:125], v[220:221], v[218:219] op_sel:[1,1] op_sel_hi:[1,0]
	s_nop 0
	v_pk_fma_f32 v[222:223], v[220:221], v[218:219], v[124:125] op_sel_hi:[0,1,1] neg_lo:[0,0,1]
	v_pk_mul_f32 v[124:125], v[220:221], v[220:221] op_sel:[1,1] op_sel_hi:[1,0]
	s_nop 0
	v_pk_fma_f32 v[244:245], v[220:221], v[220:221], v[124:125] op_sel_hi:[0,1,1] neg_lo:[0,0,1]
	s_nop 0
	v_mul_f32_e32 v241, 0xbec3ef15, v219
	v_mul_f32_e32 v250, 0x3ec3ef15, v218
	v_fmamk_f32 v224, v218, 0x3f6c835e, v241
	v_fmamk_f32 v225, v219, 0x3f6c835e, v250
	v_mul_f32_e32 v241, 0xbf3504f3, v219
	v_mul_f32_e32 v250, 0x3f3504f3, v218
	v_fmamk_f32 v230, v218, 0x3f3504f3, v241
	v_fmamk_f32 v231, v219, 0x3f3504f3, v250
	v_mul_f32_e32 v241, 0xbf6c835e, v219
	v_mul_f32_e32 v250, 0x3f6c835e, v218
	v_fmamk_f32 v236, v218, 0x3ec3ef15, v241
	v_fmamk_f32 v237, v219, 0x3ec3ef15, v250
	v_mul_f32_e32 v241, 0xbf3504f3, v221
	v_mul_f32_e32 v250, 0x3f3504f3, v220
	v_fmamk_f32 v226, v220, 0x3f3504f3, v241
	v_fmamk_f32 v227, v221, 0x3f3504f3, v250
	v_mul_f32_e32 v241, 0xbf800000, v221
	v_mul_f32_e32 v250, 0x3f800000, v220
	v_fmamk_f32 v232, v220, 0x00000000, v241
	v_fmamk_f32 v233, v221, 0x00000000, v250
	v_mul_f32_e32 v241, 0xbf3504f3, v221
	v_mul_f32_e32 v250, 0x3f3504f3, v220
	v_fmamk_f32 v238, v220, 0xbf3504f3, v241
	v_fmamk_f32 v239, v221, 0xbf3504f3, v250
	v_mul_f32_e32 v241, 0xbf6c835e, v223
	v_mul_f32_e32 v250, 0x3f6c835e, v222
	v_fmamk_f32 v228, v222, 0x3ec3ef15, v241
	v_fmamk_f32 v229, v223, 0x3ec3ef15, v250
	v_mul_f32_e32 v241, 0xbf3504f3, v223
	v_mul_f32_e32 v250, 0x3f3504f3, v222
	v_fmamk_f32 v234, v222, 0xbf3504f3, v241
	v_fmamk_f32 v235, v223, 0xbf3504f3, v250
	v_mul_f32_e32 v241, 0x3ec3ef15, v223
	v_mul_f32_e32 v250, 0xbec3ef15, v222
	v_fmamk_f32 v242, v222, 0xbf6c835e, v241
	v_fmamk_f32 v243, v223, 0xbf6c835e, v250
	v_pk_mul_f32 v[124:125], v[244:245], v[244:245] op_sel:[1,1] op_sel_hi:[1,0]
	s_nop 0
	v_pk_fma_f32 v[246:247], v[244:245], v[244:245], v[124:125] op_sel_hi:[0,1,1] neg_lo:[0,0,1]
	s_nop 0
	v_pk_mul_f32 v[124:125], v[246:247], v[244:245] op_sel:[1,1] op_sel_hi:[1,0]
	s_nop 0
	v_pk_fma_f32 v[248:249], v[246:247], v[244:245], v[124:125] op_sel_hi:[0,1,1] neg_lo:[0,0,1]
	s_nop 0
	s_waitcnt lgkmcnt(8)
	v_pk_mul_f32 v[124:125], v[82:83], v[244:245] op_sel:[1,1] op_sel_hi:[1,0]
	v_pk_mul_f32 v[128:129], v[86:87], v[244:245] op_sel:[1,1] op_sel_hi:[1,0]
	v_pk_mul_f32 v[126:127], v[76:77], v[246:247] op_sel:[1,1] op_sel_hi:[1,0]
	v_pk_mul_f32 v[130:131], v[88:89], v[246:247] op_sel:[1,1] op_sel_hi:[1,0]
	v_pk_fma_f32 v[82:83], v[82:83], v[244:245], v[124:125] op_sel_hi:[0,1,1] neg_lo:[0,0,1]
	v_pk_fma_f32 v[86:87], v[86:87], v[244:245], v[128:129] op_sel_hi:[0,1,1] neg_lo:[0,0,1]
	v_pk_mul_f32 v[124:125], v[78:79], v[248:249] op_sel:[1,1] op_sel_hi:[1,0]
	v_pk_mul_f32 v[128:129], v[90:91], v[248:249] op_sel:[1,1] op_sel_hi:[1,0]
	v_pk_fma_f32 v[76:77], v[76:77], v[246:247], v[126:127] op_sel_hi:[0,1,1] neg_lo:[0,0,1]
	v_pk_fma_f32 v[88:89], v[88:89], v[246:247], v[130:131] op_sel_hi:[0,1,1] neg_lo:[0,0,1]
	v_pk_fma_f32 v[78:79], v[78:79], v[248:249], v[124:125] op_sel_hi:[0,1,1] neg_lo:[0,0,1]
	v_pk_fma_f32 v[90:91], v[90:91], v[248:249], v[128:129] op_sel_hi:[0,1,1] neg_lo:[0,0,1]
	v_pk_add_f32 v[108:109], v[80:81], v[76:77]
	v_pk_add_f32 v[116:117], v[84:85], v[88:89]
	v_pk_add_f32 v[112:113], v[82:83], v[78:79]
	v_pk_add_f32 v[120:121], v[86:87], v[90:91]
	v_pk_add_f32 v[110:111], v[80:81], v[76:77] neg_lo:[0,1] neg_hi:[0,1]
	v_pk_add_f32 v[118:119], v[84:85], v[88:89] neg_lo:[0,1] neg_hi:[0,1]
	v_pk_add_f32 v[114:115], v[82:83], v[78:79] neg_lo:[0,1] neg_hi:[0,1]
	v_pk_add_f32 v[122:123], v[86:87], v[90:91] neg_lo:[0,1] neg_hi:[0,1]
	v_pk_add_f32 v[80:81], v[108:109], v[112:113]
	v_pk_add_f32 v[84:85], v[116:117], v[120:121]
	v_pk_add_f32 v[76:77], v[108:109], v[112:113] neg_lo:[0,1] neg_hi:[0,1]
	v_pk_add_f32 v[88:89], v[116:117], v[120:121] neg_lo:[0,1] neg_hi:[0,1]
; DI float2 twid(float r) { return float2{__builtin_amdgcn_cosf(r), -__builtin_amdgcn_sinf(r)}; }
; DI void bfly_inv(float2 s0, float2 s1, float2 s2, float2 s3, float r, float2& o0, float2& o1, float2& o2, float2& o3) {
;   float2 w1 = twid(r), w2 = cmul(w1, w1), w3 = cmul(w2, w1);
;   float2 c0 = s0, c1 = cmulc(s1, w1), c2 = cmulc(s2, w2), c3 = cmulc(s3, w3);
;   float2 t0 = {c0.x + c2.x, c0.y + c2.y}, t1 = {c0.x - c2.x, c0.y - c2.y}, t2 = {c1.x + c3.x, c1.y + c3.y}, t3 = {c1.x - c3.x, c1.y - c3.y};
;   o0 = float2{t0.x + t2.x, t0.y + t2.y}; o2 = float2{t0.x - t2.x, t0.y - t2.y}; o1 = float2{t1.x - t3.y, t1.y + t3.x}; o3 = float2{t1.x + t3.y, t1.y - t3.x};
; }
;   const int lq1 = lq2 + 2, Q1 = 1 << lq1, Q2 = 1 << lq2; const float invM1 = 1.f / (float)(4 << lq1), invM2 = 1.f / (float)(4 << lq2);
;   for (int gg = tid; gg < NBT * (N / 16); gg += NTHR) { const int g = gg & (N / 16 - 1); float2* z = z0 + (gg / (N / 16)) * N; const int jp = g & (Q2 - 1), base = ((g >> lq2) << (lq2 + 4)) + jp; float2 x[4][4];
; #pragma unroll
;     for (int q1 = 0; q1 < 4; ++q1)
; #pragma unroll
;       for (int q2 = 0; q2 < 4; ++q2) x[q1][q2] = z[base + q1 * Q1 + q2 * Q2];
; #pragma unroll
;     for (int q1 = 0; q1 < 4; ++q1) bfly_inv(x[q1][0], x[q1][1], x[q1][2], x[q1][3], (float)jp * invM2, x[q1][0], x[q1][1], x[q1][2], x[q1][3]);
; #pragma unroll
;     for (int q2 = 0; q2 < 4; ++q2) bfly_inv(x[0][q2], x[1][q2], x[2][q2], x[3][q2], (float)(jp + q2 * Q2) * invM1, x[0][q2], x[1][q2], x[2][q2], x[3][q2]);
; #pragma unroll
;     for (int q1 = 0; q1 < 4; ++q1)
; #pragma unroll
;       for (int q2 = 0; q2 < 4; ++q2) z[base + q1 * Q1 + q2 * Q2] = x[q1][q2]; }
;   __syncthreads();
; }
	v_pk_add_f32 v[82:83], v[110:111], v[114:115] op_sel:[0,1] op_sel_hi:[1,0] neg_lo:[0,1]
	v_pk_add_f32 v[86:87], v[118:119], v[122:123] op_sel:[0,1] op_sel_hi:[1,0] neg_lo:[0,1]
	v_pk_add_f32 v[78:79], v[110:111], v[114:115] op_sel:[0,1] op_sel_hi:[1,0] neg_hi:[0,1]
	v_pk_add_f32 v[90:91], v[118:119], v[122:123] op_sel:[0,1] op_sel_hi:[1,0] neg_hi:[0,1]
	v_pk_mul_f32 v[124:125], v[94:95], v[244:245] op_sel:[1,1] op_sel_hi:[1,0]
	v_pk_mul_f32 v[128:129], v[102:103], v[244:245] op_sel:[1,1] op_sel_hi:[1,0]
	v_pk_mul_f32 v[126:127], v[96:97], v[246:247] op_sel:[1,1] op_sel_hi:[1,0]
	v_pk_mul_f32 v[130:131], v[104:105], v[246:247] op_sel:[1,1] op_sel_hi:[1,0]
	v_pk_fma_f32 v[94:95], v[94:95], v[244:245], v[124:125] op_sel_hi:[0,1,1] neg_lo:[0,0,1]
	v_pk_fma_f32 v[102:103], v[102:103], v[244:245], v[128:129] op_sel_hi:[0,1,1] neg_lo:[0,0,1]
	v_pk_mul_f32 v[124:125], v[98:99], v[248:249] op_sel:[1,1] op_sel_hi:[1,0]
	v_pk_mul_f32 v[128:129], v[106:107], v[248:249] op_sel:[1,1] op_sel_hi:[1,0]
	v_pk_fma_f32 v[96:97], v[96:97], v[246:247], v[126:127] op_sel_hi:[0,1,1] neg_lo:[0,0,1]
	v_pk_fma_f32 v[104:105], v[104:105], v[246:247], v[130:131] op_sel_hi:[0,1,1] neg_lo:[0,0,1]
	v_pk_fma_f32 v[98:99], v[98:99], v[248:249], v[124:125] op_sel_hi:[0,1,1] neg_lo:[0,0,1]
	v_pk_fma_f32 v[106:107], v[106:107], v[248:249], v[128:129] op_sel_hi:[0,1,1] neg_lo:[0,0,1]
	v_pk_add_f32 v[108:109], v[92:93], v[96:97]
	v_pk_add_f32 v[116:117], v[100:101], v[104:105]
	v_pk_add_f32 v[112:113], v[94:95], v[98:99]
	v_pk_add_f32 v[120:121], v[102:103], v[106:107]
	v_pk_add_f32 v[110:111], v[92:93], v[96:97] neg_lo:[0,1] neg_hi:[0,1]
	v_pk_add_f32 v[118:119], v[100:101], v[104:105] neg_lo:[0,1] neg_hi:[0,1]
	v_pk_add_f32 v[114:115], v[94:95], v[98:99] neg_lo:[0,1] neg_hi:[0,1]
	v_pk_add_f32 v[122:123], v[102:103], v[106:107] neg_lo:[0,1] neg_hi:[0,1]
	v_pk_add_f32 v[92:93], v[108:109], v[112:113]
	v_pk_add_f32 v[100:101], v[116:117], v[120:121]
	v_pk_add_f32 v[96:97], v[108:109], v[112:113] neg_lo:[0,1] neg_hi:[0,1]
	v_pk_add_f32 v[104:105], v[116:117], v[120:121] neg_lo:[0,1] neg_hi:[0,1]
	v_pk_add_f32 v[94:95], v[110:111], v[114:115] op_sel:[0,1] op_sel_hi:[1,0] neg_lo:[0,1]
	v_pk_add_f32 v[102:103], v[118:119], v[122:123] op_sel:[0,1] op_sel_hi:[1,0] neg_lo:[0,1]
	v_pk_add_f32 v[98:99], v[110:111], v[114:115] op_sel:[0,1] op_sel_hi:[1,0] neg_hi:[0,1]
	v_pk_add_f32 v[106:107], v[118:119], v[122:123] op_sel:[0,1] op_sel_hi:[1,0] neg_hi:[0,1]
	v_pk_mul_f32 v[124:125], v[84:85], v[218:219] op_sel:[1,1] op_sel_hi:[1,0]
	v_pk_mul_f32 v[128:129], v[86:87], v[224:225] op_sel:[1,1] op_sel_hi:[1,0]
	v_pk_mul_f32 v[126:127], v[92:93], v[220:221] op_sel:[1,1] op_sel_hi:[1,0]
	v_pk_mul_f32 v[130:131], v[94:95], v[226:227] op_sel:[1,1] op_sel_hi:[1,0]
	v_pk_fma_f32 v[84:85], v[84:85], v[218:219], v[124:125] op_sel_hi:[0,1,1] neg_lo:[0,0,1]
	v_pk_fma_f32 v[86:87], v[86:87], v[224:225], v[128:129] op_sel_hi:[0,1,1] neg_lo:[0,0,1]
	v_pk_mul_f32 v[124:125], v[100:101], v[222:223] op_sel:[1,1] op_sel_hi:[1,0]
	v_pk_mul_f32 v[128:129], v[102:103], v[228:229] op_sel:[1,1] op_sel_hi:[1,0]
	v_pk_fma_f32 v[92:93], v[92:93], v[220:221], v[126:127] op_sel_hi:[0,1,1] neg_lo:[0,0,1]
	v_pk_fma_f32 v[94:95], v[94:95], v[226:227], v[130:131] op_sel_hi:[0,1,1] neg_lo:[0,0,1]
	v_pk_fma_f32 v[100:101], v[100:101], v[222:223], v[124:125] op_sel_hi:[0,1,1] neg_lo:[0,0,1]
	v_pk_fma_f32 v[102:103], v[102:103], v[228:229], v[128:129] op_sel_hi:[0,1,1] neg_lo:[0,0,1]
	v_pk_add_f32 v[108:109], v[80:81], v[92:93]
	v_pk_add_f32 v[116:117], v[82:83], v[94:95]
	v_pk_add_f32 v[112:113], v[84:85], v[100:101]
	v_pk_add_f32 v[120:121], v[86:87], v[102:103]
	v_pk_add_f32 v[110:111], v[80:81], v[92:93] neg_lo:[0,1] neg_hi:[0,1]
	v_pk_add_f32 v[118:119], v[82:83], v[94:95] neg_lo:[0,1] neg_hi:[0,1]
	v_pk_add_f32 v[114:115], v[84:85], v[100:101] neg_lo:[0,1] neg_hi:[0,1]
	v_pk_add_f32 v[122:123], v[86:87], v[102:103] neg_lo:[0,1] neg_hi:[0,1]
	v_pk_add_f32 v[80:81], v[108:109], v[112:113]
	v_pk_add_f32 v[82:83], v[116:117], v[120:121]
	v_pk_add_f32 v[92:93], v[108:109], v[112:113] neg_lo:[0,1] neg_hi:[0,1]
	v_pk_add_f32 v[94:95], v[116:117], v[120:121] neg_lo:[0,1] neg_hi:[0,1]
	v_pk_add_f32 v[84:85], v[110:111], v[114:115] op_sel:[0,1] op_sel_hi:[1,0] neg_lo:[0,1]
	v_pk_add_f32 v[86:87], v[118:119], v[122:123] op_sel:[0,1] op_sel_hi:[1,0] neg_lo:[0,1]
	v_pk_add_f32 v[100:101], v[110:111], v[114:115] op_sel:[0,1] op_sel_hi:[1,0] neg_hi:[0,1]
	v_pk_add_f32 v[102:103], v[118:119], v[122:123] op_sel:[0,1] op_sel_hi:[1,0] neg_hi:[0,1]
	v_pk_mul_f32 v[124:125], v[88:89], v[230:231] op_sel:[1,1] op_sel_hi:[1,0]
	v_pk_mul_f32 v[128:129], v[90:91], v[236:237] op_sel:[1,1] op_sel_hi:[1,0]
	v_pk_mul_f32 v[126:127], v[96:97], v[232:233] op_sel:[1,1] op_sel_hi:[1,0]
	v_pk_mul_f32 v[130:131], v[98:99], v[238:239] op_sel:[1,1] op_sel_hi:[1,0]
	v_pk_fma_f32 v[88:89], v[88:89], v[230:231], v[124:125] op_sel_hi:[0,1,1] neg_lo:[0,0,1]
	v_pk_fma_f32 v[90:91], v[90:91], v[236:237], v[128:129] op_sel_hi:[0,1,1] neg_lo:[0,0,1]
	v_pk_mul_f32 v[124:125], v[104:105], v[234:235] op_sel:[1,1] op_sel_hi:[1,0]
	v_pk_mul_f32 v[128:129], v[106:107], v[242:243] op_sel:[1,1] op_sel_hi:[1,0]
	v_pk_fma_f32 v[96:97], v[96:97], v[232:233], v[126:127] op_sel_hi:[0,1,1] neg_lo:[0,0,1]
	v_pk_fma_f32 v[98:99], v[98:99], v[238:239], v[130:131] op_sel_hi:[0,1,1] neg_lo:[0,0,1]
	v_pk_fma_f32 v[104:105], v[104:105], v[234:235], v[124:125] op_sel_hi:[0,1,1] neg_lo:[0,0,1]
	v_pk_fma_f32 v[106:107], v[106:107], v[242:243], v[128:129] op_sel_hi:[0,1,1] neg_lo:[0,0,1]
	v_pk_add_f32 v[108:109], v[76:77], v[96:97]
	v_pk_add_f32 v[116:117], v[78:79], v[98:99]
; DI float2 twid(float r) { return float2{__builtin_amdgcn_cosf(r), -__builtin_amdgcn_sinf(r)}; }
; DI void bfly_inv(float2 s0, float2 s1, float2 s2, float2 s3, float r, float2& o0, float2& o1, float2& o2, float2& o3) {
;   float2 w1 = twid(r), w2 = cmul(w1, w1), w3 = cmul(w2, w1);
;   float2 c0 = s0, c1 = cmulc(s1, w1), c2 = cmulc(s2, w2), c3 = cmulc(s3, w3);
;   float2 t0 = {c0.x + c2.x, c0.y + c2.y}, t1 = {c0.x - c2.x, c0.y - c2.y}, t2 = {c1.x + c3.x, c1.y + c3.y}, t3 = {c1.x - c3.x, c1.y - c3.y};
;   o0 = float2{t0.x + t2.x, t0.y + t2.y}; o2 = float2{t0.x - t2.x, t0.y - t2.y}; o1 = float2{t1.x - t3.y, t1.y + t3.x}; o3 = float2{t1.x + t3.y, t1.y - t3.x};
; }
;   const int lq1 = lq2 + 2, Q1 = 1 << lq1, Q2 = 1 << lq2; const float invM1 = 1.f / (float)(4 << lq1), invM2 = 1.f / (float)(4 << lq2);
;   for (int gg = tid; gg < NBT * (N / 16); gg += NTHR) { const int g = gg & (N / 16 - 1); float2* z = z0 + (gg / (N / 16)) * N; const int jp = g & (Q2 - 1), base = ((g >> lq2) << (lq2 + 4)) + jp; float2 x[4][4];
; #pragma unroll
;     for (int q1 = 0; q1 < 4; ++q1)
; #pragma unroll
;       for (int q2 = 0; q2 < 4; ++q2) x[q1][q2] = z[base + q1 * Q1 + q2 * Q2];
; #pragma unroll
;     for (int q1 = 0; q1 < 4; ++q1) bfly_inv(x[q1][0], x[q1][1], x[q1][2], x[q1][3], (float)jp * invM2, x[q1][0], x[q1][1], x[q1][2], x[q1][3]);
; #pragma unroll
;     for (int q2 = 0; q2 < 4; ++q2) bfly_inv(x[0][q2], x[1][q2], x[2][q2], x[3][q2], (float)(jp + q2 * Q2) * invM1, x[0][q2], x[1][q2], x[2][q2], x[3][q2]);
; #pragma unroll
;     for (int q1 = 0; q1 < 4; ++q1)
; #pragma unroll
;       for (int q2 = 0; q2 < 4; ++q2) z[base + q1 * Q1 + q2 * Q2] = x[q1][q2]; }
;   __syncthreads();
; }
	v_pk_add_f32 v[112:113], v[88:89], v[104:105]
	v_pk_add_f32 v[120:121], v[90:91], v[106:107]
	v_pk_add_f32 v[110:111], v[76:77], v[96:97] neg_lo:[0,1] neg_hi:[0,1]
	v_pk_add_f32 v[118:119], v[78:79], v[98:99] neg_lo:[0,1] neg_hi:[0,1]
	v_pk_add_f32 v[114:115], v[88:89], v[104:105] neg_lo:[0,1] neg_hi:[0,1]
	v_pk_add_f32 v[122:123], v[90:91], v[106:107] neg_lo:[0,1] neg_hi:[0,1]
	v_pk_add_f32 v[76:77], v[108:109], v[112:113]
	v_pk_add_f32 v[78:79], v[116:117], v[120:121]
	v_pk_add_f32 v[96:97], v[108:109], v[112:113] neg_lo:[0,1] neg_hi:[0,1]
	v_pk_add_f32 v[98:99], v[116:117], v[120:121] neg_lo:[0,1] neg_hi:[0,1]
	v_pk_add_f32 v[88:89], v[110:111], v[114:115] op_sel:[0,1] op_sel_hi:[1,0] neg_lo:[0,1]
	v_pk_add_f32 v[90:91], v[118:119], v[122:123] op_sel:[0,1] op_sel_hi:[1,0] neg_lo:[0,1]
	v_pk_add_f32 v[104:105], v[110:111], v[114:115] op_sel:[0,1] op_sel_hi:[1,0] neg_hi:[0,1]
	v_pk_add_f32 v[106:107], v[118:119], v[122:123] op_sel:[0,1] op_sel_hi:[1,0] neg_hi:[0,1]
	s_nop 0
	ds_write2st64_b64 v217, v[80:81], v[82:83] offset1:4
	ds_write2st64_b64 v217, v[76:77], v[78:79] offset0:8 offset1:12
	ds_write2st64_b64 v217, v[84:85], v[86:87] offset0:16 offset1:20
	ds_write2st64_b64 v217, v[88:89], v[90:91] offset0:24 offset1:28
	ds_write2st64_b64 v217, v[92:93], v[94:95] offset0:32 offset1:36
	ds_write2st64_b64 v217, v[96:97], v[98:99] offset0:40 offset1:44
	ds_write2st64_b64 v217, v[100:101], v[102:103] offset0:48 offset1:52
	ds_write2st64_b64 v217, v[104:105], v[106:107] offset0:56 offset1:60
	s_waitcnt lgkmcnt(8)
	v_pk_mul_f32 v[124:125], v[194:195], v[244:245] op_sel:[1,1] op_sel_hi:[1,0]
	v_pk_mul_f32 v[128:129], v[198:199], v[244:245] op_sel:[1,1] op_sel_hi:[1,0]
	v_pk_mul_f32 v[126:127], v[188:189], v[246:247] op_sel:[1,1] op_sel_hi:[1,0]
	v_pk_mul_f32 v[130:131], v[200:201], v[246:247] op_sel:[1,1] op_sel_hi:[1,0]
	v_pk_fma_f32 v[194:195], v[194:195], v[244:245], v[124:125] op_sel_hi:[0,1,1] neg_lo:[0,0,1]
	v_pk_fma_f32 v[198:199], v[198:199], v[244:245], v[128:129] op_sel_hi:[0,1,1] neg_lo:[0,0,1]
	v_pk_mul_f32 v[124:125], v[190:191], v[248:249] op_sel:[1,1] op_sel_hi:[1,0]
	v_pk_mul_f32 v[128:129], v[202:203], v[248:249] op_sel:[1,1] op_sel_hi:[1,0]
	v_pk_fma_f32 v[188:189], v[188:189], v[246:247], v[126:127] op_sel_hi:[0,1,1] neg_lo:[0,0,1]
	v_pk_fma_f32 v[200:201], v[200:201], v[246:247], v[130:131] op_sel_hi:[0,1,1] neg_lo:[0,0,1]
	v_pk_fma_f32 v[190:191], v[190:191], v[248:249], v[124:125] op_sel_hi:[0,1,1] neg_lo:[0,0,1]
	v_pk_fma_f32 v[202:203], v[202:203], v[248:249], v[128:129] op_sel_hi:[0,1,1] neg_lo:[0,0,1]
	v_pk_add_f32 v[108:109], v[192:193], v[188:189]
	v_pk_add_f32 v[116:117], v[196:197], v[200:201]
	v_pk_add_f32 v[112:113], v[194:195], v[190:191]
	v_pk_add_f32 v[120:121], v[198:199], v[202:203]
	v_pk_add_f32 v[110:111], v[192:193], v[188:189] neg_lo:[0,1] neg_hi:[0,1]
	v_pk_add_f32 v[118:119], v[196:197], v[200:201] neg_lo:[0,1] neg_hi:[0,1]
	v_pk_add_f32 v[114:115], v[194:195], v[190:191] neg_lo:[0,1] neg_hi:[0,1]
	v_pk_add_f32 v[122:123], v[198:199], v[202:203] neg_lo:[0,1] neg_hi:[0,1]
	v_pk_add_f32 v[192:193], v[108:109], v[112:113]
	v_pk_add_f32 v[196:197], v[116:117], v[120:121]
	v_pk_add_f32 v[188:189], v[108:109], v[112:113] neg_lo:[0,1] neg_hi:[0,1]
	v_pk_add_f32 v[200:201], v[116:117], v[120:121] neg_lo:[0,1] neg_hi:[0,1]
	v_pk_add_f32 v[194:195], v[110:111], v[114:115] op_sel:[0,1] op_sel_hi:[1,0] neg_lo:[0,1]
	v_pk_add_f32 v[198:199], v[118:119], v[122:123] op_sel:[0,1] op_sel_hi:[1,0] neg_lo:[0,1]
	v_pk_add_f32 v[190:191], v[110:111], v[114:115] op_sel:[0,1] op_sel_hi:[1,0] neg_hi:[0,1]
	v_pk_add_f32 v[202:203], v[118:119], v[122:123] op_sel:[0,1] op_sel_hi:[1,0] neg_hi:[0,1]
	v_pk_mul_f32 v[124:125], v[206:207], v[244:245] op_sel:[1,1] op_sel_hi:[1,0]
	v_pk_mul_f32 v[128:129], v[214:215], v[244:245] op_sel:[1,1] op_sel_hi:[1,0]
	v_pk_mul_f32 v[126:127], v[208:209], v[246:247] op_sel:[1,1] op_sel_hi:[1,0]
	v_pk_mul_f32 v[130:131], v[252:253], v[246:247] op_sel:[1,1] op_sel_hi:[1,0]
	v_pk_fma_f32 v[206:207], v[206:207], v[244:245], v[124:125] op_sel_hi:[0,1,1] neg_lo:[0,0,1]
	v_pk_fma_f32 v[214:215], v[214:215], v[244:245], v[128:129] op_sel_hi:[0,1,1] neg_lo:[0,0,1]
	v_pk_mul_f32 v[124:125], v[210:211], v[248:249] op_sel:[1,1] op_sel_hi:[1,0]
	v_pk_mul_f32 v[128:129], v[254:255], v[248:249] op_sel:[1,1] op_sel_hi:[1,0]
	v_pk_fma_f32 v[208:209], v[208:209], v[246:247], v[126:127] op_sel_hi:[0,1,1] neg_lo:[0,0,1]
	v_pk_fma_f32 v[252:253], v[252:253], v[246:247], v[130:131] op_sel_hi:[0,1,1] neg_lo:[0,0,1]
	v_pk_fma_f32 v[210:211], v[210:211], v[248:249], v[124:125] op_sel_hi:[0,1,1] neg_lo:[0,0,1]
	v_pk_fma_f32 v[254:255], v[254:255], v[248:249], v[128:129] op_sel_hi:[0,1,1] neg_lo:[0,0,1]
	v_pk_add_f32 v[108:109], v[204:205], v[208:209]
	v_pk_add_f32 v[116:117], v[212:213], v[252:253]
	v_pk_add_f32 v[112:113], v[206:207], v[210:211]
	v_pk_add_f32 v[120:121], v[214:215], v[254:255]
	v_pk_add_f32 v[110:111], v[204:205], v[208:209] neg_lo:[0,1] neg_hi:[0,1]
	v_pk_add_f32 v[118:119], v[212:213], v[252:253] neg_lo:[0,1] neg_hi:[0,1]
	v_pk_add_f32 v[114:115], v[206:207], v[210:211] neg_lo:[0,1] neg_hi:[0,1]
	v_pk_add_f32 v[122:123], v[214:215], v[254:255] neg_lo:[0,1] neg_hi:[0,1]
	v_pk_add_f32 v[204:205], v[108:109], v[112:113]
	v_pk_add_f32 v[212:213], v[116:117], v[120:121]
; DI float2 twid(float r) { return float2{__builtin_amdgcn_cosf(r), -__builtin_amdgcn_sinf(r)}; }
; DI void bfly_inv(float2 s0, float2 s1, float2 s2, float2 s3, float r, float2& o0, float2& o1, float2& o2, float2& o3) {
;   float2 w1 = twid(r), w2 = cmul(w1, w1), w3 = cmul(w2, w1);
;   float2 c0 = s0, c1 = cmulc(s1, w1), c2 = cmulc(s2, w2), c3 = cmulc(s3, w3);
;   float2 t0 = {c0.x + c2.x, c0.y + c2.y}, t1 = {c0.x - c2.x, c0.y - c2.y}, t2 = {c1.x + c3.x, c1.y + c3.y}, t3 = {c1.x - c3.x, c1.y - c3.y};
;   o0 = float2{t0.x + t2.x, t0.y + t2.y}; o2 = float2{t0.x - t2.x, t0.y - t2.y}; o1 = float2{t1.x - t3.y, t1.y + t3.x}; o3 = float2{t1.x + t3.y, t1.y - t3.x};
; }
;   const int lq1 = lq2 + 2, Q1 = 1 << lq1, Q2 = 1 << lq2; const float invM1 = 1.f / (float)(4 << lq1), invM2 = 1.f / (float)(4 << lq2);
;   for (int gg = tid; gg < NBT * (N / 16); gg += NTHR) { const int g = gg & (N / 16 - 1); float2* z = z0 + (gg / (N / 16)) * N; const int jp = g & (Q2 - 1), base = ((g >> lq2) << (lq2 + 4)) + jp; float2 x[4][4];
; #pragma unroll
;     for (int q1 = 0; q1 < 4; ++q1)
; #pragma unroll
;       for (int q2 = 0; q2 < 4; ++q2) x[q1][q2] = z[base + q1 * Q1 + q2 * Q2];
; #pragma unroll
;     for (int q1 = 0; q1 < 4; ++q1) bfly_inv(x[q1][0], x[q1][1], x[q1][2], x[q1][3], (float)jp * invM2, x[q1][0], x[q1][1], x[q1][2], x[q1][3]);
; #pragma unroll
;     for (int q2 = 0; q2 < 4; ++q2) bfly_inv(x[0][q2], x[1][q2], x[2][q2], x[3][q2], (float)(jp + q2 * Q2) * invM1, x[0][q2], x[1][q2], x[2][q2], x[3][q2]);
; #pragma unroll
;     for (int q1 = 0; q1 < 4; ++q1)
; #pragma unroll
;       for (int q2 = 0; q2 < 4; ++q2) z[base + q1 * Q1 + q2 * Q2] = x[q1][q2]; }
;   __syncthreads();
; }
	v_pk_add_f32 v[208:209], v[108:109], v[112:113] neg_lo:[0,1] neg_hi:[0,1]
	v_pk_add_f32 v[252:253], v[116:117], v[120:121] neg_lo:[0,1] neg_hi:[0,1]
	v_pk_add_f32 v[206:207], v[110:111], v[114:115] op_sel:[0,1] op_sel_hi:[1,0] neg_lo:[0,1]
	v_pk_add_f32 v[214:215], v[118:119], v[122:123] op_sel:[0,1] op_sel_hi:[1,0] neg_lo:[0,1]
	v_pk_add_f32 v[210:211], v[110:111], v[114:115] op_sel:[0,1] op_sel_hi:[1,0] neg_hi:[0,1]
	v_pk_add_f32 v[254:255], v[118:119], v[122:123] op_sel:[0,1] op_sel_hi:[1,0] neg_hi:[0,1]
	v_pk_mul_f32 v[124:125], v[196:197], v[218:219] op_sel:[1,1] op_sel_hi:[1,0]
	v_pk_mul_f32 v[128:129], v[198:199], v[224:225] op_sel:[1,1] op_sel_hi:[1,0]
	v_pk_mul_f32 v[126:127], v[204:205], v[220:221] op_sel:[1,1] op_sel_hi:[1,0]
	v_pk_mul_f32 v[130:131], v[206:207], v[226:227] op_sel:[1,1] op_sel_hi:[1,0]
	v_pk_fma_f32 v[196:197], v[196:197], v[218:219], v[124:125] op_sel_hi:[0,1,1] neg_lo:[0,0,1]
	v_pk_fma_f32 v[198:199], v[198:199], v[224:225], v[128:129] op_sel_hi:[0,1,1] neg_lo:[0,0,1]
	v_pk_mul_f32 v[124:125], v[212:213], v[222:223] op_sel:[1,1] op_sel_hi:[1,0]
	v_pk_mul_f32 v[128:129], v[214:215], v[228:229] op_sel:[1,1] op_sel_hi:[1,0]
	v_pk_fma_f32 v[204:205], v[204:205], v[220:221], v[126:127] op_sel_hi:[0,1,1] neg_lo:[0,0,1]
	v_pk_fma_f32 v[206:207], v[206:207], v[226:227], v[130:131] op_sel_hi:[0,1,1] neg_lo:[0,0,1]
	v_pk_fma_f32 v[212:213], v[212:213], v[222:223], v[124:125] op_sel_hi:[0,1,1] neg_lo:[0,0,1]
	v_pk_fma_f32 v[214:215], v[214:215], v[228:229], v[128:129] op_sel_hi:[0,1,1] neg_lo:[0,0,1]
	v_pk_add_f32 v[108:109], v[192:193], v[204:205]
	v_pk_add_f32 v[116:117], v[194:195], v[206:207]
	v_pk_add_f32 v[112:113], v[196:197], v[212:213]
	v_pk_add_f32 v[120:121], v[198:199], v[214:215]
	v_pk_add_f32 v[110:111], v[192:193], v[204:205] neg_lo:[0,1] neg_hi:[0,1]
	v_pk_add_f32 v[118:119], v[194:195], v[206:207] neg_lo:[0,1] neg_hi:[0,1]
	v_pk_add_f32 v[114:115], v[196:197], v[212:213] neg_lo:[0,1] neg_hi:[0,1]
	v_pk_add_f32 v[122:123], v[198:199], v[214:215] neg_lo:[0,1] neg_hi:[0,1]
	v_pk_add_f32 v[192:193], v[108:109], v[112:113]
	v_pk_add_f32 v[194:195], v[116:117], v[120:121]
	v_pk_add_f32 v[204:205], v[108:109], v[112:113] neg_lo:[0,1] neg_hi:[0,1]
	v_pk_add_f32 v[206:207], v[116:117], v[120:121] neg_lo:[0,1] neg_hi:[0,1]
	v_pk_add_f32 v[196:197], v[110:111], v[114:115] op_sel:[0,1] op_sel_hi:[1,0] neg_lo:[0,1]
	v_pk_add_f32 v[198:199], v[118:119], v[122:123] op_sel:[0,1] op_sel_hi:[1,0] neg_lo:[0,1]
	v_pk_add_f32 v[212:213], v[110:111], v[114:115] op_sel:[0,1] op_sel_hi:[1,0] neg_hi:[0,1]
	v_pk_add_f32 v[214:215], v[118:119], v[122:123] op_sel:[0,1] op_sel_hi:[1,0] neg_hi:[0,1]
	v_pk_mul_f32 v[124:125], v[200:201], v[230:231] op_sel:[1,1] op_sel_hi:[1,0]
	v_pk_mul_f32 v[128:129], v[202:203], v[236:237] op_sel:[1,1] op_sel_hi:[1,0]
	v_pk_mul_f32 v[126:127], v[208:209], v[232:233] op_sel:[1,1] op_sel_hi:[1,0]
	v_pk_mul_f32 v[130:131], v[210:211], v[238:239] op_sel:[1,1] op_sel_hi:[1,0]
	v_pk_fma_f32 v[200:201], v[200:201], v[230:231], v[124:125] op_sel_hi:[0,1,1] neg_lo:[0,0,1]
	v_pk_fma_f32 v[202:203], v[202:203], v[236:237], v[128:129] op_sel_hi:[0,1,1] neg_lo:[0,0,1]
	v_pk_mul_f32 v[124:125], v[252:253], v[234:235] op_sel:[1,1] op_sel_hi:[1,0]
	v_pk_mul_f32 v[128:129], v[254:255], v[242:243] op_sel:[1,1] op_sel_hi:[1,0]
	v_pk_fma_f32 v[208:209], v[208:209], v[232:233], v[126:127] op_sel_hi:[0,1,1] neg_lo:[0,0,1]
	v_pk_fma_f32 v[210:211], v[210:211], v[238:239], v[130:131] op_sel_hi:[0,1,1] neg_lo:[0,0,1]
	v_pk_fma_f32 v[252:253], v[252:253], v[234:235], v[124:125] op_sel_hi:[0,1,1] neg_lo:[0,0,1]
	v_pk_fma_f32 v[254:255], v[254:255], v[242:243], v[128:129] op_sel_hi:[0,1,1] neg_lo:[0,0,1]
	v_pk_add_f32 v[108:109], v[188:189], v[208:209]
	v_pk_add_f32 v[116:117], v[190:191], v[210:211]
	v_pk_add_f32 v[112:113], v[200:201], v[252:253]
	v_pk_add_f32 v[120:121], v[202:203], v[254:255]
	v_pk_add_f32 v[110:111], v[188:189], v[208:209] neg_lo:[0,1] neg_hi:[0,1]
	v_pk_add_f32 v[118:119], v[190:191], v[210:211] neg_lo:[0,1] neg_hi:[0,1]
	v_pk_add_f32 v[114:115], v[200:201], v[252:253] neg_lo:[0,1] neg_hi:[0,1]
	v_pk_add_f32 v[122:123], v[202:203], v[254:255] neg_lo:[0,1] neg_hi:[0,1]
	v_pk_add_f32 v[188:189], v[108:109], v[112:113]
	v_pk_add_f32 v[190:191], v[116:117], v[120:121]
	v_pk_add_f32 v[208:209], v[108:109], v[112:113] neg_lo:[0,1] neg_hi:[0,1]
	v_pk_add_f32 v[210:211], v[116:117], v[120:121] neg_lo:[0,1] neg_hi:[0,1]
	v_pk_add_f32 v[200:201], v[110:111], v[114:115] op_sel:[0,1] op_sel_hi:[1,0] neg_lo:[0,1]
	v_pk_add_f32 v[202:203], v[118:119], v[122:123] op_sel:[0,1] op_sel_hi:[1,0] neg_lo:[0,1]
	v_pk_add_f32 v[252:253], v[110:111], v[114:115] op_sel:[0,1] op_sel_hi:[1,0] neg_hi:[0,1]
	v_pk_add_f32 v[254:255], v[118:119], v[122:123] op_sel:[0,1] op_sel_hi:[1,0] neg_hi:[0,1]
	s_nop 0
	ds_write2st64_b64 v251, v[192:193], v[194:195] offset1:4
	ds_write2st64_b64 v251, v[188:189], v[190:191] offset0:8 offset1:12
	ds_write2st64_b64 v251, v[196:197], v[198:199] offset0:16 offset1:20
	ds_write2st64_b64 v251, v[200:201], v[202:203] offset0:24 offset1:28
	ds_write2st64_b64 v251, v[204:205], v[206:207] offset0:32 offset1:36
	ds_write2st64_b64 v251, v[208:209], v[210:211] offset0:40 offset1:44
	ds_write2st64_b64 v251, v[212:213], v[214:215] offset0:48 offset1:52
	ds_write2st64_b64 v251, v[252:253], v[254:255] offset0:56 offset1:60
	s_mov_b64 s[0:1], exec

; DI float2 twid(float r) { return float2{__builtin_amdgcn_cosf(r), -__builtin_amdgcn_sinf(r)}; }
; DI void bfly_fwd(float2 a0, float2 a1, float2 a2, float2 a3, float r, float2& o0, float2& o1, float2& o2, float2& o3) {
;   float2 t0 = {a0.x + a2.x, a0.y + a2.y}, t1 = {a0.x - a2.x, a0.y - a2.y}, t2 = {a1.x + a3.x, a1.y + a3.y}, t3 = {a1.x - a3.x, a1.y - a3.y};
;   float2 b0 = {t0.x + t2.x, t0.y + t2.y}, b2 = {t0.x - t2.x, t0.y - t2.y}, b1 = {t1.x + t3.y, t1.y - t3.x}, b3 = {t1.x - t3.y, t1.y + t3.x};
;   float2 w1 = twid(r), w2 = cmul(w1, w1), w3 = cmul(w2, w1);
;   o0 = b0; o1 = cmul(b1, w1); o2 = cmul(b2, w2); o3 = cmul(b3, w3);
; }
;   const int lq2 = lq1 - 2, Q1 = 1 << lq1, Q2 = 1 << lq2; const float invM1 = 1.f / (float)(4 << lq1), invM2 = 1.f / (float)(4 << lq2);
;   for (int gg = tid; gg < NBT * (N / 16); gg += NTHR) { const int g = gg & (N / 16 - 1); float2* z = z0 + (gg / (N / 16)) * N; const int jp = g & (Q2 - 1), base = ((g >> lq2) << (lq2 + 4)) + jp; float2 x[4][4];
; #pragma unroll
;     for (int q1 = 0; q1 < 4; ++q1)
; #pragma unroll
;       for (int q2 = 0; q2 < 4; ++q2) x[q1][q2] = z[base + q1 * Q1 + q2 * Q2];
; #pragma unroll
;     for (int q2 = 0; q2 < 4; ++q2) bfly_fwd(x[0][q2], x[1][q2], x[2][q2], x[3][q2], (float)(jp + q2 * Q2) * invM1, x[0][q2], x[1][q2], x[2][q2], x[3][q2]);
.LBB0_1632:
	v_ashrrev_i32_e32 v216, 31, v65
	v_lshrrev_b32_e32 v216, 22, v216
	v_add_lshl_u32 v216, v65, v216, 7
	v_and_b32_e32 v216, 0xfffe0000, v216
	v_and_b32_e32 v217, 0x3000, v64
	v_add_u32_e32 v216, 16, v216
	v_lshlrev_b32_e32 v217, 3, v217
	v_lshlrev_b32_sdwa v148, v151, v76 dst_sel:DWORD dst_unused:UNUSED_PAD src0_sel:DWORD src1_sel:BYTE_0
	v_add3_u32 v251, v216, v217, v148
	ds_read2st64_b64 v[70:73], v251 offset1:4
	ds_read2st64_b64 v[84:87], v251 offset0:8 offset1:12
	ds_read2st64_b64 v[88:91], v251 offset0:16 offset1:20
	ds_read2st64_b64 v[92:95], v251 offset0:24 offset1:28
	ds_read2st64_b64 v[96:99], v251 offset0:32 offset1:36
	ds_read2st64_b64 v[100:103], v251 offset0:40 offset1:44
	ds_read2st64_b64 v[104:107], v251 offset0:48 offset1:52
	ds_read2st64_b64 v[108:111], v251 offset0:56 offset1:60
	v_add_u32_e32 v64, 0x2000, v64
	v_add_u32_e32 v66, 0x200, v65
	v_mov_b32_e32 v65, v66
	v_ashrrev_i32_e32 v134, 31, v65
	v_lshrrev_b32_e32 v134, 22, v134
	v_add_lshl_u32 v134, v65, v134, 7
	v_and_b32_e32 v134, 0xfffe0000, v134
	v_and_b32_e32 v135, 0x3000, v64
	v_add_u32_e32 v134, 16, v134
	v_lshlrev_b32_e32 v135, 3, v135
	v_lshlrev_b32_sdwa v136, v151, v76 dst_sel:DWORD dst_unused:UNUSED_PAD src0_sel:DWORD src1_sel:BYTE_0
	v_add3_u32 v137, v134, v135, v136
	ds_read2st64_b64 v[188:191], v137 offset1:4
	ds_read2st64_b64 v[192:195], v137 offset0:8 offset1:12
	ds_read2st64_b64 v[196:199], v137 offset0:16 offset1:20
	ds_read2st64_b64 v[200:203], v137 offset0:24 offset1:28
	ds_read2st64_b64 v[204:207], v137 offset0:32 offset1:36
	ds_read2st64_b64 v[208:211], v137 offset0:40 offset1:44
	ds_read2st64_b64 v[212:215], v137 offset0:48 offset1:52
	ds_read2st64_b64 v[252:255], v137 offset0:56 offset1:60
	v_add_u32_e32 v64, 0x2000, v64
	v_add_u32_e32 v66, 0x200, v65
	v_mov_b32_e32 v65, v66
	v_and_b32_e32 v241, 0xff, v65
	v_cvt_f32_u32_e32 v250, v241
	v_mul_f32_e32 v250, 0x39800000, v250
	v_cos_f32_e32 v218, v250
	v_sin_f32_e32 v219, v250
	s_nop 1
	v_xor_b32_e32 v219, 0x80000000, v219
	s_nop 0
	v_pk_mul_f32 v[126:127], v[218:219], v[218:219] op_sel:[1,1] op_sel_hi:[1,0]
	s_nop 0
	v_pk_fma_f32 v[220:221], v[218:219], v[218:219], v[126:127] op_sel_hi:[0,1,1] neg_lo:[0,0,1]
	s_nop 0
	v_pk_mul_f32 v[126:127], v[220:221], v[218:219] op_sel:[1,1] op_sel_hi:[1,0]
	s_nop 0
	v_pk_fma_f32 v[222:223], v[220:221], v[218:219], v[126:127] op_sel_hi:[0,1,1] neg_lo:[0,0,1]
	v_pk_mul_f32 v[126:127], v[220:221], v[220:221] op_sel:[1,1] op_sel_hi:[1,0]
	s_nop 0
	v_pk_fma_f32 v[244:245], v[220:221], v[220:221], v[126:127] op_sel_hi:[0,1,1] neg_lo:[0,0,1]
	s_nop 0
	v_mul_f32_e32 v241, 0x3ec3ef15, v219
	v_mul_f32_e32 v250, 0xbec3ef15, v218
	v_fmamk_f32 v224, v218, 0x3f6c835e, v241
	v_fmamk_f32 v225, v219, 0x3f6c835e, v250
	v_mul_f32_e32 v241, 0x3f3504f3, v219
	v_mul_f32_e32 v250, 0xbf3504f3, v218
	v_fmamk_f32 v230, v218, 0x3f3504f3, v241
	v_fmamk_f32 v231, v219, 0x3f3504f3, v250
	v_mul_f32_e32 v241, 0x3f6c835e, v219
	v_mul_f32_e32 v250, 0xbf6c835e, v218
	v_fmamk_f32 v236, v218, 0x3ec3ef15, v241
	v_fmamk_f32 v237, v219, 0x3ec3ef15, v250
	v_mul_f32_e32 v241, 0x3f3504f3, v221
	v_mul_f32_e32 v250, 0xbf3504f3, v220
	v_fmamk_f32 v226, v220, 0x3f3504f3, v241
	v_fmamk_f32 v227, v221, 0x3f3504f3, v250
	v_mul_f32_e32 v241, 0x3f800000, v221
	v_mul_f32_e32 v250, 0xbf800000, v220
	v_fmamk_f32 v232, v220, 0x00000000, v241
	v_fmamk_f32 v233, v221, 0x00000000, v250
	v_mul_f32_e32 v241, 0x3f3504f3, v221
	v_mul_f32_e32 v250, 0xbf3504f3, v220
	v_fmamk_f32 v238, v220, 0xbf3504f3, v241
	v_fmamk_f32 v239, v221, 0xbf3504f3, v250
	v_mul_f32_e32 v241, 0x3f6c835e, v223
	v_mul_f32_e32 v250, 0xbf6c835e, v222
	v_fmamk_f32 v228, v222, 0x3ec3ef15, v241
	v_fmamk_f32 v229, v223, 0x3ec3ef15, v250
	v_mul_f32_e32 v241, 0x3f3504f3, v223
	v_mul_f32_e32 v250, 0xbf3504f3, v222
	v_fmamk_f32 v234, v222, 0xbf3504f3, v241
	v_fmamk_f32 v235, v223, 0xbf3504f3, v250
	v_mul_f32_e32 v241, 0xbec3ef15, v223
	v_mul_f32_e32 v250, 0x3ec3ef15, v222
	v_fmamk_f32 v242, v222, 0xbf6c835e, v241
	v_fmamk_f32 v243, v223, 0xbf6c835e, v250
	v_pk_mul_f32 v[126:127], v[244:245], v[244:245] op_sel:[1,1] op_sel_hi:[1,0]
	s_nop 0
	v_pk_fma_f32 v[246:247], v[244:245], v[244:245], v[126:127] op_sel_hi:[0,1,1] neg_lo:[0,0,1]
	s_nop 0
	v_pk_mul_f32 v[126:127], v[246:247], v[244:245] op_sel:[1,1] op_sel_hi:[1,0]
	s_nop 0
	v_pk_fma_f32 v[248:249], v[246:247], v[244:245], v[126:127] op_sel_hi:[0,1,1] neg_lo:[0,0,1]
	s_nop 0
	s_waitcnt lgkmcnt(8)
; DI float2 twid(float r) { return float2{__builtin_amdgcn_cosf(r), -__builtin_amdgcn_sinf(r)}; }
; DI void bfly_fwd(float2 a0, float2 a1, float2 a2, float2 a3, float r, float2& o0, float2& o1, float2& o2, float2& o3) {
;   float2 t0 = {a0.x + a2.x, a0.y + a2.y}, t1 = {a0.x - a2.x, a0.y - a2.y}, t2 = {a1.x + a3.x, a1.y + a3.y}, t3 = {a1.x - a3.x, a1.y - a3.y};
;   float2 b0 = {t0.x + t2.x, t0.y + t2.y}, b2 = {t0.x - t2.x, t0.y - t2.y}, b1 = {t1.x + t3.y, t1.y - t3.x}, b3 = {t1.x - t3.y, t1.y + t3.x};
;   float2 w1 = twid(r), w2 = cmul(w1, w1), w3 = cmul(w2, w1);
;   o0 = b0; o1 = cmul(b1, w1); o2 = cmul(b2, w2); o3 = cmul(b3, w3);
; }
;     ...
;     for (int q2 = 0; q2 < 4; ++q2) bfly_fwd(x[0][q2], x[1][q2], x[2][q2], x[3][q2], (float)(jp + q2 * Q2) * invM1, x[0][q2], x[1][q2], x[2][q2], x[3][q2]);
; #pragma unroll
;     for (int q1 = 0; q1 < 4; ++q1) bfly_fwd(x[q1][0], x[q1][1], x[q1][2], x[q1][3], (float)jp * invM2, x[q1][0], x[q1][1], x[q1][2], x[q1][3]);
	v_pk_add_f32 v[74:75], v[70:71], v[96:97]
	v_pk_add_f32 v[118:119], v[72:73], v[98:99]
	v_pk_add_f32 v[114:115], v[88:89], v[104:105]
	v_pk_add_f32 v[122:123], v[90:91], v[106:107]
	v_pk_add_f32 v[112:113], v[70:71], v[96:97] neg_lo:[0,1] neg_hi:[0,1]
	v_pk_add_f32 v[120:121], v[72:73], v[98:99] neg_lo:[0,1] neg_hi:[0,1]
	v_pk_add_f32 v[116:117], v[88:89], v[104:105] neg_lo:[0,1] neg_hi:[0,1]
	v_pk_add_f32 v[124:125], v[90:91], v[106:107] neg_lo:[0,1] neg_hi:[0,1]
	v_pk_add_f32 v[70:71], v[74:75], v[114:115]
	v_pk_add_f32 v[72:73], v[118:119], v[122:123]
	v_pk_add_f32 v[74:75], v[74:75], v[114:115] neg_lo:[0,1] neg_hi:[0,1]
	v_pk_add_f32 v[118:119], v[118:119], v[122:123] neg_lo:[0,1] neg_hi:[0,1]
	v_pk_add_f32 v[114:115], v[112:113], v[116:117] op_sel:[0,1] op_sel_hi:[1,0] neg_hi:[0,1]
	v_pk_add_f32 v[122:123], v[120:121], v[124:125] op_sel:[0,1] op_sel_hi:[1,0] neg_hi:[0,1]
	v_pk_add_f32 v[112:113], v[112:113], v[116:117] op_sel:[0,1] op_sel_hi:[1,0] neg_lo:[0,1]
	v_pk_add_f32 v[120:121], v[120:121], v[124:125] op_sel:[0,1] op_sel_hi:[1,0] neg_lo:[0,1]
	v_pk_mul_f32 v[126:127], v[74:75], v[220:221] op_sel:[1,1] op_sel_hi:[1,0]
	v_pk_mul_f32 v[130:131], v[118:119], v[226:227] op_sel:[1,1] op_sel_hi:[1,0]
	v_pk_mul_f32 v[128:129], v[114:115], v[218:219] op_sel:[1,1] op_sel_hi:[1,0]
	v_pk_mul_f32 v[132:133], v[122:123], v[224:225] op_sel:[1,1] op_sel_hi:[1,0]
	v_pk_fma_f32 v[96:97], v[74:75], v[220:221], v[126:127] op_sel_hi:[0,1,1] neg_lo:[0,0,1]
	v_pk_fma_f32 v[98:99], v[118:119], v[226:227], v[130:131] op_sel_hi:[0,1,1] neg_lo:[0,0,1]
	v_pk_mul_f32 v[126:127], v[112:113], v[222:223] op_sel:[1,1] op_sel_hi:[1,0]
	v_pk_mul_f32 v[130:131], v[120:121], v[228:229] op_sel:[1,1] op_sel_hi:[1,0]
	v_pk_fma_f32 v[88:89], v[114:115], v[218:219], v[128:129] op_sel_hi:[0,1,1] neg_lo:[0,0,1]
	v_pk_fma_f32 v[90:91], v[122:123], v[224:225], v[132:133] op_sel_hi:[0,1,1] neg_lo:[0,0,1]
	v_pk_fma_f32 v[104:105], v[112:113], v[222:223], v[126:127] op_sel_hi:[0,1,1] neg_lo:[0,0,1]
	v_pk_fma_f32 v[106:107], v[120:121], v[228:229], v[130:131] op_sel_hi:[0,1,1] neg_lo:[0,0,1]
	v_pk_add_f32 v[74:75], v[84:85], v[100:101]
	v_pk_add_f32 v[118:119], v[86:87], v[102:103]
	v_pk_add_f32 v[114:115], v[92:93], v[108:109]
	v_pk_add_f32 v[122:123], v[94:95], v[110:111]
	v_pk_add_f32 v[112:113], v[84:85], v[100:101] neg_lo:[0,1] neg_hi:[0,1]
	v_pk_add_f32 v[120:121], v[86:87], v[102:103] neg_lo:[0,1] neg_hi:[0,1]
	v_pk_add_f32 v[116:117], v[92:93], v[108:109] neg_lo:[0,1] neg_hi:[0,1]
	v_pk_add_f32 v[124:125], v[94:95], v[110:111] neg_lo:[0,1] neg_hi:[0,1]
	v_pk_add_f32 v[84:85], v[74:75], v[114:115]
	v_pk_add_f32 v[86:87], v[118:119], v[122:123]
	v_pk_add_f32 v[74:75], v[74:75], v[114:115] neg_lo:[0,1] neg_hi:[0,1]
	v_pk_add_f32 v[118:119], v[118:119], v[122:123] neg_lo:[0,1] neg_hi:[0,1]
	v_pk_add_f32 v[114:115], v[112:113], v[116:117] op_sel:[0,1] op_sel_hi:[1,0] neg_hi:[0,1]
	v_pk_add_f32 v[122:123], v[120:121], v[124:125] op_sel:[0,1] op_sel_hi:[1,0] neg_hi:[0,1]
	v_pk_add_f32 v[112:113], v[112:113], v[116:117] op_sel:[0,1] op_sel_hi:[1,0] neg_lo:[0,1]
	v_pk_add_f32 v[120:121], v[120:121], v[124:125] op_sel:[0,1] op_sel_hi:[1,0] neg_lo:[0,1]
	v_pk_mul_f32 v[126:127], v[74:75], v[232:233] op_sel:[1,1] op_sel_hi:[1,0]
	v_pk_mul_f32 v[130:131], v[118:119], v[238:239] op_sel:[1,1] op_sel_hi:[1,0]
	v_pk_mul_f32 v[128:129], v[114:115], v[230:231] op_sel:[1,1] op_sel_hi:[1,0]
	v_pk_mul_f32 v[132:133], v[122:123], v[236:237] op_sel:[1,1] op_sel_hi:[1,0]
	v_pk_fma_f32 v[100:101], v[74:75], v[232:233], v[126:127] op_sel_hi:[0,1,1] neg_lo:[0,0,1]
	v_pk_fma_f32 v[102:103], v[118:119], v[238:239], v[130:131] op_sel_hi:[0,1,1] neg_lo:[0,0,1]
	v_pk_mul_f32 v[126:127], v[112:113], v[234:235] op_sel:[1,1] op_sel_hi:[1,0]
	v_pk_mul_f32 v[130:131], v[120:121], v[242:243] op_sel:[1,1] op_sel_hi:[1,0]
	v_pk_fma_f32 v[92:93], v[114:115], v[230:231], v[128:129] op_sel_hi:[0,1,1] neg_lo:[0,0,1]
	v_pk_fma_f32 v[94:95], v[122:123], v[236:237], v[132:133] op_sel_hi:[0,1,1] neg_lo:[0,0,1]
	v_pk_fma_f32 v[108:109], v[112:113], v[234:235], v[126:127] op_sel_hi:[0,1,1] neg_lo:[0,0,1]
	v_pk_fma_f32 v[110:111], v[120:121], v[242:243], v[130:131] op_sel_hi:[0,1,1] neg_lo:[0,0,1]
	v_pk_add_f32 v[74:75], v[70:71], v[84:85]
	v_pk_add_f32 v[118:119], v[88:89], v[92:93]
	v_pk_add_f32 v[114:115], v[72:73], v[86:87]
	v_pk_add_f32 v[122:123], v[90:91], v[94:95]
	v_pk_add_f32 v[112:113], v[70:71], v[84:85] neg_lo:[0,1] neg_hi:[0,1]
	v_pk_add_f32 v[120:121], v[88:89], v[92:93] neg_lo:[0,1] neg_hi:[0,1]
	v_pk_add_f32 v[116:117], v[72:73], v[86:87] neg_lo:[0,1] neg_hi:[0,1]
	v_pk_add_f32 v[124:125], v[90:91], v[94:95] neg_lo:[0,1] neg_hi:[0,1]
	v_pk_add_f32 v[70:71], v[74:75], v[114:115]
	v_pk_add_f32 v[88:89], v[118:119], v[122:123]
	v_pk_add_f32 v[74:75], v[74:75], v[114:115] neg_lo:[0,1] neg_hi:[0,1]
	v_pk_add_f32 v[118:119], v[118:119], v[122:123] neg_lo:[0,1] neg_hi:[0,1]
	v_pk_add_f32 v[114:115], v[112:113], v[116:117] op_sel:[0,1] op_sel_hi:[1,0] neg_hi:[0,1]
	v_pk_add_f32 v[122:123], v[120:121], v[124:125] op_sel:[0,1] op_sel_hi:[1,0] neg_hi:[0,1]
	v_pk_add_f32 v[112:113], v[112:113], v[116:117] op_sel:[0,1] op_sel_hi:[1,0] neg_lo:[0,1]
	v_pk_add_f32 v[120:121], v[120:121], v[124:125] op_sel:[0,1] op_sel_hi:[1,0] neg_lo:[0,1]
	v_pk_mul_f32 v[126:127], v[74:75], v[246:247] op_sel:[1,1] op_sel_hi:[1,0]
	v_pk_mul_f32 v[130:131], v[118:119], v[246:247] op_sel:[1,1] op_sel_hi:[1,0]
	v_pk_mul_f32 v[128:129], v[114:115], v[244:245] op_sel:[1,1] op_sel_hi:[1,0]
	v_pk_mul_f32 v[132:133], v[122:123], v[244:245] op_sel:[1,1] op_sel_hi:[1,0]
	v_pk_fma_f32 v[84:85], v[74:75], v[246:247], v[126:127] op_sel_hi:[0,1,1] neg_lo:[0,0,1]
; DI float2 twid(float r) { return float2{__builtin_amdgcn_cosf(r), -__builtin_amdgcn_sinf(r)}; }
; DI void bfly_fwd(float2 a0, float2 a1, float2 a2, float2 a3, float r, float2& o0, float2& o1, float2& o2, float2& o3) {
;   float2 t0 = {a0.x + a2.x, a0.y + a2.y}, t1 = {a0.x - a2.x, a0.y - a2.y}, t2 = {a1.x + a3.x, a1.y + a3.y}, t3 = {a1.x - a3.x, a1.y - a3.y};
;   float2 b0 = {t0.x + t2.x, t0.y + t2.y}, b2 = {t0.x - t2.x, t0.y - t2.y}, b1 = {t1.x + t3.y, t1.y - t3.x}, b3 = {t1.x - t3.y, t1.y + t3.x};
;   float2 w1 = twid(r), w2 = cmul(w1, w1), w3 = cmul(w2, w1);
;   o0 = b0; o1 = cmul(b1, w1); o2 = cmul(b2, w2); o3 = cmul(b3, w3);
; }
;   const int lq2 = lq1 - 2, Q1 = 1 << lq1, Q2 = 1 << lq2; const float invM1 = 1.f / (float)(4 << lq1), invM2 = 1.f / (float)(4 << lq2);
;   for (int gg = tid; gg < NBT * (N / 16); gg += NTHR) { const int g = gg & (N / 16 - 1); float2* z = z0 + (gg / (N / 16)) * N; const int jp = g & (Q2 - 1), base = ((g >> lq2) << (lq2 + 4)) + jp; float2 x[4][4];
; #pragma unroll
;     for (int q1 = 0; q1 < 4; ++q1)
; #pragma unroll
;       for (int q2 = 0; q2 < 4; ++q2) x[q1][q2] = z[base + q1 * Q1 + q2 * Q2];
; #pragma unroll
;     for (int q2 = 0; q2 < 4; ++q2) bfly_fwd(x[0][q2], x[1][q2], x[2][q2], x[3][q2], (float)(jp + q2 * Q2) * invM1, x[0][q2], x[1][q2], x[2][q2], x[3][q2]);
; #pragma unroll
;     for (int q1 = 0; q1 < 4; ++q1) bfly_fwd(x[q1][0], x[q1][1], x[q1][2], x[q1][3], (float)jp * invM2, x[q1][0], x[q1][1], x[q1][2], x[q1][3]);
; #pragma unroll
;     for (int q1 = 0; q1 < 4; ++q1)
; #pragma unroll
;       for (int q2 = 0; q2 < 4; ++q2) z[base + q1 * Q1 + q2 * Q2] = x[q1][q2]; }
;   __syncthreads();
; }
	v_pk_fma_f32 v[92:93], v[118:119], v[246:247], v[130:131] op_sel_hi:[0,1,1] neg_lo:[0,0,1]
	v_pk_mul_f32 v[126:127], v[112:113], v[248:249] op_sel:[1,1] op_sel_hi:[1,0]
	v_pk_mul_f32 v[130:131], v[120:121], v[248:249] op_sel:[1,1] op_sel_hi:[1,0]
	v_pk_fma_f32 v[72:73], v[114:115], v[244:245], v[128:129] op_sel_hi:[0,1,1] neg_lo:[0,0,1]
	v_pk_fma_f32 v[90:91], v[122:123], v[244:245], v[132:133] op_sel_hi:[0,1,1] neg_lo:[0,0,1]
	v_pk_fma_f32 v[86:87], v[112:113], v[248:249], v[126:127] op_sel_hi:[0,1,1] neg_lo:[0,0,1]
	v_pk_fma_f32 v[94:95], v[120:121], v[248:249], v[130:131] op_sel_hi:[0,1,1] neg_lo:[0,0,1]
	v_pk_add_f32 v[74:75], v[96:97], v[100:101]
	v_pk_add_f32 v[118:119], v[104:105], v[108:109]
	v_pk_add_f32 v[114:115], v[98:99], v[102:103]
	v_pk_add_f32 v[122:123], v[106:107], v[110:111]
	v_pk_add_f32 v[112:113], v[96:97], v[100:101] neg_lo:[0,1] neg_hi:[0,1]
	v_pk_add_f32 v[120:121], v[104:105], v[108:109] neg_lo:[0,1] neg_hi:[0,1]
	v_pk_add_f32 v[116:117], v[98:99], v[102:103] neg_lo:[0,1] neg_hi:[0,1]
	v_pk_add_f32 v[124:125], v[106:107], v[110:111] neg_lo:[0,1] neg_hi:[0,1]
	v_pk_add_f32 v[96:97], v[74:75], v[114:115]
	v_pk_add_f32 v[104:105], v[118:119], v[122:123]
	v_pk_add_f32 v[74:75], v[74:75], v[114:115] neg_lo:[0,1] neg_hi:[0,1]
	v_pk_add_f32 v[118:119], v[118:119], v[122:123] neg_lo:[0,1] neg_hi:[0,1]
	v_pk_add_f32 v[114:115], v[112:113], v[116:117] op_sel:[0,1] op_sel_hi:[1,0] neg_hi:[0,1]
	v_pk_add_f32 v[122:123], v[120:121], v[124:125] op_sel:[0,1] op_sel_hi:[1,0] neg_hi:[0,1]
	v_pk_add_f32 v[112:113], v[112:113], v[116:117] op_sel:[0,1] op_sel_hi:[1,0] neg_lo:[0,1]
	v_pk_add_f32 v[120:121], v[120:121], v[124:125] op_sel:[0,1] op_sel_hi:[1,0] neg_lo:[0,1]
	v_pk_mul_f32 v[126:127], v[74:75], v[246:247] op_sel:[1,1] op_sel_hi:[1,0]
	v_pk_mul_f32 v[130:131], v[118:119], v[246:247] op_sel:[1,1] op_sel_hi:[1,0]
	v_pk_mul_f32 v[128:129], v[114:115], v[244:245] op_sel:[1,1] op_sel_hi:[1,0]
	v_pk_mul_f32 v[132:133], v[122:123], v[244:245] op_sel:[1,1] op_sel_hi:[1,0]
	v_pk_fma_f32 v[100:101], v[74:75], v[246:247], v[126:127] op_sel_hi:[0,1,1] neg_lo:[0,0,1]
	v_pk_fma_f32 v[108:109], v[118:119], v[246:247], v[130:131] op_sel_hi:[0,1,1] neg_lo:[0,0,1]
	v_pk_mul_f32 v[126:127], v[112:113], v[248:249] op_sel:[1,1] op_sel_hi:[1,0]
	v_pk_mul_f32 v[130:131], v[120:121], v[248:249] op_sel:[1,1] op_sel_hi:[1,0]
	v_pk_fma_f32 v[98:99], v[114:115], v[244:245], v[128:129] op_sel_hi:[0,1,1] neg_lo:[0,0,1]
	v_pk_fma_f32 v[106:107], v[122:123], v[244:245], v[132:133] op_sel_hi:[0,1,1] neg_lo:[0,0,1]
	v_pk_fma_f32 v[102:103], v[112:113], v[248:249], v[126:127] op_sel_hi:[0,1,1] neg_lo:[0,0,1]
	v_pk_fma_f32 v[110:111], v[120:121], v[248:249], v[130:131] op_sel_hi:[0,1,1] neg_lo:[0,0,1]
	s_nop 0
	ds_write2st64_b64 v251, v[70:71], v[72:73] offset1:4
	ds_write2st64_b64 v251, v[84:85], v[86:87] offset0:8 offset1:12
	ds_write2st64_b64 v251, v[88:89], v[90:91] offset0:16 offset1:20
	ds_write2st64_b64 v251, v[92:93], v[94:95] offset0:24 offset1:28
	ds_write2st64_b64 v251, v[96:97], v[98:99] offset0:32 offset1:36
	ds_write2st64_b64 v251, v[100:101], v[102:103] offset0:40 offset1:44
	ds_write2st64_b64 v251, v[104:105], v[106:107] offset0:48 offset1:52
	ds_write2st64_b64 v251, v[108:109], v[110:111] offset0:56 offset1:60
	s_waitcnt lgkmcnt(8)
	v_pk_add_f32 v[74:75], v[188:189], v[204:205]
	v_pk_add_f32 v[118:119], v[190:191], v[206:207]
	v_pk_add_f32 v[114:115], v[196:197], v[212:213]
	v_pk_add_f32 v[122:123], v[198:199], v[214:215]
	v_pk_add_f32 v[112:113], v[188:189], v[204:205] neg_lo:[0,1] neg_hi:[0,1]
	v_pk_add_f32 v[120:121], v[190:191], v[206:207] neg_lo:[0,1] neg_hi:[0,1]
	v_pk_add_f32 v[116:117], v[196:197], v[212:213] neg_lo:[0,1] neg_hi:[0,1]
	v_pk_add_f32 v[124:125], v[198:199], v[214:215] neg_lo:[0,1] neg_hi:[0,1]
	v_pk_add_f32 v[188:189], v[74:75], v[114:115]
	v_pk_add_f32 v[190:191], v[118:119], v[122:123]
	v_pk_add_f32 v[74:75], v[74:75], v[114:115] neg_lo:[0,1] neg_hi:[0,1]
	v_pk_add_f32 v[118:119], v[118:119], v[122:123] neg_lo:[0,1] neg_hi:[0,1]
	v_pk_add_f32 v[114:115], v[112:113], v[116:117] op_sel:[0,1] op_sel_hi:[1,0] neg_hi:[0,1]
	v_pk_add_f32 v[122:123], v[120:121], v[124:125] op_sel:[0,1] op_sel_hi:[1,0] neg_hi:[0,1]
	v_pk_add_f32 v[112:113], v[112:113], v[116:117] op_sel:[0,1] op_sel_hi:[1,0] neg_lo:[0,1]
	v_pk_add_f32 v[120:121], v[120:121], v[124:125] op_sel:[0,1] op_sel_hi:[1,0] neg_lo:[0,1]
	v_pk_mul_f32 v[126:127], v[74:75], v[220:221] op_sel:[1,1] op_sel_hi:[1,0]
	v_pk_mul_f32 v[130:131], v[118:119], v[226:227] op_sel:[1,1] op_sel_hi:[1,0]
	v_pk_mul_f32 v[128:129], v[114:115], v[218:219] op_sel:[1,1] op_sel_hi:[1,0]
	v_pk_mul_f32 v[132:133], v[122:123], v[224:225] op_sel:[1,1] op_sel_hi:[1,0]
	v_pk_fma_f32 v[204:205], v[74:75], v[220:221], v[126:127] op_sel_hi:[0,1,1] neg_lo:[0,0,1]
	v_pk_fma_f32 v[206:207], v[118:119], v[226:227], v[130:131] op_sel_hi:[0,1,1] neg_lo:[0,0,1]
	v_pk_mul_f32 v[126:127], v[112:113], v[222:223] op_sel:[1,1] op_sel_hi:[1,0]
	v_pk_mul_f32 v[130:131], v[120:121], v[228:229] op_sel:[1,1] op_sel_hi:[1,0]
	v_pk_fma_f32 v[196:197], v[114:115], v[218:219], v[128:129] op_sel_hi:[0,1,1] neg_lo:[0,0,1]
	v_pk_fma_f32 v[198:199], v[122:123], v[224:225], v[132:133] op_sel_hi:[0,1,1] neg_lo:[0,0,1]
	v_pk_fma_f32 v[212:213], v[112:113], v[222:223], v[126:127] op_sel_hi:[0,1,1] neg_lo:[0,0,1]
	v_pk_fma_f32 v[214:215], v[120:121], v[228:229], v[130:131] op_sel_hi:[0,1,1] neg_lo:[0,0,1]
	v_pk_add_f32 v[74:75], v[192:193], v[208:209]
	v_pk_add_f32 v[118:119], v[194:195], v[210:211]
	v_pk_add_f32 v[114:115], v[200:201], v[252:253]
	v_pk_add_f32 v[122:123], v[202:203], v[254:255]
; DI float2 twid(float r) { return float2{__builtin_amdgcn_cosf(r), -__builtin_amdgcn_sinf(r)}; }
; DI void bfly_fwd(float2 a0, float2 a1, float2 a2, float2 a3, float r, float2& o0, float2& o1, float2& o2, float2& o3) {
;   float2 t0 = {a0.x + a2.x, a0.y + a2.y}, t1 = {a0.x - a2.x, a0.y - a2.y}, t2 = {a1.x + a3.x, a1.y + a3.y}, t3 = {a1.x - a3.x, a1.y - a3.y};
;   float2 b0 = {t0.x + t2.x, t0.y + t2.y}, b2 = {t0.x - t2.x, t0.y - t2.y}, b1 = {t1.x + t3.y, t1.y - t3.x}, b3 = {t1.x - t3.y, t1.y + t3.x};
;   float2 w1 = twid(r), w2 = cmul(w1, w1), w3 = cmul(w2, w1);
;   o0 = b0; o1 = cmul(b1, w1); o2 = cmul(b2, w2); o3 = cmul(b3, w3);
; }
;   const int lq2 = lq1 - 2, Q1 = 1 << lq1, Q2 = 1 << lq2; const float invM1 = 1.f / (float)(4 << lq1), invM2 = 1.f / (float)(4 << lq2);
;   for (int gg = tid; gg < NBT * (N / 16); gg += NTHR) { const int g = gg & (N / 16 - 1); float2* z = z0 + (gg / (N / 16)) * N; const int jp = g & (Q2 - 1), base = ((g >> lq2) << (lq2 + 4)) + jp; float2 x[4][4];
; #pragma unroll
;     for (int q1 = 0; q1 < 4; ++q1)
; #pragma unroll
;       for (int q2 = 0; q2 < 4; ++q2) x[q1][q2] = z[base + q1 * Q1 + q2 * Q2];
; #pragma unroll
;     for (int q2 = 0; q2 < 4; ++q2) bfly_fwd(x[0][q2], x[1][q2], x[2][q2], x[3][q2], (float)(jp + q2 * Q2) * invM1, x[0][q2], x[1][q2], x[2][q2], x[3][q2]);
; #pragma unroll
;     for (int q1 = 0; q1 < 4; ++q1) bfly_fwd(x[q1][0], x[q1][1], x[q1][2], x[q1][3], (float)jp * invM2, x[q1][0], x[q1][1], x[q1][2], x[q1][3]);
; #pragma unroll
;     for (int q1 = 0; q1 < 4; ++q1)
; #pragma unroll
;       for (int q2 = 0; q2 < 4; ++q2) z[base + q1 * Q1 + q2 * Q2] = x[q1][q2]; }
;   __syncthreads();
; }
	v_pk_add_f32 v[112:113], v[192:193], v[208:209] neg_lo:[0,1] neg_hi:[0,1]
	v_pk_add_f32 v[120:121], v[194:195], v[210:211] neg_lo:[0,1] neg_hi:[0,1]
	v_pk_add_f32 v[116:117], v[200:201], v[252:253] neg_lo:[0,1] neg_hi:[0,1]
	v_pk_add_f32 v[124:125], v[202:203], v[254:255] neg_lo:[0,1] neg_hi:[0,1]
	v_pk_add_f32 v[192:193], v[74:75], v[114:115]
	v_pk_add_f32 v[194:195], v[118:119], v[122:123]
	v_pk_add_f32 v[74:75], v[74:75], v[114:115] neg_lo:[0,1] neg_hi:[0,1]
	v_pk_add_f32 v[118:119], v[118:119], v[122:123] neg_lo:[0,1] neg_hi:[0,1]
	v_pk_add_f32 v[114:115], v[112:113], v[116:117] op_sel:[0,1] op_sel_hi:[1,0] neg_hi:[0,1]
	v_pk_add_f32 v[122:123], v[120:121], v[124:125] op_sel:[0,1] op_sel_hi:[1,0] neg_hi:[0,1]
	v_pk_add_f32 v[112:113], v[112:113], v[116:117] op_sel:[0,1] op_sel_hi:[1,0] neg_lo:[0,1]
	v_pk_add_f32 v[120:121], v[120:121], v[124:125] op_sel:[0,1] op_sel_hi:[1,0] neg_lo:[0,1]
	v_pk_mul_f32 v[126:127], v[74:75], v[232:233] op_sel:[1,1] op_sel_hi:[1,0]
	v_pk_mul_f32 v[130:131], v[118:119], v[238:239] op_sel:[1,1] op_sel_hi:[1,0]
	v_pk_mul_f32 v[128:129], v[114:115], v[230:231] op_sel:[1,1] op_sel_hi:[1,0]
	v_pk_mul_f32 v[132:133], v[122:123], v[236:237] op_sel:[1,1] op_sel_hi:[1,0]
	v_pk_fma_f32 v[208:209], v[74:75], v[232:233], v[126:127] op_sel_hi:[0,1,1] neg_lo:[0,0,1]
	v_pk_fma_f32 v[210:211], v[118:119], v[238:239], v[130:131] op_sel_hi:[0,1,1] neg_lo:[0,0,1]
	v_pk_mul_f32 v[126:127], v[112:113], v[234:235] op_sel:[1,1] op_sel_hi:[1,0]
	v_pk_mul_f32 v[130:131], v[120:121], v[242:243] op_sel:[1,1] op_sel_hi:[1,0]
	v_pk_fma_f32 v[200:201], v[114:115], v[230:231], v[128:129] op_sel_hi:[0,1,1] neg_lo:[0,0,1]
	v_pk_fma_f32 v[202:203], v[122:123], v[236:237], v[132:133] op_sel_hi:[0,1,1] neg_lo:[0,0,1]
	v_pk_fma_f32 v[252:253], v[112:113], v[234:235], v[126:127] op_sel_hi:[0,1,1] neg_lo:[0,0,1]
	v_pk_fma_f32 v[254:255], v[120:121], v[242:243], v[130:131] op_sel_hi:[0,1,1] neg_lo:[0,0,1]
	v_pk_add_f32 v[74:75], v[188:189], v[192:193]
	v_pk_add_f32 v[118:119], v[196:197], v[200:201]
	v_pk_add_f32 v[114:115], v[190:191], v[194:195]
	v_pk_add_f32 v[122:123], v[198:199], v[202:203]
	v_pk_add_f32 v[112:113], v[188:189], v[192:193] neg_lo:[0,1] neg_hi:[0,1]
	v_pk_add_f32 v[120:121], v[196:197], v[200:201] neg_lo:[0,1] neg_hi:[0,1]
	v_pk_add_f32 v[116:117], v[190:191], v[194:195] neg_lo:[0,1] neg_hi:[0,1]
	v_pk_add_f32 v[124:125], v[198:199], v[202:203] neg_lo:[0,1] neg_hi:[0,1]
	v_pk_add_f32 v[188:189], v[74:75], v[114:115]
	v_pk_add_f32 v[196:197], v[118:119], v[122:123]
	v_pk_add_f32 v[74:75], v[74:75], v[114:115] neg_lo:[0,1] neg_hi:[0,1]
	v_pk_add_f32 v[118:119], v[118:119], v[122:123] neg_lo:[0,1] neg_hi:[0,1]
	v_pk_add_f32 v[114:115], v[112:113], v[116:117] op_sel:[0,1] op_sel_hi:[1,0] neg_hi:[0,1]
	v_pk_add_f32 v[122:123], v[120:121], v[124:125] op_sel:[0,1] op_sel_hi:[1,0] neg_hi:[0,1]
	v_pk_add_f32 v[112:113], v[112:113], v[116:117] op_sel:[0,1] op_sel_hi:[1,0] neg_lo:[0,1]
	v_pk_add_f32 v[120:121], v[120:121], v[124:125] op_sel:[0,1] op_sel_hi:[1,0] neg_lo:[0,1]
	v_pk_mul_f32 v[126:127], v[74:75], v[246:247] op_sel:[1,1] op_sel_hi:[1,0]
	v_pk_mul_f32 v[130:131], v[118:119], v[246:247] op_sel:[1,1] op_sel_hi:[1,0]
	v_pk_mul_f32 v[128:129], v[114:115], v[244:245] op_sel:[1,1] op_sel_hi:[1,0]
	v_pk_mul_f32 v[132:133], v[122:123], v[244:245] op_sel:[1,1] op_sel_hi:[1,0]
	v_pk_fma_f32 v[192:193], v[74:75], v[246:247], v[126:127] op_sel_hi:[0,1,1] neg_lo:[0,0,1]
	v_pk_fma_f32 v[200:201], v[118:119], v[246:247], v[130:131] op_sel_hi:[0,1,1] neg_lo:[0,0,1]
	v_pk_mul_f32 v[126:127], v[112:113], v[248:249] op_sel:[1,1] op_sel_hi:[1,0]
	v_pk_mul_f32 v[130:131], v[120:121], v[248:249] op_sel:[1,1] op_sel_hi:[1,0]
	v_pk_fma_f32 v[190:191], v[114:115], v[244:245], v[128:129] op_sel_hi:[0,1,1] neg_lo:[0,0,1]
	v_pk_fma_f32 v[198:199], v[122:123], v[244:245], v[132:133] op_sel_hi:[0,1,1] neg_lo:[0,0,1]
	v_pk_fma_f32 v[194:195], v[112:113], v[248:249], v[126:127] op_sel_hi:[0,1,1] neg_lo:[0,0,1]
	v_pk_fma_f32 v[202:203], v[120:121], v[248:249], v[130:131] op_sel_hi:[0,1,1] neg_lo:[0,0,1]
	v_pk_add_f32 v[74:75], v[204:205], v[208:209]
	v_pk_add_f32 v[118:119], v[212:213], v[252:253]
	v_pk_add_f32 v[114:115], v[206:207], v[210:211]
	v_pk_add_f32 v[122:123], v[214:215], v[254:255]
	v_pk_add_f32 v[112:113], v[204:205], v[208:209] neg_lo:[0,1] neg_hi:[0,1]
	v_pk_add_f32 v[120:121], v[212:213], v[252:253] neg_lo:[0,1] neg_hi:[0,1]
	v_pk_add_f32 v[116:117], v[206:207], v[210:211] neg_lo:[0,1] neg_hi:[0,1]
	v_pk_add_f32 v[124:125], v[214:215], v[254:255] neg_lo:[0,1] neg_hi:[0,1]
	v_pk_add_f32 v[204:205], v[74:75], v[114:115]
	v_pk_add_f32 v[212:213], v[118:119], v[122:123]
	v_pk_add_f32 v[74:75], v[74:75], v[114:115] neg_lo:[0,1] neg_hi:[0,1]
	v_pk_add_f32 v[118:119], v[118:119], v[122:123] neg_lo:[0,1] neg_hi:[0,1]
	v_pk_add_f32 v[114:115], v[112:113], v[116:117] op_sel:[0,1] op_sel_hi:[1,0] neg_hi:[0,1]
	v_pk_add_f32 v[122:123], v[120:121], v[124:125] op_sel:[0,1] op_sel_hi:[1,0] neg_hi:[0,1]
	v_pk_add_f32 v[112:113], v[112:113], v[116:117] op_sel:[0,1] op_sel_hi:[1,0] neg_lo:[0,1]
	v_pk_add_f32 v[120:121], v[120:121], v[124:125] op_sel:[0,1] op_sel_hi:[1,0] neg_lo:[0,1]
	v_pk_mul_f32 v[126:127], v[74:75], v[246:247] op_sel:[1,1] op_sel_hi:[1,0]
	v_pk_mul_f32 v[130:131], v[118:119], v[246:247] op_sel:[1,1] op_sel_hi:[1,0]
	v_pk_mul_f32 v[128:129], v[114:115], v[244:245] op_sel:[1,1] op_sel_hi:[1,0]
	v_pk_mul_f32 v[132:133], v[122:123], v[244:245] op_sel:[1,1] op_sel_hi:[1,0]
	v_pk_fma_f32 v[208:209], v[74:75], v[246:247], v[126:127] op_sel_hi:[0,1,1] neg_lo:[0,0,1]
	v_pk_fma_f32 v[252:253], v[118:119], v[246:247], v[130:131] op_sel_hi:[0,1,1] neg_lo:[0,0,1]
	v_pk_mul_f32 v[126:127], v[112:113], v[248:249] op_sel:[1,1] op_sel_hi:[1,0]
	v_pk_mul_f32 v[130:131], v[120:121], v[248:249] op_sel:[1,1] op_sel_hi:[1,0]
	v_pk_fma_f32 v[206:207], v[114:115], v[244:245], v[128:129] op_sel_hi:[0,1,1] neg_lo:[0,0,1]
	v_pk_fma_f32 v[214:215], v[122:123], v[244:245], v[132:133] op_sel_hi:[0,1,1] neg_lo:[0,0,1]
	v_pk_fma_f32 v[210:211], v[112:113], v[248:249], v[126:127] op_sel_hi:[0,1,1] neg_lo:[0,0,1]
	v_pk_fma_f32 v[254:255], v[120:121], v[248:249], v[130:131] op_sel_hi:[0,1,1] neg_lo:[0,0,1]
	s_nop 0
	ds_write2st64_b64 v137, v[188:189], v[190:191] offset1:4
	ds_write2st64_b64 v137, v[192:193], v[194:195] offset0:8 offset1:12
	ds_write2st64_b64 v137, v[196:197], v[198:199] offset0:16 offset1:20
	ds_write2st64_b64 v137, v[200:201], v[202:203] offset0:24 offset1:28
	ds_write2st64_b64 v137, v[204:205], v[206:207] offset0:32 offset1:36
	ds_write2st64_b64 v137, v[208:209], v[210:211] offset0:40 offset1:44
	ds_write2st64_b64 v137, v[212:213], v[214:215] offset0:48 offset1:52
	ds_write2st64_b64 v137, v[252:253], v[254:255] offset0:56 offset1:60
	s_mov_b64 s[14:15], exec

; DI float2 twid(float r) { return float2{__builtin_amdgcn_cosf(r), -__builtin_amdgcn_sinf(r)}; }
; DI void bfly_fwd(float2 a0, float2 a1, float2 a2, float2 a3, float r, float2& o0, float2& o1, float2& o2, float2& o3) {
;   float2 t0 = {a0.x + a2.x, a0.y + a2.y}, t1 = {a0.x - a2.x, a0.y - a2.y}, t2 = {a1.x + a3.x, a1.y + a3.y}, t3 = {a1.x - a3.x, a1.y - a3.y};
;   float2 b0 = {t0.x + t2.x, t0.y + t2.y}, b2 = {t0.x - t2.x, t0.y - t2.y}, b1 = {t1.x + t3.y, t1.y - t3.x}, b3 = {t1.x - t3.y, t1.y + t3.x};
;   float2 w1 = twid(r), w2 = cmul(w1, w1), w3 = cmul(w2, w1);
;   o0 = b0; o1 = cmul(b1, w1); o2 = cmul(b2, w2); o3 = cmul(b3, w3);
; }
;   const int lq2 = lq1 - 2, Q1 = 1 << lq1, Q2 = 1 << lq2; const float invM1 = 1.f / (float)(4 << lq1), invM2 = 1.f / (float)(4 << lq2);
;   for (int gg = tid; gg < NBT * (N / 16); gg += NTHR) { const int g = gg & (N / 16 - 1); float2* z = z0 + (gg / (N / 16)) * N; const int jp = g & (Q2 - 1), base = ((g >> lq2) << (lq2 + 4)) + jp; float2 x[4][4];
; #pragma unroll
;     for (int q1 = 0; q1 < 4; ++q1)
; #pragma unroll
;       for (int q2 = 0; q2 < 4; ++q2) x[q1][q2] = z[base + q1 * Q1 + q2 * Q2];
; #pragma unroll
;     for (int q2 = 0; q2 < 4; ++q2) bfly_fwd(x[0][q2], x[1][q2], x[2][q2], x[3][q2], (float)(jp + q2 * Q2) * invM1, x[0][q2], x[1][q2], x[2][q2], x[3][q2]);
.LBB0_1635:
	v_ashrrev_i32_e32 v216, 31, v69
	v_lshrrev_b32_e32 v216, 22, v216
	v_add_lshl_u32 v216, v69, v216, 7
	v_and_b32_e32 v216, 0xfffe0000, v216
	v_and_b32_e32 v217, 0x3f00, v68
	v_add_u32_e32 v216, 16, v216
	v_lshlrev_b32_e32 v217, 3, v217
	v_lshlrev_b32_e32 v148, 3, v83
	v_add3_u32 v251, v216, v217, v148
	ds_read2_b64 v[84:87], v251 offset1:16
	ds_read2_b64 v[88:91], v251 offset0:32 offset1:48
	ds_read2_b64 v[92:95], v251 offset0:64 offset1:80
	ds_read2_b64 v[96:99], v251 offset0:96 offset1:112
	ds_read2_b64 v[100:103], v251 offset0:128 offset1:144
	ds_read2_b64 v[104:107], v251 offset0:160 offset1:176
	ds_read2_b64 v[108:111], v251 offset0:192 offset1:208
	ds_read2_b64 v[112:115], v251 offset0:224 offset1:240
	v_add_u32_e32 v68, 0x2000, v68
	v_add_u32_e32 v70, 0x200, v69
	v_mov_b32_e32 v69, v70
	v_ashrrev_i32_e32 v138, 31, v69
	v_lshrrev_b32_e32 v138, 22, v138
	v_add_lshl_u32 v138, v69, v138, 7
	v_and_b32_e32 v138, 0xfffe0000, v138
	v_and_b32_e32 v139, 0x3f00, v68
	v_add_u32_e32 v138, 16, v138
	v_lshlrev_b32_e32 v139, 3, v139
	v_lshlrev_b32_e32 v140, 3, v83
	v_add3_u32 v141, v138, v139, v140
	ds_read2_b64 v[188:191], v141 offset1:16
	ds_read2_b64 v[192:195], v141 offset0:32 offset1:48
	ds_read2_b64 v[196:199], v141 offset0:64 offset1:80
	ds_read2_b64 v[200:203], v141 offset0:96 offset1:112
	ds_read2_b64 v[204:207], v141 offset0:128 offset1:144
	ds_read2_b64 v[208:211], v141 offset0:160 offset1:176
	ds_read2_b64 v[212:215], v141 offset0:192 offset1:208
	ds_read2_b64 v[252:255], v141 offset0:224 offset1:240
	v_add_u32_e32 v68, 0x2000, v68
	v_add_u32_e32 v70, 0x200, v69
	v_mov_b32_e32 v69, v70
	v_and_b32_e32 v241, 0xf, v69
	v_cvt_f32_u32_e32 v250, v241
	v_mul_f32_e32 v250, 0x3b800000, v250
	v_cos_f32_e32 v218, v250
	v_sin_f32_e32 v219, v250
	s_nop 1
	v_xor_b32_e32 v219, 0x80000000, v219
	s_nop 0
	v_pk_mul_f32 v[130:131], v[218:219], v[218:219] op_sel:[1,1] op_sel_hi:[1,0]
	s_nop 0
	v_pk_fma_f32 v[220:221], v[218:219], v[218:219], v[130:131] op_sel_hi:[0,1,1] neg_lo:[0,0,1]
	s_nop 0
	v_pk_mul_f32 v[130:131], v[220:221], v[218:219] op_sel:[1,1] op_sel_hi:[1,0]
	s_nop 0
	v_pk_fma_f32 v[222:223], v[220:221], v[218:219], v[130:131] op_sel_hi:[0,1,1] neg_lo:[0,0,1]
	v_pk_mul_f32 v[130:131], v[220:221], v[220:221] op_sel:[1,1] op_sel_hi:[1,0]
	s_nop 0
	v_pk_fma_f32 v[244:245], v[220:221], v[220:221], v[130:131] op_sel_hi:[0,1,1] neg_lo:[0,0,1]
	s_nop 0
	v_mul_f32_e32 v241, 0x3ec3ef15, v219
	v_mul_f32_e32 v250, 0xbec3ef15, v218
	v_fmamk_f32 v224, v218, 0x3f6c835e, v241
	v_fmamk_f32 v225, v219, 0x3f6c835e, v250
	v_mul_f32_e32 v241, 0x3f3504f3, v219
	v_mul_f32_e32 v250, 0xbf3504f3, v218
	v_fmamk_f32 v230, v218, 0x3f3504f3, v241
	v_fmamk_f32 v231, v219, 0x3f3504f3, v250
	v_mul_f32_e32 v241, 0x3f6c835e, v219
	v_mul_f32_e32 v250, 0xbf6c835e, v218
	v_fmamk_f32 v236, v218, 0x3ec3ef15, v241
	v_fmamk_f32 v237, v219, 0x3ec3ef15, v250
	v_mul_f32_e32 v241, 0x3f3504f3, v221
	v_mul_f32_e32 v250, 0xbf3504f3, v220
	v_fmamk_f32 v226, v220, 0x3f3504f3, v241
	v_fmamk_f32 v227, v221, 0x3f3504f3, v250
	v_mul_f32_e32 v241, 0x3f800000, v221
	v_mul_f32_e32 v250, 0xbf800000, v220
	v_fmamk_f32 v232, v220, 0x00000000, v241
	v_fmamk_f32 v233, v221, 0x00000000, v250
	v_mul_f32_e32 v241, 0x3f3504f3, v221
	v_mul_f32_e32 v250, 0xbf3504f3, v220
	v_fmamk_f32 v238, v220, 0xbf3504f3, v241
	v_fmamk_f32 v239, v221, 0xbf3504f3, v250
	v_mul_f32_e32 v241, 0x3f6c835e, v223
	v_mul_f32_e32 v250, 0xbf6c835e, v222
	v_fmamk_f32 v228, v222, 0x3ec3ef15, v241
	v_fmamk_f32 v229, v223, 0x3ec3ef15, v250
	v_mul_f32_e32 v241, 0x3f3504f3, v223
	v_mul_f32_e32 v250, 0xbf3504f3, v222
	v_fmamk_f32 v234, v222, 0xbf3504f3, v241
	v_fmamk_f32 v235, v223, 0xbf3504f3, v250
	v_mul_f32_e32 v241, 0xbec3ef15, v223
	v_mul_f32_e32 v250, 0x3ec3ef15, v222
	v_fmamk_f32 v242, v222, 0xbf6c835e, v241
	v_fmamk_f32 v243, v223, 0xbf6c835e, v250
	v_pk_mul_f32 v[130:131], v[244:245], v[244:245] op_sel:[1,1] op_sel_hi:[1,0]
	s_nop 0
	v_pk_fma_f32 v[246:247], v[244:245], v[244:245], v[130:131] op_sel_hi:[0,1,1] neg_lo:[0,0,1]
	s_nop 0
	v_pk_mul_f32 v[130:131], v[246:247], v[244:245] op_sel:[1,1] op_sel_hi:[1,0]
	s_nop 0
	v_pk_fma_f32 v[248:249], v[246:247], v[244:245], v[130:131] op_sel_hi:[0,1,1] neg_lo:[0,0,1]
	s_nop 0
	s_waitcnt lgkmcnt(8)
; DI float2 twid(float r) { return float2{__builtin_amdgcn_cosf(r), -__builtin_amdgcn_sinf(r)}; }
; DI void bfly_fwd(float2 a0, float2 a1, float2 a2, float2 a3, float r, float2& o0, float2& o1, float2& o2, float2& o3) {
;   float2 t0 = {a0.x + a2.x, a0.y + a2.y}, t1 = {a0.x - a2.x, a0.y - a2.y}, t2 = {a1.x + a3.x, a1.y + a3.y}, t3 = {a1.x - a3.x, a1.y - a3.y};
;   float2 b0 = {t0.x + t2.x, t0.y + t2.y}, b2 = {t0.x - t2.x, t0.y - t2.y}, b1 = {t1.x + t3.y, t1.y - t3.x}, b3 = {t1.x - t3.y, t1.y + t3.x};
;   float2 w1 = twid(r), w2 = cmul(w1, w1), w3 = cmul(w2, w1);
;   o0 = b0; o1 = cmul(b1, w1); o2 = cmul(b2, w2); o3 = cmul(b3, w3);
; }
;     ...
;     for (int q2 = 0; q2 < 4; ++q2) bfly_fwd(x[0][q2], x[1][q2], x[2][q2], x[3][q2], (float)(jp + q2 * Q2) * invM1, x[0][q2], x[1][q2], x[2][q2], x[3][q2]);
; #pragma unroll
;     for (int q1 = 0; q1 < 4; ++q1) bfly_fwd(x[q1][0], x[q1][1], x[q1][2], x[q1][3], (float)jp * invM2, x[q1][0], x[q1][1], x[q1][2], x[q1][3]);
	v_pk_add_f32 v[74:75], v[84:85], v[100:101]
	v_pk_add_f32 v[122:123], v[86:87], v[102:103]
	v_pk_add_f32 v[118:119], v[92:93], v[108:109]
	v_pk_add_f32 v[126:127], v[94:95], v[110:111]
	v_pk_add_f32 v[116:117], v[84:85], v[100:101] neg_lo:[0,1] neg_hi:[0,1]
	v_pk_add_f32 v[124:125], v[86:87], v[102:103] neg_lo:[0,1] neg_hi:[0,1]
	v_pk_add_f32 v[120:121], v[92:93], v[108:109] neg_lo:[0,1] neg_hi:[0,1]
	v_pk_add_f32 v[128:129], v[94:95], v[110:111] neg_lo:[0,1] neg_hi:[0,1]
	v_pk_add_f32 v[84:85], v[74:75], v[118:119]
	v_pk_add_f32 v[86:87], v[122:123], v[126:127]
	v_pk_add_f32 v[74:75], v[74:75], v[118:119] neg_lo:[0,1] neg_hi:[0,1]
	v_pk_add_f32 v[122:123], v[122:123], v[126:127] neg_lo:[0,1] neg_hi:[0,1]
	v_pk_add_f32 v[118:119], v[116:117], v[120:121] op_sel:[0,1] op_sel_hi:[1,0] neg_hi:[0,1]
	v_pk_add_f32 v[126:127], v[124:125], v[128:129] op_sel:[0,1] op_sel_hi:[1,0] neg_hi:[0,1]
	v_pk_add_f32 v[116:117], v[116:117], v[120:121] op_sel:[0,1] op_sel_hi:[1,0] neg_lo:[0,1]
	v_pk_add_f32 v[124:125], v[124:125], v[128:129] op_sel:[0,1] op_sel_hi:[1,0] neg_lo:[0,1]
	v_pk_mul_f32 v[130:131], v[74:75], v[220:221] op_sel:[1,1] op_sel_hi:[1,0]
	v_pk_mul_f32 v[134:135], v[122:123], v[226:227] op_sel:[1,1] op_sel_hi:[1,0]
	v_pk_mul_f32 v[132:133], v[118:119], v[218:219] op_sel:[1,1] op_sel_hi:[1,0]
	v_pk_mul_f32 v[136:137], v[126:127], v[224:225] op_sel:[1,1] op_sel_hi:[1,0]
	v_pk_fma_f32 v[100:101], v[74:75], v[220:221], v[130:131] op_sel_hi:[0,1,1] neg_lo:[0,0,1]
	v_pk_fma_f32 v[102:103], v[122:123], v[226:227], v[134:135] op_sel_hi:[0,1,1] neg_lo:[0,0,1]
	v_pk_mul_f32 v[130:131], v[116:117], v[222:223] op_sel:[1,1] op_sel_hi:[1,0]
	v_pk_mul_f32 v[134:135], v[124:125], v[228:229] op_sel:[1,1] op_sel_hi:[1,0]
	v_pk_fma_f32 v[92:93], v[118:119], v[218:219], v[132:133] op_sel_hi:[0,1,1] neg_lo:[0,0,1]
	v_pk_fma_f32 v[94:95], v[126:127], v[224:225], v[136:137] op_sel_hi:[0,1,1] neg_lo:[0,0,1]
	v_pk_fma_f32 v[108:109], v[116:117], v[222:223], v[130:131] op_sel_hi:[0,1,1] neg_lo:[0,0,1]
	v_pk_fma_f32 v[110:111], v[124:125], v[228:229], v[134:135] op_sel_hi:[0,1,1] neg_lo:[0,0,1]
	v_pk_add_f32 v[74:75], v[88:89], v[104:105]
	v_pk_add_f32 v[122:123], v[90:91], v[106:107]
	v_pk_add_f32 v[118:119], v[96:97], v[112:113]
	v_pk_add_f32 v[126:127], v[98:99], v[114:115]
	v_pk_add_f32 v[116:117], v[88:89], v[104:105] neg_lo:[0,1] neg_hi:[0,1]
	v_pk_add_f32 v[124:125], v[90:91], v[106:107] neg_lo:[0,1] neg_hi:[0,1]
	v_pk_add_f32 v[120:121], v[96:97], v[112:113] neg_lo:[0,1] neg_hi:[0,1]
	v_pk_add_f32 v[128:129], v[98:99], v[114:115] neg_lo:[0,1] neg_hi:[0,1]
	v_pk_add_f32 v[88:89], v[74:75], v[118:119]
	v_pk_add_f32 v[90:91], v[122:123], v[126:127]
	v_pk_add_f32 v[74:75], v[74:75], v[118:119] neg_lo:[0,1] neg_hi:[0,1]
	v_pk_add_f32 v[122:123], v[122:123], v[126:127] neg_lo:[0,1] neg_hi:[0,1]
	v_pk_add_f32 v[118:119], v[116:117], v[120:121] op_sel:[0,1] op_sel_hi:[1,0] neg_hi:[0,1]
	v_pk_add_f32 v[126:127], v[124:125], v[128:129] op_sel:[0,1] op_sel_hi:[1,0] neg_hi:[0,1]
	v_pk_add_f32 v[116:117], v[116:117], v[120:121] op_sel:[0,1] op_sel_hi:[1,0] neg_lo:[0,1]
	v_pk_add_f32 v[124:125], v[124:125], v[128:129] op_sel:[0,1] op_sel_hi:[1,0] neg_lo:[0,1]
	v_pk_mul_f32 v[130:131], v[74:75], v[232:233] op_sel:[1,1] op_sel_hi:[1,0]
	v_pk_mul_f32 v[134:135], v[122:123], v[238:239] op_sel:[1,1] op_sel_hi:[1,0]
	v_pk_mul_f32 v[132:133], v[118:119], v[230:231] op_sel:[1,1] op_sel_hi:[1,0]
	v_pk_mul_f32 v[136:137], v[126:127], v[236:237] op_sel:[1,1] op_sel_hi:[1,0]
	v_pk_fma_f32 v[104:105], v[74:75], v[232:233], v[130:131] op_sel_hi:[0,1,1] neg_lo:[0,0,1]
	v_pk_fma_f32 v[106:107], v[122:123], v[238:239], v[134:135] op_sel_hi:[0,1,1] neg_lo:[0,0,1]
	v_pk_mul_f32 v[130:131], v[116:117], v[234:235] op_sel:[1,1] op_sel_hi:[1,0]
	v_pk_mul_f32 v[134:135], v[124:125], v[242:243] op_sel:[1,1] op_sel_hi:[1,0]
	v_pk_fma_f32 v[96:97], v[118:119], v[230:231], v[132:133] op_sel_hi:[0,1,1] neg_lo:[0,0,1]
	v_pk_fma_f32 v[98:99], v[126:127], v[236:237], v[136:137] op_sel_hi:[0,1,1] neg_lo:[0,0,1]
	v_pk_fma_f32 v[112:113], v[116:117], v[234:235], v[130:131] op_sel_hi:[0,1,1] neg_lo:[0,0,1]
	v_pk_fma_f32 v[114:115], v[124:125], v[242:243], v[134:135] op_sel_hi:[0,1,1] neg_lo:[0,0,1]
	v_pk_add_f32 v[74:75], v[84:85], v[88:89]
	v_pk_add_f32 v[122:123], v[92:93], v[96:97]
	v_pk_add_f32 v[118:119], v[86:87], v[90:91]
	v_pk_add_f32 v[126:127], v[94:95], v[98:99]
	v_pk_add_f32 v[116:117], v[84:85], v[88:89] neg_lo:[0,1] neg_hi:[0,1]
	v_pk_add_f32 v[124:125], v[92:93], v[96:97] neg_lo:[0,1] neg_hi:[0,1]
	v_pk_add_f32 v[120:121], v[86:87], v[90:91] neg_lo:[0,1] neg_hi:[0,1]
	v_pk_add_f32 v[128:129], v[94:95], v[98:99] neg_lo:[0,1] neg_hi:[0,1]
	v_pk_add_f32 v[84:85], v[74:75], v[118:119]
	v_pk_add_f32 v[92:93], v[122:123], v[126:127]
	v_pk_add_f32 v[74:75], v[74:75], v[118:119] neg_lo:[0,1] neg_hi:[0,1]
	v_pk_add_f32 v[122:123], v[122:123], v[126:127] neg_lo:[0,1] neg_hi:[0,1]
	v_pk_add_f32 v[118:119], v[116:117], v[120:121] op_sel:[0,1] op_sel_hi:[1,0] neg_hi:[0,1]
	v_pk_add_f32 v[126:127], v[124:125], v[128:129] op_sel:[0,1] op_sel_hi:[1,0] neg_hi:[0,1]
	v_pk_add_f32 v[116:117], v[116:117], v[120:121] op_sel:[0,1] op_sel_hi:[1,0] neg_lo:[0,1]
	v_pk_add_f32 v[124:125], v[124:125], v[128:129] op_sel:[0,1] op_sel_hi:[1,0] neg_lo:[0,1]
	v_pk_mul_f32 v[130:131], v[74:75], v[246:247] op_sel:[1,1] op_sel_hi:[1,0]
	v_pk_mul_f32 v[134:135], v[122:123], v[246:247] op_sel:[1,1] op_sel_hi:[1,0]
	v_pk_mul_f32 v[132:133], v[118:119], v[244:245] op_sel:[1,1] op_sel_hi:[1,0]
	v_pk_mul_f32 v[136:137], v[126:127], v[244:245] op_sel:[1,1] op_sel_hi:[1,0]
	v_pk_fma_f32 v[88:89], v[74:75], v[246:247], v[130:131] op_sel_hi:[0,1,1] neg_lo:[0,0,1]
; DI float2 twid(float r) { return float2{__builtin_amdgcn_cosf(r), -__builtin_amdgcn_sinf(r)}; }
; DI void bfly_fwd(float2 a0, float2 a1, float2 a2, float2 a3, float r, float2& o0, float2& o1, float2& o2, float2& o3) {
;   float2 t0 = {a0.x + a2.x, a0.y + a2.y}, t1 = {a0.x - a2.x, a0.y - a2.y}, t2 = {a1.x + a3.x, a1.y + a3.y}, t3 = {a1.x - a3.x, a1.y - a3.y};
;   float2 b0 = {t0.x + t2.x, t0.y + t2.y}, b2 = {t0.x - t2.x, t0.y - t2.y}, b1 = {t1.x + t3.y, t1.y - t3.x}, b3 = {t1.x - t3.y, t1.y + t3.x};
;   float2 w1 = twid(r), w2 = cmul(w1, w1), w3 = cmul(w2, w1);
;   o0 = b0; o1 = cmul(b1, w1); o2 = cmul(b2, w2); o3 = cmul(b3, w3);
; }
;   const int lq2 = lq1 - 2, Q1 = 1 << lq1, Q2 = 1 << lq2; const float invM1 = 1.f / (float)(4 << lq1), invM2 = 1.f / (float)(4 << lq2);
;   for (int gg = tid; gg < NBT * (N / 16); gg += NTHR) { const int g = gg & (N / 16 - 1); float2* z = z0 + (gg / (N / 16)) * N; const int jp = g & (Q2 - 1), base = ((g >> lq2) << (lq2 + 4)) + jp; float2 x[4][4];
; #pragma unroll
;     for (int q1 = 0; q1 < 4; ++q1)
; #pragma unroll
;       for (int q2 = 0; q2 < 4; ++q2) x[q1][q2] = z[base + q1 * Q1 + q2 * Q2];
; #pragma unroll
;     for (int q2 = 0; q2 < 4; ++q2) bfly_fwd(x[0][q2], x[1][q2], x[2][q2], x[3][q2], (float)(jp + q2 * Q2) * invM1, x[0][q2], x[1][q2], x[2][q2], x[3][q2]);
; #pragma unroll
;     for (int q1 = 0; q1 < 4; ++q1) bfly_fwd(x[q1][0], x[q1][1], x[q1][2], x[q1][3], (float)jp * invM2, x[q1][0], x[q1][1], x[q1][2], x[q1][3]);
; #pragma unroll
;     for (int q1 = 0; q1 < 4; ++q1)
; #pragma unroll
;       for (int q2 = 0; q2 < 4; ++q2) z[base + q1 * Q1 + q2 * Q2] = x[q1][q2]; }
;   __syncthreads();
; }
	v_pk_fma_f32 v[96:97], v[122:123], v[246:247], v[134:135] op_sel_hi:[0,1,1] neg_lo:[0,0,1]
	v_pk_mul_f32 v[130:131], v[116:117], v[248:249] op_sel:[1,1] op_sel_hi:[1,0]
	v_pk_mul_f32 v[134:135], v[124:125], v[248:249] op_sel:[1,1] op_sel_hi:[1,0]
	v_pk_fma_f32 v[86:87], v[118:119], v[244:245], v[132:133] op_sel_hi:[0,1,1] neg_lo:[0,0,1]
	v_pk_fma_f32 v[94:95], v[126:127], v[244:245], v[136:137] op_sel_hi:[0,1,1] neg_lo:[0,0,1]
	v_pk_fma_f32 v[90:91], v[116:117], v[248:249], v[130:131] op_sel_hi:[0,1,1] neg_lo:[0,0,1]
	v_pk_fma_f32 v[98:99], v[124:125], v[248:249], v[134:135] op_sel_hi:[0,1,1] neg_lo:[0,0,1]
	v_pk_add_f32 v[74:75], v[100:101], v[104:105]
	v_pk_add_f32 v[122:123], v[108:109], v[112:113]
	v_pk_add_f32 v[118:119], v[102:103], v[106:107]
	v_pk_add_f32 v[126:127], v[110:111], v[114:115]
	v_pk_add_f32 v[116:117], v[100:101], v[104:105] neg_lo:[0,1] neg_hi:[0,1]
	v_pk_add_f32 v[124:125], v[108:109], v[112:113] neg_lo:[0,1] neg_hi:[0,1]
	v_pk_add_f32 v[120:121], v[102:103], v[106:107] neg_lo:[0,1] neg_hi:[0,1]
	v_pk_add_f32 v[128:129], v[110:111], v[114:115] neg_lo:[0,1] neg_hi:[0,1]
	v_pk_add_f32 v[100:101], v[74:75], v[118:119]
	v_pk_add_f32 v[108:109], v[122:123], v[126:127]
	v_pk_add_f32 v[74:75], v[74:75], v[118:119] neg_lo:[0,1] neg_hi:[0,1]
	v_pk_add_f32 v[122:123], v[122:123], v[126:127] neg_lo:[0,1] neg_hi:[0,1]
	v_pk_add_f32 v[118:119], v[116:117], v[120:121] op_sel:[0,1] op_sel_hi:[1,0] neg_hi:[0,1]
	v_pk_add_f32 v[126:127], v[124:125], v[128:129] op_sel:[0,1] op_sel_hi:[1,0] neg_hi:[0,1]
	v_pk_add_f32 v[116:117], v[116:117], v[120:121] op_sel:[0,1] op_sel_hi:[1,0] neg_lo:[0,1]
	v_pk_add_f32 v[124:125], v[124:125], v[128:129] op_sel:[0,1] op_sel_hi:[1,0] neg_lo:[0,1]
	v_pk_mul_f32 v[130:131], v[74:75], v[246:247] op_sel:[1,1] op_sel_hi:[1,0]
	v_pk_mul_f32 v[134:135], v[122:123], v[246:247] op_sel:[1,1] op_sel_hi:[1,0]
	v_pk_mul_f32 v[132:133], v[118:119], v[244:245] op_sel:[1,1] op_sel_hi:[1,0]
	v_pk_mul_f32 v[136:137], v[126:127], v[244:245] op_sel:[1,1] op_sel_hi:[1,0]
	v_pk_fma_f32 v[104:105], v[74:75], v[246:247], v[130:131] op_sel_hi:[0,1,1] neg_lo:[0,0,1]
	v_pk_fma_f32 v[112:113], v[122:123], v[246:247], v[134:135] op_sel_hi:[0,1,1] neg_lo:[0,0,1]
	v_pk_mul_f32 v[130:131], v[116:117], v[248:249] op_sel:[1,1] op_sel_hi:[1,0]
	v_pk_mul_f32 v[134:135], v[124:125], v[248:249] op_sel:[1,1] op_sel_hi:[1,0]
	v_pk_fma_f32 v[102:103], v[118:119], v[244:245], v[132:133] op_sel_hi:[0,1,1] neg_lo:[0,0,1]
	v_pk_fma_f32 v[110:111], v[126:127], v[244:245], v[136:137] op_sel_hi:[0,1,1] neg_lo:[0,0,1]
	v_pk_fma_f32 v[106:107], v[116:117], v[248:249], v[130:131] op_sel_hi:[0,1,1] neg_lo:[0,0,1]
	v_pk_fma_f32 v[114:115], v[124:125], v[248:249], v[134:135] op_sel_hi:[0,1,1] neg_lo:[0,0,1]
	s_nop 0
	ds_write2_b64 v251, v[84:85], v[86:87] offset1:16
	ds_write2_b64 v251, v[88:89], v[90:91] offset0:32 offset1:48
	ds_write2_b64 v251, v[92:93], v[94:95] offset0:64 offset1:80
	ds_write2_b64 v251, v[96:97], v[98:99] offset0:96 offset1:112
	ds_write2_b64 v251, v[100:101], v[102:103] offset0:128 offset1:144
	ds_write2_b64 v251, v[104:105], v[106:107] offset0:160 offset1:176
	ds_write2_b64 v251, v[108:109], v[110:111] offset0:192 offset1:208
	ds_write2_b64 v251, v[112:113], v[114:115] offset0:224 offset1:240
	s_waitcnt lgkmcnt(8)
	v_pk_add_f32 v[74:75], v[188:189], v[204:205]
	v_pk_add_f32 v[122:123], v[190:191], v[206:207]
	v_pk_add_f32 v[118:119], v[196:197], v[212:213]
	v_pk_add_f32 v[126:127], v[198:199], v[214:215]
	v_pk_add_f32 v[116:117], v[188:189], v[204:205] neg_lo:[0,1] neg_hi:[0,1]
	v_pk_add_f32 v[124:125], v[190:191], v[206:207] neg_lo:[0,1] neg_hi:[0,1]
	v_pk_add_f32 v[120:121], v[196:197], v[212:213] neg_lo:[0,1] neg_hi:[0,1]
	v_pk_add_f32 v[128:129], v[198:199], v[214:215] neg_lo:[0,1] neg_hi:[0,1]
	v_pk_add_f32 v[188:189], v[74:75], v[118:119]
	v_pk_add_f32 v[190:191], v[122:123], v[126:127]
	v_pk_add_f32 v[74:75], v[74:75], v[118:119] neg_lo:[0,1] neg_hi:[0,1]
	v_pk_add_f32 v[122:123], v[122:123], v[126:127] neg_lo:[0,1] neg_hi:[0,1]
	v_pk_add_f32 v[118:119], v[116:117], v[120:121] op_sel:[0,1] op_sel_hi:[1,0] neg_hi:[0,1]
	v_pk_add_f32 v[126:127], v[124:125], v[128:129] op_sel:[0,1] op_sel_hi:[1,0] neg_hi:[0,1]
	v_pk_add_f32 v[116:117], v[116:117], v[120:121] op_sel:[0,1] op_sel_hi:[1,0] neg_lo:[0,1]
	v_pk_add_f32 v[124:125], v[124:125], v[128:129] op_sel:[0,1] op_sel_hi:[1,0] neg_lo:[0,1]
	v_pk_mul_f32 v[130:131], v[74:75], v[220:221] op_sel:[1,1] op_sel_hi:[1,0]
	v_pk_mul_f32 v[134:135], v[122:123], v[226:227] op_sel:[1,1] op_sel_hi:[1,0]
	v_pk_mul_f32 v[132:133], v[118:119], v[218:219] op_sel:[1,1] op_sel_hi:[1,0]
	v_pk_mul_f32 v[136:137], v[126:127], v[224:225] op_sel:[1,1] op_sel_hi:[1,0]
	v_pk_fma_f32 v[204:205], v[74:75], v[220:221], v[130:131] op_sel_hi:[0,1,1] neg_lo:[0,0,1]
	v_pk_fma_f32 v[206:207], v[122:123], v[226:227], v[134:135] op_sel_hi:[0,1,1] neg_lo:[0,0,1]
	v_pk_mul_f32 v[130:131], v[116:117], v[222:223] op_sel:[1,1] op_sel_hi:[1,0]
	v_pk_mul_f32 v[134:135], v[124:125], v[228:229] op_sel:[1,1] op_sel_hi:[1,0]
	v_pk_fma_f32 v[196:197], v[118:119], v[218:219], v[132:133] op_sel_hi:[0,1,1] neg_lo:[0,0,1]
	v_pk_fma_f32 v[198:199], v[126:127], v[224:225], v[136:137] op_sel_hi:[0,1,1] neg_lo:[0,0,1]
	v_pk_fma_f32 v[212:213], v[116:117], v[222:223], v[130:131] op_sel_hi:[0,1,1] neg_lo:[0,0,1]
	v_pk_fma_f32 v[214:215], v[124:125], v[228:229], v[134:135] op_sel_hi:[0,1,1] neg_lo:[0,0,1]
	v_pk_add_f32 v[74:75], v[192:193], v[208:209]
	v_pk_add_f32 v[122:123], v[194:195], v[210:211]
	v_pk_add_f32 v[118:119], v[200:201], v[252:253]
	v_pk_add_f32 v[126:127], v[202:203], v[254:255]
; DI float2 twid(float r) { return float2{__builtin_amdgcn_cosf(r), -__builtin_amdgcn_sinf(r)}; }
; DI void bfly_fwd(float2 a0, float2 a1, float2 a2, float2 a3, float r, float2& o0, float2& o1, float2& o2, float2& o3) {
;   float2 t0 = {a0.x + a2.x, a0.y + a2.y}, t1 = {a0.x - a2.x, a0.y - a2.y}, t2 = {a1.x + a3.x, a1.y + a3.y}, t3 = {a1.x - a3.x, a1.y - a3.y};
;   float2 b0 = {t0.x + t2.x, t0.y + t2.y}, b2 = {t0.x - t2.x, t0.y - t2.y}, b1 = {t1.x + t3.y, t1.y - t3.x}, b3 = {t1.x - t3.y, t1.y + t3.x};
;   float2 w1 = twid(r), w2 = cmul(w1, w1), w3 = cmul(w2, w1);
;   o0 = b0; o1 = cmul(b1, w1); o2 = cmul(b2, w2); o3 = cmul(b3, w3);
; }
;   const int lq2 = lq1 - 2, Q1 = 1 << lq1, Q2 = 1 << lq2; const float invM1 = 1.f / (float)(4 << lq1), invM2 = 1.f / (float)(4 << lq2);
;   for (int gg = tid; gg < NBT * (N / 16); gg += NTHR) { const int g = gg & (N / 16 - 1); float2* z = z0 + (gg / (N / 16)) * N; const int jp = g & (Q2 - 1), base = ((g >> lq2) << (lq2 + 4)) + jp; float2 x[4][4];
; #pragma unroll
;     for (int q1 = 0; q1 < 4; ++q1)
; #pragma unroll
;       for (int q2 = 0; q2 < 4; ++q2) x[q1][q2] = z[base + q1 * Q1 + q2 * Q2];
; #pragma unroll
;     for (int q2 = 0; q2 < 4; ++q2) bfly_fwd(x[0][q2], x[1][q2], x[2][q2], x[3][q2], (float)(jp + q2 * Q2) * invM1, x[0][q2], x[1][q2], x[2][q2], x[3][q2]);
; #pragma unroll
;     for (int q1 = 0; q1 < 4; ++q1) bfly_fwd(x[q1][0], x[q1][1], x[q1][2], x[q1][3], (float)jp * invM2, x[q1][0], x[q1][1], x[q1][2], x[q1][3]);
; #pragma unroll
;     for (int q1 = 0; q1 < 4; ++q1)
; #pragma unroll
;       for (int q2 = 0; q2 < 4; ++q2) z[base + q1 * Q1 + q2 * Q2] = x[q1][q2]; }
;   __syncthreads();
; }
	v_pk_add_f32 v[116:117], v[192:193], v[208:209] neg_lo:[0,1] neg_hi:[0,1]
	v_pk_add_f32 v[124:125], v[194:195], v[210:211] neg_lo:[0,1] neg_hi:[0,1]
	v_pk_add_f32 v[120:121], v[200:201], v[252:253] neg_lo:[0,1] neg_hi:[0,1]
	v_pk_add_f32 v[128:129], v[202:203], v[254:255] neg_lo:[0,1] neg_hi:[0,1]
	v_pk_add_f32 v[192:193], v[74:75], v[118:119]
	v_pk_add_f32 v[194:195], v[122:123], v[126:127]
	v_pk_add_f32 v[74:75], v[74:75], v[118:119] neg_lo:[0,1] neg_hi:[0,1]
	v_pk_add_f32 v[122:123], v[122:123], v[126:127] neg_lo:[0,1] neg_hi:[0,1]
	v_pk_add_f32 v[118:119], v[116:117], v[120:121] op_sel:[0,1] op_sel_hi:[1,0] neg_hi:[0,1]
	v_pk_add_f32 v[126:127], v[124:125], v[128:129] op_sel:[0,1] op_sel_hi:[1,0] neg_hi:[0,1]
	v_pk_add_f32 v[116:117], v[116:117], v[120:121] op_sel:[0,1] op_sel_hi:[1,0] neg_lo:[0,1]
	v_pk_add_f32 v[124:125], v[124:125], v[128:129] op_sel:[0,1] op_sel_hi:[1,0] neg_lo:[0,1]
	v_pk_mul_f32 v[130:131], v[74:75], v[232:233] op_sel:[1,1] op_sel_hi:[1,0]
	v_pk_mul_f32 v[134:135], v[122:123], v[238:239] op_sel:[1,1] op_sel_hi:[1,0]
	v_pk_mul_f32 v[132:133], v[118:119], v[230:231] op_sel:[1,1] op_sel_hi:[1,0]
	v_pk_mul_f32 v[136:137], v[126:127], v[236:237] op_sel:[1,1] op_sel_hi:[1,0]
	v_pk_fma_f32 v[208:209], v[74:75], v[232:233], v[130:131] op_sel_hi:[0,1,1] neg_lo:[0,0,1]
	v_pk_fma_f32 v[210:211], v[122:123], v[238:239], v[134:135] op_sel_hi:[0,1,1] neg_lo:[0,0,1]
	v_pk_mul_f32 v[130:131], v[116:117], v[234:235] op_sel:[1,1] op_sel_hi:[1,0]
	v_pk_mul_f32 v[134:135], v[124:125], v[242:243] op_sel:[1,1] op_sel_hi:[1,0]
	v_pk_fma_f32 v[200:201], v[118:119], v[230:231], v[132:133] op_sel_hi:[0,1,1] neg_lo:[0,0,1]
	v_pk_fma_f32 v[202:203], v[126:127], v[236:237], v[136:137] op_sel_hi:[0,1,1] neg_lo:[0,0,1]
	v_pk_fma_f32 v[252:253], v[116:117], v[234:235], v[130:131] op_sel_hi:[0,1,1] neg_lo:[0,0,1]
	v_pk_fma_f32 v[254:255], v[124:125], v[242:243], v[134:135] op_sel_hi:[0,1,1] neg_lo:[0,0,1]
	v_pk_add_f32 v[74:75], v[188:189], v[192:193]
	v_pk_add_f32 v[122:123], v[196:197], v[200:201]
	v_pk_add_f32 v[118:119], v[190:191], v[194:195]
	v_pk_add_f32 v[126:127], v[198:199], v[202:203]
	v_pk_add_f32 v[116:117], v[188:189], v[192:193] neg_lo:[0,1] neg_hi:[0,1]
	v_pk_add_f32 v[124:125], v[196:197], v[200:201] neg_lo:[0,1] neg_hi:[0,1]
	v_pk_add_f32 v[120:121], v[190:191], v[194:195] neg_lo:[0,1] neg_hi:[0,1]
	v_pk_add_f32 v[128:129], v[198:199], v[202:203] neg_lo:[0,1] neg_hi:[0,1]
	v_pk_add_f32 v[188:189], v[74:75], v[118:119]
	v_pk_add_f32 v[196:197], v[122:123], v[126:127]
	v_pk_add_f32 v[74:75], v[74:75], v[118:119] neg_lo:[0,1] neg_hi:[0,1]
	v_pk_add_f32 v[122:123], v[122:123], v[126:127] neg_lo:[0,1] neg_hi:[0,1]
	v_pk_add_f32 v[118:119], v[116:117], v[120:121] op_sel:[0,1] op_sel_hi:[1,0] neg_hi:[0,1]
	v_pk_add_f32 v[126:127], v[124:125], v[128:129] op_sel:[0,1] op_sel_hi:[1,0] neg_hi:[0,1]
	v_pk_add_f32 v[116:117], v[116:117], v[120:121] op_sel:[0,1] op_sel_hi:[1,0] neg_lo:[0,1]
	v_pk_add_f32 v[124:125], v[124:125], v[128:129] op_sel:[0,1] op_sel_hi:[1,0] neg_lo:[0,1]
	v_pk_mul_f32 v[130:131], v[74:75], v[246:247] op_sel:[1,1] op_sel_hi:[1,0]
	v_pk_mul_f32 v[134:135], v[122:123], v[246:247] op_sel:[1,1] op_sel_hi:[1,0]
	v_pk_mul_f32 v[132:133], v[118:119], v[244:245] op_sel:[1,1] op_sel_hi:[1,0]
	v_pk_mul_f32 v[136:137], v[126:127], v[244:245] op_sel:[1,1] op_sel_hi:[1,0]
	v_pk_fma_f32 v[192:193], v[74:75], v[246:247], v[130:131] op_sel_hi:[0,1,1] neg_lo:[0,0,1]
	v_pk_fma_f32 v[200:201], v[122:123], v[246:247], v[134:135] op_sel_hi:[0,1,1] neg_lo:[0,0,1]
	v_pk_mul_f32 v[130:131], v[116:117], v[248:249] op_sel:[1,1] op_sel_hi:[1,0]
	v_pk_mul_f32 v[134:135], v[124:125], v[248:249] op_sel:[1,1] op_sel_hi:[1,0]
	v_pk_fma_f32 v[190:191], v[118:119], v[244:245], v[132:133] op_sel_hi:[0,1,1] neg_lo:[0,0,1]
	v_pk_fma_f32 v[198:199], v[126:127], v[244:245], v[136:137] op_sel_hi:[0,1,1] neg_lo:[0,0,1]
	v_pk_fma_f32 v[194:195], v[116:117], v[248:249], v[130:131] op_sel_hi:[0,1,1] neg_lo:[0,0,1]
	v_pk_fma_f32 v[202:203], v[124:125], v[248:249], v[134:135] op_sel_hi:[0,1,1] neg_lo:[0,0,1]
	v_pk_add_f32 v[74:75], v[204:205], v[208:209]
	v_pk_add_f32 v[122:123], v[212:213], v[252:253]
	v_pk_add_f32 v[118:119], v[206:207], v[210:211]
	v_pk_add_f32 v[126:127], v[214:215], v[254:255]
	v_pk_add_f32 v[116:117], v[204:205], v[208:209] neg_lo:[0,1] neg_hi:[0,1]
	v_pk_add_f32 v[124:125], v[212:213], v[252:253] neg_lo:[0,1] neg_hi:[0,1]
	v_pk_add_f32 v[120:121], v[206:207], v[210:211] neg_lo:[0,1] neg_hi:[0,1]
	v_pk_add_f32 v[128:129], v[214:215], v[254:255] neg_lo:[0,1] neg_hi:[0,1]
	v_pk_add_f32 v[204:205], v[74:75], v[118:119]
	v_pk_add_f32 v[212:213], v[122:123], v[126:127]
	v_pk_add_f32 v[74:75], v[74:75], v[118:119] neg_lo:[0,1] neg_hi:[0,1]
	v_pk_add_f32 v[122:123], v[122:123], v[126:127] neg_lo:[0,1] neg_hi:[0,1]
	v_pk_add_f32 v[118:119], v[116:117], v[120:121] op_sel:[0,1] op_sel_hi:[1,0] neg_hi:[0,1]
	v_pk_add_f32 v[126:127], v[124:125], v[128:129] op_sel:[0,1] op_sel_hi:[1,0] neg_hi:[0,1]
	v_pk_add_f32 v[116:117], v[116:117], v[120:121] op_sel:[0,1] op_sel_hi:[1,0] neg_lo:[0,1]
	v_pk_add_f32 v[124:125], v[124:125], v[128:129] op_sel:[0,1] op_sel_hi:[1,0] neg_lo:[0,1]
	v_pk_mul_f32 v[130:131], v[74:75], v[246:247] op_sel:[1,1] op_sel_hi:[1,0]
	v_pk_mul_f32 v[134:135], v[122:123], v[246:247] op_sel:[1,1] op_sel_hi:[1,0]
	v_pk_mul_f32 v[132:133], v[118:119], v[244:245] op_sel:[1,1] op_sel_hi:[1,0]
	v_pk_mul_f32 v[136:137], v[126:127], v[244:245] op_sel:[1,1] op_sel_hi:[1,0]
	v_pk_fma_f32 v[208:209], v[74:75], v[246:247], v[130:131] op_sel_hi:[0,1,1] neg_lo:[0,0,1]
	v_pk_fma_f32 v[252:253], v[122:123], v[246:247], v[134:135] op_sel_hi:[0,1,1] neg_lo:[0,0,1]
	v_pk_mul_f32 v[130:131], v[116:117], v[248:249] op_sel:[1,1] op_sel_hi:[1,0]
	v_pk_mul_f32 v[134:135], v[124:125], v[248:249] op_sel:[1,1] op_sel_hi:[1,0]
	v_pk_fma_f32 v[206:207], v[118:119], v[244:245], v[132:133] op_sel_hi:[0,1,1] neg_lo:[0,0,1]
	v_pk_fma_f32 v[214:215], v[126:127], v[244:245], v[136:137] op_sel_hi:[0,1,1] neg_lo:[0,0,1]
	v_pk_fma_f32 v[210:211], v[116:117], v[248:249], v[130:131] op_sel_hi:[0,1,1] neg_lo:[0,0,1]
	v_pk_fma_f32 v[254:255], v[124:125], v[248:249], v[134:135] op_sel_hi:[0,1,1] neg_lo:[0,0,1]
	s_nop 0
	ds_write2_b64 v141, v[188:189], v[190:191] offset1:16
	ds_write2_b64 v141, v[192:193], v[194:195] offset0:32 offset1:48
	ds_write2_b64 v141, v[196:197], v[198:199] offset0:64 offset1:80
	ds_write2_b64 v141, v[200:201], v[202:203] offset0:96 offset1:112
	ds_write2_b64 v141, v[204:205], v[206:207] offset0:128 offset1:144
	ds_write2_b64 v141, v[208:209], v[210:211] offset0:160 offset1:176
	ds_write2_b64 v141, v[212:213], v[214:215] offset0:192 offset1:208
	ds_write2_b64 v141, v[252:253], v[254:255] offset0:224 offset1:240
	s_mov_b64 s[14:15], exec

; DI float2 twid(float r) { return float2{__builtin_amdgcn_cosf(r), -__builtin_amdgcn_sinf(r)}; }
; DI void bfly_inv(float2 s0, float2 s1, float2 s2, float2 s3, float r, float2& o0, float2& o1, float2& o2, float2& o3) {
;   float2 w1 = twid(r), w2 = cmul(w1, w1), w3 = cmul(w2, w1);
;   float2 c0 = s0, c1 = cmulc(s1, w1), c2 = cmulc(s2, w2), c3 = cmulc(s3, w3);
;   float2 t0 = {c0.x + c2.x, c0.y + c2.y}, t1 = {c0.x - c2.x, c0.y - c2.y}, t2 = {c1.x + c3.x, c1.y + c3.y}, t3 = {c1.x - c3.x, c1.y - c3.y};
;   o0 = float2{t0.x + t2.x, t0.y + t2.y}; o2 = float2{t0.x - t2.x, t0.y - t2.y}; o1 = float2{t1.x - t3.y, t1.y + t3.x}; o3 = float2{t1.x + t3.y, t1.y - t3.x};
; }
;   const int lq1 = lq2 + 2, Q1 = 1 << lq1, Q2 = 1 << lq2; const float invM1 = 1.f / (float)(4 << lq1), invM2 = 1.f / (float)(4 << lq2);
;   for (int gg = tid; gg < NBT * (N / 16); gg += NTHR) { const int g = gg & (N / 16 - 1); float2* z = z0 + (gg / (N / 16)) * N; const int jp = g & (Q2 - 1), base = ((g >> lq2) << (lq2 + 4)) + jp; float2 x[4][4];
; #pragma unroll
;     for (int q1 = 0; q1 < 4; ++q1)
; #pragma unroll
;       for (int q2 = 0; q2 < 4; ++q2) x[q1][q2] = z[base + q1 * Q1 + q2 * Q2];
; #pragma unroll
;     for (int q1 = 0; q1 < 4; ++q1) bfly_inv(x[q1][0], x[q1][1], x[q1][2], x[q1][3], (float)jp * invM2, x[q1][0], x[q1][1], x[q1][2], x[q1][3]);
.LBB0_1650:
	v_ashrrev_i32_e32 v216, 31, v84
	v_lshrrev_b32_e32 v216, 22, v216
	v_add_lshl_u32 v216, v84, v216, 7
	v_and_b32_e32 v216, 0xfffe0000, v216
	v_and_b32_e32 v217, 0x3f00, v62
	v_add_u32_e32 v216, 16, v216
	v_lshlrev_b32_e32 v217, 3, v217
	v_lshlrev_b32_e32 v148, 3, v83
	v_add3_u32 v148, v216, v217, v148
	ds_read2_b64 v[86:89], v148 offset0:32 offset1:48
	ds_read2_b64 v[90:93], v148 offset1:16
	ds_read2_b64 v[94:97], v148 offset0:64 offset1:80
	ds_read2_b64 v[98:101], v148 offset0:96 offset1:112
	ds_read2_b64 v[102:105], v148 offset0:128 offset1:144
	ds_read2_b64 v[106:109], v148 offset0:160 offset1:176
	ds_read2_b64 v[110:113], v148 offset0:192 offset1:208
	ds_read2_b64 v[114:117], v148 offset0:224 offset1:240
	v_add_u32_e32 v15, 0x200, v84
	v_add_u32_e32 v62, 0x2000, v62
	v_mov_b32_e32 v84, v15
	v_ashrrev_i32_e32 v251, 31, v84
	v_lshrrev_b32_e32 v251, 22, v251
	v_add_lshl_u32 v251, v84, v251, 7
	v_and_b32_e32 v251, 0xfffe0000, v251
	v_and_b32_e32 v142, 0x3f00, v62
	v_add_u32_e32 v251, 16, v251
	v_lshlrev_b32_e32 v142, 3, v142
	v_lshlrev_b32_e32 v143, 3, v83
	v_add3_u32 v143, v251, v142, v143
	ds_read2_b64 v[188:191], v143 offset0:32 offset1:48
	ds_read2_b64 v[192:195], v143 offset1:16
	ds_read2_b64 v[196:199], v143 offset0:64 offset1:80
	ds_read2_b64 v[200:203], v143 offset0:96 offset1:112
	ds_read2_b64 v[204:207], v143 offset0:128 offset1:144
	ds_read2_b64 v[208:211], v143 offset0:160 offset1:176
	ds_read2_b64 v[212:215], v143 offset0:192 offset1:208
	ds_read2_b64 v[252:255], v143 offset0:224 offset1:240
	v_add_u32_e32 v15, 0x200, v84
	v_add_u32_e32 v62, 0x2000, v62
	v_mov_b32_e32 v84, v15
	v_and_b32_e32 v241, 0xf, v84
	v_cvt_f32_u32_e32 v250, v241
	v_mul_f32_e32 v250, 0x3b800000, v250
	v_cos_f32_e32 v218, v250
	v_sin_f32_e32 v219, v250
	s_nop 1
	s_nop 0
	v_pk_mul_f32 v[134:135], v[218:219], v[218:219] op_sel:[1,1] op_sel_hi:[1,0]
	s_nop 0
	v_pk_fma_f32 v[220:221], v[218:219], v[218:219], v[134:135] op_sel_hi:[0,1,1] neg_lo:[0,0,1]
	s_nop 0
	v_pk_mul_f32 v[134:135], v[220:221], v[218:219] op_sel:[1,1] op_sel_hi:[1,0]
	s_nop 0
	v_pk_fma_f32 v[222:223], v[220:221], v[218:219], v[134:135] op_sel_hi:[0,1,1] neg_lo:[0,0,1]
	v_pk_mul_f32 v[134:135], v[220:221], v[220:221] op_sel:[1,1] op_sel_hi:[1,0]
	s_nop 0
	v_pk_fma_f32 v[244:245], v[220:221], v[220:221], v[134:135] op_sel_hi:[0,1,1] neg_lo:[0,0,1]
	s_nop 0
	v_mul_f32_e32 v241, 0xbec3ef15, v219
	v_mul_f32_e32 v250, 0x3ec3ef15, v218
	v_fmamk_f32 v224, v218, 0x3f6c835e, v241
	v_fmamk_f32 v225, v219, 0x3f6c835e, v250
	v_mul_f32_e32 v241, 0xbf3504f3, v219
	v_mul_f32_e32 v250, 0x3f3504f3, v218
	v_fmamk_f32 v230, v218, 0x3f3504f3, v241
	v_fmamk_f32 v231, v219, 0x3f3504f3, v250
	v_mul_f32_e32 v241, 0xbf6c835e, v219
	v_mul_f32_e32 v250, 0x3f6c835e, v218
	v_fmamk_f32 v236, v218, 0x3ec3ef15, v241
	v_fmamk_f32 v237, v219, 0x3ec3ef15, v250
	v_mul_f32_e32 v241, 0xbf3504f3, v221
	v_mul_f32_e32 v250, 0x3f3504f3, v220
	v_fmamk_f32 v226, v220, 0x3f3504f3, v241
	v_fmamk_f32 v227, v221, 0x3f3504f3, v250
	v_mul_f32_e32 v241, 0xbf800000, v221
	v_mul_f32_e32 v250, 0x3f800000, v220
	v_fmamk_f32 v232, v220, 0x00000000, v241
	v_fmamk_f32 v233, v221, 0x00000000, v250
	v_mul_f32_e32 v241, 0xbf3504f3, v221
	v_mul_f32_e32 v250, 0x3f3504f3, v220
	v_fmamk_f32 v238, v220, 0xbf3504f3, v241
	v_fmamk_f32 v239, v221, 0xbf3504f3, v250
	v_mul_f32_e32 v241, 0xbf6c835e, v223
	v_mul_f32_e32 v250, 0x3f6c835e, v222
	v_fmamk_f32 v228, v222, 0x3ec3ef15, v241
	v_fmamk_f32 v229, v223, 0x3ec3ef15, v250
	v_mul_f32_e32 v241, 0xbf3504f3, v223
	v_mul_f32_e32 v250, 0x3f3504f3, v222
	v_fmamk_f32 v234, v222, 0xbf3504f3, v241
	v_fmamk_f32 v235, v223, 0xbf3504f3, v250
	v_mul_f32_e32 v241, 0x3ec3ef15, v223
	v_mul_f32_e32 v250, 0xbec3ef15, v222
	v_fmamk_f32 v242, v222, 0xbf6c835e, v241
	v_fmamk_f32 v243, v223, 0xbf6c835e, v250
	v_pk_mul_f32 v[134:135], v[244:245], v[244:245] op_sel:[1,1] op_sel_hi:[1,0]
	s_nop 0
	v_pk_fma_f32 v[246:247], v[244:245], v[244:245], v[134:135] op_sel_hi:[0,1,1] neg_lo:[0,0,1]
	s_nop 0
	v_pk_mul_f32 v[134:135], v[246:247], v[244:245] op_sel:[1,1] op_sel_hi:[1,0]
	s_nop 0
	v_pk_fma_f32 v[248:249], v[246:247], v[244:245], v[134:135] op_sel_hi:[0,1,1] neg_lo:[0,0,1]
	s_nop 0
	s_waitcnt lgkmcnt(8)
	v_pk_mul_f32 v[134:135], v[92:93], v[244:245] op_sel:[1,1] op_sel_hi:[1,0]
	v_pk_mul_f32 v[138:139], v[96:97], v[244:245] op_sel:[1,1] op_sel_hi:[1,0]
	v_pk_mul_f32 v[136:137], v[86:87], v[246:247] op_sel:[1,1] op_sel_hi:[1,0]
	v_pk_mul_f32 v[140:141], v[98:99], v[246:247] op_sel:[1,1] op_sel_hi:[1,0]
	v_pk_fma_f32 v[92:93], v[92:93], v[244:245], v[134:135] op_sel_hi:[0,1,1] neg_lo:[0,0,1]
	v_pk_fma_f32 v[96:97], v[96:97], v[244:245], v[138:139] op_sel_hi:[0,1,1] neg_lo:[0,0,1]
	v_pk_mul_f32 v[134:135], v[88:89], v[248:249] op_sel:[1,1] op_sel_hi:[1,0]
	v_pk_mul_f32 v[138:139], v[100:101], v[248:249] op_sel:[1,1] op_sel_hi:[1,0]
	v_pk_fma_f32 v[86:87], v[86:87], v[246:247], v[136:137] op_sel_hi:[0,1,1] neg_lo:[0,0,1]
	v_pk_fma_f32 v[98:99], v[98:99], v[246:247], v[140:141] op_sel_hi:[0,1,1] neg_lo:[0,0,1]
	v_pk_fma_f32 v[88:89], v[88:89], v[248:249], v[134:135] op_sel_hi:[0,1,1] neg_lo:[0,0,1]
	v_pk_fma_f32 v[100:101], v[100:101], v[248:249], v[138:139] op_sel_hi:[0,1,1] neg_lo:[0,0,1]
	v_pk_add_f32 v[118:119], v[90:91], v[86:87]
	v_pk_add_f32 v[126:127], v[94:95], v[98:99]
	v_pk_add_f32 v[122:123], v[92:93], v[88:89]
	v_pk_add_f32 v[130:131], v[96:97], v[100:101]
	v_pk_add_f32 v[120:121], v[90:91], v[86:87] neg_lo:[0,1] neg_hi:[0,1]
	v_pk_add_f32 v[128:129], v[94:95], v[98:99] neg_lo:[0,1] neg_hi:[0,1]
	v_pk_add_f32 v[124:125], v[92:93], v[88:89] neg_lo:[0,1] neg_hi:[0,1]
	v_pk_add_f32 v[132:133], v[96:97], v[100:101] neg_lo:[0,1] neg_hi:[0,1]
; DI float2 twid(float r) { return float2{__builtin_amdgcn_cosf(r), -__builtin_amdgcn_sinf(r)}; }
; DI void bfly_inv(float2 s0, float2 s1, float2 s2, float2 s3, float r, float2& o0, float2& o1, float2& o2, float2& o3) {
;   float2 w1 = twid(r), w2 = cmul(w1, w1), w3 = cmul(w2, w1);
;   float2 c0 = s0, c1 = cmulc(s1, w1), c2 = cmulc(s2, w2), c3 = cmulc(s3, w3);
;   float2 t0 = {c0.x + c2.x, c0.y + c2.y}, t1 = {c0.x - c2.x, c0.y - c2.y}, t2 = {c1.x + c3.x, c1.y + c3.y}, t3 = {c1.x - c3.x, c1.y - c3.y};
;   o0 = float2{t0.x + t2.x, t0.y + t2.y}; o2 = float2{t0.x - t2.x, t0.y - t2.y}; o1 = float2{t1.x - t3.y, t1.y + t3.x}; o3 = float2{t1.x + t3.y, t1.y - t3.x};
; }
;     ...
;     for (int q1 = 0; q1 < 4; ++q1) bfly_inv(x[q1][0], x[q1][1], x[q1][2], x[q1][3], (float)jp * invM2, x[q1][0], x[q1][1], x[q1][2], x[q1][3]);
; #pragma unroll
;     for (int q2 = 0; q2 < 4; ++q2) bfly_inv(x[0][q2], x[1][q2], x[2][q2], x[3][q2], (float)(jp + q2 * Q2) * invM1, x[0][q2], x[1][q2], x[2][q2], x[3][q2]);
	v_pk_add_f32 v[90:91], v[118:119], v[122:123]
	v_pk_add_f32 v[94:95], v[126:127], v[130:131]
	v_pk_add_f32 v[86:87], v[118:119], v[122:123] neg_lo:[0,1] neg_hi:[0,1]
	v_pk_add_f32 v[98:99], v[126:127], v[130:131] neg_lo:[0,1] neg_hi:[0,1]
	v_pk_add_f32 v[92:93], v[120:121], v[124:125] op_sel:[0,1] op_sel_hi:[1,0] neg_lo:[0,1]
	v_pk_add_f32 v[96:97], v[128:129], v[132:133] op_sel:[0,1] op_sel_hi:[1,0] neg_lo:[0,1]
	v_pk_add_f32 v[88:89], v[120:121], v[124:125] op_sel:[0,1] op_sel_hi:[1,0] neg_hi:[0,1]
	v_pk_add_f32 v[100:101], v[128:129], v[132:133] op_sel:[0,1] op_sel_hi:[1,0] neg_hi:[0,1]
	v_pk_mul_f32 v[134:135], v[104:105], v[244:245] op_sel:[1,1] op_sel_hi:[1,0]
	v_pk_mul_f32 v[138:139], v[112:113], v[244:245] op_sel:[1,1] op_sel_hi:[1,0]
	v_pk_mul_f32 v[136:137], v[106:107], v[246:247] op_sel:[1,1] op_sel_hi:[1,0]
	v_pk_mul_f32 v[140:141], v[114:115], v[246:247] op_sel:[1,1] op_sel_hi:[1,0]
	v_pk_fma_f32 v[104:105], v[104:105], v[244:245], v[134:135] op_sel_hi:[0,1,1] neg_lo:[0,0,1]
	v_pk_fma_f32 v[112:113], v[112:113], v[244:245], v[138:139] op_sel_hi:[0,1,1] neg_lo:[0,0,1]
	v_pk_mul_f32 v[134:135], v[108:109], v[248:249] op_sel:[1,1] op_sel_hi:[1,0]
	v_pk_mul_f32 v[138:139], v[116:117], v[248:249] op_sel:[1,1] op_sel_hi:[1,0]
	v_pk_fma_f32 v[106:107], v[106:107], v[246:247], v[136:137] op_sel_hi:[0,1,1] neg_lo:[0,0,1]
	v_pk_fma_f32 v[114:115], v[114:115], v[246:247], v[140:141] op_sel_hi:[0,1,1] neg_lo:[0,0,1]
	v_pk_fma_f32 v[108:109], v[108:109], v[248:249], v[134:135] op_sel_hi:[0,1,1] neg_lo:[0,0,1]
	v_pk_fma_f32 v[116:117], v[116:117], v[248:249], v[138:139] op_sel_hi:[0,1,1] neg_lo:[0,0,1]
	v_pk_add_f32 v[118:119], v[102:103], v[106:107]
	v_pk_add_f32 v[126:127], v[110:111], v[114:115]
	v_pk_add_f32 v[122:123], v[104:105], v[108:109]
	v_pk_add_f32 v[130:131], v[112:113], v[116:117]
	v_pk_add_f32 v[120:121], v[102:103], v[106:107] neg_lo:[0,1] neg_hi:[0,1]
	v_pk_add_f32 v[128:129], v[110:111], v[114:115] neg_lo:[0,1] neg_hi:[0,1]
	v_pk_add_f32 v[124:125], v[104:105], v[108:109] neg_lo:[0,1] neg_hi:[0,1]
	v_pk_add_f32 v[132:133], v[112:113], v[116:117] neg_lo:[0,1] neg_hi:[0,1]
	v_pk_add_f32 v[102:103], v[118:119], v[122:123]
	v_pk_add_f32 v[110:111], v[126:127], v[130:131]
	v_pk_add_f32 v[106:107], v[118:119], v[122:123] neg_lo:[0,1] neg_hi:[0,1]
	v_pk_add_f32 v[114:115], v[126:127], v[130:131] neg_lo:[0,1] neg_hi:[0,1]
	v_pk_add_f32 v[104:105], v[120:121], v[124:125] op_sel:[0,1] op_sel_hi:[1,0] neg_lo:[0,1]
	v_pk_add_f32 v[112:113], v[128:129], v[132:133] op_sel:[0,1] op_sel_hi:[1,0] neg_lo:[0,1]
	v_pk_add_f32 v[108:109], v[120:121], v[124:125] op_sel:[0,1] op_sel_hi:[1,0] neg_hi:[0,1]
	v_pk_add_f32 v[116:117], v[128:129], v[132:133] op_sel:[0,1] op_sel_hi:[1,0] neg_hi:[0,1]
	v_pk_mul_f32 v[134:135], v[94:95], v[218:219] op_sel:[1,1] op_sel_hi:[1,0]
	v_pk_mul_f32 v[138:139], v[96:97], v[224:225] op_sel:[1,1] op_sel_hi:[1,0]
	v_pk_mul_f32 v[136:137], v[102:103], v[220:221] op_sel:[1,1] op_sel_hi:[1,0]
	v_pk_mul_f32 v[140:141], v[104:105], v[226:227] op_sel:[1,1] op_sel_hi:[1,0]
	v_pk_fma_f32 v[94:95], v[94:95], v[218:219], v[134:135] op_sel_hi:[0,1,1] neg_lo:[0,0,1]
	v_pk_fma_f32 v[96:97], v[96:97], v[224:225], v[138:139] op_sel_hi:[0,1,1] neg_lo:[0,0,1]
	v_pk_mul_f32 v[134:135], v[110:111], v[222:223] op_sel:[1,1] op_sel_hi:[1,0]
	v_pk_mul_f32 v[138:139], v[112:113], v[228:229] op_sel:[1,1] op_sel_hi:[1,0]
	v_pk_fma_f32 v[102:103], v[102:103], v[220:221], v[136:137] op_sel_hi:[0,1,1] neg_lo:[0,0,1]
	v_pk_fma_f32 v[104:105], v[104:105], v[226:227], v[140:141] op_sel_hi:[0,1,1] neg_lo:[0,0,1]
	v_pk_fma_f32 v[110:111], v[110:111], v[222:223], v[134:135] op_sel_hi:[0,1,1] neg_lo:[0,0,1]
	v_pk_fma_f32 v[112:113], v[112:113], v[228:229], v[138:139] op_sel_hi:[0,1,1] neg_lo:[0,0,1]
	v_pk_add_f32 v[118:119], v[90:91], v[102:103]
	v_pk_add_f32 v[126:127], v[92:93], v[104:105]
	v_pk_add_f32 v[122:123], v[94:95], v[110:111]
	v_pk_add_f32 v[130:131], v[96:97], v[112:113]
	v_pk_add_f32 v[120:121], v[90:91], v[102:103] neg_lo:[0,1] neg_hi:[0,1]
	v_pk_add_f32 v[128:129], v[92:93], v[104:105] neg_lo:[0,1] neg_hi:[0,1]
	v_pk_add_f32 v[124:125], v[94:95], v[110:111] neg_lo:[0,1] neg_hi:[0,1]
	v_pk_add_f32 v[132:133], v[96:97], v[112:113] neg_lo:[0,1] neg_hi:[0,1]
	v_pk_add_f32 v[90:91], v[118:119], v[122:123]
	v_pk_add_f32 v[92:93], v[126:127], v[130:131]
	v_pk_add_f32 v[102:103], v[118:119], v[122:123] neg_lo:[0,1] neg_hi:[0,1]
	v_pk_add_f32 v[104:105], v[126:127], v[130:131] neg_lo:[0,1] neg_hi:[0,1]
	v_pk_add_f32 v[94:95], v[120:121], v[124:125] op_sel:[0,1] op_sel_hi:[1,0] neg_lo:[0,1]
	v_pk_add_f32 v[96:97], v[128:129], v[132:133] op_sel:[0,1] op_sel_hi:[1,0] neg_lo:[0,1]
	v_pk_add_f32 v[110:111], v[120:121], v[124:125] op_sel:[0,1] op_sel_hi:[1,0] neg_hi:[0,1]
	v_pk_add_f32 v[112:113], v[128:129], v[132:133] op_sel:[0,1] op_sel_hi:[1,0] neg_hi:[0,1]
	v_pk_mul_f32 v[134:135], v[98:99], v[230:231] op_sel:[1,1] op_sel_hi:[1,0]
	v_pk_mul_f32 v[138:139], v[100:101], v[236:237] op_sel:[1,1] op_sel_hi:[1,0]
	v_pk_mul_f32 v[136:137], v[106:107], v[232:233] op_sel:[1,1] op_sel_hi:[1,0]
	v_pk_mul_f32 v[140:141], v[108:109], v[238:239] op_sel:[1,1] op_sel_hi:[1,0]
	v_pk_fma_f32 v[98:99], v[98:99], v[230:231], v[134:135] op_sel_hi:[0,1,1] neg_lo:[0,0,1]
	v_pk_fma_f32 v[100:101], v[100:101], v[236:237], v[138:139] op_sel_hi:[0,1,1] neg_lo:[0,0,1]
	v_pk_mul_f32 v[134:135], v[114:115], v[234:235] op_sel:[1,1] op_sel_hi:[1,0]
	v_pk_mul_f32 v[138:139], v[116:117], v[242:243] op_sel:[1,1] op_sel_hi:[1,0]
	v_pk_fma_f32 v[106:107], v[106:107], v[232:233], v[136:137] op_sel_hi:[0,1,1] neg_lo:[0,0,1]
	v_pk_fma_f32 v[108:109], v[108:109], v[238:239], v[140:141] op_sel_hi:[0,1,1] neg_lo:[0,0,1]
; DI float2 twid(float r) { return float2{__builtin_amdgcn_cosf(r), -__builtin_amdgcn_sinf(r)}; }
; DI void bfly_inv(float2 s0, float2 s1, float2 s2, float2 s3, float r, float2& o0, float2& o1, float2& o2, float2& o3) {
;   float2 w1 = twid(r), w2 = cmul(w1, w1), w3 = cmul(w2, w1);
;   float2 c0 = s0, c1 = cmulc(s1, w1), c2 = cmulc(s2, w2), c3 = cmulc(s3, w3);
;   float2 t0 = {c0.x + c2.x, c0.y + c2.y}, t1 = {c0.x - c2.x, c0.y - c2.y}, t2 = {c1.x + c3.x, c1.y + c3.y}, t3 = {c1.x - c3.x, c1.y - c3.y};
;   o0 = float2{t0.x + t2.x, t0.y + t2.y}; o2 = float2{t0.x - t2.x, t0.y - t2.y}; o1 = float2{t1.x - t3.y, t1.y + t3.x}; o3 = float2{t1.x + t3.y, t1.y - t3.x};
; }
;   const int lq1 = lq2 + 2, Q1 = 1 << lq1, Q2 = 1 << lq2; const float invM1 = 1.f / (float)(4 << lq1), invM2 = 1.f / (float)(4 << lq2);
;   for (int gg = tid; gg < NBT * (N / 16); gg += NTHR) { const int g = gg & (N / 16 - 1); float2* z = z0 + (gg / (N / 16)) * N; const int jp = g & (Q2 - 1), base = ((g >> lq2) << (lq2 + 4)) + jp; float2 x[4][4];
; #pragma unroll
;     for (int q1 = 0; q1 < 4; ++q1)
; #pragma unroll
;       for (int q2 = 0; q2 < 4; ++q2) x[q1][q2] = z[base + q1 * Q1 + q2 * Q2];
; #pragma unroll
;     for (int q1 = 0; q1 < 4; ++q1) bfly_inv(x[q1][0], x[q1][1], x[q1][2], x[q1][3], (float)jp * invM2, x[q1][0], x[q1][1], x[q1][2], x[q1][3]);
; #pragma unroll
;     for (int q2 = 0; q2 < 4; ++q2) bfly_inv(x[0][q2], x[1][q2], x[2][q2], x[3][q2], (float)(jp + q2 * Q2) * invM1, x[0][q2], x[1][q2], x[2][q2], x[3][q2]);
; #pragma unroll
;     for (int q1 = 0; q1 < 4; ++q1)
; #pragma unroll
;       for (int q2 = 0; q2 < 4; ++q2) z[base + q1 * Q1 + q2 * Q2] = x[q1][q2]; }
;   __syncthreads();
; }
	v_pk_fma_f32 v[114:115], v[114:115], v[234:235], v[134:135] op_sel_hi:[0,1,1] neg_lo:[0,0,1]
	v_pk_fma_f32 v[116:117], v[116:117], v[242:243], v[138:139] op_sel_hi:[0,1,1] neg_lo:[0,0,1]
	v_pk_add_f32 v[118:119], v[86:87], v[106:107]
	v_pk_add_f32 v[126:127], v[88:89], v[108:109]
	v_pk_add_f32 v[122:123], v[98:99], v[114:115]
	v_pk_add_f32 v[130:131], v[100:101], v[116:117]
	v_pk_add_f32 v[120:121], v[86:87], v[106:107] neg_lo:[0,1] neg_hi:[0,1]
	v_pk_add_f32 v[128:129], v[88:89], v[108:109] neg_lo:[0,1] neg_hi:[0,1]
	v_pk_add_f32 v[124:125], v[98:99], v[114:115] neg_lo:[0,1] neg_hi:[0,1]
	v_pk_add_f32 v[132:133], v[100:101], v[116:117] neg_lo:[0,1] neg_hi:[0,1]
	v_pk_add_f32 v[86:87], v[118:119], v[122:123]
	v_pk_add_f32 v[88:89], v[126:127], v[130:131]
	v_pk_add_f32 v[106:107], v[118:119], v[122:123] neg_lo:[0,1] neg_hi:[0,1]
	v_pk_add_f32 v[108:109], v[126:127], v[130:131] neg_lo:[0,1] neg_hi:[0,1]
	v_pk_add_f32 v[98:99], v[120:121], v[124:125] op_sel:[0,1] op_sel_hi:[1,0] neg_lo:[0,1]
	v_pk_add_f32 v[100:101], v[128:129], v[132:133] op_sel:[0,1] op_sel_hi:[1,0] neg_lo:[0,1]
	v_pk_add_f32 v[114:115], v[120:121], v[124:125] op_sel:[0,1] op_sel_hi:[1,0] neg_hi:[0,1]
	v_pk_add_f32 v[116:117], v[128:129], v[132:133] op_sel:[0,1] op_sel_hi:[1,0] neg_hi:[0,1]
	s_nop 0
	ds_write2_b64 v148, v[90:91], v[92:93] offset1:16
	ds_write2_b64 v148, v[86:87], v[88:89] offset0:32 offset1:48
	ds_write2_b64 v148, v[94:95], v[96:97] offset0:64 offset1:80
	ds_write2_b64 v148, v[98:99], v[100:101] offset0:96 offset1:112
	ds_write2_b64 v148, v[102:103], v[104:105] offset0:128 offset1:144
	ds_write2_b64 v148, v[106:107], v[108:109] offset0:160 offset1:176
	ds_write2_b64 v148, v[110:111], v[112:113] offset0:192 offset1:208
	ds_write2_b64 v148, v[114:115], v[116:117] offset0:224 offset1:240
	s_waitcnt lgkmcnt(8)
	v_pk_mul_f32 v[134:135], v[194:195], v[244:245] op_sel:[1,1] op_sel_hi:[1,0]
	v_pk_mul_f32 v[138:139], v[198:199], v[244:245] op_sel:[1,1] op_sel_hi:[1,0]
	v_pk_mul_f32 v[136:137], v[188:189], v[246:247] op_sel:[1,1] op_sel_hi:[1,0]
	v_pk_mul_f32 v[140:141], v[200:201], v[246:247] op_sel:[1,1] op_sel_hi:[1,0]
	v_pk_fma_f32 v[194:195], v[194:195], v[244:245], v[134:135] op_sel_hi:[0,1,1] neg_lo:[0,0,1]
	v_pk_fma_f32 v[198:199], v[198:199], v[244:245], v[138:139] op_sel_hi:[0,1,1] neg_lo:[0,0,1]
	v_pk_mul_f32 v[134:135], v[190:191], v[248:249] op_sel:[1,1] op_sel_hi:[1,0]
	v_pk_mul_f32 v[138:139], v[202:203], v[248:249] op_sel:[1,1] op_sel_hi:[1,0]
	v_pk_fma_f32 v[188:189], v[188:189], v[246:247], v[136:137] op_sel_hi:[0,1,1] neg_lo:[0,0,1]
	v_pk_fma_f32 v[200:201], v[200:201], v[246:247], v[140:141] op_sel_hi:[0,1,1] neg_lo:[0,0,1]
	v_pk_fma_f32 v[190:191], v[190:191], v[248:249], v[134:135] op_sel_hi:[0,1,1] neg_lo:[0,0,1]
	v_pk_fma_f32 v[202:203], v[202:203], v[248:249], v[138:139] op_sel_hi:[0,1,1] neg_lo:[0,0,1]
	v_pk_add_f32 v[118:119], v[192:193], v[188:189]
	v_pk_add_f32 v[126:127], v[196:197], v[200:201]
	v_pk_add_f32 v[122:123], v[194:195], v[190:191]
	v_pk_add_f32 v[130:131], v[198:199], v[202:203]
	v_pk_add_f32 v[120:121], v[192:193], v[188:189] neg_lo:[0,1] neg_hi:[0,1]
	v_pk_add_f32 v[128:129], v[196:197], v[200:201] neg_lo:[0,1] neg_hi:[0,1]
	v_pk_add_f32 v[124:125], v[194:195], v[190:191] neg_lo:[0,1] neg_hi:[0,1]
	v_pk_add_f32 v[132:133], v[198:199], v[202:203] neg_lo:[0,1] neg_hi:[0,1]
	v_pk_add_f32 v[192:193], v[118:119], v[122:123]
	v_pk_add_f32 v[196:197], v[126:127], v[130:131]
	v_pk_add_f32 v[188:189], v[118:119], v[122:123] neg_lo:[0,1] neg_hi:[0,1]
	v_pk_add_f32 v[200:201], v[126:127], v[130:131] neg_lo:[0,1] neg_hi:[0,1]
	v_pk_add_f32 v[194:195], v[120:121], v[124:125] op_sel:[0,1] op_sel_hi:[1,0] neg_lo:[0,1]
	v_pk_add_f32 v[198:199], v[128:129], v[132:133] op_sel:[0,1] op_sel_hi:[1,0] neg_lo:[0,1]
	v_pk_add_f32 v[190:191], v[120:121], v[124:125] op_sel:[0,1] op_sel_hi:[1,0] neg_hi:[0,1]
	v_pk_add_f32 v[202:203], v[128:129], v[132:133] op_sel:[0,1] op_sel_hi:[1,0] neg_hi:[0,1]
	v_pk_mul_f32 v[134:135], v[206:207], v[244:245] op_sel:[1,1] op_sel_hi:[1,0]
	v_pk_mul_f32 v[138:139], v[214:215], v[244:245] op_sel:[1,1] op_sel_hi:[1,0]
	v_pk_mul_f32 v[136:137], v[208:209], v[246:247] op_sel:[1,1] op_sel_hi:[1,0]
	v_pk_mul_f32 v[140:141], v[252:253], v[246:247] op_sel:[1,1] op_sel_hi:[1,0]
	v_pk_fma_f32 v[206:207], v[206:207], v[244:245], v[134:135] op_sel_hi:[0,1,1] neg_lo:[0,0,1]
	v_pk_fma_f32 v[214:215], v[214:215], v[244:245], v[138:139] op_sel_hi:[0,1,1] neg_lo:[0,0,1]
	v_pk_mul_f32 v[134:135], v[210:211], v[248:249] op_sel:[1,1] op_sel_hi:[1,0]
	v_pk_mul_f32 v[138:139], v[254:255], v[248:249] op_sel:[1,1] op_sel_hi:[1,0]
	v_pk_fma_f32 v[208:209], v[208:209], v[246:247], v[136:137] op_sel_hi:[0,1,1] neg_lo:[0,0,1]
	v_pk_fma_f32 v[252:253], v[252:253], v[246:247], v[140:141] op_sel_hi:[0,1,1] neg_lo:[0,0,1]
	v_pk_fma_f32 v[210:211], v[210:211], v[248:249], v[134:135] op_sel_hi:[0,1,1] neg_lo:[0,0,1]
	v_pk_fma_f32 v[254:255], v[254:255], v[248:249], v[138:139] op_sel_hi:[0,1,1] neg_lo:[0,0,1]
	v_pk_add_f32 v[118:119], v[204:205], v[208:209]
	v_pk_add_f32 v[126:127], v[212:213], v[252:253]
	v_pk_add_f32 v[122:123], v[206:207], v[210:211]
	v_pk_add_f32 v[130:131], v[214:215], v[254:255]
	v_pk_add_f32 v[120:121], v[204:205], v[208:209] neg_lo:[0,1] neg_hi:[0,1]
	v_pk_add_f32 v[128:129], v[212:213], v[252:253] neg_lo:[0,1] neg_hi:[0,1]
	v_pk_add_f32 v[124:125], v[206:207], v[210:211] neg_lo:[0,1] neg_hi:[0,1]
	v_pk_add_f32 v[132:133], v[214:215], v[254:255] neg_lo:[0,1] neg_hi:[0,1]
; DI float2 twid(float r) { return float2{__builtin_amdgcn_cosf(r), -__builtin_amdgcn_sinf(r)}; }
; DI void bfly_inv(float2 s0, float2 s1, float2 s2, float2 s3, float r, float2& o0, float2& o1, float2& o2, float2& o3) {
;   float2 w1 = twid(r), w2 = cmul(w1, w1), w3 = cmul(w2, w1);
;   float2 c0 = s0, c1 = cmulc(s1, w1), c2 = cmulc(s2, w2), c3 = cmulc(s3, w3);
;   float2 t0 = {c0.x + c2.x, c0.y + c2.y}, t1 = {c0.x - c2.x, c0.y - c2.y}, t2 = {c1.x + c3.x, c1.y + c3.y}, t3 = {c1.x - c3.x, c1.y - c3.y};
;   o0 = float2{t0.x + t2.x, t0.y + t2.y}; o2 = float2{t0.x - t2.x, t0.y - t2.y}; o1 = float2{t1.x - t3.y, t1.y + t3.x}; o3 = float2{t1.x + t3.y, t1.y - t3.x};
; }
;   const int lq1 = lq2 + 2, Q1 = 1 << lq1, Q2 = 1 << lq2; const float invM1 = 1.f / (float)(4 << lq1), invM2 = 1.f / (float)(4 << lq2);
;   for (int gg = tid; gg < NBT * (N / 16); gg += NTHR) { const int g = gg & (N / 16 - 1); float2* z = z0 + (gg / (N / 16)) * N; const int jp = g & (Q2 - 1), base = ((g >> lq2) << (lq2 + 4)) + jp; float2 x[4][4];
; #pragma unroll
;     for (int q1 = 0; q1 < 4; ++q1)
; #pragma unroll
;       for (int q2 = 0; q2 < 4; ++q2) x[q1][q2] = z[base + q1 * Q1 + q2 * Q2];
; #pragma unroll
;     for (int q1 = 0; q1 < 4; ++q1) bfly_inv(x[q1][0], x[q1][1], x[q1][2], x[q1][3], (float)jp * invM2, x[q1][0], x[q1][1], x[q1][2], x[q1][3]);
; #pragma unroll
;     for (int q2 = 0; q2 < 4; ++q2) bfly_inv(x[0][q2], x[1][q2], x[2][q2], x[3][q2], (float)(jp + q2 * Q2) * invM1, x[0][q2], x[1][q2], x[2][q2], x[3][q2]);
; #pragma unroll
;     for (int q1 = 0; q1 < 4; ++q1)
; #pragma unroll
;       for (int q2 = 0; q2 < 4; ++q2) z[base + q1 * Q1 + q2 * Q2] = x[q1][q2]; }
;   __syncthreads();
; }
	v_pk_add_f32 v[204:205], v[118:119], v[122:123]
	v_pk_add_f32 v[212:213], v[126:127], v[130:131]
	v_pk_add_f32 v[208:209], v[118:119], v[122:123] neg_lo:[0,1] neg_hi:[0,1]
	v_pk_add_f32 v[252:253], v[126:127], v[130:131] neg_lo:[0,1] neg_hi:[0,1]
	v_pk_add_f32 v[206:207], v[120:121], v[124:125] op_sel:[0,1] op_sel_hi:[1,0] neg_lo:[0,1]
	v_pk_add_f32 v[214:215], v[128:129], v[132:133] op_sel:[0,1] op_sel_hi:[1,0] neg_lo:[0,1]
	v_pk_add_f32 v[210:211], v[120:121], v[124:125] op_sel:[0,1] op_sel_hi:[1,0] neg_hi:[0,1]
	v_pk_add_f32 v[254:255], v[128:129], v[132:133] op_sel:[0,1] op_sel_hi:[1,0] neg_hi:[0,1]
	v_pk_mul_f32 v[134:135], v[196:197], v[218:219] op_sel:[1,1] op_sel_hi:[1,0]
	v_pk_mul_f32 v[138:139], v[198:199], v[224:225] op_sel:[1,1] op_sel_hi:[1,0]
	v_pk_mul_f32 v[136:137], v[204:205], v[220:221] op_sel:[1,1] op_sel_hi:[1,0]
	v_pk_mul_f32 v[140:141], v[206:207], v[226:227] op_sel:[1,1] op_sel_hi:[1,0]
	v_pk_fma_f32 v[196:197], v[196:197], v[218:219], v[134:135] op_sel_hi:[0,1,1] neg_lo:[0,0,1]
	v_pk_fma_f32 v[198:199], v[198:199], v[224:225], v[138:139] op_sel_hi:[0,1,1] neg_lo:[0,0,1]
	v_pk_mul_f32 v[134:135], v[212:213], v[222:223] op_sel:[1,1] op_sel_hi:[1,0]
	v_pk_mul_f32 v[138:139], v[214:215], v[228:229] op_sel:[1,1] op_sel_hi:[1,0]
	v_pk_fma_f32 v[204:205], v[204:205], v[220:221], v[136:137] op_sel_hi:[0,1,1] neg_lo:[0,0,1]
	v_pk_fma_f32 v[206:207], v[206:207], v[226:227], v[140:141] op_sel_hi:[0,1,1] neg_lo:[0,0,1]
	v_pk_fma_f32 v[212:213], v[212:213], v[222:223], v[134:135] op_sel_hi:[0,1,1] neg_lo:[0,0,1]
	v_pk_fma_f32 v[214:215], v[214:215], v[228:229], v[138:139] op_sel_hi:[0,1,1] neg_lo:[0,0,1]
	v_pk_add_f32 v[118:119], v[192:193], v[204:205]
	v_pk_add_f32 v[126:127], v[194:195], v[206:207]
	v_pk_add_f32 v[122:123], v[196:197], v[212:213]
	v_pk_add_f32 v[130:131], v[198:199], v[214:215]
	v_pk_add_f32 v[120:121], v[192:193], v[204:205] neg_lo:[0,1] neg_hi:[0,1]
	v_pk_add_f32 v[128:129], v[194:195], v[206:207] neg_lo:[0,1] neg_hi:[0,1]
	v_pk_add_f32 v[124:125], v[196:197], v[212:213] neg_lo:[0,1] neg_hi:[0,1]
	v_pk_add_f32 v[132:133], v[198:199], v[214:215] neg_lo:[0,1] neg_hi:[0,1]
	v_pk_add_f32 v[192:193], v[118:119], v[122:123]
	v_pk_add_f32 v[194:195], v[126:127], v[130:131]
	v_pk_add_f32 v[204:205], v[118:119], v[122:123] neg_lo:[0,1] neg_hi:[0,1]
	v_pk_add_f32 v[206:207], v[126:127], v[130:131] neg_lo:[0,1] neg_hi:[0,1]
	v_pk_add_f32 v[196:197], v[120:121], v[124:125] op_sel:[0,1] op_sel_hi:[1,0] neg_lo:[0,1]
	v_pk_add_f32 v[198:199], v[128:129], v[132:133] op_sel:[0,1] op_sel_hi:[1,0] neg_lo:[0,1]
	v_pk_add_f32 v[212:213], v[120:121], v[124:125] op_sel:[0,1] op_sel_hi:[1,0] neg_hi:[0,1]
	v_pk_add_f32 v[214:215], v[128:129], v[132:133] op_sel:[0,1] op_sel_hi:[1,0] neg_hi:[0,1]
	v_pk_mul_f32 v[134:135], v[200:201], v[230:231] op_sel:[1,1] op_sel_hi:[1,0]
	v_pk_mul_f32 v[138:139], v[202:203], v[236:237] op_sel:[1,1] op_sel_hi:[1,0]
	v_pk_mul_f32 v[136:137], v[208:209], v[232:233] op_sel:[1,1] op_sel_hi:[1,0]
	v_pk_mul_f32 v[140:141], v[210:211], v[238:239] op_sel:[1,1] op_sel_hi:[1,0]
	v_pk_fma_f32 v[200:201], v[200:201], v[230:231], v[134:135] op_sel_hi:[0,1,1] neg_lo:[0,0,1]
	v_pk_fma_f32 v[202:203], v[202:203], v[236:237], v[138:139] op_sel_hi:[0,1,1] neg_lo:[0,0,1]
	v_pk_mul_f32 v[134:135], v[252:253], v[234:235] op_sel:[1,1] op_sel_hi:[1,0]
	v_pk_mul_f32 v[138:139], v[254:255], v[242:243] op_sel:[1,1] op_sel_hi:[1,0]
	v_pk_fma_f32 v[208:209], v[208:209], v[232:233], v[136:137] op_sel_hi:[0,1,1] neg_lo:[0,0,1]
	v_pk_fma_f32 v[210:211], v[210:211], v[238:239], v[140:141] op_sel_hi:[0,1,1] neg_lo:[0,0,1]
	v_pk_fma_f32 v[252:253], v[252:253], v[234:235], v[134:135] op_sel_hi:[0,1,1] neg_lo:[0,0,1]
	v_pk_fma_f32 v[254:255], v[254:255], v[242:243], v[138:139] op_sel_hi:[0,1,1] neg_lo:[0,0,1]
	v_pk_add_f32 v[118:119], v[188:189], v[208:209]
	v_pk_add_f32 v[126:127], v[190:191], v[210:211]
	v_pk_add_f32 v[122:123], v[200:201], v[252:253]
	v_pk_add_f32 v[130:131], v[202:203], v[254:255]
	v_pk_add_f32 v[120:121], v[188:189], v[208:209] neg_lo:[0,1] neg_hi:[0,1]
	v_pk_add_f32 v[128:129], v[190:191], v[210:211] neg_lo:[0,1] neg_hi:[0,1]
	v_pk_add_f32 v[124:125], v[200:201], v[252:253] neg_lo:[0,1] neg_hi:[0,1]
	v_pk_add_f32 v[132:133], v[202:203], v[254:255] neg_lo:[0,1] neg_hi:[0,1]
	v_pk_add_f32 v[188:189], v[118:119], v[122:123]
	v_pk_add_f32 v[190:191], v[126:127], v[130:131]
	v_pk_add_f32 v[208:209], v[118:119], v[122:123] neg_lo:[0,1] neg_hi:[0,1]
	v_pk_add_f32 v[210:211], v[126:127], v[130:131] neg_lo:[0,1] neg_hi:[0,1]
	v_pk_add_f32 v[200:201], v[120:121], v[124:125] op_sel:[0,1] op_sel_hi:[1,0] neg_lo:[0,1]
	v_pk_add_f32 v[202:203], v[128:129], v[132:133] op_sel:[0,1] op_sel_hi:[1,0] neg_lo:[0,1]
	v_pk_add_f32 v[252:253], v[120:121], v[124:125] op_sel:[0,1] op_sel_hi:[1,0] neg_hi:[0,1]
	v_pk_add_f32 v[254:255], v[128:129], v[132:133] op_sel:[0,1] op_sel_hi:[1,0] neg_hi:[0,1]
	s_nop 0
	ds_write2_b64 v143, v[192:193], v[194:195] offset1:16
	ds_write2_b64 v143, v[188:189], v[190:191] offset0:32 offset1:48
	ds_write2_b64 v143, v[196:197], v[198:199] offset0:64 offset1:80
	ds_write2_b64 v143, v[200:201], v[202:203] offset0:96 offset1:112
	ds_write2_b64 v143, v[204:205], v[206:207] offset0:128 offset1:144
	ds_write2_b64 v143, v[208:209], v[210:211] offset0:160 offset1:176
	ds_write2_b64 v143, v[212:213], v[214:215] offset0:192 offset1:208
	ds_write2_b64 v143, v[252:253], v[254:255] offset0:224 offset1:240
	s_mov_b64 s[0:1], exec

; DI float2 twid(float r) { return float2{__builtin_amdgcn_cosf(r), -__builtin_amdgcn_sinf(r)}; }
; DI void bfly_inv(float2 s0, float2 s1, float2 s2, float2 s3, float r, float2& o0, float2& o1, float2& o2, float2& o3) {
;   float2 w1 = twid(r), w2 = cmul(w1, w1), w3 = cmul(w2, w1);
;   float2 c0 = s0, c1 = cmulc(s1, w1), c2 = cmulc(s2, w2), c3 = cmulc(s3, w3);
;   float2 t0 = {c0.x + c2.x, c0.y + c2.y}, t1 = {c0.x - c2.x, c0.y - c2.y}, t2 = {c1.x + c3.x, c1.y + c3.y}, t3 = {c1.x - c3.x, c1.y - c3.y};
;   o0 = float2{t0.x + t2.x, t0.y + t2.y}; o2 = float2{t0.x - t2.x, t0.y - t2.y}; o1 = float2{t1.x - t3.y, t1.y + t3.x}; o3 = float2{t1.x + t3.y, t1.y - t3.x};
; }
;   const int lq1 = lq2 + 2, Q1 = 1 << lq1, Q2 = 1 << lq2; const float invM1 = 1.f / (float)(4 << lq1), invM2 = 1.f / (float)(4 << lq2);
;   for (int gg = tid; gg < NBT * (N / 16); gg += NTHR) { const int g = gg & (N / 16 - 1); float2* z = z0 + (gg / (N / 16)) * N; const int jp = g & (Q2 - 1), base = ((g >> lq2) << (lq2 + 4)) + jp; float2 x[4][4];
; #pragma unroll
;     for (int q1 = 0; q1 < 4; ++q1)
; #pragma unroll
;       for (int q2 = 0; q2 < 4; ++q2) x[q1][q2] = z[base + q1 * Q1 + q2 * Q2];
; #pragma unroll
;     for (int q1 = 0; q1 < 4; ++q1) bfly_inv(x[q1][0], x[q1][1], x[q1][2], x[q1][3], (float)jp * invM2, x[q1][0], x[q1][1], x[q1][2], x[q1][3]);
.LBB0_1653:
	v_ashrrev_i32_e32 v216, 31, v62
	v_lshrrev_b32_e32 v216, 22, v216
	v_add_lshl_u32 v216, v62, v216, 7
	v_and_b32_e32 v216, 0xfffe0000, v216
	v_and_b32_e32 v217, 0x3000, v77
	v_add_u32_e32 v216, 16, v216
	v_lshlrev_b32_e32 v217, 3, v217
	v_lshlrev_b32_sdwa v148, v151, v76 dst_sel:DWORD dst_unused:UNUSED_PAD src0_sel:DWORD src1_sel:BYTE_0
	v_add3_u32 v251, v216, v217, v148
	ds_read2st64_b64 v[80:83], v251 offset0:8 offset1:12
	ds_read2st64_b64 v[84:87], v251 offset1:4
	ds_read2st64_b64 v[88:91], v251 offset0:16 offset1:20
	ds_read2st64_b64 v[92:95], v251 offset0:24 offset1:28
	ds_read2st64_b64 v[96:99], v251 offset0:32 offset1:36
	ds_read2st64_b64 v[100:103], v251 offset0:40 offset1:44
	ds_read2st64_b64 v[104:107], v251 offset0:48 offset1:52
	ds_read2st64_b64 v[108:111], v251 offset0:56 offset1:60
	v_add_u32_e32 v77, 0x2000, v77
	v_add_u32_e32 v15, 0x200, v62
	v_mov_b32_e32 v62, v15
	v_ashrrev_i32_e32 v136, 31, v62
	v_lshrrev_b32_e32 v136, 22, v136
	v_add_lshl_u32 v136, v62, v136, 7
	v_and_b32_e32 v136, 0xfffe0000, v136
	v_and_b32_e32 v137, 0x3000, v77
	v_add_u32_e32 v136, 16, v136
	v_lshlrev_b32_e32 v137, 3, v137
	v_lshlrev_b32_sdwa v138, v151, v76 dst_sel:DWORD dst_unused:UNUSED_PAD src0_sel:DWORD src1_sel:BYTE_0
	v_add3_u32 v139, v136, v137, v138
	ds_read2st64_b64 v[188:191], v139 offset0:8 offset1:12
	ds_read2st64_b64 v[192:195], v139 offset1:4
	ds_read2st64_b64 v[196:199], v139 offset0:16 offset1:20
	ds_read2st64_b64 v[200:203], v139 offset0:24 offset1:28
	ds_read2st64_b64 v[204:207], v139 offset0:32 offset1:36
	ds_read2st64_b64 v[208:211], v139 offset0:40 offset1:44
	ds_read2st64_b64 v[212:215], v139 offset0:48 offset1:52
	ds_read2st64_b64 v[252:255], v139 offset0:56 offset1:60
	v_add_u32_e32 v77, 0x2000, v77
	v_add_u32_e32 v15, 0x200, v62
	v_mov_b32_e32 v62, v15
	v_and_b32_e32 v241, 0xff, v62
	v_cvt_f32_u32_e32 v250, v241
	v_mul_f32_e32 v250, 0x39800000, v250
	v_cos_f32_e32 v218, v250
	v_sin_f32_e32 v219, v250
	s_nop 1
	s_nop 0
	v_pk_mul_f32 v[128:129], v[218:219], v[218:219] op_sel:[1,1] op_sel_hi:[1,0]
	s_nop 0
	v_pk_fma_f32 v[220:221], v[218:219], v[218:219], v[128:129] op_sel_hi:[0,1,1] neg_lo:[0,0,1]
	s_nop 0
	v_pk_mul_f32 v[128:129], v[220:221], v[218:219] op_sel:[1,1] op_sel_hi:[1,0]
	s_nop 0
	v_pk_fma_f32 v[222:223], v[220:221], v[218:219], v[128:129] op_sel_hi:[0,1,1] neg_lo:[0,0,1]
	v_pk_mul_f32 v[128:129], v[220:221], v[220:221] op_sel:[1,1] op_sel_hi:[1,0]
	s_nop 0
	v_pk_fma_f32 v[244:245], v[220:221], v[220:221], v[128:129] op_sel_hi:[0,1,1] neg_lo:[0,0,1]
	s_nop 0
	v_mul_f32_e32 v241, 0xbec3ef15, v219
	v_mul_f32_e32 v250, 0x3ec3ef15, v218
	v_fmamk_f32 v224, v218, 0x3f6c835e, v241
	v_fmamk_f32 v225, v219, 0x3f6c835e, v250
	v_mul_f32_e32 v241, 0xbf3504f3, v219
	v_mul_f32_e32 v250, 0x3f3504f3, v218
	v_fmamk_f32 v230, v218, 0x3f3504f3, v241
	v_fmamk_f32 v231, v219, 0x3f3504f3, v250
	v_mul_f32_e32 v241, 0xbf6c835e, v219
	v_mul_f32_e32 v250, 0x3f6c835e, v218
	v_fmamk_f32 v236, v218, 0x3ec3ef15, v241
	v_fmamk_f32 v237, v219, 0x3ec3ef15, v250
	v_mul_f32_e32 v241, 0xbf3504f3, v221
	v_mul_f32_e32 v250, 0x3f3504f3, v220
	v_fmamk_f32 v226, v220, 0x3f3504f3, v241
	v_fmamk_f32 v227, v221, 0x3f3504f3, v250
	v_mul_f32_e32 v241, 0xbf800000, v221
	v_mul_f32_e32 v250, 0x3f800000, v220
	v_fmamk_f32 v232, v220, 0x00000000, v241
	v_fmamk_f32 v233, v221, 0x00000000, v250
	v_mul_f32_e32 v241, 0xbf3504f3, v221
	v_mul_f32_e32 v250, 0x3f3504f3, v220
	v_fmamk_f32 v238, v220, 0xbf3504f3, v241
	v_fmamk_f32 v239, v221, 0xbf3504f3, v250
	v_mul_f32_e32 v241, 0xbf6c835e, v223
	v_mul_f32_e32 v250, 0x3f6c835e, v222
	v_fmamk_f32 v228, v222, 0x3ec3ef15, v241
	v_fmamk_f32 v229, v223, 0x3ec3ef15, v250
	v_mul_f32_e32 v241, 0xbf3504f3, v223
	v_mul_f32_e32 v250, 0x3f3504f3, v222
	v_fmamk_f32 v234, v222, 0xbf3504f3, v241
	v_fmamk_f32 v235, v223, 0xbf3504f3, v250
	v_mul_f32_e32 v241, 0x3ec3ef15, v223
	v_mul_f32_e32 v250, 0xbec3ef15, v222
	v_fmamk_f32 v242, v222, 0xbf6c835e, v241
	v_fmamk_f32 v243, v223, 0xbf6c835e, v250
	v_pk_mul_f32 v[128:129], v[244:245], v[244:245] op_sel:[1,1] op_sel_hi:[1,0]
	s_nop 0
	v_pk_fma_f32 v[246:247], v[244:245], v[244:245], v[128:129] op_sel_hi:[0,1,1] neg_lo:[0,0,1]
	s_nop 0
	v_pk_mul_f32 v[128:129], v[246:247], v[244:245] op_sel:[1,1] op_sel_hi:[1,0]
	s_nop 0
	v_pk_fma_f32 v[248:249], v[246:247], v[244:245], v[128:129] op_sel_hi:[0,1,1] neg_lo:[0,0,1]
	s_nop 0
	s_waitcnt lgkmcnt(8)
; DI float2 twid(float r) { return float2{__builtin_amdgcn_cosf(r), -__builtin_amdgcn_sinf(r)}; }
; DI void bfly_inv(float2 s0, float2 s1, float2 s2, float2 s3, float r, float2& o0, float2& o1, float2& o2, float2& o3) {
;   float2 w1 = twid(r), w2 = cmul(w1, w1), w3 = cmul(w2, w1);
;   float2 c0 = s0, c1 = cmulc(s1, w1), c2 = cmulc(s2, w2), c3 = cmulc(s3, w3);
;   float2 t0 = {c0.x + c2.x, c0.y + c2.y}, t1 = {c0.x - c2.x, c0.y - c2.y}, t2 = {c1.x + c3.x, c1.y + c3.y}, t3 = {c1.x - c3.x, c1.y - c3.y};
;   o0 = float2{t0.x + t2.x, t0.y + t2.y}; o2 = float2{t0.x - t2.x, t0.y - t2.y}; o1 = float2{t1.x - t3.y, t1.y + t3.x}; o3 = float2{t1.x + t3.y, t1.y - t3.x};
; }
;     ...
;     for (int q1 = 0; q1 < 4; ++q1) bfly_inv(x[q1][0], x[q1][1], x[q1][2], x[q1][3], (float)jp * invM2, x[q1][0], x[q1][1], x[q1][2], x[q1][3]);
; #pragma unroll
;     for (int q2 = 0; q2 < 4; ++q2) bfly_inv(x[0][q2], x[1][q2], x[2][q2], x[3][q2], (float)(jp + q2 * Q2) * invM1, x[0][q2], x[1][q2], x[2][q2], x[3][q2]);
	v_pk_mul_f32 v[128:129], v[86:87], v[244:245] op_sel:[1,1] op_sel_hi:[1,0]
	v_pk_mul_f32 v[132:133], v[90:91], v[244:245] op_sel:[1,1] op_sel_hi:[1,0]
	v_pk_mul_f32 v[130:131], v[80:81], v[246:247] op_sel:[1,1] op_sel_hi:[1,0]
	v_pk_mul_f32 v[134:135], v[92:93], v[246:247] op_sel:[1,1] op_sel_hi:[1,0]
	v_pk_fma_f32 v[86:87], v[86:87], v[244:245], v[128:129] op_sel_hi:[0,1,1] neg_lo:[0,0,1]
	v_pk_fma_f32 v[90:91], v[90:91], v[244:245], v[132:133] op_sel_hi:[0,1,1] neg_lo:[0,0,1]
	v_pk_mul_f32 v[128:129], v[82:83], v[248:249] op_sel:[1,1] op_sel_hi:[1,0]
	v_pk_mul_f32 v[132:133], v[94:95], v[248:249] op_sel:[1,1] op_sel_hi:[1,0]
	v_pk_fma_f32 v[80:81], v[80:81], v[246:247], v[130:131] op_sel_hi:[0,1,1] neg_lo:[0,0,1]
	v_pk_fma_f32 v[92:93], v[92:93], v[246:247], v[134:135] op_sel_hi:[0,1,1] neg_lo:[0,0,1]
	v_pk_fma_f32 v[82:83], v[82:83], v[248:249], v[128:129] op_sel_hi:[0,1,1] neg_lo:[0,0,1]
	v_pk_fma_f32 v[94:95], v[94:95], v[248:249], v[132:133] op_sel_hi:[0,1,1] neg_lo:[0,0,1]
	v_pk_add_f32 v[112:113], v[84:85], v[80:81]
	v_pk_add_f32 v[120:121], v[88:89], v[92:93]
	v_pk_add_f32 v[116:117], v[86:87], v[82:83]
	v_pk_add_f32 v[124:125], v[90:91], v[94:95]
	v_pk_add_f32 v[114:115], v[84:85], v[80:81] neg_lo:[0,1] neg_hi:[0,1]
	v_pk_add_f32 v[122:123], v[88:89], v[92:93] neg_lo:[0,1] neg_hi:[0,1]
	v_pk_add_f32 v[118:119], v[86:87], v[82:83] neg_lo:[0,1] neg_hi:[0,1]
	v_pk_add_f32 v[126:127], v[90:91], v[94:95] neg_lo:[0,1] neg_hi:[0,1]
	v_pk_add_f32 v[84:85], v[112:113], v[116:117]
	v_pk_add_f32 v[88:89], v[120:121], v[124:125]
	v_pk_add_f32 v[80:81], v[112:113], v[116:117] neg_lo:[0,1] neg_hi:[0,1]
	v_pk_add_f32 v[92:93], v[120:121], v[124:125] neg_lo:[0,1] neg_hi:[0,1]
	v_pk_add_f32 v[86:87], v[114:115], v[118:119] op_sel:[0,1] op_sel_hi:[1,0] neg_lo:[0,1]
	v_pk_add_f32 v[90:91], v[122:123], v[126:127] op_sel:[0,1] op_sel_hi:[1,0] neg_lo:[0,1]
	v_pk_add_f32 v[82:83], v[114:115], v[118:119] op_sel:[0,1] op_sel_hi:[1,0] neg_hi:[0,1]
	v_pk_add_f32 v[94:95], v[122:123], v[126:127] op_sel:[0,1] op_sel_hi:[1,0] neg_hi:[0,1]
	v_pk_mul_f32 v[128:129], v[98:99], v[244:245] op_sel:[1,1] op_sel_hi:[1,0]
	v_pk_mul_f32 v[132:133], v[106:107], v[244:245] op_sel:[1,1] op_sel_hi:[1,0]
	v_pk_mul_f32 v[130:131], v[100:101], v[246:247] op_sel:[1,1] op_sel_hi:[1,0]
	v_pk_mul_f32 v[134:135], v[108:109], v[246:247] op_sel:[1,1] op_sel_hi:[1,0]
	v_pk_fma_f32 v[98:99], v[98:99], v[244:245], v[128:129] op_sel_hi:[0,1,1] neg_lo:[0,0,1]
	v_pk_fma_f32 v[106:107], v[106:107], v[244:245], v[132:133] op_sel_hi:[0,1,1] neg_lo:[0,0,1]
	v_pk_mul_f32 v[128:129], v[102:103], v[248:249] op_sel:[1,1] op_sel_hi:[1,0]
	v_pk_mul_f32 v[132:133], v[110:111], v[248:249] op_sel:[1,1] op_sel_hi:[1,0]
	v_pk_fma_f32 v[100:101], v[100:101], v[246:247], v[130:131] op_sel_hi:[0,1,1] neg_lo:[0,0,1]
	v_pk_fma_f32 v[108:109], v[108:109], v[246:247], v[134:135] op_sel_hi:[0,1,1] neg_lo:[0,0,1]
	v_pk_fma_f32 v[102:103], v[102:103], v[248:249], v[128:129] op_sel_hi:[0,1,1] neg_lo:[0,0,1]
	v_pk_fma_f32 v[110:111], v[110:111], v[248:249], v[132:133] op_sel_hi:[0,1,1] neg_lo:[0,0,1]
	v_pk_add_f32 v[112:113], v[96:97], v[100:101]
	v_pk_add_f32 v[120:121], v[104:105], v[108:109]
	v_pk_add_f32 v[116:117], v[98:99], v[102:103]
	v_pk_add_f32 v[124:125], v[106:107], v[110:111]
	v_pk_add_f32 v[114:115], v[96:97], v[100:101] neg_lo:[0,1] neg_hi:[0,1]
	v_pk_add_f32 v[122:123], v[104:105], v[108:109] neg_lo:[0,1] neg_hi:[0,1]
	v_pk_add_f32 v[118:119], v[98:99], v[102:103] neg_lo:[0,1] neg_hi:[0,1]
	v_pk_add_f32 v[126:127], v[106:107], v[110:111] neg_lo:[0,1] neg_hi:[0,1]
	v_pk_add_f32 v[96:97], v[112:113], v[116:117]
	v_pk_add_f32 v[104:105], v[120:121], v[124:125]
	v_pk_add_f32 v[100:101], v[112:113], v[116:117] neg_lo:[0,1] neg_hi:[0,1]
	v_pk_add_f32 v[108:109], v[120:121], v[124:125] neg_lo:[0,1] neg_hi:[0,1]
	v_pk_add_f32 v[98:99], v[114:115], v[118:119] op_sel:[0,1] op_sel_hi:[1,0] neg_lo:[0,1]
	v_pk_add_f32 v[106:107], v[122:123], v[126:127] op_sel:[0,1] op_sel_hi:[1,0] neg_lo:[0,1]
	v_pk_add_f32 v[102:103], v[114:115], v[118:119] op_sel:[0,1] op_sel_hi:[1,0] neg_hi:[0,1]
	v_pk_add_f32 v[110:111], v[122:123], v[126:127] op_sel:[0,1] op_sel_hi:[1,0] neg_hi:[0,1]
	v_pk_mul_f32 v[128:129], v[88:89], v[218:219] op_sel:[1,1] op_sel_hi:[1,0]
	v_pk_mul_f32 v[132:133], v[90:91], v[224:225] op_sel:[1,1] op_sel_hi:[1,0]
	v_pk_mul_f32 v[130:131], v[96:97], v[220:221] op_sel:[1,1] op_sel_hi:[1,0]
	v_pk_mul_f32 v[134:135], v[98:99], v[226:227] op_sel:[1,1] op_sel_hi:[1,0]
	v_pk_fma_f32 v[88:89], v[88:89], v[218:219], v[128:129] op_sel_hi:[0,1,1] neg_lo:[0,0,1]
	v_pk_fma_f32 v[90:91], v[90:91], v[224:225], v[132:133] op_sel_hi:[0,1,1] neg_lo:[0,0,1]
	v_pk_mul_f32 v[128:129], v[104:105], v[222:223] op_sel:[1,1] op_sel_hi:[1,0]
	v_pk_mul_f32 v[132:133], v[106:107], v[228:229] op_sel:[1,1] op_sel_hi:[1,0]
	v_pk_fma_f32 v[96:97], v[96:97], v[220:221], v[130:131] op_sel_hi:[0,1,1] neg_lo:[0,0,1]
	v_pk_fma_f32 v[98:99], v[98:99], v[226:227], v[134:135] op_sel_hi:[0,1,1] neg_lo:[0,0,1]
	v_pk_fma_f32 v[104:105], v[104:105], v[222:223], v[128:129] op_sel_hi:[0,1,1] neg_lo:[0,0,1]
	v_pk_fma_f32 v[106:107], v[106:107], v[228:229], v[132:133] op_sel_hi:[0,1,1] neg_lo:[0,0,1]
	v_pk_add_f32 v[112:113], v[84:85], v[96:97]
	v_pk_add_f32 v[120:121], v[86:87], v[98:99]
	v_pk_add_f32 v[116:117], v[88:89], v[104:105]
	v_pk_add_f32 v[124:125], v[90:91], v[106:107]
	v_pk_add_f32 v[114:115], v[84:85], v[96:97] neg_lo:[0,1] neg_hi:[0,1]
	v_pk_add_f32 v[122:123], v[86:87], v[98:99] neg_lo:[0,1] neg_hi:[0,1]
	v_pk_add_f32 v[118:119], v[88:89], v[104:105] neg_lo:[0,1] neg_hi:[0,1]
	v_pk_add_f32 v[126:127], v[90:91], v[106:107] neg_lo:[0,1] neg_hi:[0,1]
; DI float2 twid(float r) { return float2{__builtin_amdgcn_cosf(r), -__builtin_amdgcn_sinf(r)}; }
; DI void bfly_inv(float2 s0, float2 s1, float2 s2, float2 s3, float r, float2& o0, float2& o1, float2& o2, float2& o3) {
;   float2 w1 = twid(r), w2 = cmul(w1, w1), w3 = cmul(w2, w1);
;   float2 c0 = s0, c1 = cmulc(s1, w1), c2 = cmulc(s2, w2), c3 = cmulc(s3, w3);
;   float2 t0 = {c0.x + c2.x, c0.y + c2.y}, t1 = {c0.x - c2.x, c0.y - c2.y}, t2 = {c1.x + c3.x, c1.y + c3.y}, t3 = {c1.x - c3.x, c1.y - c3.y};
;   o0 = float2{t0.x + t2.x, t0.y + t2.y}; o2 = float2{t0.x - t2.x, t0.y - t2.y}; o1 = float2{t1.x - t3.y, t1.y + t3.x}; o3 = float2{t1.x + t3.y, t1.y - t3.x};
; }
;   const int lq1 = lq2 + 2, Q1 = 1 << lq1, Q2 = 1 << lq2; const float invM1 = 1.f / (float)(4 << lq1), invM2 = 1.f / (float)(4 << lq2);
;   for (int gg = tid; gg < NBT * (N / 16); gg += NTHR) { const int g = gg & (N / 16 - 1); float2* z = z0 + (gg / (N / 16)) * N; const int jp = g & (Q2 - 1), base = ((g >> lq2) << (lq2 + 4)) + jp; float2 x[4][4];
; #pragma unroll
;     for (int q1 = 0; q1 < 4; ++q1)
; #pragma unroll
;       for (int q2 = 0; q2 < 4; ++q2) x[q1][q2] = z[base + q1 * Q1 + q2 * Q2];
; #pragma unroll
;     for (int q1 = 0; q1 < 4; ++q1) bfly_inv(x[q1][0], x[q1][1], x[q1][2], x[q1][3], (float)jp * invM2, x[q1][0], x[q1][1], x[q1][2], x[q1][3]);
; #pragma unroll
;     for (int q2 = 0; q2 < 4; ++q2) bfly_inv(x[0][q2], x[1][q2], x[2][q2], x[3][q2], (float)(jp + q2 * Q2) * invM1, x[0][q2], x[1][q2], x[2][q2], x[3][q2]);
; #pragma unroll
;     for (int q1 = 0; q1 < 4; ++q1)
; #pragma unroll
;       for (int q2 = 0; q2 < 4; ++q2) z[base + q1 * Q1 + q2 * Q2] = x[q1][q2]; }
;   __syncthreads();
; }
	v_pk_add_f32 v[84:85], v[112:113], v[116:117]
	v_pk_add_f32 v[86:87], v[120:121], v[124:125]
	v_pk_add_f32 v[96:97], v[112:113], v[116:117] neg_lo:[0,1] neg_hi:[0,1]
	v_pk_add_f32 v[98:99], v[120:121], v[124:125] neg_lo:[0,1] neg_hi:[0,1]
	v_pk_add_f32 v[88:89], v[114:115], v[118:119] op_sel:[0,1] op_sel_hi:[1,0] neg_lo:[0,1]
	v_pk_add_f32 v[90:91], v[122:123], v[126:127] op_sel:[0,1] op_sel_hi:[1,0] neg_lo:[0,1]
	v_pk_add_f32 v[104:105], v[114:115], v[118:119] op_sel:[0,1] op_sel_hi:[1,0] neg_hi:[0,1]
	v_pk_add_f32 v[106:107], v[122:123], v[126:127] op_sel:[0,1] op_sel_hi:[1,0] neg_hi:[0,1]
	v_pk_mul_f32 v[128:129], v[92:93], v[230:231] op_sel:[1,1] op_sel_hi:[1,0]
	v_pk_mul_f32 v[132:133], v[94:95], v[236:237] op_sel:[1,1] op_sel_hi:[1,0]
	v_pk_mul_f32 v[130:131], v[100:101], v[232:233] op_sel:[1,1] op_sel_hi:[1,0]
	v_pk_mul_f32 v[134:135], v[102:103], v[238:239] op_sel:[1,1] op_sel_hi:[1,0]
	v_pk_fma_f32 v[92:93], v[92:93], v[230:231], v[128:129] op_sel_hi:[0,1,1] neg_lo:[0,0,1]
	v_pk_fma_f32 v[94:95], v[94:95], v[236:237], v[132:133] op_sel_hi:[0,1,1] neg_lo:[0,0,1]
	v_pk_mul_f32 v[128:129], v[108:109], v[234:235] op_sel:[1,1] op_sel_hi:[1,0]
	v_pk_mul_f32 v[132:133], v[110:111], v[242:243] op_sel:[1,1] op_sel_hi:[1,0]
	v_pk_fma_f32 v[100:101], v[100:101], v[232:233], v[130:131] op_sel_hi:[0,1,1] neg_lo:[0,0,1]
	v_pk_fma_f32 v[102:103], v[102:103], v[238:239], v[134:135] op_sel_hi:[0,1,1] neg_lo:[0,0,1]
	v_pk_fma_f32 v[108:109], v[108:109], v[234:235], v[128:129] op_sel_hi:[0,1,1] neg_lo:[0,0,1]
	v_pk_fma_f32 v[110:111], v[110:111], v[242:243], v[132:133] op_sel_hi:[0,1,1] neg_lo:[0,0,1]
	v_pk_add_f32 v[112:113], v[80:81], v[100:101]
	v_pk_add_f32 v[120:121], v[82:83], v[102:103]
	v_pk_add_f32 v[116:117], v[92:93], v[108:109]
	v_pk_add_f32 v[124:125], v[94:95], v[110:111]
	v_pk_add_f32 v[114:115], v[80:81], v[100:101] neg_lo:[0,1] neg_hi:[0,1]
	v_pk_add_f32 v[122:123], v[82:83], v[102:103] neg_lo:[0,1] neg_hi:[0,1]
	v_pk_add_f32 v[118:119], v[92:93], v[108:109] neg_lo:[0,1] neg_hi:[0,1]
	v_pk_add_f32 v[126:127], v[94:95], v[110:111] neg_lo:[0,1] neg_hi:[0,1]
	v_pk_add_f32 v[80:81], v[112:113], v[116:117]
	v_pk_add_f32 v[82:83], v[120:121], v[124:125]
	v_pk_add_f32 v[100:101], v[112:113], v[116:117] neg_lo:[0,1] neg_hi:[0,1]
	v_pk_add_f32 v[102:103], v[120:121], v[124:125] neg_lo:[0,1] neg_hi:[0,1]
	v_pk_add_f32 v[92:93], v[114:115], v[118:119] op_sel:[0,1] op_sel_hi:[1,0] neg_lo:[0,1]
	v_pk_add_f32 v[94:95], v[122:123], v[126:127] op_sel:[0,1] op_sel_hi:[1,0] neg_lo:[0,1]
	v_pk_add_f32 v[108:109], v[114:115], v[118:119] op_sel:[0,1] op_sel_hi:[1,0] neg_hi:[0,1]
	v_pk_add_f32 v[110:111], v[122:123], v[126:127] op_sel:[0,1] op_sel_hi:[1,0] neg_hi:[0,1]
	s_nop 0
	ds_write2st64_b64 v251, v[84:85], v[86:87] offset1:4
	ds_write2st64_b64 v251, v[80:81], v[82:83] offset0:8 offset1:12
	ds_write2st64_b64 v251, v[88:89], v[90:91] offset0:16 offset1:20
	ds_write2st64_b64 v251, v[92:93], v[94:95] offset0:24 offset1:28
	ds_write2st64_b64 v251, v[96:97], v[98:99] offset0:32 offset1:36
	ds_write2st64_b64 v251, v[100:101], v[102:103] offset0:40 offset1:44
	ds_write2st64_b64 v251, v[104:105], v[106:107] offset0:48 offset1:52
	ds_write2st64_b64 v251, v[108:109], v[110:111] offset0:56 offset1:60
	s_waitcnt lgkmcnt(8)
	v_pk_mul_f32 v[128:129], v[194:195], v[244:245] op_sel:[1,1] op_sel_hi:[1,0]
	v_pk_mul_f32 v[132:133], v[198:199], v[244:245] op_sel:[1,1] op_sel_hi:[1,0]
	v_pk_mul_f32 v[130:131], v[188:189], v[246:247] op_sel:[1,1] op_sel_hi:[1,0]
	v_pk_mul_f32 v[134:135], v[200:201], v[246:247] op_sel:[1,1] op_sel_hi:[1,0]
	v_pk_fma_f32 v[194:195], v[194:195], v[244:245], v[128:129] op_sel_hi:[0,1,1] neg_lo:[0,0,1]
	v_pk_fma_f32 v[198:199], v[198:199], v[244:245], v[132:133] op_sel_hi:[0,1,1] neg_lo:[0,0,1]
	v_pk_mul_f32 v[128:129], v[190:191], v[248:249] op_sel:[1,1] op_sel_hi:[1,0]
	v_pk_mul_f32 v[132:133], v[202:203], v[248:249] op_sel:[1,1] op_sel_hi:[1,0]
	v_pk_fma_f32 v[188:189], v[188:189], v[246:247], v[130:131] op_sel_hi:[0,1,1] neg_lo:[0,0,1]
	v_pk_fma_f32 v[200:201], v[200:201], v[246:247], v[134:135] op_sel_hi:[0,1,1] neg_lo:[0,0,1]
	v_pk_fma_f32 v[190:191], v[190:191], v[248:249], v[128:129] op_sel_hi:[0,1,1] neg_lo:[0,0,1]
	v_pk_fma_f32 v[202:203], v[202:203], v[248:249], v[132:133] op_sel_hi:[0,1,1] neg_lo:[0,0,1]
	v_pk_add_f32 v[112:113], v[192:193], v[188:189]
	v_pk_add_f32 v[120:121], v[196:197], v[200:201]
	v_pk_add_f32 v[116:117], v[194:195], v[190:191]
	v_pk_add_f32 v[124:125], v[198:199], v[202:203]
	v_pk_add_f32 v[114:115], v[192:193], v[188:189] neg_lo:[0,1] neg_hi:[0,1]
	v_pk_add_f32 v[122:123], v[196:197], v[200:201] neg_lo:[0,1] neg_hi:[0,1]
	v_pk_add_f32 v[118:119], v[194:195], v[190:191] neg_lo:[0,1] neg_hi:[0,1]
	v_pk_add_f32 v[126:127], v[198:199], v[202:203] neg_lo:[0,1] neg_hi:[0,1]
	v_pk_add_f32 v[192:193], v[112:113], v[116:117]
	v_pk_add_f32 v[196:197], v[120:121], v[124:125]
	v_pk_add_f32 v[188:189], v[112:113], v[116:117] neg_lo:[0,1] neg_hi:[0,1]
	v_pk_add_f32 v[200:201], v[120:121], v[124:125] neg_lo:[0,1] neg_hi:[0,1]
	v_pk_add_f32 v[194:195], v[114:115], v[118:119] op_sel:[0,1] op_sel_hi:[1,0] neg_lo:[0,1]
	v_pk_add_f32 v[198:199], v[122:123], v[126:127] op_sel:[0,1] op_sel_hi:[1,0] neg_lo:[0,1]
	v_pk_add_f32 v[190:191], v[114:115], v[118:119] op_sel:[0,1] op_sel_hi:[1,0] neg_hi:[0,1]
	v_pk_add_f32 v[202:203], v[122:123], v[126:127] op_sel:[0,1] op_sel_hi:[1,0] neg_hi:[0,1]
	v_pk_mul_f32 v[128:129], v[206:207], v[244:245] op_sel:[1,1] op_sel_hi:[1,0]
	v_pk_mul_f32 v[132:133], v[214:215], v[244:245] op_sel:[1,1] op_sel_hi:[1,0]
	v_pk_mul_f32 v[130:131], v[208:209], v[246:247] op_sel:[1,1] op_sel_hi:[1,0]
; DI float2 twid(float r) { return float2{__builtin_amdgcn_cosf(r), -__builtin_amdgcn_sinf(r)}; }
; DI void bfly_inv(float2 s0, float2 s1, float2 s2, float2 s3, float r, float2& o0, float2& o1, float2& o2, float2& o3) {
;   float2 w1 = twid(r), w2 = cmul(w1, w1), w3 = cmul(w2, w1);
;   float2 c0 = s0, c1 = cmulc(s1, w1), c2 = cmulc(s2, w2), c3 = cmulc(s3, w3);
;   float2 t0 = {c0.x + c2.x, c0.y + c2.y}, t1 = {c0.x - c2.x, c0.y - c2.y}, t2 = {c1.x + c3.x, c1.y + c3.y}, t3 = {c1.x - c3.x, c1.y - c3.y};
;   o0 = float2{t0.x + t2.x, t0.y + t2.y}; o2 = float2{t0.x - t2.x, t0.y - t2.y}; o1 = float2{t1.x - t3.y, t1.y + t3.x}; o3 = float2{t1.x + t3.y, t1.y - t3.x};
; }
;   const int lq1 = lq2 + 2, Q1 = 1 << lq1, Q2 = 1 << lq2; const float invM1 = 1.f / (float)(4 << lq1), invM2 = 1.f / (float)(4 << lq2);
;   for (int gg = tid; gg < NBT * (N / 16); gg += NTHR) { const int g = gg & (N / 16 - 1); float2* z = z0 + (gg / (N / 16)) * N; const int jp = g & (Q2 - 1), base = ((g >> lq2) << (lq2 + 4)) + jp; float2 x[4][4];
; #pragma unroll
;     for (int q1 = 0; q1 < 4; ++q1)
; #pragma unroll
;       for (int q2 = 0; q2 < 4; ++q2) x[q1][q2] = z[base + q1 * Q1 + q2 * Q2];
; #pragma unroll
;     for (int q1 = 0; q1 < 4; ++q1) bfly_inv(x[q1][0], x[q1][1], x[q1][2], x[q1][3], (float)jp * invM2, x[q1][0], x[q1][1], x[q1][2], x[q1][3]);
; #pragma unroll
;     for (int q2 = 0; q2 < 4; ++q2) bfly_inv(x[0][q2], x[1][q2], x[2][q2], x[3][q2], (float)(jp + q2 * Q2) * invM1, x[0][q2], x[1][q2], x[2][q2], x[3][q2]);
; #pragma unroll
;     for (int q1 = 0; q1 < 4; ++q1)
; #pragma unroll
;       for (int q2 = 0; q2 < 4; ++q2) z[base + q1 * Q1 + q2 * Q2] = x[q1][q2]; }
;   __syncthreads();
; }
	v_pk_mul_f32 v[134:135], v[252:253], v[246:247] op_sel:[1,1] op_sel_hi:[1,0]
	v_pk_fma_f32 v[206:207], v[206:207], v[244:245], v[128:129] op_sel_hi:[0,1,1] neg_lo:[0,0,1]
	v_pk_fma_f32 v[214:215], v[214:215], v[244:245], v[132:133] op_sel_hi:[0,1,1] neg_lo:[0,0,1]
	v_pk_mul_f32 v[128:129], v[210:211], v[248:249] op_sel:[1,1] op_sel_hi:[1,0]
	v_pk_mul_f32 v[132:133], v[254:255], v[248:249] op_sel:[1,1] op_sel_hi:[1,0]
	v_pk_fma_f32 v[208:209], v[208:209], v[246:247], v[130:131] op_sel_hi:[0,1,1] neg_lo:[0,0,1]
	v_pk_fma_f32 v[252:253], v[252:253], v[246:247], v[134:135] op_sel_hi:[0,1,1] neg_lo:[0,0,1]
	v_pk_fma_f32 v[210:211], v[210:211], v[248:249], v[128:129] op_sel_hi:[0,1,1] neg_lo:[0,0,1]
	v_pk_fma_f32 v[254:255], v[254:255], v[248:249], v[132:133] op_sel_hi:[0,1,1] neg_lo:[0,0,1]
	v_pk_add_f32 v[112:113], v[204:205], v[208:209]
	v_pk_add_f32 v[120:121], v[212:213], v[252:253]
	v_pk_add_f32 v[116:117], v[206:207], v[210:211]
	v_pk_add_f32 v[124:125], v[214:215], v[254:255]
	v_pk_add_f32 v[114:115], v[204:205], v[208:209] neg_lo:[0,1] neg_hi:[0,1]
	v_pk_add_f32 v[122:123], v[212:213], v[252:253] neg_lo:[0,1] neg_hi:[0,1]
	v_pk_add_f32 v[118:119], v[206:207], v[210:211] neg_lo:[0,1] neg_hi:[0,1]
	v_pk_add_f32 v[126:127], v[214:215], v[254:255] neg_lo:[0,1] neg_hi:[0,1]
	v_pk_add_f32 v[204:205], v[112:113], v[116:117]
	v_pk_add_f32 v[212:213], v[120:121], v[124:125]
	v_pk_add_f32 v[208:209], v[112:113], v[116:117] neg_lo:[0,1] neg_hi:[0,1]
	v_pk_add_f32 v[252:253], v[120:121], v[124:125] neg_lo:[0,1] neg_hi:[0,1]
	v_pk_add_f32 v[206:207], v[114:115], v[118:119] op_sel:[0,1] op_sel_hi:[1,0] neg_lo:[0,1]
	v_pk_add_f32 v[214:215], v[122:123], v[126:127] op_sel:[0,1] op_sel_hi:[1,0] neg_lo:[0,1]
	v_pk_add_f32 v[210:211], v[114:115], v[118:119] op_sel:[0,1] op_sel_hi:[1,0] neg_hi:[0,1]
	v_pk_add_f32 v[254:255], v[122:123], v[126:127] op_sel:[0,1] op_sel_hi:[1,0] neg_hi:[0,1]
	v_pk_mul_f32 v[128:129], v[196:197], v[218:219] op_sel:[1,1] op_sel_hi:[1,0]
	v_pk_mul_f32 v[132:133], v[198:199], v[224:225] op_sel:[1,1] op_sel_hi:[1,0]
	v_pk_mul_f32 v[130:131], v[204:205], v[220:221] op_sel:[1,1] op_sel_hi:[1,0]
	v_pk_mul_f32 v[134:135], v[206:207], v[226:227] op_sel:[1,1] op_sel_hi:[1,0]
	v_pk_fma_f32 v[196:197], v[196:197], v[218:219], v[128:129] op_sel_hi:[0,1,1] neg_lo:[0,0,1]
	v_pk_fma_f32 v[198:199], v[198:199], v[224:225], v[132:133] op_sel_hi:[0,1,1] neg_lo:[0,0,1]
	v_pk_mul_f32 v[128:129], v[212:213], v[222:223] op_sel:[1,1] op_sel_hi:[1,0]
	v_pk_mul_f32 v[132:133], v[214:215], v[228:229] op_sel:[1,1] op_sel_hi:[1,0]
	v_pk_fma_f32 v[204:205], v[204:205], v[220:221], v[130:131] op_sel_hi:[0,1,1] neg_lo:[0,0,1]
	v_pk_fma_f32 v[206:207], v[206:207], v[226:227], v[134:135] op_sel_hi:[0,1,1] neg_lo:[0,0,1]
	v_pk_fma_f32 v[212:213], v[212:213], v[222:223], v[128:129] op_sel_hi:[0,1,1] neg_lo:[0,0,1]
	v_pk_fma_f32 v[214:215], v[214:215], v[228:229], v[132:133] op_sel_hi:[0,1,1] neg_lo:[0,0,1]
	v_pk_add_f32 v[112:113], v[192:193], v[204:205]
	v_pk_add_f32 v[120:121], v[194:195], v[206:207]
	v_pk_add_f32 v[116:117], v[196:197], v[212:213]
	v_pk_add_f32 v[124:125], v[198:199], v[214:215]
	v_pk_add_f32 v[114:115], v[192:193], v[204:205] neg_lo:[0,1] neg_hi:[0,1]
	v_pk_add_f32 v[122:123], v[194:195], v[206:207] neg_lo:[0,1] neg_hi:[0,1]
	v_pk_add_f32 v[118:119], v[196:197], v[212:213] neg_lo:[0,1] neg_hi:[0,1]
	v_pk_add_f32 v[126:127], v[198:199], v[214:215] neg_lo:[0,1] neg_hi:[0,1]
	v_pk_add_f32 v[192:193], v[112:113], v[116:117]
	v_pk_add_f32 v[194:195], v[120:121], v[124:125]
	v_pk_add_f32 v[204:205], v[112:113], v[116:117] neg_lo:[0,1] neg_hi:[0,1]
	v_pk_add_f32 v[206:207], v[120:121], v[124:125] neg_lo:[0,1] neg_hi:[0,1]
	v_pk_add_f32 v[196:197], v[114:115], v[118:119] op_sel:[0,1] op_sel_hi:[1,0] neg_lo:[0,1]
	v_pk_add_f32 v[198:199], v[122:123], v[126:127] op_sel:[0,1] op_sel_hi:[1,0] neg_lo:[0,1]
	v_pk_add_f32 v[212:213], v[114:115], v[118:119] op_sel:[0,1] op_sel_hi:[1,0] neg_hi:[0,1]
	v_pk_add_f32 v[214:215], v[122:123], v[126:127] op_sel:[0,1] op_sel_hi:[1,0] neg_hi:[0,1]
	v_pk_mul_f32 v[128:129], v[200:201], v[230:231] op_sel:[1,1] op_sel_hi:[1,0]
	v_pk_mul_f32 v[132:133], v[202:203], v[236:237] op_sel:[1,1] op_sel_hi:[1,0]
	v_pk_mul_f32 v[130:131], v[208:209], v[232:233] op_sel:[1,1] op_sel_hi:[1,0]
	v_pk_mul_f32 v[134:135], v[210:211], v[238:239] op_sel:[1,1] op_sel_hi:[1,0]
	v_pk_fma_f32 v[200:201], v[200:201], v[230:231], v[128:129] op_sel_hi:[0,1,1] neg_lo:[0,0,1]
	v_pk_fma_f32 v[202:203], v[202:203], v[236:237], v[132:133] op_sel_hi:[0,1,1] neg_lo:[0,0,1]
	v_pk_mul_f32 v[128:129], v[252:253], v[234:235] op_sel:[1,1] op_sel_hi:[1,0]
	v_pk_mul_f32 v[132:133], v[254:255], v[242:243] op_sel:[1,1] op_sel_hi:[1,0]
	v_pk_fma_f32 v[208:209], v[208:209], v[232:233], v[130:131] op_sel_hi:[0,1,1] neg_lo:[0,0,1]
	v_pk_fma_f32 v[210:211], v[210:211], v[238:239], v[134:135] op_sel_hi:[0,1,1] neg_lo:[0,0,1]
	v_pk_fma_f32 v[252:253], v[252:253], v[234:235], v[128:129] op_sel_hi:[0,1,1] neg_lo:[0,0,1]
	v_pk_fma_f32 v[254:255], v[254:255], v[242:243], v[132:133] op_sel_hi:[0,1,1] neg_lo:[0,0,1]
	v_pk_add_f32 v[112:113], v[188:189], v[208:209]
	v_pk_add_f32 v[120:121], v[190:191], v[210:211]
	v_pk_add_f32 v[116:117], v[200:201], v[252:253]
	v_pk_add_f32 v[124:125], v[202:203], v[254:255]
	v_pk_add_f32 v[114:115], v[188:189], v[208:209] neg_lo:[0,1] neg_hi:[0,1]
	v_pk_add_f32 v[122:123], v[190:191], v[210:211] neg_lo:[0,1] neg_hi:[0,1]
	v_pk_add_f32 v[118:119], v[200:201], v[252:253] neg_lo:[0,1] neg_hi:[0,1]
	v_pk_add_f32 v[126:127], v[202:203], v[254:255] neg_lo:[0,1] neg_hi:[0,1]
	v_pk_add_f32 v[188:189], v[112:113], v[116:117]
	v_pk_add_f32 v[190:191], v[120:121], v[124:125]
	v_pk_add_f32 v[208:209], v[112:113], v[116:117] neg_lo:[0,1] neg_hi:[0,1]
	v_pk_add_f32 v[210:211], v[120:121], v[124:125] neg_lo:[0,1] neg_hi:[0,1]
	v_pk_add_f32 v[200:201], v[114:115], v[118:119] op_sel:[0,1] op_sel_hi:[1,0] neg_lo:[0,1]
	v_pk_add_f32 v[202:203], v[122:123], v[126:127] op_sel:[0,1] op_sel_hi:[1,0] neg_lo:[0,1]
	v_pk_add_f32 v[252:253], v[114:115], v[118:119] op_sel:[0,1] op_sel_hi:[1,0] neg_hi:[0,1]
	v_pk_add_f32 v[254:255], v[122:123], v[126:127] op_sel:[0,1] op_sel_hi:[1,0] neg_hi:[0,1]
	s_nop 0
	ds_write2st64_b64 v139, v[192:193], v[194:195] offset1:4
	ds_write2st64_b64 v139, v[188:189], v[190:191] offset0:8 offset1:12
	ds_write2st64_b64 v139, v[196:197], v[198:199] offset0:16 offset1:20
	ds_write2st64_b64 v139, v[200:201], v[202:203] offset0:24 offset1:28
	ds_write2st64_b64 v139, v[204:205], v[206:207] offset0:32 offset1:36
	ds_write2st64_b64 v139, v[208:209], v[210:211] offset0:40 offset1:44
	ds_write2st64_b64 v139, v[212:213], v[214:215] offset0:48 offset1:52
	ds_write2st64_b64 v139, v[252:253], v[254:255] offset0:56 offset1:60
	s_mov_b64 s[0:1], exec
